# stacked: rs-load hoists (GU/IN/Q), EpiRes lane-permuted coalesced epilogue, flat->global
# speedup vs baseline: 1.0211x; 1.0211x over previous
.LBB0_103:
	ds_read_b128 v[128:131], v161
	ds_read_b128 v[154:157], v161 offset:1024
	ds_read_b128 v[166:169], v161 offset:2048
	ds_read_b128 v[170:173], v161 offset:3072
	ds_read_b128 v[174:177], v162
	ds_read_b128 v[178:181], v162 offset:1024
	ds_read_b128 v[182:185], v162 offset:2048
	ds_read_b128 v[186:189], v162 offset:3072
	s_add_u32 s52, s50, 0xfffc0080
	s_addc_u32 s53, s51, -1
	s_cmp_eq_u32 s77, 12
	s_cselect_b32 s55, s33, s53
	s_cselect_b32 s54, s39, s52
	s_cselect_b32 s53, s41, s76
	s_cselect_b32 s52, s43, s49
	v_lshl_add_u64 v[158:159], s[50:51], 0, v[146:147]
	s_add_i32 m0, s63, 0xc000
	ds_read_b128 v[192:195], v163
	ds_read_b128 v[196:199], v163 offset:1024
	ds_read_b128 v[200:203], v163 offset:2048
	ds_read_b128 v[204:207], v163 offset:3072
	ds_read_b128 v[208:211], v163 offset:4096
	ds_read_b128 v[212:215], v163 offset:5120
	ds_read_b128 v[216:219], v163 offset:6144
	ds_read_b128 v[220:223], v163 offset:7168
	global_load_lds_dwordx4 v[158:159], off
	v_lshl_add_u64 v[158:159], s[50:51], 0, v[144:145]
	s_add_i32 m0, s63, 0xe000
	s_nop 0
	global_load_lds_dwordx4 v[158:159], off
	s_waitcnt vmcnt(8)
	s_waitcnt lgkmcnt(0)
	s_barrier
	s_setprio 1
	s_waitcnt lgkmcnt(0)
	v_mfma_f32_16x16x32_bf16 v[124:127], v[128:131], v[192:195], v[124:127]
	v_mfma_f32_16x16x32_bf16 v[120:123], v[166:169], v[192:195], v[120:123]
	v_mfma_f32_16x16x32_bf16 v[108:111], v[128:131], v[200:203], v[108:111]
	v_mfma_f32_16x16x32_bf16 v[104:107], v[166:169], v[200:203], v[104:107]
	v_mfma_f32_16x16x32_bf16 v[92:95], v[128:131], v[208:211], v[92:95]
	v_mfma_f32_16x16x32_bf16 v[88:91], v[166:169], v[208:211], v[88:91]
	v_mfma_f32_16x16x32_bf16 v[76:79], v[128:131], v[216:219], v[76:79]
	v_mfma_f32_16x16x32_bf16 v[72:75], v[166:169], v[216:219], v[72:75]
	v_mfma_f32_16x16x32_bf16 v[124:127], v[154:157], v[196:199], v[124:127]
	v_mfma_f32_16x16x32_bf16 v[120:123], v[170:173], v[196:199], v[120:123]
	v_mfma_f32_16x16x32_bf16 v[108:111], v[154:157], v[204:207], v[108:111]
	v_mfma_f32_16x16x32_bf16 v[104:107], v[170:173], v[204:207], v[104:107]
	v_mfma_f32_16x16x32_bf16 v[92:95], v[154:157], v[212:215], v[92:95]
	v_mfma_f32_16x16x32_bf16 v[88:91], v[170:173], v[212:215], v[88:91]
	v_mfma_f32_16x16x32_bf16 v[76:79], v[154:157], v[220:223], v[76:79]
	v_mfma_f32_16x16x32_bf16 v[72:75], v[170:173], v[220:223], v[72:75]
	s_setprio 0
	s_setprio 1
	v_mfma_f32_16x16x32_bf16 v[116:119], v[174:177], v[192:195], v[116:119]
	v_mfma_f32_16x16x32_bf16 v[112:115], v[182:185], v[192:195], v[112:115]
	v_mfma_f32_16x16x32_bf16 v[100:103], v[174:177], v[200:203], v[100:103]
	v_mfma_f32_16x16x32_bf16 v[96:99], v[182:185], v[200:203], v[96:99]
	v_mfma_f32_16x16x32_bf16 v[84:87], v[174:177], v[208:211], v[84:87]
	v_mfma_f32_16x16x32_bf16 v[80:83], v[182:185], v[208:211], v[80:83]
	v_mfma_f32_16x16x32_bf16 v[68:71], v[174:177], v[216:219], v[68:71]
	v_mfma_f32_16x16x32_bf16 v[64:67], v[182:185], v[216:219], v[64:67]
	v_mfma_f32_16x16x32_bf16 v[116:119], v[178:181], v[196:199], v[116:119]
	v_mfma_f32_16x16x32_bf16 v[112:115], v[186:189], v[196:199], v[112:115]
	v_mfma_f32_16x16x32_bf16 v[100:103], v[178:181], v[204:207], v[100:103]
	v_mfma_f32_16x16x32_bf16 v[96:99], v[186:189], v[204:207], v[96:99]
	v_mfma_f32_16x16x32_bf16 v[84:87], v[178:181], v[212:215], v[84:87]
	v_mfma_f32_16x16x32_bf16 v[80:83], v[186:189], v[212:215], v[80:83]
	v_mfma_f32_16x16x32_bf16 v[68:71], v[178:181], v[220:223], v[68:71]
	v_mfma_f32_16x16x32_bf16 v[64:67], v[186:189], v[220:223], v[64:67]
	s_setprio 0
	s_barrier
	s_add_i32 s78, s71, s60
	v_lshl_add_u64 v[158:159], s[52:53], 0, v[136:137]
	s_mov_b32 m0, s78
	ds_read_b128 v[192:195], v163 offset:16384
	ds_read_b128 v[196:199], v163 offset:17408
	ds_read_b128 v[200:203], v163 offset:18432
	ds_read_b128 v[204:207], v163 offset:19456
	ds_read_b128 v[208:211], v163 offset:20480
	ds_read_b128 v[212:215], v163 offset:21504
	ds_read_b128 v[216:219], v163 offset:22528
	ds_read_b128 v[220:223], v163 offset:23552
	global_load_lds_dwordx4 v[158:159], off
	s_add_i32 m0, s78, 0x2000
	s_add_u32 s78, s52, 0x40000
	v_lshl_add_u64 v[224:225], s[52:53], 0, v[132:133]
	s_addc_u32 s79, s53, 0
	s_add_i32 s80, s72, s60
	global_load_lds_dwordx4 v[224:225], off
	v_lshl_add_u64 v[226:227], s[78:79], 0, v[136:137]
	s_mov_b32 m0, s80
	v_lshl_add_u64 v[228:229], s[54:55], 0, v[134:135]
	global_load_lds_dwordx4 v[226:227], off
	v_lshl_add_u64 v[226:227], s[78:79], 0, v[132:133]
	s_add_i32 m0, s80, 0x2000
	s_nop 0
	global_load_lds_dwordx4 v[226:227], off
	v_lshl_add_u64 v[226:227], s[54:55], 0, v[138:139]
	s_mov_b32 m0, s63
	s_nop 0
	global_load_lds_dwordx4 v[226:227], off
	s_mov_b32 m0, s64
	s_nop 0
	global_load_lds_dwordx4 v[228:229], off
	s_waitcnt vmcnt(8)
	s_waitcnt lgkmcnt(0)
	s_barrier
	s_setprio 1
	s_waitcnt lgkmcnt(0)
	v_mfma_f32_16x16x32_bf16 v[60:63], v[128:131], v[192:195], v[60:63]
	v_mfma_f32_16x16x32_bf16 v[56:59], v[166:169], v[192:195], v[56:59]
	v_mfma_f32_16x16x32_bf16 v[44:47], v[128:131], v[200:203], v[44:47]
	v_mfma_f32_16x16x32_bf16 v[40:43], v[166:169], v[200:203], v[40:43]
	v_mfma_f32_16x16x32_bf16 v[28:31], v[128:131], v[208:211], v[28:31]
	v_mfma_f32_16x16x32_bf16 v[24:27], v[166:169], v[208:211], v[24:27]
	v_mfma_f32_16x16x32_bf16 v[12:15], v[128:131], v[216:219], v[12:15]
	v_mfma_f32_16x16x32_bf16 v[8:11], v[166:169], v[216:219], v[8:11]
	v_mfma_f32_16x16x32_bf16 v[60:63], v[154:157], v[196:199], v[60:63]
	v_mfma_f32_16x16x32_bf16 v[56:59], v[170:173], v[196:199], v[56:59]
	v_mfma_f32_16x16x32_bf16 v[44:47], v[154:157], v[204:207], v[44:47]
	v_mfma_f32_16x16x32_bf16 v[40:43], v[170:173], v[204:207], v[40:43]
	v_mfma_f32_16x16x32_bf16 v[28:31], v[154:157], v[212:215], v[28:31]
	v_mfma_f32_16x16x32_bf16 v[24:27], v[170:173], v[212:215], v[24:27]
	v_mfma_f32_16x16x32_bf16 v[12:15], v[154:157], v[220:223], v[12:15]
	v_mfma_f32_16x16x32_bf16 v[8:11], v[170:173], v[220:223], v[8:11]
	s_setprio 0
	s_setprio 1
	v_mfma_f32_16x16x32_bf16 v[52:55], v[174:177], v[192:195], v[52:55]
	v_mfma_f32_16x16x32_bf16 v[48:51], v[182:185], v[192:195], v[48:51]
	v_mfma_f32_16x16x32_bf16 v[36:39], v[174:177], v[200:203], v[36:39]
	v_mfma_f32_16x16x32_bf16 v[32:35], v[182:185], v[200:203], v[32:35]
	v_mfma_f32_16x16x32_bf16 v[20:23], v[174:177], v[208:211], v[20:23]
	v_mfma_f32_16x16x32_bf16 v[16:19], v[182:185], v[208:211], v[16:19]
	v_mfma_f32_16x16x32_bf16 v[4:7], v[174:177], v[216:219], v[4:7]
	v_mfma_f32_16x16x32_bf16 v[0:3], v[182:185], v[216:219], v[0:3]
	v_mfma_f32_16x16x32_bf16 v[52:55], v[178:181], v[196:199], v[52:55]
	v_mfma_f32_16x16x32_bf16 v[48:51], v[186:189], v[196:199], v[48:51]
	v_mfma_f32_16x16x32_bf16 v[36:39], v[178:181], v[204:207], v[36:39]
	v_mfma_f32_16x16x32_bf16 v[32:35], v[186:189], v[204:207], v[32:35]
	v_mfma_f32_16x16x32_bf16 v[20:23], v[178:181], v[212:215], v[20:23]
	v_mfma_f32_16x16x32_bf16 v[16:19], v[186:189], v[212:215], v[16:19]
	v_mfma_f32_16x16x32_bf16 v[4:7], v[178:181], v[220:223], v[4:7]
	v_mfma_f32_16x16x32_bf16 v[0:3], v[186:189], v[220:223], v[0:3]
	s_setprio 0
	s_barrier
	s_add_i32 s78, 0, 0x18000
	v_add_u32_e32 v140, s78, v160
	s_add_i32 s79, 0, 0x1c000
	ds_read_b128 v[128:131], v140
	ds_read_b128 v[154:157], v140 offset:1024
	ds_read_b128 v[166:169], v140 offset:2048
	ds_read_b128 v[170:173], v140 offset:3072
	v_add_u32_e32 v140, s79, v160
	ds_read_b128 v[174:177], v140
	ds_read_b128 v[178:181], v140 offset:1024
	ds_read_b128 v[182:185], v140 offset:2048
	ds_read_b128 v[186:189], v140 offset:3072
	s_add_u32 s54, s54, 0x40000
	s_addc_u32 s55, s55, 0
	s_mov_b32 m0, s65
	v_lshl_add_u64 v[230:231], s[54:55], 0, v[138:139]
	ds_read_b128 v[192:195], v163 offset:32768
	ds_read_b128 v[196:199], v163 offset:33792
	ds_read_b128 v[200:203], v163 offset:34816
	ds_read_b128 v[204:207], v163 offset:35840
	ds_read_b128 v[208:211], v163 offset:36864
	ds_read_b128 v[212:215], v163 offset:37888
	ds_read_b128 v[216:219], v163 offset:38912
	ds_read_b128 v[220:223], v163 offset:39936
	global_load_lds_dwordx4 v[230:231], off
	v_lshl_add_u64 v[230:231], s[54:55], 0, v[134:135]
	s_mov_b32 m0, s66
	s_nop 0
	global_load_lds_dwordx4 v[230:231], off
	s_waitcnt vmcnt(8)
	s_waitcnt lgkmcnt(0)
	s_barrier
	s_setprio 1
	s_waitcnt lgkmcnt(0)
	v_mfma_f32_16x16x32_bf16 v[124:127], v[128:131], v[192:195], v[124:127]
	v_mfma_f32_16x16x32_bf16 v[120:123], v[166:169], v[192:195], v[120:123]
	v_mfma_f32_16x16x32_bf16 v[108:111], v[128:131], v[200:203], v[108:111]
	v_mfma_f32_16x16x32_bf16 v[104:107], v[166:169], v[200:203], v[104:107]
	v_mfma_f32_16x16x32_bf16 v[92:95], v[128:131], v[208:211], v[92:95]
	v_mfma_f32_16x16x32_bf16 v[88:91], v[166:169], v[208:211], v[88:91]
	v_mfma_f32_16x16x32_bf16 v[76:79], v[128:131], v[216:219], v[76:79]
	v_mfma_f32_16x16x32_bf16 v[72:75], v[166:169], v[216:219], v[72:75]
	v_mfma_f32_16x16x32_bf16 v[124:127], v[154:157], v[196:199], v[124:127]
	v_mfma_f32_16x16x32_bf16 v[120:123], v[170:173], v[196:199], v[120:123]
	v_mfma_f32_16x16x32_bf16 v[108:111], v[154:157], v[204:207], v[108:111]
	v_mfma_f32_16x16x32_bf16 v[104:107], v[170:173], v[204:207], v[104:107]
	v_mfma_f32_16x16x32_bf16 v[92:95], v[154:157], v[212:215], v[92:95]
	v_mfma_f32_16x16x32_bf16 v[88:91], v[170:173], v[212:215], v[88:91]
	v_mfma_f32_16x16x32_bf16 v[76:79], v[154:157], v[220:223], v[76:79]
	v_mfma_f32_16x16x32_bf16 v[72:75], v[170:173], v[220:223], v[72:75]
	s_setprio 0
	s_setprio 1
	v_mfma_f32_16x16x32_bf16 v[116:119], v[174:177], v[192:195], v[116:119]
	v_mfma_f32_16x16x32_bf16 v[112:115], v[182:185], v[192:195], v[112:115]
	v_mfma_f32_16x16x32_bf16 v[100:103], v[174:177], v[200:203], v[100:103]
	v_mfma_f32_16x16x32_bf16 v[96:99], v[182:185], v[200:203], v[96:99]
	v_mfma_f32_16x16x32_bf16 v[84:87], v[174:177], v[208:211], v[84:87]
	v_mfma_f32_16x16x32_bf16 v[80:83], v[182:185], v[208:211], v[80:83]
	v_mfma_f32_16x16x32_bf16 v[68:71], v[174:177], v[216:219], v[68:71]
	v_mfma_f32_16x16x32_bf16 v[64:67], v[182:185], v[216:219], v[64:67]
	v_mfma_f32_16x16x32_bf16 v[116:119], v[178:181], v[196:199], v[116:119]
	v_mfma_f32_16x16x32_bf16 v[112:115], v[186:189], v[196:199], v[112:115]
	v_mfma_f32_16x16x32_bf16 v[100:103], v[178:181], v[204:207], v[100:103]
	v_mfma_f32_16x16x32_bf16 v[96:99], v[186:189], v[204:207], v[96:99]
	v_mfma_f32_16x16x32_bf16 v[84:87], v[178:181], v[212:215], v[84:87]
	v_mfma_f32_16x16x32_bf16 v[80:83], v[186:189], v[212:215], v[80:83]
	v_mfma_f32_16x16x32_bf16 v[68:71], v[178:181], v[220:223], v[68:71]
	v_mfma_f32_16x16x32_bf16 v[64:67], v[186:189], v[220:223], v[64:67]
	s_setprio 0
	s_barrier
	s_add_i32 s54, s78, s60
	v_lshl_add_u64 v[158:159], v[158:159], 0, s[34:35]
	s_mov_b32 m0, s54
	ds_read_b128 v[192:195], v163 offset:49152
	ds_read_b128 v[196:199], v163 offset:50176
	ds_read_b128 v[200:203], v163 offset:51200
	ds_read_b128 v[204:207], v163 offset:52224
	ds_read_b128 v[208:211], v163 offset:53248
	ds_read_b128 v[212:215], v163 offset:54272
	ds_read_b128 v[216:219], v163 offset:55296
	ds_read_b128 v[220:223], v163 offset:56320
	global_load_lds_dwordx4 v[158:159], off
	s_add_i32 m0, s54, 0x2000
	s_add_u32 s52, s52, 0x40080
	v_lshl_add_u64 v[158:159], v[224:225], 0, s[34:35]
	s_addc_u32 s53, s53, 0
	s_add_i32 s54, s79, s60
	global_load_lds_dwordx4 v[158:159], off
	v_lshl_add_u64 v[158:159], s[52:53], 0, v[136:137]
	s_mov_b32 m0, s54
	s_nop 0
	global_load_lds_dwordx4 v[158:159], off
	v_lshl_add_u64 v[158:159], s[52:53], 0, v[132:133]
	s_add_i32 m0, s54, 0x2000
	s_nop 0
	global_load_lds_dwordx4 v[158:159], off
	v_lshl_add_u64 v[158:159], v[226:227], 0, s[34:35]
	s_mov_b32 m0, s67
	s_nop 0
	global_load_lds_dwordx4 v[158:159], off
	v_lshl_add_u64 v[158:159], v[228:229], 0, s[34:35]
	s_mov_b32 m0, s68
	s_nop 0
	global_load_lds_dwordx4 v[158:159], off
	s_waitcnt vmcnt(8)
	s_waitcnt lgkmcnt(0)
	s_barrier
	s_setprio 1
	s_waitcnt lgkmcnt(0)
	v_mfma_f32_16x16x32_bf16 v[60:63], v[128:131], v[192:195], v[60:63]
	v_mfma_f32_16x16x32_bf16 v[56:59], v[166:169], v[192:195], v[56:59]
	v_mfma_f32_16x16x32_bf16 v[44:47], v[128:131], v[200:203], v[44:47]
	v_mfma_f32_16x16x32_bf16 v[40:43], v[166:169], v[200:203], v[40:43]
	v_mfma_f32_16x16x32_bf16 v[28:31], v[128:131], v[208:211], v[28:31]
	v_mfma_f32_16x16x32_bf16 v[24:27], v[166:169], v[208:211], v[24:27]
	v_mfma_f32_16x16x32_bf16 v[12:15], v[128:131], v[216:219], v[12:15]
	v_mfma_f32_16x16x32_bf16 v[8:11], v[166:169], v[216:219], v[8:11]
	v_mfma_f32_16x16x32_bf16 v[60:63], v[154:157], v[196:199], v[60:63]
	v_mfma_f32_16x16x32_bf16 v[56:59], v[170:173], v[196:199], v[56:59]
	v_mfma_f32_16x16x32_bf16 v[44:47], v[154:157], v[204:207], v[44:47]
	v_mfma_f32_16x16x32_bf16 v[40:43], v[170:173], v[204:207], v[40:43]
	v_mfma_f32_16x16x32_bf16 v[28:31], v[154:157], v[212:215], v[28:31]
	v_mfma_f32_16x16x32_bf16 v[24:27], v[170:173], v[212:215], v[24:27]
	v_mfma_f32_16x16x32_bf16 v[12:15], v[154:157], v[220:223], v[12:15]
	v_mfma_f32_16x16x32_bf16 v[8:11], v[170:173], v[220:223], v[8:11]
	s_setprio 0
	s_setprio 1
	v_mfma_f32_16x16x32_bf16 v[52:55], v[174:177], v[192:195], v[52:55]
	v_mfma_f32_16x16x32_bf16 v[48:51], v[182:185], v[192:195], v[48:51]
	v_mfma_f32_16x16x32_bf16 v[36:39], v[174:177], v[200:203], v[36:39]
	v_mfma_f32_16x16x32_bf16 v[32:35], v[182:185], v[200:203], v[32:35]
	v_mfma_f32_16x16x32_bf16 v[20:23], v[174:177], v[208:211], v[20:23]
	v_mfma_f32_16x16x32_bf16 v[16:19], v[182:185], v[208:211], v[16:19]
	v_mfma_f32_16x16x32_bf16 v[4:7], v[174:177], v[216:219], v[4:7]
	v_mfma_f32_16x16x32_bf16 v[0:3], v[182:185], v[216:219], v[0:3]
	v_mfma_f32_16x16x32_bf16 v[52:55], v[178:181], v[196:199], v[52:55]
	v_mfma_f32_16x16x32_bf16 v[48:51], v[186:189], v[196:199], v[48:51]
	v_mfma_f32_16x16x32_bf16 v[36:39], v[178:181], v[204:207], v[36:39]
	v_mfma_f32_16x16x32_bf16 v[32:35], v[186:189], v[204:207], v[32:35]
	v_mfma_f32_16x16x32_bf16 v[20:23], v[178:181], v[212:215], v[20:23]
	v_mfma_f32_16x16x32_bf16 v[16:19], v[186:189], v[212:215], v[16:19]
	v_mfma_f32_16x16x32_bf16 v[4:7], v[178:181], v[220:223], v[4:7]
	v_mfma_f32_16x16x32_bf16 v[0:3], v[186:189], v[220:223], v[0:3]
	s_setprio 0
	s_barrier
	s_add_i32 s77, s77, 2
	s_add_u32 s49, s49, 0x100
	s_addc_u32 s76, s76, 0
	s_add_u32 s50, s50, 0x100
	s_addc_u32 s51, s51, 0
	s_cmp_gt_u32 s77, 13
	s_cbranch_scc0 .LBB0_103
	v_lshl_add_u32 v214, s48, 8, v143
	v_ashrrev_i32_e32 v215, 31, v214
	v_lshl_add_u64 v[212:213], v[214:215], 2, s[4:5]
	global_load_dword v204, v[212:213], off
	global_load_dword v205, v[212:213], off offset:64
	global_load_dword v206, v[212:213], off offset:128
	global_load_dword v207, v[212:213], off offset:192
	global_load_dword v208, v[212:213], off offset:512
	global_load_dword v209, v[212:213], off offset:576
	global_load_dword v210, v[212:213], off offset:640
	global_load_dword v211, v[212:213], off offset:704
	s_and_b64 vcc, exec, s[36:37]
	s_cbranch_vccz .LBB0_106
	s_barrier

.LBB0_109:
	v_lshl_add_u64 v[158:159], v[154:155], 2, s[4:5]
	s_lshl_b32 s8, s8, 8
	s_mov_b32 s39, s9
	v_mov_b32_e32 v153, v141
	v_or_b32_e32 v140, 16, v154
	s_waitcnt vmcnt(0) lgkmcnt(0)
	v_fmamk_f32 v128, v204, 0x3a800000, v164
	v_cmp_gt_f32_e32 vcc, s73, v128
	v_mul_f32_e32 v129, 0x4b800000, v128
	s_nop 0
	v_cndmask_b32_e32 v128, v128, v129, vcc
	v_rsq_f32_e32 v128, v128
	s_nop 0
	v_mul_f32_e32 v129, 0x45800000, v128
	v_cndmask_b32_e32 v128, v128, v129, vcc
	v_pk_mul_f32 v[156:157], v[124:125], v[128:129] op_sel_hi:[1,0]
	v_pk_mul_f32 v[130:131], v[126:127], v[128:129] op_sel_hi:[1,0]
	v_pk_mul_f32 v[166:167], v[122:123], v[128:129] op_sel_hi:[1,0]
	v_pk_mul_f32 v[168:169], v[120:121], v[128:129] op_sel_hi:[1,0]
	v_pk_mul_f32 v[170:171], v[118:119], v[128:129] op_sel_hi:[1,0]
	v_pk_mul_f32 v[172:173], v[116:117], v[128:129] op_sel_hi:[1,0]
	v_pk_mul_f32 v[174:175], v[114:115], v[128:129] op_sel_hi:[1,0]
	v_pk_mul_f32 v[176:177], v[112:113], v[128:129] op_sel_hi:[1,0]
	v_mul_f32_e32 v128, 0xbfb8aa3b, v156
	v_mul_f32_e32 v129, 0xbfb8aa3b, v157
	v_exp_f32_e32 v128, v128
	v_exp_f32_e32 v129, v129
	v_add_f32_e32 v128, 1.0, v128
	v_add_f32_e32 v129, 1.0, v129
	v_rcp_f32_e32 v128, v128
	v_rcp_f32_e32 v129, v129
	s_nop 0
	v_pk_mul_f32 v[128:129], v[156:157], v[128:129]
	s_nop 0
	v_pk_mul_f32 v[128:129], v[172:173], v[128:129]
	s_nop 0
	v_cvt_pk_bf16_f32 v128, v128, v129
	v_mul_f32_e32 v129, 0xbfb8aa3b, v130
	v_exp_f32_e32 v129, v129
	s_nop 0
	v_add_f32_e32 v129, 1.0, v129
	v_rcp_f32_e32 v156, v129
	v_mul_f32_e32 v129, 0xbfb8aa3b, v131
	v_exp_f32_e32 v129, v129
	s_nop 0
	v_add_f32_e32 v129, 1.0, v129
	v_rcp_f32_e32 v157, v129
	s_nop 0
	v_pk_mul_f32 v[130:131], v[130:131], v[156:157]
	s_nop 0
	v_pk_mul_f32 v[130:131], v[170:171], v[130:131]
	s_nop 0
	v_cvt_pk_bf16_f32 v129, v130, v131
	v_mul_f32_e32 v130, 0xbfb8aa3b, v168
	v_mul_f32_e32 v131, 0xbfb8aa3b, v169
	v_exp_f32_e32 v130, v130
	v_exp_f32_e32 v131, v131
	v_add_f32_e32 v130, 1.0, v130
	v_add_f32_e32 v131, 1.0, v131
	v_rcp_f32_e32 v130, v130
	v_rcp_f32_e32 v131, v131
	s_nop 0
	v_pk_mul_f32 v[130:131], v[168:169], v[130:131]
	s_nop 0
	v_pk_mul_f32 v[130:131], v[176:177], v[130:131]
	s_nop 0
	v_cvt_pk_bf16_f32 v130, v130, v131
	v_mul_f32_e32 v131, 0xbfb8aa3b, v166
	v_exp_f32_e32 v131, v131
	s_nop 0
	v_add_f32_e32 v131, 1.0, v131
	v_rcp_f32_e32 v156, v131
	v_mul_f32_e32 v131, 0xbfb8aa3b, v167
	v_exp_f32_e32 v131, v131
	s_nop 0
	v_add_f32_e32 v131, 1.0, v131
	v_rcp_f32_e32 v157, v131
	s_nop 0
	v_pk_mul_f32 v[156:157], v[166:167], v[156:157]
	s_nop 0
	v_pk_mul_f32 v[156:157], v[174:175], v[156:157]
	s_nop 0
	v_cvt_pk_bf16_f32 v131, v156, v157
	v_mov_b64_e32 v[156:157], s[30:31]
	v_mad_i64_i32 v[166:167], s[50:51], v154, s74, v[156:157]
	v_lshl_add_u64 v[166:167], v[166:167], 0, s[8:9]
	v_lshl_add_u64 v[166:167], v[166:167], 0, s[38:39]
	v_lshl_add_u64 v[166:167], v[166:167], 0, v[152:153]
	global_store_dwordx4 v[166:167], v[128:131], off
	s_nop 1
	v_fmamk_f32 v128, v205, 0x3a800000, v164
	v_cmp_gt_f32_e32 vcc, s73, v128
	v_mul_f32_e32 v129, 0x4b800000, v128
	s_nop 0
	v_cndmask_b32_e32 v128, v128, v129, vcc
	v_rsq_f32_e32 v128, v128
	s_nop 0
	v_mul_f32_e32 v129, 0x45800000, v128
	v_cndmask_b32_e32 v128, v128, v129, vcc
	v_pk_mul_f32 v[166:167], v[108:109], v[128:129] op_sel_hi:[1,0]
	v_pk_mul_f32 v[130:131], v[110:111], v[128:129] op_sel_hi:[1,0]
	v_pk_mul_f32 v[168:169], v[106:107], v[128:129] op_sel_hi:[1,0]
	v_pk_mul_f32 v[170:171], v[104:105], v[128:129] op_sel_hi:[1,0]
	v_pk_mul_f32 v[172:173], v[102:103], v[128:129] op_sel_hi:[1,0]
	v_pk_mul_f32 v[174:175], v[100:101], v[128:129] op_sel_hi:[1,0]
	v_pk_mul_f32 v[176:177], v[98:99], v[128:129] op_sel_hi:[1,0]
	v_pk_mul_f32 v[178:179], v[96:97], v[128:129] op_sel_hi:[1,0]
	v_mul_f32_e32 v128, 0xbfb8aa3b, v166
	v_mul_f32_e32 v129, 0xbfb8aa3b, v167
	v_exp_f32_e32 v128, v128
	v_exp_f32_e32 v129, v129
	v_add_f32_e32 v128, 1.0, v128
	v_add_f32_e32 v129, 1.0, v129
	v_rcp_f32_e32 v128, v128
	v_rcp_f32_e32 v129, v129
	s_nop 0
	v_pk_mul_f32 v[128:129], v[166:167], v[128:129]
	s_nop 0
	v_pk_mul_f32 v[128:129], v[174:175], v[128:129]
	s_nop 0
	v_cvt_pk_bf16_f32 v128, v128, v129
	v_mul_f32_e32 v129, 0xbfb8aa3b, v130
	v_exp_f32_e32 v129, v129
	s_nop 0
	v_add_f32_e32 v129, 1.0, v129
	v_rcp_f32_e32 v166, v129
	v_mul_f32_e32 v129, 0xbfb8aa3b, v131
	v_exp_f32_e32 v129, v129
	s_nop 0
	v_add_f32_e32 v129, 1.0, v129
	v_rcp_f32_e32 v167, v129
	s_nop 0
	v_pk_mul_f32 v[130:131], v[130:131], v[166:167]
	s_nop 0
	v_pk_mul_f32 v[130:131], v[172:173], v[130:131]
	s_nop 0
	v_cvt_pk_bf16_f32 v129, v130, v131
	v_mul_f32_e32 v130, 0xbfb8aa3b, v170
	v_mul_f32_e32 v131, 0xbfb8aa3b, v171
	v_exp_f32_e32 v130, v130
	v_exp_f32_e32 v131, v131
	v_add_f32_e32 v130, 1.0, v130
	v_add_f32_e32 v131, 1.0, v131
	v_rcp_f32_e32 v130, v130
	v_rcp_f32_e32 v131, v131
	s_nop 0
	v_pk_mul_f32 v[130:131], v[170:171], v[130:131]
	s_nop 0
	v_pk_mul_f32 v[130:131], v[178:179], v[130:131]
	s_nop 0
	v_cvt_pk_bf16_f32 v130, v130, v131
	v_mul_f32_e32 v131, 0xbfb8aa3b, v168
	v_exp_f32_e32 v131, v131
	s_nop 0
	v_add_f32_e32 v131, 1.0, v131
	v_rcp_f32_e32 v166, v131
	v_mul_f32_e32 v131, 0xbfb8aa3b, v169
	v_exp_f32_e32 v131, v131
	s_nop 0
	v_add_f32_e32 v131, 1.0, v131
	v_rcp_f32_e32 v167, v131
	s_nop 0
	v_pk_mul_f32 v[166:167], v[168:169], v[166:167]
	s_nop 0
	v_pk_mul_f32 v[166:167], v[176:177], v[166:167]
	s_nop 0
	v_cvt_pk_bf16_f32 v131, v166, v167
	v_mad_i64_i32 v[166:167], s[50:51], v140, s74, v[156:157]
	v_lshl_add_u64 v[166:167], v[166:167], 0, s[8:9]
	v_lshl_add_u64 v[166:167], v[166:167], 0, s[38:39]
	v_lshl_add_u64 v[166:167], v[166:167], 0, v[152:153]
	global_store_dwordx4 v[166:167], v[128:131], off
	s_nop 1
	v_or_b32_e32 v140, 32, v154
	v_fmamk_f32 v128, v206, 0x3a800000, v164
	v_cmp_gt_f32_e32 vcc, s73, v128
	v_mul_f32_e32 v129, 0x4b800000, v128
	s_nop 0
	v_cndmask_b32_e32 v128, v128, v129, vcc
	v_rsq_f32_e32 v128, v128
	s_nop 0
	v_mul_f32_e32 v129, 0x45800000, v128
	v_cndmask_b32_e32 v128, v128, v129, vcc
	v_pk_mul_f32 v[166:167], v[92:93], v[128:129] op_sel_hi:[1,0]
	v_pk_mul_f32 v[130:131], v[94:95], v[128:129] op_sel_hi:[1,0]
	v_pk_mul_f32 v[168:169], v[90:91], v[128:129] op_sel_hi:[1,0]
	v_pk_mul_f32 v[170:171], v[88:89], v[128:129] op_sel_hi:[1,0]
	v_pk_mul_f32 v[172:173], v[86:87], v[128:129] op_sel_hi:[1,0]
	v_pk_mul_f32 v[174:175], v[84:85], v[128:129] op_sel_hi:[1,0]
	v_pk_mul_f32 v[176:177], v[82:83], v[128:129] op_sel_hi:[1,0]
	v_pk_mul_f32 v[178:179], v[80:81], v[128:129] op_sel_hi:[1,0]
	v_mul_f32_e32 v128, 0xbfb8aa3b, v166
	v_mul_f32_e32 v129, 0xbfb8aa3b, v167
	v_exp_f32_e32 v128, v128
	v_exp_f32_e32 v129, v129
	v_add_f32_e32 v128, 1.0, v128
	v_add_f32_e32 v129, 1.0, v129
	v_rcp_f32_e32 v128, v128
	v_rcp_f32_e32 v129, v129
	s_nop 0
	v_pk_mul_f32 v[128:129], v[166:167], v[128:129]
	s_nop 0
	v_pk_mul_f32 v[128:129], v[174:175], v[128:129]
	s_nop 0
	v_cvt_pk_bf16_f32 v128, v128, v129
	v_mul_f32_e32 v129, 0xbfb8aa3b, v130
	v_exp_f32_e32 v129, v129
	s_nop 0
	v_add_f32_e32 v129, 1.0, v129
	v_rcp_f32_e32 v166, v129
	v_mul_f32_e32 v129, 0xbfb8aa3b, v131
	v_exp_f32_e32 v129, v129
	s_nop 0
	v_add_f32_e32 v129, 1.0, v129
	v_rcp_f32_e32 v167, v129
	s_nop 0
	v_pk_mul_f32 v[130:131], v[130:131], v[166:167]
	s_nop 0
	v_pk_mul_f32 v[130:131], v[172:173], v[130:131]
	s_nop 0
	v_cvt_pk_bf16_f32 v129, v130, v131
	v_mul_f32_e32 v130, 0xbfb8aa3b, v170
	v_mul_f32_e32 v131, 0xbfb8aa3b, v171
	v_exp_f32_e32 v130, v130
	v_exp_f32_e32 v131, v131
	v_add_f32_e32 v130, 1.0, v130
	v_add_f32_e32 v131, 1.0, v131
	v_rcp_f32_e32 v130, v130
	v_rcp_f32_e32 v131, v131
	s_nop 0
	v_pk_mul_f32 v[130:131], v[170:171], v[130:131]
	s_nop 0
	v_pk_mul_f32 v[130:131], v[178:179], v[130:131]
	s_nop 0
	v_cvt_pk_bf16_f32 v130, v130, v131
	v_mul_f32_e32 v131, 0xbfb8aa3b, v168
	v_exp_f32_e32 v131, v131
	s_nop 0
	v_add_f32_e32 v131, 1.0, v131
	v_rcp_f32_e32 v166, v131
	v_mul_f32_e32 v131, 0xbfb8aa3b, v169
	v_exp_f32_e32 v131, v131
	s_nop 0
	v_add_f32_e32 v131, 1.0, v131
	v_rcp_f32_e32 v167, v131
	s_nop 0
	v_pk_mul_f32 v[166:167], v[168:169], v[166:167]
	s_nop 0
	v_pk_mul_f32 v[166:167], v[176:177], v[166:167]
	s_nop 0
	v_cvt_pk_bf16_f32 v131, v166, v167
	v_mad_i64_i32 v[166:167], s[50:51], v140, s74, v[156:157]
	v_lshl_add_u64 v[166:167], v[166:167], 0, s[8:9]
	v_lshl_add_u64 v[166:167], v[166:167], 0, s[38:39]
	v_lshl_add_u64 v[166:167], v[166:167], 0, v[152:153]
	global_store_dwordx4 v[166:167], v[128:131], off
	s_nop 1
	v_or_b32_e32 v140, 48, v154
	v_fmamk_f32 v128, v207, 0x3a800000, v164
	v_cmp_gt_f32_e32 vcc, s73, v128
	v_mul_f32_e32 v129, 0x4b800000, v128
	s_nop 0
	v_cndmask_b32_e32 v128, v128, v129, vcc
	v_rsq_f32_e32 v128, v128
	s_nop 0
	v_mul_f32_e32 v129, 0x45800000, v128
	v_cndmask_b32_e32 v128, v128, v129, vcc
	v_pk_mul_f32 v[166:167], v[76:77], v[128:129] op_sel_hi:[1,0]
	v_pk_mul_f32 v[130:131], v[78:79], v[128:129] op_sel_hi:[1,0]
	v_pk_mul_f32 v[168:169], v[74:75], v[128:129] op_sel_hi:[1,0]
	v_pk_mul_f32 v[170:171], v[72:73], v[128:129] op_sel_hi:[1,0]
	v_pk_mul_f32 v[172:173], v[70:71], v[128:129] op_sel_hi:[1,0]
	v_pk_mul_f32 v[174:175], v[68:69], v[128:129] op_sel_hi:[1,0]
	v_pk_mul_f32 v[176:177], v[66:67], v[128:129] op_sel_hi:[1,0]
	v_pk_mul_f32 v[178:179], v[64:65], v[128:129] op_sel_hi:[1,0]
	v_mul_f32_e32 v128, 0xbfb8aa3b, v166
	v_mul_f32_e32 v129, 0xbfb8aa3b, v167
	v_exp_f32_e32 v128, v128
	v_exp_f32_e32 v129, v129
	v_add_f32_e32 v128, 1.0, v128
	v_add_f32_e32 v129, 1.0, v129
	v_rcp_f32_e32 v128, v128
	v_rcp_f32_e32 v129, v129
	s_nop 0
	v_pk_mul_f32 v[128:129], v[166:167], v[128:129]
	s_nop 0
	v_pk_mul_f32 v[128:129], v[174:175], v[128:129]
	s_nop 0
	v_cvt_pk_bf16_f32 v128, v128, v129
	v_mul_f32_e32 v129, 0xbfb8aa3b, v130
	v_exp_f32_e32 v129, v129
	s_nop 0
	v_add_f32_e32 v129, 1.0, v129
	v_rcp_f32_e32 v166, v129
	v_mul_f32_e32 v129, 0xbfb8aa3b, v131
	v_exp_f32_e32 v129, v129
	s_nop 0
	v_add_f32_e32 v129, 1.0, v129
	v_rcp_f32_e32 v167, v129
	s_nop 0
	v_pk_mul_f32 v[130:131], v[130:131], v[166:167]
	s_nop 0
	v_pk_mul_f32 v[130:131], v[172:173], v[130:131]
	s_nop 0
	v_cvt_pk_bf16_f32 v129, v130, v131
	v_mul_f32_e32 v130, 0xbfb8aa3b, v170
	v_mul_f32_e32 v131, 0xbfb8aa3b, v171
	v_exp_f32_e32 v130, v130
	v_exp_f32_e32 v131, v131
	v_add_f32_e32 v130, 1.0, v130
	v_add_f32_e32 v131, 1.0, v131
	v_rcp_f32_e32 v130, v130
	v_rcp_f32_e32 v131, v131
	s_nop 0
	v_pk_mul_f32 v[130:131], v[170:171], v[130:131]
	s_nop 0
	v_pk_mul_f32 v[130:131], v[178:179], v[130:131]
	s_nop 0
	v_cvt_pk_bf16_f32 v130, v130, v131
	v_mul_f32_e32 v131, 0xbfb8aa3b, v168
	v_exp_f32_e32 v131, v131
	s_nop 0
	v_add_f32_e32 v131, 1.0, v131
	v_rcp_f32_e32 v166, v131
	v_mul_f32_e32 v131, 0xbfb8aa3b, v169
	v_exp_f32_e32 v131, v131
	s_nop 0
	v_add_f32_e32 v131, 1.0, v131
	v_rcp_f32_e32 v167, v131
	s_nop 0
	v_pk_mul_f32 v[166:167], v[168:169], v[166:167]
	s_nop 0
	v_pk_mul_f32 v[166:167], v[176:177], v[166:167]
	s_nop 0
	v_cvt_pk_bf16_f32 v131, v166, v167
	v_mad_i64_i32 v[166:167], s[50:51], v140, s74, v[156:157]
	v_lshl_add_u64 v[166:167], v[166:167], 0, s[8:9]
	v_lshl_add_u64 v[166:167], v[166:167], 0, s[38:39]
	v_lshl_add_u64 v[166:167], v[166:167], 0, v[152:153]
	global_store_dwordx4 v[166:167], v[128:131], off
	s_nop 1
	v_add_u32_e32 v140, 0x80, v154
	v_fmamk_f32 v128, v208, 0x3a800000, v164
	v_cmp_gt_f32_e32 vcc, s73, v128
	v_mul_f32_e32 v129, 0x4b800000, v128
	s_nop 0
	v_cndmask_b32_e32 v128, v128, v129, vcc
	v_rsq_f32_e32 v128, v128
	s_nop 0
	v_mul_f32_e32 v129, 0x45800000, v128
	v_cndmask_b32_e32 v128, v128, v129, vcc
	v_pk_mul_f32 v[166:167], v[60:61], v[128:129] op_sel_hi:[1,0]
	v_pk_mul_f32 v[130:131], v[62:63], v[128:129] op_sel_hi:[1,0]
	v_pk_mul_f32 v[168:169], v[58:59], v[128:129] op_sel_hi:[1,0]
	v_pk_mul_f32 v[170:171], v[56:57], v[128:129] op_sel_hi:[1,0]
	v_pk_mul_f32 v[172:173], v[54:55], v[128:129] op_sel_hi:[1,0]
	v_pk_mul_f32 v[174:175], v[52:53], v[128:129] op_sel_hi:[1,0]
	v_pk_mul_f32 v[176:177], v[50:51], v[128:129] op_sel_hi:[1,0]
	v_pk_mul_f32 v[178:179], v[48:49], v[128:129] op_sel_hi:[1,0]
	v_mul_f32_e32 v128, 0xbfb8aa3b, v166
	v_mul_f32_e32 v129, 0xbfb8aa3b, v167
	v_exp_f32_e32 v128, v128
	v_exp_f32_e32 v129, v129
	v_add_f32_e32 v128, 1.0, v128
	v_add_f32_e32 v129, 1.0, v129
	v_rcp_f32_e32 v128, v128
	v_rcp_f32_e32 v129, v129
	s_nop 0
	v_pk_mul_f32 v[128:129], v[166:167], v[128:129]
	s_nop 0
	v_pk_mul_f32 v[128:129], v[174:175], v[128:129]
	s_nop 0
	v_cvt_pk_bf16_f32 v128, v128, v129
	v_mul_f32_e32 v129, 0xbfb8aa3b, v130
	v_exp_f32_e32 v129, v129
	s_nop 0
	v_add_f32_e32 v129, 1.0, v129
	v_rcp_f32_e32 v166, v129
	v_mul_f32_e32 v129, 0xbfb8aa3b, v131
	v_exp_f32_e32 v129, v129
	s_nop 0
	v_add_f32_e32 v129, 1.0, v129
	v_rcp_f32_e32 v167, v129
	s_nop 0
	v_pk_mul_f32 v[130:131], v[130:131], v[166:167]
	s_nop 0
	v_pk_mul_f32 v[130:131], v[172:173], v[130:131]
	s_nop 0
	v_cvt_pk_bf16_f32 v129, v130, v131
	v_mul_f32_e32 v130, 0xbfb8aa3b, v170
	v_mul_f32_e32 v131, 0xbfb8aa3b, v171
	v_exp_f32_e32 v130, v130
	v_exp_f32_e32 v131, v131
	v_add_f32_e32 v130, 1.0, v130
	v_add_f32_e32 v131, 1.0, v131
	v_rcp_f32_e32 v130, v130
	v_rcp_f32_e32 v131, v131
	s_nop 0
	v_pk_mul_f32 v[130:131], v[170:171], v[130:131]
	s_nop 0
	v_pk_mul_f32 v[130:131], v[178:179], v[130:131]
	s_nop 0
	v_cvt_pk_bf16_f32 v130, v130, v131
	v_mul_f32_e32 v131, 0xbfb8aa3b, v168
	v_exp_f32_e32 v131, v131
	s_nop 0
	v_add_f32_e32 v131, 1.0, v131
	v_rcp_f32_e32 v166, v131
	v_mul_f32_e32 v131, 0xbfb8aa3b, v169
	v_exp_f32_e32 v131, v131
	s_nop 0
	v_add_f32_e32 v131, 1.0, v131
	v_rcp_f32_e32 v167, v131
	s_nop 0
	v_pk_mul_f32 v[166:167], v[168:169], v[166:167]
	s_nop 0
	v_pk_mul_f32 v[166:167], v[176:177], v[166:167]
	s_nop 0
	v_cvt_pk_bf16_f32 v131, v166, v167
	v_mad_i64_i32 v[166:167], s[50:51], v140, s74, v[156:157]
	v_lshl_add_u64 v[166:167], v[166:167], 0, s[8:9]
	v_lshl_add_u64 v[166:167], v[166:167], 0, s[38:39]
	v_lshl_add_u64 v[166:167], v[166:167], 0, v[152:153]
	global_store_dwordx4 v[166:167], v[128:131], off
	s_nop 1
	v_add_u32_e32 v140, 0x90, v154
	v_fmamk_f32 v128, v209, 0x3a800000, v164
	v_cmp_gt_f32_e32 vcc, s73, v128
	v_mul_f32_e32 v129, 0x4b800000, v128
	s_nop 0
	v_cndmask_b32_e32 v128, v128, v129, vcc
	v_rsq_f32_e32 v128, v128
	s_nop 0
	v_mul_f32_e32 v129, 0x45800000, v128
	v_cndmask_b32_e32 v128, v128, v129, vcc
	v_pk_mul_f32 v[166:167], v[44:45], v[128:129] op_sel_hi:[1,0]
	v_pk_mul_f32 v[130:131], v[46:47], v[128:129] op_sel_hi:[1,0]
	v_pk_mul_f32 v[168:169], v[42:43], v[128:129] op_sel_hi:[1,0]
	v_pk_mul_f32 v[170:171], v[40:41], v[128:129] op_sel_hi:[1,0]
	v_pk_mul_f32 v[172:173], v[38:39], v[128:129] op_sel_hi:[1,0]
	v_pk_mul_f32 v[174:175], v[36:37], v[128:129] op_sel_hi:[1,0]
	v_pk_mul_f32 v[176:177], v[34:35], v[128:129] op_sel_hi:[1,0]
	v_pk_mul_f32 v[178:179], v[32:33], v[128:129] op_sel_hi:[1,0]
	v_mul_f32_e32 v128, 0xbfb8aa3b, v166
	v_mul_f32_e32 v129, 0xbfb8aa3b, v167
	v_exp_f32_e32 v128, v128
	v_exp_f32_e32 v129, v129
	v_add_f32_e32 v128, 1.0, v128
	v_add_f32_e32 v129, 1.0, v129
	v_rcp_f32_e32 v128, v128
	v_rcp_f32_e32 v129, v129
	s_nop 0
	v_pk_mul_f32 v[128:129], v[166:167], v[128:129]
	s_nop 0
	v_pk_mul_f32 v[128:129], v[174:175], v[128:129]
	s_nop 0
	v_cvt_pk_bf16_f32 v128, v128, v129
	v_mul_f32_e32 v129, 0xbfb8aa3b, v130
	v_exp_f32_e32 v129, v129
	s_nop 0
	v_add_f32_e32 v129, 1.0, v129
	v_rcp_f32_e32 v166, v129
	v_mul_f32_e32 v129, 0xbfb8aa3b, v131
	v_exp_f32_e32 v129, v129
	s_nop 0
	v_add_f32_e32 v129, 1.0, v129
	v_rcp_f32_e32 v167, v129
	s_nop 0
	v_pk_mul_f32 v[130:131], v[130:131], v[166:167]
	s_nop 0
	v_pk_mul_f32 v[130:131], v[172:173], v[130:131]
	s_nop 0
	v_cvt_pk_bf16_f32 v129, v130, v131
	v_mul_f32_e32 v130, 0xbfb8aa3b, v170
	v_mul_f32_e32 v131, 0xbfb8aa3b, v171
	v_exp_f32_e32 v130, v130
	v_exp_f32_e32 v131, v131
	v_add_f32_e32 v130, 1.0, v130
	v_add_f32_e32 v131, 1.0, v131
	v_rcp_f32_e32 v130, v130
	v_rcp_f32_e32 v131, v131
	s_nop 0
	v_pk_mul_f32 v[130:131], v[170:171], v[130:131]
	s_nop 0
	v_pk_mul_f32 v[130:131], v[178:179], v[130:131]
	s_nop 0
	v_cvt_pk_bf16_f32 v130, v130, v131
	v_mul_f32_e32 v131, 0xbfb8aa3b, v168
	v_exp_f32_e32 v131, v131
	s_nop 0
	v_add_f32_e32 v131, 1.0, v131
	v_rcp_f32_e32 v166, v131
	v_mul_f32_e32 v131, 0xbfb8aa3b, v169
	v_exp_f32_e32 v131, v131
	s_nop 0
	v_add_f32_e32 v131, 1.0, v131
	v_rcp_f32_e32 v167, v131
	s_nop 0
	v_pk_mul_f32 v[166:167], v[168:169], v[166:167]
	s_nop 0
	v_pk_mul_f32 v[166:167], v[176:177], v[166:167]
	s_nop 0
	v_cvt_pk_bf16_f32 v131, v166, v167
	v_mad_i64_i32 v[166:167], s[50:51], v140, s74, v[156:157]
	v_lshl_add_u64 v[166:167], v[166:167], 0, s[8:9]
	v_lshl_add_u64 v[166:167], v[166:167], 0, s[38:39]
	v_lshl_add_u64 v[166:167], v[166:167], 0, v[152:153]
	global_store_dwordx4 v[166:167], v[128:131], off
	s_nop 1
	v_add_u32_e32 v140, 0xa0, v154
	v_fmamk_f32 v128, v210, 0x3a800000, v164
	v_cmp_gt_f32_e32 vcc, s73, v128
	v_mul_f32_e32 v129, 0x4b800000, v128
	s_nop 0
	v_cndmask_b32_e32 v128, v128, v129, vcc
	v_rsq_f32_e32 v128, v128
	s_nop 0
	v_mul_f32_e32 v129, 0x45800000, v128
	v_cndmask_b32_e32 v128, v128, v129, vcc
	v_pk_mul_f32 v[166:167], v[28:29], v[128:129] op_sel_hi:[1,0]
	v_pk_mul_f32 v[130:131], v[30:31], v[128:129] op_sel_hi:[1,0]
	v_pk_mul_f32 v[168:169], v[26:27], v[128:129] op_sel_hi:[1,0]
	v_pk_mul_f32 v[170:171], v[24:25], v[128:129] op_sel_hi:[1,0]
	v_pk_mul_f32 v[172:173], v[22:23], v[128:129] op_sel_hi:[1,0]
	v_pk_mul_f32 v[174:175], v[20:21], v[128:129] op_sel_hi:[1,0]
	v_pk_mul_f32 v[176:177], v[18:19], v[128:129] op_sel_hi:[1,0]
	v_pk_mul_f32 v[178:179], v[16:17], v[128:129] op_sel_hi:[1,0]
	v_mul_f32_e32 v128, 0xbfb8aa3b, v166
	v_mul_f32_e32 v129, 0xbfb8aa3b, v167
	v_exp_f32_e32 v128, v128
	v_exp_f32_e32 v129, v129
	v_add_f32_e32 v128, 1.0, v128
	v_add_f32_e32 v129, 1.0, v129
	v_rcp_f32_e32 v128, v128
	v_rcp_f32_e32 v129, v129
	s_nop 0
	v_pk_mul_f32 v[128:129], v[166:167], v[128:129]
	s_nop 0
	v_pk_mul_f32 v[128:129], v[174:175], v[128:129]
	s_nop 0
	v_cvt_pk_bf16_f32 v128, v128, v129
	v_mul_f32_e32 v129, 0xbfb8aa3b, v130
	v_exp_f32_e32 v129, v129
	s_nop 0
	v_add_f32_e32 v129, 1.0, v129
	v_rcp_f32_e32 v166, v129
	v_mul_f32_e32 v129, 0xbfb8aa3b, v131
	v_exp_f32_e32 v129, v129
	s_nop 0
	v_add_f32_e32 v129, 1.0, v129
	v_rcp_f32_e32 v167, v129
	s_nop 0
	v_pk_mul_f32 v[130:131], v[130:131], v[166:167]
	s_nop 0
	v_pk_mul_f32 v[130:131], v[172:173], v[130:131]
	s_nop 0
	v_cvt_pk_bf16_f32 v129, v130, v131
	v_mul_f32_e32 v130, 0xbfb8aa3b, v170
	v_mul_f32_e32 v131, 0xbfb8aa3b, v171
	v_exp_f32_e32 v130, v130
	v_exp_f32_e32 v131, v131
	v_add_f32_e32 v130, 1.0, v130
	v_add_f32_e32 v131, 1.0, v131
	v_rcp_f32_e32 v130, v130
	v_rcp_f32_e32 v131, v131
	s_nop 0
	v_pk_mul_f32 v[130:131], v[170:171], v[130:131]
	s_nop 0
	v_pk_mul_f32 v[130:131], v[178:179], v[130:131]
	s_nop 0
	v_cvt_pk_bf16_f32 v130, v130, v131
	v_mul_f32_e32 v131, 0xbfb8aa3b, v168
	v_exp_f32_e32 v131, v131
	s_nop 0
	v_add_f32_e32 v131, 1.0, v131
	v_rcp_f32_e32 v166, v131
	v_mul_f32_e32 v131, 0xbfb8aa3b, v169
	v_exp_f32_e32 v131, v131
	s_nop 0
	v_add_f32_e32 v131, 1.0, v131
	v_rcp_f32_e32 v167, v131
	s_nop 0
	v_pk_mul_f32 v[166:167], v[168:169], v[166:167]
	s_nop 0
	v_pk_mul_f32 v[166:167], v[176:177], v[166:167]
	s_nop 0
	v_cvt_pk_bf16_f32 v131, v166, v167
	v_mad_i64_i32 v[166:167], s[50:51], v140, s74, v[156:157]
	v_lshl_add_u64 v[166:167], v[166:167], 0, s[8:9]
	v_lshl_add_u64 v[166:167], v[166:167], 0, s[38:39]
	v_lshl_add_u64 v[166:167], v[166:167], 0, v[152:153]
	global_store_dwordx4 v[166:167], v[128:131], off
	s_nop 1
	v_add_u32_e32 v140, 0xb0, v154
	v_mad_i64_i32 v[156:157], s[50:51], v140, s74, v[156:157]
	v_lshl_add_u64 v[156:157], v[156:157], 0, s[8:9]
	v_lshl_add_u64 v[156:157], v[156:157], 0, s[38:39]
	v_lshl_add_u64 v[156:157], v[156:157], 0, v[152:153]
	v_fmamk_f32 v128, v211, 0x3a800000, v164
	v_cmp_gt_f32_e32 vcc, s73, v128
	v_mul_f32_e32 v129, 0x4b800000, v128
	s_nop 0
	v_cndmask_b32_e32 v128, v128, v129, vcc
	v_rsq_f32_e32 v128, v128
	s_nop 0
	v_mul_f32_e32 v129, 0x45800000, v128
	v_cndmask_b32_e32 v128, v128, v129, vcc
	v_pk_mul_f32 v[158:159], v[12:13], v[128:129] op_sel_hi:[1,0]
	v_pk_mul_f32 v[130:131], v[14:15], v[128:129] op_sel_hi:[1,0]
	v_pk_mul_f32 v[166:167], v[10:11], v[128:129] op_sel_hi:[1,0]
	v_pk_mul_f32 v[168:169], v[8:9], v[128:129] op_sel_hi:[1,0]
	v_pk_mul_f32 v[170:171], v[6:7], v[128:129] op_sel_hi:[1,0]
	v_pk_mul_f32 v[172:173], v[4:5], v[128:129] op_sel_hi:[1,0]
	v_pk_mul_f32 v[174:175], v[2:3], v[128:129] op_sel_hi:[1,0]
	v_pk_mul_f32 v[176:177], v[0:1], v[128:129] op_sel_hi:[1,0]
	v_mul_f32_e32 v128, 0xbfb8aa3b, v158
	v_mul_f32_e32 v129, 0xbfb8aa3b, v159
	v_exp_f32_e32 v128, v128
	v_exp_f32_e32 v129, v129
	v_add_f32_e32 v128, 1.0, v128
	v_add_f32_e32 v129, 1.0, v129
	v_rcp_f32_e32 v128, v128
	v_rcp_f32_e32 v129, v129
	s_nop 0
	v_pk_mul_f32 v[128:129], v[158:159], v[128:129]
	s_nop 0
	v_pk_mul_f32 v[128:129], v[172:173], v[128:129]
	s_nop 0
	v_cvt_pk_bf16_f32 v128, v128, v129
	v_mul_f32_e32 v129, 0xbfb8aa3b, v130
	v_exp_f32_e32 v129, v129
	s_nop 0
	v_add_f32_e32 v129, 1.0, v129
	v_rcp_f32_e32 v158, v129
	v_mul_f32_e32 v129, 0xbfb8aa3b, v131
	v_exp_f32_e32 v129, v129
	s_nop 0
	v_add_f32_e32 v129, 1.0, v129
	v_rcp_f32_e32 v159, v129
	s_nop 0
	v_pk_mul_f32 v[130:131], v[130:131], v[158:159]
	s_nop 0
	v_pk_mul_f32 v[130:131], v[170:171], v[130:131]
	s_nop 0
	v_cvt_pk_bf16_f32 v129, v130, v131
	v_mul_f32_e32 v130, 0xbfb8aa3b, v168
	v_mul_f32_e32 v131, 0xbfb8aa3b, v169
	v_exp_f32_e32 v130, v130
	v_exp_f32_e32 v131, v131
	v_add_f32_e32 v130, 1.0, v130
	v_add_f32_e32 v131, 1.0, v131
	v_rcp_f32_e32 v130, v130
	v_rcp_f32_e32 v131, v131
	s_nop 0
	v_pk_mul_f32 v[130:131], v[168:169], v[130:131]
	s_nop 0
	v_pk_mul_f32 v[130:131], v[176:177], v[130:131]
	s_nop 0
	v_cvt_pk_bf16_f32 v130, v130, v131
	v_mul_f32_e32 v131, 0xbfb8aa3b, v166
	v_exp_f32_e32 v131, v131
	s_nop 0
	v_add_f32_e32 v131, 1.0, v131
	v_rcp_f32_e32 v158, v131
	v_mul_f32_e32 v131, 0xbfb8aa3b, v167
	v_exp_f32_e32 v131, v131
	s_nop 0
	v_add_f32_e32 v131, 1.0, v131
	v_rcp_f32_e32 v159, v131
	s_nop 0
	v_pk_mul_f32 v[158:159], v[166:167], v[158:159]
	s_nop 0
	v_pk_mul_f32 v[158:159], v[174:175], v[158:159]
	s_nop 0
	v_cvt_pk_bf16_f32 v131, v158, v159
	global_store_dwordx4 v[156:157], v[128:131], off
	s_load_dwordx16 s[76:91], s[0:1], 0xc0
	s_cbranch_execnz .LBB0_108

.LBB0_253:
	v_mbcnt_lo_u32_b32 v235, -1, 0
	v_mbcnt_hi_u32_b32 v235, -1, v235
	v_lshrrev_b32_e32 v236, 2, v235
	v_and_b32_e32 v237, 3, v235
	v_lshl_add_u32 v232, v237, 4, v236
	v_lshlrev_b32_e32 v232, 2, v232
	v_and_b32_e32 v233, -16, v170
	v_or_b32_e32 v233, v233, v236
	v_lshlrev_b32_e32 v237, 2, v237
	v_and_b32_e32 v234, -13, v172
	v_or_b32_e32 v234, v234, v237
	ds_bpermute_b32 v127, v232, v127
	ds_bpermute_b32 v126, v232, v126
	ds_bpermute_b32 v125, v232, v125
	ds_bpermute_b32 v124, v232, v124
	ds_bpermute_b32 v123, v232, v123
	ds_bpermute_b32 v122, v232, v122
	ds_bpermute_b32 v121, v232, v121
	ds_bpermute_b32 v120, v232, v120
	ds_bpermute_b32 v119, v232, v119
	ds_bpermute_b32 v118, v232, v118
	ds_bpermute_b32 v117, v232, v117
	ds_bpermute_b32 v116, v232, v116
	ds_bpermute_b32 v115, v232, v115
	ds_bpermute_b32 v114, v232, v114
	ds_bpermute_b32 v113, v232, v113
	ds_bpermute_b32 v112, v232, v112
	ds_bpermute_b32 v111, v232, v111
	ds_bpermute_b32 v110, v232, v110
	ds_bpermute_b32 v109, v232, v109
	ds_bpermute_b32 v108, v232, v108
	ds_bpermute_b32 v107, v232, v107
	ds_bpermute_b32 v106, v232, v106
	ds_bpermute_b32 v105, v232, v105
	ds_bpermute_b32 v104, v232, v104
	ds_bpermute_b32 v103, v232, v103
	ds_bpermute_b32 v102, v232, v102
	ds_bpermute_b32 v101, v232, v101
	ds_bpermute_b32 v100, v232, v100
	ds_bpermute_b32 v99, v232, v99
	ds_bpermute_b32 v98, v232, v98
	ds_bpermute_b32 v97, v232, v97
	ds_bpermute_b32 v96, v232, v96
	ds_bpermute_b32 v95, v232, v95
	ds_bpermute_b32 v94, v232, v94
	ds_bpermute_b32 v93, v232, v93
	ds_bpermute_b32 v92, v232, v92
	ds_bpermute_b32 v91, v232, v91
	ds_bpermute_b32 v90, v232, v90
	ds_bpermute_b32 v89, v232, v89
	ds_bpermute_b32 v88, v232, v88
	ds_bpermute_b32 v87, v232, v87
	ds_bpermute_b32 v86, v232, v86
	ds_bpermute_b32 v85, v232, v85
	ds_bpermute_b32 v84, v232, v84
	ds_bpermute_b32 v83, v232, v83
	ds_bpermute_b32 v82, v232, v82
	ds_bpermute_b32 v81, v232, v81
	ds_bpermute_b32 v80, v232, v80
	ds_bpermute_b32 v79, v232, v79
	ds_bpermute_b32 v78, v232, v78
	ds_bpermute_b32 v77, v232, v77
	ds_bpermute_b32 v76, v232, v76
	ds_bpermute_b32 v75, v232, v75
	ds_bpermute_b32 v74, v232, v74
	ds_bpermute_b32 v73, v232, v73
	ds_bpermute_b32 v72, v232, v72
	ds_bpermute_b32 v71, v232, v71
	ds_bpermute_b32 v70, v232, v70
	ds_bpermute_b32 v69, v232, v69
	ds_bpermute_b32 v68, v232, v68
	ds_bpermute_b32 v67, v232, v67
	ds_bpermute_b32 v66, v232, v66
	ds_bpermute_b32 v65, v232, v65
	ds_bpermute_b32 v64, v232, v64
	ds_bpermute_b32 v63, v232, v63
	ds_bpermute_b32 v62, v232, v62
	ds_bpermute_b32 v61, v232, v61
	ds_bpermute_b32 v60, v232, v60
	ds_bpermute_b32 v59, v232, v59
	ds_bpermute_b32 v58, v232, v58
	ds_bpermute_b32 v57, v232, v57
	ds_bpermute_b32 v56, v232, v56
	ds_bpermute_b32 v55, v232, v55
	ds_bpermute_b32 v54, v232, v54
	ds_bpermute_b32 v53, v232, v53
	ds_bpermute_b32 v52, v232, v52
	ds_bpermute_b32 v51, v232, v51
	ds_bpermute_b32 v50, v232, v50
	ds_bpermute_b32 v49, v232, v49
	ds_bpermute_b32 v48, v232, v48
	ds_bpermute_b32 v47, v232, v47
	ds_bpermute_b32 v46, v232, v46
	ds_bpermute_b32 v45, v232, v45
	ds_bpermute_b32 v44, v232, v44
	ds_bpermute_b32 v43, v232, v43
	ds_bpermute_b32 v42, v232, v42
	ds_bpermute_b32 v41, v232, v41
	ds_bpermute_b32 v40, v232, v40
	ds_bpermute_b32 v39, v232, v39
	ds_bpermute_b32 v38, v232, v38
	ds_bpermute_b32 v37, v232, v37
	ds_bpermute_b32 v36, v232, v36
	ds_bpermute_b32 v35, v232, v35
	ds_bpermute_b32 v34, v232, v34
	ds_bpermute_b32 v33, v232, v33
	ds_bpermute_b32 v32, v232, v32
	ds_bpermute_b32 v31, v232, v31
	ds_bpermute_b32 v30, v232, v30
	ds_bpermute_b32 v29, v232, v29
	ds_bpermute_b32 v28, v232, v28
	ds_bpermute_b32 v27, v232, v27
	ds_bpermute_b32 v26, v232, v26
	ds_bpermute_b32 v25, v232, v25
	ds_bpermute_b32 v24, v232, v24
	ds_bpermute_b32 v23, v232, v23
	ds_bpermute_b32 v22, v232, v22
	ds_bpermute_b32 v21, v232, v21
	ds_bpermute_b32 v20, v232, v20
	ds_bpermute_b32 v19, v232, v19
	ds_bpermute_b32 v18, v232, v18
	ds_bpermute_b32 v17, v232, v17
	ds_bpermute_b32 v16, v232, v16
	ds_bpermute_b32 v15, v232, v15
	ds_bpermute_b32 v14, v232, v14
	ds_bpermute_b32 v13, v232, v13
	ds_bpermute_b32 v12, v232, v12
	ds_bpermute_b32 v11, v232, v11
	ds_bpermute_b32 v10, v232, v10
	ds_bpermute_b32 v9, v232, v9
	ds_bpermute_b32 v8, v232, v8
	ds_bpermute_b32 v7, v232, v7
	ds_bpermute_b32 v6, v232, v6
	ds_bpermute_b32 v5, v232, v5
	ds_bpermute_b32 v4, v232, v4
	ds_bpermute_b32 v3, v232, v3
	ds_bpermute_b32 v2, v232, v2
	ds_bpermute_b32 v1, v232, v1
	ds_bpermute_b32 v0, v232, v0
	s_waitcnt lgkmcnt(0)
	v_readlane_b32 s12, v254, 0
	v_lshl_add_u32 v160, s82, 8, v233
	v_lshl_or_b32 v156, s83, 8, v234
	s_cmpk_lt_i32 s82, 0x100
	v_readlane_b32 s13, v254, 1
	v_ashrrev_i32_e32 v161, 31, v160
	s_cselect_b32 s55, s13, s78
	s_cselect_b32 s54, s12, s77
	v_lshlrev_b64 v[192:193], 12, v[160:161]
	v_ashrrev_i32_e32 v157, 31, v156
	v_lshl_add_u64 v[128:129], s[54:55], 0, v[192:193]
	v_lshlrev_b64 v[158:159], 2, v[156:157]
	v_lshl_add_u64 v[128:129], v[128:129], 0, v[158:159]
	global_load_dwordx4 v[166:169], v[128:129], off
	global_load_dwordx4 v[178:181], v[128:129], off offset:64
	global_load_dwordx4 v[182:185], v[128:129], off offset:512
	global_load_dwordx4 v[186:189], v[128:129], off offset:576
	v_or_b32_e32 v162, 16, v160
	v_ashrrev_i32_e32 v163, 31, v162
	v_lshlrev_b64 v[164:165], 12, v[162:163]
	v_lshl_add_u64 v[128:129], s[54:55], 0, v[164:165]
	v_lshl_add_u64 v[128:129], v[128:129], 0, v[158:159]
	global_load_dwordx4 v[140:143], v[128:129], off
	global_load_dwordx4 v[136:139], v[128:129], off offset:64
	global_load_dwordx4 v[132:135], v[128:129], off offset:512
	s_nop 0
	global_load_dwordx4 v[128:131], v[128:129], off offset:576
	v_readlane_b32 s14, v254, 2
	v_readlane_b32 s15, v254, 3
	v_readlane_b32 s16, v254, 4
	v_readlane_b32 s17, v254, 5
	v_readlane_b32 s18, v254, 6
	v_readlane_b32 s19, v254, 7
	v_readlane_b32 s20, v254, 8
	v_readlane_b32 s21, v254, 9
	v_readlane_b32 s22, v254, 10
	v_readlane_b32 s23, v254, 11
	v_readlane_b32 s24, v254, 12
	v_readlane_b32 s25, v254, 13
	v_readlane_b32 s26, v254, 14
	v_readlane_b32 s27, v254, 15
	s_waitcnt vmcnt(0)
	v_pk_fma_f32 v[126:127], v[126:127], 0.5, v[168:169] op_sel_hi:[1,0,1]
	v_pk_fma_f32 v[124:125], v[124:125], 0.5, v[166:167] op_sel_hi:[1,0,1]
	v_mul_f32_e32 v167, v127, v127
	v_mul_f32_e32 v166, v125, v125
	v_fmac_f32_e32 v166, v124, v124
	v_fmac_f32_e32 v167, v126, v126
	v_add_f32_e32 v177, v166, v167
	v_lshl_add_u64 v[166:167], s[6:7], 0, v[192:193]
	v_lshlrev_b64 v[168:169], 11, v[160:161]
	v_lshl_add_u64 v[166:167], v[166:167], 0, v[158:159]
	v_lshl_add_u64 v[168:169], s[10:11], 0, v[168:169]
	global_store_dwordx4 v[166:167], v[124:127], off
	v_lshl_add_u64 v[168:169], v[156:157], 1, v[168:169]
	v_pk_fma_f32 v[120:121], v[120:121], 0.5, v[178:179] op_sel_hi:[1,0,1]
	v_cvt_pk_bf16_f32 v124, v124, v125
	v_cvt_pk_bf16_f32 v125, v126, v127
	global_store_dwordx2 v[168:169], v[124:125], off
	v_pk_fma_f32 v[122:123], v[122:123], 0.5, v[180:181] op_sel_hi:[1,0,1]
	v_mul_f32_e32 v124, v121, v121
	v_fmac_f32_e32 v124, v120, v120
	global_store_dwordx4 v[166:167], v[120:123], off offset:64
	v_pk_fma_f32 v[116:117], v[116:117], 0.5, v[182:183] op_sel_hi:[1,0,1]
	v_pk_fma_f32 v[118:119], v[118:119], 0.5, v[184:185] op_sel_hi:[1,0,1]
	v_cvt_pk_bf16_f32 v120, v120, v121
	v_cvt_pk_bf16_f32 v121, v122, v123
	global_store_dwordx2 v[168:169], v[120:121], off offset:32
	v_mul_f32_e32 v120, v117, v117
	v_fmac_f32_e32 v120, v116, v116
	global_store_dwordx4 v[166:167], v[116:119], off offset:512
	v_pk_fma_f32 v[112:113], v[112:113], 0.5, v[186:187] op_sel_hi:[1,0,1]
	v_pk_fma_f32 v[114:115], v[114:115], 0.5, v[188:189] op_sel_hi:[1,0,1]
	v_cvt_pk_bf16_f32 v116, v116, v117
	v_cvt_pk_bf16_f32 v117, v118, v119
	global_store_dwordx2 v[168:169], v[116:117], off offset:256
	v_mul_f32_e32 v116, v113, v113
	v_mul_f32_e32 v125, v123, v123
	v_fmac_f32_e32 v116, v112, v112
	global_store_dwordx4 v[166:167], v[112:115], off offset:576
	v_fmac_f32_e32 v125, v122, v122
	v_mul_f32_e32 v121, v119, v119
	v_cvt_pk_bf16_f32 v112, v112, v113
	v_cvt_pk_bf16_f32 v113, v114, v115
	global_store_dwordx2 v[168:169], v[112:113], off offset:288
	v_and_b32_e32 v113, 64, v176
	v_add_f32_e32 v124, v124, v125
	v_fmac_f32_e32 v121, v118, v118
	v_mul_f32_e32 v117, v115, v115
	v_xor_b32_e32 v112, 1, v176
	v_add_u32_e32 v113, 64, v113
	v_add_f32_e32 v124, v177, v124
	v_add_f32_e32 v120, v120, v121
	v_fmac_f32_e32 v117, v114, v114
	v_cmp_lt_i32_e32 vcc, v112, v113
	v_add_f32_e32 v120, v124, v120
	v_add_f32_e32 v116, v116, v117
	v_cndmask_b32_e32 v112, v176, v112, vcc
	v_add_f32_e32 v116, v120, v116
	v_lshlrev_b32_e32 v177, 2, v112
	ds_bpermute_b32 v112, v177, v116
	v_xor_b32_e32 v114, 2, v176
	v_cmp_lt_i32_e32 vcc, v114, v113
	s_waitcnt lgkmcnt(0)
	v_add_f32_e32 v112, v116, v112
	v_cndmask_b32_e32 v113, v176, v114, vcc
	v_lshlrev_b32_e32 v178, 2, v113
	ds_bpermute_b32 v113, v178, v112
	s_mov_b32 vcc_lo, 0x11111111
	s_mov_b32 vcc_hi, 0x11111111
	s_and_saveexec_b64 s[56:57], vcc
	s_cbranch_execz .LBB0_255
	v_lshl_add_u64 v[114:115], v[160:161], 2, s[90:91]
	s_waitcnt lgkmcnt(0)
	v_add_f32_e32 v112, v112, v113
	global_atomic_add_f32 v[114:115], v112, off
.LBB0_255:
	s_or_b64 exec, exec, s[56:57]
	v_or_b32_e32 v166, 32, v160
	v_ashrrev_i32_e32 v167, 31, v166
	v_lshlrev_b64 v[168:169], 12, v[166:167]
	s_waitcnt lgkmcnt(0)
	v_lshl_add_u64 v[112:113], s[54:55], 0, v[168:169]
	v_lshl_add_u64 v[112:113], v[112:113], 0, v[158:159]
	global_load_dwordx4 v[124:127], v[112:113], off
	global_load_dwordx4 v[120:123], v[112:113], off offset:64
	global_load_dwordx4 v[116:119], v[112:113], off offset:512
	s_nop 0
	global_load_dwordx4 v[112:115], v[112:113], off offset:576
	v_pk_fma_f32 v[110:111], v[110:111], 0.5, v[142:143] op_sel_hi:[1,0,1]
	v_pk_fma_f32 v[108:109], v[108:109], 0.5, v[140:141] op_sel_hi:[1,0,1]
	v_mul_f32_e32 v141, v111, v111
	v_mul_f32_e32 v140, v109, v109
	v_fmac_f32_e32 v140, v108, v108
	v_fmac_f32_e32 v141, v110, v110
	v_add_f32_e32 v161, v140, v141
	v_lshl_add_u64 v[140:141], s[6:7], 0, v[164:165]
	v_lshlrev_b64 v[142:143], 11, v[162:163]
	v_lshl_add_u64 v[140:141], v[140:141], 0, v[158:159]
	v_lshl_add_u64 v[142:143], s[10:11], 0, v[142:143]
	global_store_dwordx4 v[140:141], v[108:111], off
	v_lshl_add_u64 v[142:143], v[156:157], 1, v[142:143]
	v_pk_fma_f32 v[104:105], v[104:105], 0.5, v[136:137] op_sel_hi:[1,0,1]
	v_cvt_pk_bf16_f32 v108, v108, v109
	v_cvt_pk_bf16_f32 v109, v110, v111
	global_store_dwordx2 v[142:143], v[108:109], off
	v_pk_fma_f32 v[106:107], v[106:107], 0.5, v[138:139] op_sel_hi:[1,0,1]
	v_mul_f32_e32 v108, v105, v105
	v_fmac_f32_e32 v108, v104, v104
	v_mul_f32_e32 v109, v107, v107
	global_store_dwordx4 v[140:141], v[104:107], off offset:64
	v_pk_fma_f32 v[102:103], v[102:103], 0.5, v[134:135] op_sel_hi:[1,0,1]
	v_pk_fma_f32 v[100:101], v[100:101], 0.5, v[132:133] op_sel_hi:[1,0,1]
	v_cvt_pk_bf16_f32 v104, v104, v105
	v_cvt_pk_bf16_f32 v105, v106, v107
	v_fmac_f32_e32 v109, v106, v106
	global_store_dwordx2 v[142:143], v[104:105], off offset:32
	v_mul_f32_e32 v104, v101, v101
	v_mul_f32_e32 v105, v103, v103
	v_add_f32_e32 v108, v108, v109
	v_fmac_f32_e32 v104, v100, v100
	v_fmac_f32_e32 v105, v102, v102
	v_add_f32_e32 v108, v161, v108
	v_add_f32_e32 v104, v104, v105
	v_add_f32_e32 v108, v108, v104
	v_pk_fma_f32 v[106:107], v[98:99], 0.5, v[130:131] op_sel_hi:[1,0,1]
	v_pk_fma_f32 v[104:105], v[96:97], 0.5, v[128:129] op_sel_hi:[1,0,1]
	v_mul_f32_e32 v97, v107, v107
	v_mul_f32_e32 v96, v105, v105
	v_fmac_f32_e32 v96, v104, v104
	v_fmac_f32_e32 v97, v106, v106
	v_add_f32_e32 v96, v96, v97
	v_add_f32_e32 v98, v108, v96
	ds_bpermute_b32 v99, v177, v98
	v_cvt_pk_bf16_f32 v96, v100, v101
	v_cvt_pk_bf16_f32 v97, v102, v103
	global_store_dwordx4 v[140:141], v[100:103], off offset:512
	global_store_dwordx2 v[142:143], v[96:97], off offset:256
	s_waitcnt lgkmcnt(0)
	v_add_f32_e32 v96, v98, v99
	ds_bpermute_b32 v97, v178, v96
	v_cvt_pk_bf16_f32 v98, v104, v105
	v_cvt_pk_bf16_f32 v99, v106, v107
	global_store_dwordx4 v[140:141], v[104:107], off offset:576
	global_store_dwordx2 v[142:143], v[98:99], off offset:288
	s_mov_b32 vcc_lo, 0x11111111
	s_mov_b32 vcc_hi, 0x11111111
	s_and_saveexec_b64 s[56:57], vcc
	s_cbranch_execz .LBB0_257
	v_lshl_add_u64 v[98:99], v[162:163], 2, s[90:91]
	s_waitcnt lgkmcnt(0)
	v_add_f32_e32 v96, v96, v97
	global_atomic_add_f32 v[98:99], v96, off
.LBB0_257:
	s_or_b64 exec, exec, s[56:57]
	v_or_b32_e32 v128, 48, v160
	v_ashrrev_i32_e32 v129, 31, v128
	v_lshlrev_b64 v[130:131], 12, v[128:129]
	s_waitcnt lgkmcnt(0)
	v_lshl_add_u64 v[96:97], s[54:55], 0, v[130:131]
	v_lshl_add_u64 v[96:97], v[96:97], 0, v[158:159]
	global_load_dwordx4 v[108:111], v[96:97], off
	global_load_dwordx4 v[104:107], v[96:97], off offset:64
	global_load_dwordx4 v[100:103], v[96:97], off offset:512
	s_nop 0
	global_load_dwordx4 v[96:99], v[96:97], off offset:576
	s_waitcnt vmcnt(0)
	v_pk_fma_f32 v[94:95], v[94:95], 0.5, v[126:127] op_sel_hi:[1,0,1]
	v_pk_fma_f32 v[92:93], v[92:93], 0.5, v[124:125] op_sel_hi:[1,0,1]
	v_mul_f32_e32 v125, v95, v95
	v_mul_f32_e32 v124, v93, v93
	v_fmac_f32_e32 v124, v92, v92
	v_fmac_f32_e32 v125, v94, v94
	v_add_f32_e32 v132, v124, v125
	v_lshl_add_u64 v[124:125], s[6:7], 0, v[168:169]
	v_lshlrev_b64 v[126:127], 11, v[166:167]
	v_lshl_add_u64 v[124:125], v[124:125], 0, v[158:159]
	v_lshl_add_u64 v[126:127], s[10:11], 0, v[126:127]
	global_store_dwordx4 v[124:125], v[92:95], off
	v_lshl_add_u64 v[126:127], v[156:157], 1, v[126:127]
	v_pk_fma_f32 v[88:89], v[88:89], 0.5, v[120:121] op_sel_hi:[1,0,1]
	v_cvt_pk_bf16_f32 v92, v92, v93
	v_cvt_pk_bf16_f32 v93, v94, v95
	global_store_dwordx2 v[126:127], v[92:93], off
	v_pk_fma_f32 v[90:91], v[90:91], 0.5, v[122:123] op_sel_hi:[1,0,1]
	v_mul_f32_e32 v92, v89, v89
	v_fmac_f32_e32 v92, v88, v88
	v_mul_f32_e32 v93, v91, v91
	global_store_dwordx4 v[124:125], v[88:91], off offset:64
	v_pk_fma_f32 v[86:87], v[86:87], 0.5, v[118:119] op_sel_hi:[1,0,1]
	v_pk_fma_f32 v[84:85], v[84:85], 0.5, v[116:117] op_sel_hi:[1,0,1]
	v_cvt_pk_bf16_f32 v88, v88, v89
	v_cvt_pk_bf16_f32 v89, v90, v91
	v_fmac_f32_e32 v93, v90, v90
	global_store_dwordx2 v[126:127], v[88:89], off offset:32
	v_mul_f32_e32 v88, v85, v85
	v_mul_f32_e32 v89, v87, v87
	v_add_f32_e32 v92, v92, v93
	v_fmac_f32_e32 v88, v84, v84
	v_fmac_f32_e32 v89, v86, v86
	v_add_f32_e32 v92, v132, v92
	v_add_f32_e32 v88, v88, v89
	v_add_f32_e32 v92, v92, v88
	v_pk_fma_f32 v[90:91], v[82:83], 0.5, v[114:115] op_sel_hi:[1,0,1]
	v_pk_fma_f32 v[88:89], v[80:81], 0.5, v[112:113] op_sel_hi:[1,0,1]
	v_mul_f32_e32 v81, v91, v91
	v_mul_f32_e32 v80, v89, v89
	v_fmac_f32_e32 v80, v88, v88
	v_fmac_f32_e32 v81, v90, v90
	v_add_f32_e32 v80, v80, v81
	v_add_f32_e32 v82, v92, v80
	ds_bpermute_b32 v83, v177, v82
	v_cvt_pk_bf16_f32 v80, v84, v85
	v_cvt_pk_bf16_f32 v81, v86, v87
	global_store_dwordx4 v[124:125], v[84:87], off offset:512
	global_store_dwordx2 v[126:127], v[80:81], off offset:256
	s_waitcnt lgkmcnt(0)
	v_add_f32_e32 v80, v82, v83
	ds_bpermute_b32 v81, v178, v80
	v_cvt_pk_bf16_f32 v82, v88, v89
	v_cvt_pk_bf16_f32 v83, v90, v91
	global_store_dwordx4 v[124:125], v[88:91], off offset:576
	global_store_dwordx2 v[126:127], v[82:83], off offset:288
	s_mov_b32 vcc_lo, 0x11111111
	s_mov_b32 vcc_hi, 0x11111111
	s_and_saveexec_b64 s[56:57], vcc
	s_cbranch_execz .LBB0_259
	v_lshl_add_u64 v[82:83], v[166:167], 2, s[90:91]
	s_waitcnt lgkmcnt(0)
	v_add_f32_e32 v80, v80, v81
	global_atomic_add_f32 v[82:83], v80, off
.LBB0_259:
	s_or_b64 exec, exec, s[56:57]
	v_add_u32_e32 v112, 0x80, v160
	v_ashrrev_i32_e32 v113, 31, v112
	v_lshlrev_b64 v[114:115], 12, v[112:113]
	s_waitcnt lgkmcnt(0)
	v_lshl_add_u64 v[80:81], s[54:55], 0, v[114:115]
	v_lshl_add_u64 v[80:81], v[80:81], 0, v[158:159]
	global_load_dwordx4 v[92:95], v[80:81], off
	global_load_dwordx4 v[88:91], v[80:81], off offset:64
	global_load_dwordx4 v[84:87], v[80:81], off offset:512
	s_nop 0
	global_load_dwordx4 v[80:83], v[80:81], off offset:576
	v_pk_fma_f32 v[78:79], v[78:79], 0.5, v[110:111] op_sel_hi:[1,0,1]
	v_pk_fma_f32 v[76:77], v[76:77], 0.5, v[108:109] op_sel_hi:[1,0,1]
	v_mul_f32_e32 v109, v79, v79
	v_mul_f32_e32 v108, v77, v77
	v_fmac_f32_e32 v108, v76, v76
	v_fmac_f32_e32 v109, v78, v78
	v_add_f32_e32 v116, v108, v109
	v_lshl_add_u64 v[108:109], s[6:7], 0, v[130:131]
	v_lshlrev_b64 v[110:111], 11, v[128:129]
	v_lshl_add_u64 v[108:109], v[108:109], 0, v[158:159]
	v_lshl_add_u64 v[110:111], s[10:11], 0, v[110:111]
	global_store_dwordx4 v[108:109], v[76:79], off
	v_lshl_add_u64 v[110:111], v[156:157], 1, v[110:111]
	v_pk_fma_f32 v[72:73], v[72:73], 0.5, v[104:105] op_sel_hi:[1,0,1]
	v_cvt_pk_bf16_f32 v76, v76, v77
	v_cvt_pk_bf16_f32 v77, v78, v79
	global_store_dwordx2 v[110:111], v[76:77], off
	v_pk_fma_f32 v[74:75], v[74:75], 0.5, v[106:107] op_sel_hi:[1,0,1]
	v_mul_f32_e32 v76, v73, v73
	v_fmac_f32_e32 v76, v72, v72
	v_mul_f32_e32 v77, v75, v75
	global_store_dwordx4 v[108:109], v[72:75], off offset:64
	v_pk_fma_f32 v[70:71], v[70:71], 0.5, v[102:103] op_sel_hi:[1,0,1]
	v_pk_fma_f32 v[68:69], v[68:69], 0.5, v[100:101] op_sel_hi:[1,0,1]
	v_cvt_pk_bf16_f32 v72, v72, v73
	v_cvt_pk_bf16_f32 v73, v74, v75
	v_fmac_f32_e32 v77, v74, v74
	global_store_dwordx2 v[110:111], v[72:73], off offset:32
	v_mul_f32_e32 v72, v69, v69
	v_mul_f32_e32 v73, v71, v71
	v_add_f32_e32 v76, v76, v77
	v_fmac_f32_e32 v72, v68, v68
	v_fmac_f32_e32 v73, v70, v70
	v_add_f32_e32 v76, v116, v76
	v_add_f32_e32 v72, v72, v73
	v_add_f32_e32 v76, v76, v72
	v_pk_fma_f32 v[74:75], v[66:67], 0.5, v[98:99] op_sel_hi:[1,0,1]
	v_pk_fma_f32 v[72:73], v[64:65], 0.5, v[96:97] op_sel_hi:[1,0,1]
	v_mul_f32_e32 v65, v75, v75
	v_mul_f32_e32 v64, v73, v73
	v_fmac_f32_e32 v64, v72, v72
	v_fmac_f32_e32 v65, v74, v74
	v_add_f32_e32 v64, v64, v65
	v_add_f32_e32 v66, v76, v64
	ds_bpermute_b32 v67, v177, v66
	v_cvt_pk_bf16_f32 v64, v68, v69
	v_cvt_pk_bf16_f32 v65, v70, v71
	global_store_dwordx4 v[108:109], v[68:71], off offset:512
	global_store_dwordx2 v[110:111], v[64:65], off offset:256
	s_waitcnt lgkmcnt(0)
	v_add_f32_e32 v64, v66, v67
	ds_bpermute_b32 v65, v178, v64
	v_cvt_pk_bf16_f32 v66, v72, v73
	v_cvt_pk_bf16_f32 v67, v74, v75
	global_store_dwordx4 v[108:109], v[72:75], off offset:576
	global_store_dwordx2 v[110:111], v[66:67], off offset:288
	s_mov_b32 vcc_lo, 0x11111111
	s_mov_b32 vcc_hi, 0x11111111
	s_and_saveexec_b64 s[56:57], vcc
	s_cbranch_execz .LBB0_261
	v_lshl_add_u64 v[66:67], v[128:129], 2, s[90:91]
	s_waitcnt lgkmcnt(0)
	v_add_f32_e32 v64, v64, v65
	global_atomic_add_f32 v[66:67], v64, off
.LBB0_261:
	s_or_b64 exec, exec, s[56:57]
	v_or_b32_e32 v96, 16, v112
	v_ashrrev_i32_e32 v97, 31, v96
	v_lshlrev_b64 v[98:99], 12, v[96:97]
	s_waitcnt lgkmcnt(0)
	v_lshl_add_u64 v[64:65], s[54:55], 0, v[98:99]
	v_lshl_add_u64 v[64:65], v[64:65], 0, v[158:159]
	global_load_dwordx4 v[76:79], v[64:65], off
	global_load_dwordx4 v[72:75], v[64:65], off offset:64
	global_load_dwordx4 v[68:71], v[64:65], off offset:512
	s_nop 0
	global_load_dwordx4 v[64:67], v[64:65], off offset:576
	s_waitcnt vmcnt(0)
	v_pk_fma_f32 v[62:63], v[62:63], 0.5, v[94:95] op_sel_hi:[1,0,1]
	v_pk_fma_f32 v[60:61], v[60:61], 0.5, v[92:93] op_sel_hi:[1,0,1]
	v_mul_f32_e32 v93, v63, v63
	v_mul_f32_e32 v92, v61, v61
	v_fmac_f32_e32 v92, v60, v60
	v_fmac_f32_e32 v93, v62, v62
	v_add_f32_e32 v100, v92, v93
	v_lshl_add_u64 v[92:93], s[6:7], 0, v[114:115]
	v_lshlrev_b64 v[94:95], 11, v[112:113]
	v_lshl_add_u64 v[92:93], v[92:93], 0, v[158:159]
	v_lshl_add_u64 v[94:95], s[10:11], 0, v[94:95]
	global_store_dwordx4 v[92:93], v[60:63], off
	v_lshl_add_u64 v[94:95], v[156:157], 1, v[94:95]
	v_pk_fma_f32 v[56:57], v[56:57], 0.5, v[88:89] op_sel_hi:[1,0,1]
	v_cvt_pk_bf16_f32 v60, v60, v61
	v_cvt_pk_bf16_f32 v61, v62, v63
	global_store_dwordx2 v[94:95], v[60:61], off
	v_pk_fma_f32 v[58:59], v[58:59], 0.5, v[90:91] op_sel_hi:[1,0,1]
	v_mul_f32_e32 v60, v57, v57
	v_fmac_f32_e32 v60, v56, v56
	v_mul_f32_e32 v61, v59, v59
	global_store_dwordx4 v[92:93], v[56:59], off offset:64
	v_pk_fma_f32 v[54:55], v[54:55], 0.5, v[86:87] op_sel_hi:[1,0,1]
	v_pk_fma_f32 v[52:53], v[52:53], 0.5, v[84:85] op_sel_hi:[1,0,1]
	v_cvt_pk_bf16_f32 v56, v56, v57
	v_cvt_pk_bf16_f32 v57, v58, v59
	v_fmac_f32_e32 v61, v58, v58
	global_store_dwordx2 v[94:95], v[56:57], off offset:32
	v_mul_f32_e32 v56, v53, v53
	v_mul_f32_e32 v57, v55, v55
	v_add_f32_e32 v60, v60, v61
	v_fmac_f32_e32 v56, v52, v52
	v_fmac_f32_e32 v57, v54, v54
	v_add_f32_e32 v60, v100, v60
	v_add_f32_e32 v56, v56, v57
	v_add_f32_e32 v60, v60, v56
	v_pk_fma_f32 v[58:59], v[50:51], 0.5, v[82:83] op_sel_hi:[1,0,1]
	v_pk_fma_f32 v[56:57], v[48:49], 0.5, v[80:81] op_sel_hi:[1,0,1]
	v_mul_f32_e32 v49, v59, v59
	v_mul_f32_e32 v48, v57, v57
	v_fmac_f32_e32 v48, v56, v56
	v_fmac_f32_e32 v49, v58, v58
	v_add_f32_e32 v48, v48, v49
	v_add_f32_e32 v50, v60, v48
	ds_bpermute_b32 v51, v177, v50
	v_cvt_pk_bf16_f32 v48, v52, v53
	v_cvt_pk_bf16_f32 v49, v54, v55
	global_store_dwordx4 v[92:93], v[52:55], off offset:512
	global_store_dwordx2 v[94:95], v[48:49], off offset:256
	s_waitcnt lgkmcnt(0)
	v_add_f32_e32 v48, v50, v51
	ds_bpermute_b32 v49, v178, v48
	v_cvt_pk_bf16_f32 v50, v56, v57
	v_cvt_pk_bf16_f32 v51, v58, v59
	global_store_dwordx4 v[92:93], v[56:59], off offset:576
	global_store_dwordx2 v[94:95], v[50:51], off offset:288
	s_mov_b32 vcc_lo, 0x11111111
	s_mov_b32 vcc_hi, 0x11111111
	s_and_saveexec_b64 s[56:57], vcc
	s_cbranch_execz .LBB0_263
	v_lshl_add_u64 v[50:51], v[112:113], 2, s[90:91]
	s_waitcnt lgkmcnt(0)
	v_add_f32_e32 v48, v48, v49
	global_atomic_add_f32 v[50:51], v48, off
.LBB0_263:
	s_or_b64 exec, exec, s[56:57]
	v_or_b32_e32 v80, 32, v112
	v_ashrrev_i32_e32 v81, 31, v80
	v_lshlrev_b64 v[82:83], 12, v[80:81]
	s_waitcnt lgkmcnt(0)
	v_lshl_add_u64 v[48:49], s[54:55], 0, v[82:83]
	v_lshl_add_u64 v[48:49], v[48:49], 0, v[158:159]
	global_load_dwordx4 v[60:63], v[48:49], off
	global_load_dwordx4 v[56:59], v[48:49], off offset:64
	global_load_dwordx4 v[52:55], v[48:49], off offset:512
	s_nop 0
	global_load_dwordx4 v[48:51], v[48:49], off offset:576
	v_pk_fma_f32 v[46:47], v[46:47], 0.5, v[78:79] op_sel_hi:[1,0,1]
	v_pk_fma_f32 v[44:45], v[44:45], 0.5, v[76:77] op_sel_hi:[1,0,1]
	v_mul_f32_e32 v77, v47, v47
	v_mul_f32_e32 v76, v45, v45
	v_fmac_f32_e32 v76, v44, v44
	v_fmac_f32_e32 v77, v46, v46
	v_add_f32_e32 v84, v76, v77
	v_lshl_add_u64 v[76:77], s[6:7], 0, v[98:99]
	v_lshlrev_b64 v[78:79], 11, v[96:97]
	v_lshl_add_u64 v[76:77], v[76:77], 0, v[158:159]
	v_lshl_add_u64 v[78:79], s[10:11], 0, v[78:79]
	global_store_dwordx4 v[76:77], v[44:47], off
	v_lshl_add_u64 v[78:79], v[156:157], 1, v[78:79]
	v_pk_fma_f32 v[40:41], v[40:41], 0.5, v[72:73] op_sel_hi:[1,0,1]
	v_cvt_pk_bf16_f32 v44, v44, v45
	v_cvt_pk_bf16_f32 v45, v46, v47
	global_store_dwordx2 v[78:79], v[44:45], off
	v_pk_fma_f32 v[42:43], v[42:43], 0.5, v[74:75] op_sel_hi:[1,0,1]
	v_mul_f32_e32 v44, v41, v41
	v_fmac_f32_e32 v44, v40, v40
	v_mul_f32_e32 v45, v43, v43
	global_store_dwordx4 v[76:77], v[40:43], off offset:64
	v_pk_fma_f32 v[38:39], v[38:39], 0.5, v[70:71] op_sel_hi:[1,0,1]
	v_pk_fma_f32 v[36:37], v[36:37], 0.5, v[68:69] op_sel_hi:[1,0,1]
	v_cvt_pk_bf16_f32 v40, v40, v41
	v_cvt_pk_bf16_f32 v41, v42, v43
	v_fmac_f32_e32 v45, v42, v42
	global_store_dwordx2 v[78:79], v[40:41], off offset:32
	v_mul_f32_e32 v40, v37, v37
	v_mul_f32_e32 v41, v39, v39
	v_add_f32_e32 v44, v44, v45
	v_fmac_f32_e32 v40, v36, v36
	v_fmac_f32_e32 v41, v38, v38
	v_add_f32_e32 v44, v84, v44
	v_add_f32_e32 v40, v40, v41
	v_add_f32_e32 v44, v44, v40
	v_pk_fma_f32 v[42:43], v[34:35], 0.5, v[66:67] op_sel_hi:[1,0,1]
	v_pk_fma_f32 v[40:41], v[32:33], 0.5, v[64:65] op_sel_hi:[1,0,1]
	v_mul_f32_e32 v33, v43, v43
	v_mul_f32_e32 v32, v41, v41
	v_fmac_f32_e32 v32, v40, v40
	v_fmac_f32_e32 v33, v42, v42
	v_add_f32_e32 v32, v32, v33
	v_add_f32_e32 v34, v44, v32
	ds_bpermute_b32 v35, v177, v34
	v_cvt_pk_bf16_f32 v32, v36, v37
	v_cvt_pk_bf16_f32 v33, v38, v39
	global_store_dwordx4 v[76:77], v[36:39], off offset:512
	global_store_dwordx2 v[78:79], v[32:33], off offset:256
	s_waitcnt lgkmcnt(0)
	v_add_f32_e32 v32, v34, v35
	ds_bpermute_b32 v33, v178, v32
	v_cvt_pk_bf16_f32 v34, v40, v41
	v_cvt_pk_bf16_f32 v35, v42, v43
	global_store_dwordx4 v[76:77], v[40:43], off offset:576
	global_store_dwordx2 v[78:79], v[34:35], off offset:288
	s_mov_b32 vcc_lo, 0x11111111
	s_mov_b32 vcc_hi, 0x11111111
	s_and_saveexec_b64 s[56:57], vcc
	s_cbranch_execz .LBB0_265
	v_lshl_add_u64 v[34:35], v[96:97], 2, s[90:91]
	s_waitcnt lgkmcnt(0)
	v_add_f32_e32 v32, v32, v33
	global_atomic_add_f32 v[34:35], v32, off
.LBB0_265:
	s_or_b64 exec, exec, s[56:57]
	v_or_b32_e32 v64, 48, v112
	v_ashrrev_i32_e32 v65, 31, v64
	v_lshlrev_b64 v[66:67], 12, v[64:65]
	s_waitcnt lgkmcnt(0)
	v_lshl_add_u64 v[32:33], s[54:55], 0, v[66:67]
	v_lshl_add_u64 v[32:33], v[32:33], 0, v[158:159]
	global_load_dwordx4 v[44:47], v[32:33], off
	global_load_dwordx4 v[40:43], v[32:33], off offset:64
	global_load_dwordx4 v[36:39], v[32:33], off offset:512
	s_nop 0
	global_load_dwordx4 v[32:35], v[32:33], off offset:576
	s_waitcnt vmcnt(0)
	v_pk_fma_f32 v[30:31], v[30:31], 0.5, v[62:63] op_sel_hi:[1,0,1]
	v_pk_fma_f32 v[28:29], v[28:29], 0.5, v[60:61] op_sel_hi:[1,0,1]
	v_mul_f32_e32 v61, v31, v31
	v_mul_f32_e32 v60, v29, v29
	v_fmac_f32_e32 v60, v28, v28
	v_fmac_f32_e32 v61, v30, v30
	v_add_f32_e32 v68, v60, v61
	v_lshl_add_u64 v[60:61], s[6:7], 0, v[82:83]
	v_lshlrev_b64 v[62:63], 11, v[80:81]
	v_lshl_add_u64 v[60:61], v[60:61], 0, v[158:159]
	v_lshl_add_u64 v[62:63], s[10:11], 0, v[62:63]
	global_store_dwordx4 v[60:61], v[28:31], off
	v_lshl_add_u64 v[62:63], v[156:157], 1, v[62:63]
	v_pk_fma_f32 v[24:25], v[24:25], 0.5, v[56:57] op_sel_hi:[1,0,1]
	v_cvt_pk_bf16_f32 v28, v28, v29
	v_cvt_pk_bf16_f32 v29, v30, v31
	global_store_dwordx2 v[62:63], v[28:29], off
	v_pk_fma_f32 v[26:27], v[26:27], 0.5, v[58:59] op_sel_hi:[1,0,1]
	v_mul_f32_e32 v28, v25, v25
	v_fmac_f32_e32 v28, v24, v24
	v_mul_f32_e32 v29, v27, v27
	global_store_dwordx4 v[60:61], v[24:27], off offset:64
	v_pk_fma_f32 v[22:23], v[22:23], 0.5, v[54:55] op_sel_hi:[1,0,1]
	v_pk_fma_f32 v[20:21], v[20:21], 0.5, v[52:53] op_sel_hi:[1,0,1]
	v_cvt_pk_bf16_f32 v24, v24, v25
	v_cvt_pk_bf16_f32 v25, v26, v27
	v_fmac_f32_e32 v29, v26, v26
	global_store_dwordx2 v[62:63], v[24:25], off offset:32
	v_mul_f32_e32 v24, v21, v21
	v_mul_f32_e32 v25, v23, v23
	v_add_f32_e32 v28, v28, v29
	v_fmac_f32_e32 v24, v20, v20
	v_fmac_f32_e32 v25, v22, v22
	v_add_f32_e32 v28, v68, v28
	v_add_f32_e32 v24, v24, v25
	v_add_f32_e32 v28, v28, v24
	v_pk_fma_f32 v[26:27], v[18:19], 0.5, v[50:51] op_sel_hi:[1,0,1]
	v_pk_fma_f32 v[24:25], v[16:17], 0.5, v[48:49] op_sel_hi:[1,0,1]
	v_mul_f32_e32 v17, v27, v27
	v_mul_f32_e32 v16, v25, v25
	v_fmac_f32_e32 v16, v24, v24
	v_fmac_f32_e32 v17, v26, v26
	v_add_f32_e32 v16, v16, v17
	v_add_f32_e32 v18, v28, v16
	ds_bpermute_b32 v19, v177, v18
	v_cvt_pk_bf16_f32 v16, v20, v21
	v_cvt_pk_bf16_f32 v17, v22, v23
	global_store_dwordx4 v[60:61], v[20:23], off offset:512
	global_store_dwordx2 v[62:63], v[16:17], off offset:256
	s_waitcnt lgkmcnt(0)
	v_add_f32_e32 v16, v18, v19
	ds_bpermute_b32 v17, v178, v16
	v_cvt_pk_bf16_f32 v18, v24, v25
	v_cvt_pk_bf16_f32 v19, v26, v27
	global_store_dwordx4 v[60:61], v[24:27], off offset:576
	global_store_dwordx2 v[62:63], v[18:19], off offset:288
	s_mov_b32 vcc_lo, 0x11111111
	s_mov_b32 vcc_hi, 0x11111111
	s_and_saveexec_b64 s[54:55], vcc
	s_cbranch_execz .LBB0_267
	v_lshl_add_u64 v[18:19], v[80:81], 2, s[90:91]
	s_waitcnt lgkmcnt(0)
	v_add_f32_e32 v16, v16, v17
	global_atomic_add_f32 v[18:19], v16, off
.LBB0_267:
	s_or_b64 exec, exec, s[54:55]
	v_pk_fma_f32 v[14:15], v[14:15], 0.5, v[46:47] op_sel_hi:[1,0,1]
	v_pk_fma_f32 v[12:13], v[12:13], 0.5, v[44:45] op_sel_hi:[1,0,1]
	s_waitcnt lgkmcnt(0)
	v_mul_f32_e32 v17, v15, v15
	v_mul_f32_e32 v16, v13, v13
	v_fmac_f32_e32 v16, v12, v12
	v_fmac_f32_e32 v17, v14, v14
	v_add_f32_e32 v20, v16, v17
	v_lshl_add_u64 v[16:17], s[6:7], 0, v[66:67]
	v_lshlrev_b64 v[18:19], 11, v[64:65]
	v_lshl_add_u64 v[16:17], v[156:157], 2, v[16:17]
	v_lshl_add_u64 v[18:19], s[10:11], 0, v[18:19]
	global_store_dwordx4 v[16:17], v[12:15], off
	v_lshl_add_u64 v[18:19], v[156:157], 1, v[18:19]
	v_pk_fma_f32 v[8:9], v[8:9], 0.5, v[40:41] op_sel_hi:[1,0,1]
	v_cvt_pk_bf16_f32 v12, v12, v13
	v_cvt_pk_bf16_f32 v13, v14, v15
	global_store_dwordx2 v[18:19], v[12:13], off
	v_pk_fma_f32 v[10:11], v[10:11], 0.5, v[42:43] op_sel_hi:[1,0,1]
	v_mul_f32_e32 v12, v9, v9
	v_fmac_f32_e32 v12, v8, v8
	v_mul_f32_e32 v13, v11, v11
	global_store_dwordx4 v[16:17], v[8:11], off offset:64
	v_pk_fma_f32 v[6:7], v[6:7], 0.5, v[38:39] op_sel_hi:[1,0,1]
	v_pk_fma_f32 v[4:5], v[4:5], 0.5, v[36:37] op_sel_hi:[1,0,1]
	v_cvt_pk_bf16_f32 v8, v8, v9
	v_cvt_pk_bf16_f32 v9, v10, v11
	v_fmac_f32_e32 v13, v10, v10
	global_store_dwordx2 v[18:19], v[8:9], off offset:32
	v_mul_f32_e32 v8, v5, v5
	v_mul_f32_e32 v9, v7, v7
	v_add_f32_e32 v12, v12, v13
	v_fmac_f32_e32 v8, v4, v4
	v_fmac_f32_e32 v9, v6, v6
	v_add_f32_e32 v12, v20, v12
	v_add_f32_e32 v8, v8, v9
	v_add_f32_e32 v12, v12, v8
	v_pk_fma_f32 v[10:11], v[2:3], 0.5, v[34:35] op_sel_hi:[1,0,1]
	v_pk_fma_f32 v[8:9], v[0:1], 0.5, v[32:33] op_sel_hi:[1,0,1]
	v_mul_f32_e32 v1, v11, v11
	v_mul_f32_e32 v0, v9, v9
	v_fmac_f32_e32 v0, v8, v8
	v_fmac_f32_e32 v1, v10, v10
	v_add_f32_e32 v0, v0, v1
	v_add_f32_e32 v2, v12, v0
	ds_bpermute_b32 v3, v177, v2
	v_cvt_pk_bf16_f32 v0, v4, v5
	v_cvt_pk_bf16_f32 v1, v6, v7
	global_store_dwordx4 v[16:17], v[4:7], off offset:512
	global_store_dwordx2 v[18:19], v[0:1], off offset:256
	s_waitcnt lgkmcnt(0)
	v_add_f32_e32 v0, v2, v3
	ds_bpermute_b32 v1, v178, v0
	v_cvt_pk_bf16_f32 v2, v8, v9
	v_cvt_pk_bf16_f32 v3, v10, v11
	global_store_dwordx4 v[16:17], v[8:11], off offset:576
	global_store_dwordx2 v[18:19], v[2:3], off offset:288
	s_mov_b32 vcc_lo, 0x11111111
	s_mov_b32 vcc_hi, 0x11111111
	s_and_saveexec_b64 s[54:55], vcc
	s_cbranch_execz .LBB0_269
	v_lshl_add_u64 v[2:3], v[64:65], 2, s[90:91]
	s_waitcnt lgkmcnt(0)
	v_add_f32_e32 v0, v0, v1
	global_atomic_add_f32 v[2:3], v0, off

.LBB0_571:
	ds_read_b128 v[150:153], v163
	ds_read_b128 v[154:157], v163 offset:1024
	ds_read_b128 v[158:161], v163 offset:2048
	ds_read_b128 v[168:171], v163 offset:3072
	ds_read_b128 v[172:175], v164
	ds_read_b128 v[176:179], v164 offset:1024
	ds_read_b128 v[180:183], v164 offset:2048
	ds_read_b128 v[184:187], v164 offset:3072
	s_add_u32 s8, s6, 0xfffc0080
	s_addc_u32 s9, s7, -1
	s_cmp_eq_u32 s65, 12
	s_cselect_b32 s11, s3, s9
	s_cselect_b32 s10, s5, s8
	s_cselect_b32 s9, s20, s64
	s_cselect_b32 s8, s57, s59
	v_lshl_add_u64 v[188:189], s[6:7], 0, v[144:145]
	s_add_i32 m0, s73, 0xc000
	ds_read_b128 v[192:195], v165
	ds_read_b128 v[196:199], v165 offset:1024
	ds_read_b128 v[200:203], v165 offset:2048
	ds_read_b128 v[204:207], v165 offset:3072
	ds_read_b128 v[208:211], v165 offset:4096
	ds_read_b128 v[212:215], v165 offset:5120
	ds_read_b128 v[216:219], v165 offset:6144
	ds_read_b128 v[220:223], v165 offset:7168
	global_load_lds_dwordx4 v[188:189], off
	v_lshl_add_u64 v[188:189], s[6:7], 0, v[142:143]
	s_add_i32 m0, s73, 0xe000
	s_nop 0
	global_load_lds_dwordx4 v[188:189], off
	s_waitcnt vmcnt(8)
	s_waitcnt lgkmcnt(0)
	s_barrier
	s_setprio 1
	s_waitcnt lgkmcnt(0)
	v_mfma_f32_16x16x32_bf16 v[124:127], v[150:153], v[192:195], v[124:127]
	v_mfma_f32_16x16x32_bf16 v[120:123], v[158:161], v[192:195], v[120:123]
	v_mfma_f32_16x16x32_bf16 v[108:111], v[150:153], v[200:203], v[108:111]
	v_mfma_f32_16x16x32_bf16 v[104:107], v[158:161], v[200:203], v[104:107]
	v_mfma_f32_16x16x32_bf16 v[92:95], v[150:153], v[208:211], v[92:95]
	v_mfma_f32_16x16x32_bf16 v[88:91], v[158:161], v[208:211], v[88:91]
	v_mfma_f32_16x16x32_bf16 v[76:79], v[150:153], v[216:219], v[76:79]
	v_mfma_f32_16x16x32_bf16 v[72:75], v[158:161], v[216:219], v[72:75]
	v_mfma_f32_16x16x32_bf16 v[124:127], v[154:157], v[196:199], v[124:127]
	v_mfma_f32_16x16x32_bf16 v[120:123], v[168:171], v[196:199], v[120:123]
	v_mfma_f32_16x16x32_bf16 v[108:111], v[154:157], v[204:207], v[108:111]
	v_mfma_f32_16x16x32_bf16 v[104:107], v[168:171], v[204:207], v[104:107]
	v_mfma_f32_16x16x32_bf16 v[92:95], v[154:157], v[212:215], v[92:95]
	v_mfma_f32_16x16x32_bf16 v[88:91], v[168:171], v[212:215], v[88:91]
	v_mfma_f32_16x16x32_bf16 v[76:79], v[154:157], v[220:223], v[76:79]
	v_mfma_f32_16x16x32_bf16 v[72:75], v[168:171], v[220:223], v[72:75]
	s_setprio 0
	s_setprio 1
	v_mfma_f32_16x16x32_bf16 v[116:119], v[172:175], v[192:195], v[116:119]
	v_mfma_f32_16x16x32_bf16 v[112:115], v[180:183], v[192:195], v[112:115]
	v_mfma_f32_16x16x32_bf16 v[100:103], v[172:175], v[200:203], v[100:103]
	v_mfma_f32_16x16x32_bf16 v[96:99], v[180:183], v[200:203], v[96:99]
	v_mfma_f32_16x16x32_bf16 v[84:87], v[172:175], v[208:211], v[84:87]
	v_mfma_f32_16x16x32_bf16 v[80:83], v[180:183], v[208:211], v[80:83]
	v_mfma_f32_16x16x32_bf16 v[68:71], v[172:175], v[216:219], v[68:71]
	v_mfma_f32_16x16x32_bf16 v[64:67], v[180:183], v[216:219], v[64:67]
	v_mfma_f32_16x16x32_bf16 v[116:119], v[176:179], v[196:199], v[116:119]
	v_mfma_f32_16x16x32_bf16 v[112:115], v[184:187], v[196:199], v[112:115]
	v_mfma_f32_16x16x32_bf16 v[100:103], v[176:179], v[204:207], v[100:103]
	v_mfma_f32_16x16x32_bf16 v[96:99], v[184:187], v[204:207], v[96:99]
	v_mfma_f32_16x16x32_bf16 v[84:87], v[176:179], v[212:215], v[84:87]
	v_mfma_f32_16x16x32_bf16 v[80:83], v[184:187], v[212:215], v[80:83]
	v_mfma_f32_16x16x32_bf16 v[68:71], v[176:179], v[220:223], v[68:71]
	v_mfma_f32_16x16x32_bf16 v[64:67], v[184:187], v[220:223], v[64:67]
	s_setprio 0
	s_barrier
	s_add_i32 s66, s82, s72
	v_lshl_add_u64 v[188:189], s[8:9], 0, v[130:131]
	s_mov_b32 m0, s66
	ds_read_b128 v[192:195], v165 offset:16384
	ds_read_b128 v[196:199], v165 offset:17408
	ds_read_b128 v[200:203], v165 offset:18432
	ds_read_b128 v[204:207], v165 offset:19456
	ds_read_b128 v[208:211], v165 offset:20480
	ds_read_b128 v[212:215], v165 offset:21504
	ds_read_b128 v[216:219], v165 offset:22528
	ds_read_b128 v[220:223], v165 offset:23552
	global_load_lds_dwordx4 v[188:189], off
	s_add_i32 m0, s66, 0x2000
	s_add_u32 s66, s8, 0x40000
	v_lshl_add_u64 v[224:225], s[8:9], 0, v[134:135]
	s_addc_u32 s67, s9, 0
	s_add_i32 s86, s83, s72
	global_load_lds_dwordx4 v[224:225], off
	v_lshl_add_u64 v[226:227], s[66:67], 0, v[130:131]
	s_mov_b32 m0, s86
	v_lshl_add_u64 v[228:229], s[10:11], 0, v[132:133]
	global_load_lds_dwordx4 v[226:227], off
	v_lshl_add_u64 v[226:227], s[66:67], 0, v[134:135]
	s_add_i32 m0, s86, 0x2000
	s_nop 0
	global_load_lds_dwordx4 v[226:227], off
	v_lshl_add_u64 v[226:227], s[10:11], 0, v[128:129]
	s_mov_b32 m0, s73
	s_nop 0
	global_load_lds_dwordx4 v[226:227], off
	s_mov_b32 m0, s74
	s_nop 0
	global_load_lds_dwordx4 v[228:229], off
	s_waitcnt vmcnt(8)
	s_waitcnt lgkmcnt(0)
	s_barrier
	s_setprio 1
	s_waitcnt lgkmcnt(0)
	v_mfma_f32_16x16x32_bf16 v[60:63], v[150:153], v[192:195], v[60:63]
	v_mfma_f32_16x16x32_bf16 v[56:59], v[158:161], v[192:195], v[56:59]
	v_mfma_f32_16x16x32_bf16 v[44:47], v[150:153], v[200:203], v[44:47]
	v_mfma_f32_16x16x32_bf16 v[40:43], v[158:161], v[200:203], v[40:43]
	v_mfma_f32_16x16x32_bf16 v[28:31], v[150:153], v[208:211], v[28:31]
	v_mfma_f32_16x16x32_bf16 v[24:27], v[158:161], v[208:211], v[24:27]
	v_mfma_f32_16x16x32_bf16 v[12:15], v[150:153], v[216:219], v[12:15]
	v_mfma_f32_16x16x32_bf16 v[8:11], v[158:161], v[216:219], v[8:11]
	v_mfma_f32_16x16x32_bf16 v[60:63], v[154:157], v[196:199], v[60:63]
	v_mfma_f32_16x16x32_bf16 v[56:59], v[168:171], v[196:199], v[56:59]
	v_mfma_f32_16x16x32_bf16 v[44:47], v[154:157], v[204:207], v[44:47]
	v_mfma_f32_16x16x32_bf16 v[40:43], v[168:171], v[204:207], v[40:43]
	v_mfma_f32_16x16x32_bf16 v[28:31], v[154:157], v[212:215], v[28:31]
	v_mfma_f32_16x16x32_bf16 v[24:27], v[168:171], v[212:215], v[24:27]
	v_mfma_f32_16x16x32_bf16 v[12:15], v[154:157], v[220:223], v[12:15]
	v_mfma_f32_16x16x32_bf16 v[8:11], v[168:171], v[220:223], v[8:11]
	s_setprio 0
	s_setprio 1
	v_mfma_f32_16x16x32_bf16 v[52:55], v[172:175], v[192:195], v[52:55]
	v_mfma_f32_16x16x32_bf16 v[48:51], v[180:183], v[192:195], v[48:51]
	v_mfma_f32_16x16x32_bf16 v[36:39], v[172:175], v[200:203], v[36:39]
	v_mfma_f32_16x16x32_bf16 v[32:35], v[180:183], v[200:203], v[32:35]
	v_mfma_f32_16x16x32_bf16 v[20:23], v[172:175], v[208:211], v[20:23]
	v_mfma_f32_16x16x32_bf16 v[16:19], v[180:183], v[208:211], v[16:19]
	v_mfma_f32_16x16x32_bf16 v[4:7], v[172:175], v[216:219], v[4:7]
	v_mfma_f32_16x16x32_bf16 v[0:3], v[180:183], v[216:219], v[0:3]
	v_mfma_f32_16x16x32_bf16 v[52:55], v[176:179], v[196:199], v[52:55]
	v_mfma_f32_16x16x32_bf16 v[48:51], v[184:187], v[196:199], v[48:51]
	v_mfma_f32_16x16x32_bf16 v[36:39], v[176:179], v[204:207], v[36:39]
	v_mfma_f32_16x16x32_bf16 v[32:35], v[184:187], v[204:207], v[32:35]
	v_mfma_f32_16x16x32_bf16 v[20:23], v[176:179], v[212:215], v[20:23]
	v_mfma_f32_16x16x32_bf16 v[16:19], v[184:187], v[212:215], v[16:19]
	v_mfma_f32_16x16x32_bf16 v[4:7], v[176:179], v[220:223], v[4:7]
	v_mfma_f32_16x16x32_bf16 v[0:3], v[184:187], v[220:223], v[0:3]
	s_setprio 0
	s_barrier
	s_add_i32 s66, 0, 0x18000
	v_add_u32_e32 v136, s66, v162
	s_add_i32 s67, 0, 0x1c000
	ds_read_b128 v[150:153], v136
	ds_read_b128 v[154:157], v136 offset:1024
	ds_read_b128 v[158:161], v136 offset:2048
	ds_read_b128 v[168:171], v136 offset:3072
	v_add_u32_e32 v136, s67, v162
	ds_read_b128 v[172:175], v136
	ds_read_b128 v[176:179], v136 offset:1024
	ds_read_b128 v[180:183], v136 offset:2048
	ds_read_b128 v[184:187], v136 offset:3072
	s_add_u32 s10, s10, 0x40000
	s_addc_u32 s11, s11, 0
	s_mov_b32 m0, s75
	v_lshl_add_u64 v[230:231], s[10:11], 0, v[128:129]
	ds_read_b128 v[192:195], v165 offset:32768
	ds_read_b128 v[196:199], v165 offset:33792
	ds_read_b128 v[200:203], v165 offset:34816
	ds_read_b128 v[204:207], v165 offset:35840
	ds_read_b128 v[208:211], v165 offset:36864
	ds_read_b128 v[212:215], v165 offset:37888
	ds_read_b128 v[216:219], v165 offset:38912
	ds_read_b128 v[220:223], v165 offset:39936
	global_load_lds_dwordx4 v[230:231], off
	v_lshl_add_u64 v[230:231], s[10:11], 0, v[132:133]
	s_mov_b32 m0, s76
	s_nop 0
	global_load_lds_dwordx4 v[230:231], off
	s_waitcnt vmcnt(8)
	s_waitcnt lgkmcnt(0)
	s_barrier
	s_setprio 1
	s_waitcnt lgkmcnt(0)
	v_mfma_f32_16x16x32_bf16 v[124:127], v[150:153], v[192:195], v[124:127]
	v_mfma_f32_16x16x32_bf16 v[120:123], v[158:161], v[192:195], v[120:123]
	v_mfma_f32_16x16x32_bf16 v[108:111], v[150:153], v[200:203], v[108:111]
	v_mfma_f32_16x16x32_bf16 v[104:107], v[158:161], v[200:203], v[104:107]
	v_mfma_f32_16x16x32_bf16 v[92:95], v[150:153], v[208:211], v[92:95]
	v_mfma_f32_16x16x32_bf16 v[88:91], v[158:161], v[208:211], v[88:91]
	v_mfma_f32_16x16x32_bf16 v[76:79], v[150:153], v[216:219], v[76:79]
	v_mfma_f32_16x16x32_bf16 v[72:75], v[158:161], v[216:219], v[72:75]
	v_mfma_f32_16x16x32_bf16 v[124:127], v[154:157], v[196:199], v[124:127]
	v_mfma_f32_16x16x32_bf16 v[120:123], v[168:171], v[196:199], v[120:123]
	v_mfma_f32_16x16x32_bf16 v[108:111], v[154:157], v[204:207], v[108:111]
	v_mfma_f32_16x16x32_bf16 v[104:107], v[168:171], v[204:207], v[104:107]
	v_mfma_f32_16x16x32_bf16 v[92:95], v[154:157], v[212:215], v[92:95]
	v_mfma_f32_16x16x32_bf16 v[88:91], v[168:171], v[212:215], v[88:91]
	v_mfma_f32_16x16x32_bf16 v[76:79], v[154:157], v[220:223], v[76:79]
	v_mfma_f32_16x16x32_bf16 v[72:75], v[168:171], v[220:223], v[72:75]
	s_setprio 0
	s_setprio 1
	v_mfma_f32_16x16x32_bf16 v[116:119], v[172:175], v[192:195], v[116:119]
	v_mfma_f32_16x16x32_bf16 v[112:115], v[180:183], v[192:195], v[112:115]
	v_mfma_f32_16x16x32_bf16 v[100:103], v[172:175], v[200:203], v[100:103]
	v_mfma_f32_16x16x32_bf16 v[96:99], v[180:183], v[200:203], v[96:99]
	v_mfma_f32_16x16x32_bf16 v[84:87], v[172:175], v[208:211], v[84:87]
	v_mfma_f32_16x16x32_bf16 v[80:83], v[180:183], v[208:211], v[80:83]
	v_mfma_f32_16x16x32_bf16 v[68:71], v[172:175], v[216:219], v[68:71]
	v_mfma_f32_16x16x32_bf16 v[64:67], v[180:183], v[216:219], v[64:67]
	v_mfma_f32_16x16x32_bf16 v[116:119], v[176:179], v[196:199], v[116:119]
	v_mfma_f32_16x16x32_bf16 v[112:115], v[184:187], v[196:199], v[112:115]
	v_mfma_f32_16x16x32_bf16 v[100:103], v[176:179], v[204:207], v[100:103]
	v_mfma_f32_16x16x32_bf16 v[96:99], v[184:187], v[204:207], v[96:99]
	v_mfma_f32_16x16x32_bf16 v[84:87], v[176:179], v[212:215], v[84:87]
	v_mfma_f32_16x16x32_bf16 v[80:83], v[184:187], v[212:215], v[80:83]
	v_mfma_f32_16x16x32_bf16 v[68:71], v[176:179], v[220:223], v[68:71]
	v_mfma_f32_16x16x32_bf16 v[64:67], v[184:187], v[220:223], v[64:67]
	s_setprio 0
	s_barrier
	s_add_i32 s10, s66, s72
	v_lshl_add_u64 v[188:189], v[188:189], 0, s[48:49]
	s_mov_b32 m0, s10
	ds_read_b128 v[192:195], v165 offset:49152
	ds_read_b128 v[196:199], v165 offset:50176
	ds_read_b128 v[200:203], v165 offset:51200
	ds_read_b128 v[204:207], v165 offset:52224
	ds_read_b128 v[208:211], v165 offset:53248
	ds_read_b128 v[212:215], v165 offset:54272
	ds_read_b128 v[216:219], v165 offset:55296
	ds_read_b128 v[220:223], v165 offset:56320
	global_load_lds_dwordx4 v[188:189], off
	s_add_i32 m0, s10, 0x2000
	s_add_u32 s8, s8, 0x40080
	v_lshl_add_u64 v[188:189], v[224:225], 0, s[48:49]
	s_addc_u32 s9, s9, 0
	s_add_i32 s10, s67, s72
	global_load_lds_dwordx4 v[188:189], off
	v_lshl_add_u64 v[188:189], s[8:9], 0, v[130:131]
	s_mov_b32 m0, s10
	s_nop 0
	global_load_lds_dwordx4 v[188:189], off
	v_lshl_add_u64 v[188:189], s[8:9], 0, v[134:135]
	s_add_i32 m0, s10, 0x2000
	s_nop 0
	global_load_lds_dwordx4 v[188:189], off
	v_lshl_add_u64 v[188:189], v[226:227], 0, s[48:49]
	s_mov_b32 m0, s77
	s_nop 0
	global_load_lds_dwordx4 v[188:189], off
	v_lshl_add_u64 v[188:189], v[228:229], 0, s[48:49]
	s_mov_b32 m0, s78
	s_nop 0
	global_load_lds_dwordx4 v[188:189], off
	s_waitcnt vmcnt(8)
	s_waitcnt lgkmcnt(0)
	s_barrier
	s_setprio 1
	s_waitcnt lgkmcnt(0)
	v_mfma_f32_16x16x32_bf16 v[60:63], v[150:153], v[192:195], v[60:63]
	v_mfma_f32_16x16x32_bf16 v[56:59], v[158:161], v[192:195], v[56:59]
	v_mfma_f32_16x16x32_bf16 v[44:47], v[150:153], v[200:203], v[44:47]
	v_mfma_f32_16x16x32_bf16 v[40:43], v[158:161], v[200:203], v[40:43]
	v_mfma_f32_16x16x32_bf16 v[28:31], v[150:153], v[208:211], v[28:31]
	v_mfma_f32_16x16x32_bf16 v[24:27], v[158:161], v[208:211], v[24:27]
	v_mfma_f32_16x16x32_bf16 v[12:15], v[150:153], v[216:219], v[12:15]
	v_mfma_f32_16x16x32_bf16 v[8:11], v[158:161], v[216:219], v[8:11]
	v_mfma_f32_16x16x32_bf16 v[60:63], v[154:157], v[196:199], v[60:63]
	v_mfma_f32_16x16x32_bf16 v[56:59], v[168:171], v[196:199], v[56:59]
	v_mfma_f32_16x16x32_bf16 v[44:47], v[154:157], v[204:207], v[44:47]
	v_mfma_f32_16x16x32_bf16 v[40:43], v[168:171], v[204:207], v[40:43]
	v_mfma_f32_16x16x32_bf16 v[28:31], v[154:157], v[212:215], v[28:31]
	v_mfma_f32_16x16x32_bf16 v[24:27], v[168:171], v[212:215], v[24:27]
	v_mfma_f32_16x16x32_bf16 v[12:15], v[154:157], v[220:223], v[12:15]
	v_mfma_f32_16x16x32_bf16 v[8:11], v[168:171], v[220:223], v[8:11]
	s_setprio 0
	s_setprio 1
	v_mfma_f32_16x16x32_bf16 v[52:55], v[172:175], v[192:195], v[52:55]
	v_mfma_f32_16x16x32_bf16 v[48:51], v[180:183], v[192:195], v[48:51]
	v_mfma_f32_16x16x32_bf16 v[36:39], v[172:175], v[200:203], v[36:39]
	v_mfma_f32_16x16x32_bf16 v[32:35], v[180:183], v[200:203], v[32:35]
	v_mfma_f32_16x16x32_bf16 v[20:23], v[172:175], v[208:211], v[20:23]
	v_mfma_f32_16x16x32_bf16 v[16:19], v[180:183], v[208:211], v[16:19]
	v_mfma_f32_16x16x32_bf16 v[4:7], v[172:175], v[216:219], v[4:7]
	v_mfma_f32_16x16x32_bf16 v[0:3], v[180:183], v[216:219], v[0:3]
	v_mfma_f32_16x16x32_bf16 v[52:55], v[176:179], v[196:199], v[52:55]
	v_mfma_f32_16x16x32_bf16 v[48:51], v[184:187], v[196:199], v[48:51]
	v_mfma_f32_16x16x32_bf16 v[36:39], v[176:179], v[204:207], v[36:39]
	v_mfma_f32_16x16x32_bf16 v[32:35], v[184:187], v[204:207], v[32:35]
	v_mfma_f32_16x16x32_bf16 v[20:23], v[176:179], v[212:215], v[20:23]
	v_mfma_f32_16x16x32_bf16 v[16:19], v[184:187], v[212:215], v[16:19]
	v_mfma_f32_16x16x32_bf16 v[4:7], v[176:179], v[220:223], v[4:7]
	v_mfma_f32_16x16x32_bf16 v[0:3], v[184:187], v[220:223], v[0:3]
	s_setprio 0
	s_barrier
	s_add_i32 s65, s65, 2
	s_add_u32 s59, s59, 0x100
	s_addc_u32 s64, s64, 0
	s_add_u32 s6, s6, 0x100
	s_addc_u32 s7, s7, 0
	s_cmp_gt_u32 s65, 13
	s_cbranch_scc0 .LBB0_571
	v_lshl_add_u32 v210, s2, 8, v139
	v_ashrrev_i32_e32 v211, 31, v210
	v_lshl_add_u64 v[208:209], v[210:211], 2, s[46:47]
	global_load_dword v200, v[208:209], off
	global_load_dword v201, v[208:209], off offset:64
	global_load_dword v202, v[208:209], off offset:128
	global_load_dword v203, v[208:209], off offset:192
	global_load_dword v204, v[208:209], off offset:512
	global_load_dword v205, v[208:209], off offset:576
	global_load_dword v206, v[208:209], off offset:640
	global_load_dword v207, v[208:209], off offset:704
	s_and_b64 vcc, exec, s[50:51]
	s_cbranch_vccz .LBB0_574
	s_barrier
.LBB0_574:
	v_lshl_add_u32 v150, s2, 8, v139
	v_ashrrev_i32_e32 v151, 31, v150
	v_lshl_add_u64 v[152:153], v[150:151], 2, s[46:47]
	s_cmp_lt_i32 s4, 20
	s_cselect_b64 s[8:9], -1, 0
	s_cmp_gt_i32 s4, 19
	s_cselect_b64 s[66:67], -1, 0
	s_cmp_gt_i32 s4, 7
	s_cselect_b64 s[10:11], -1, 0
	s_mov_b64 s[6:7], -1
	s_waitcnt vmcnt(0) lgkmcnt(0)
	v_fmamk_f32 v136, v200, 0x3a800000, v166
	v_cmp_gt_f32_e32 vcc, s84, v136
	v_mul_f32_e32 v154, 0x4b800000, v136
	s_nop 0
	v_cndmask_b32_e32 v136, v136, v154, vcc
	v_rsq_f32_e32 v136, v136
	s_nop 0
	v_mul_f32_e32 v154, 0x45800000, v136
	v_cndmask_b32_e32 v154, v136, v154, vcc
	v_cndmask_b32_e64 v136, 0, 1, s[52:53]
	v_pk_mul_f32 v[126:127], v[126:127], v[154:155] op_sel_hi:[1,0]
	v_pk_mul_f32 v[124:125], v[124:125], v[154:155] op_sel_hi:[1,0]
	v_pk_mul_f32 v[122:123], v[122:123], v[154:155] op_sel_hi:[1,0]
	v_pk_mul_f32 v[120:121], v[120:121], v[154:155] op_sel_hi:[1,0]
	s_and_b64 vcc, exec, s[66:67]
	v_cmp_ne_u32_e64 s[2:3], 1, v136
	s_cbranch_vccz .LBB0_578
	s_and_b64 vcc, exec, s[2:3]
	s_cbranch_vccnz .LBB0_577
	v_lshlrev_b64 v[156:157], 7, v[150:151]
	v_lshl_add_u64 v[156:157], v[140:141], 0, v[156:157]
	global_store_dwordx4 v[156:157], v[124:127], off
	global_store_dwordx4 v[156:157], v[120:123], off offset:16

.LBB0_590:
	s_nop 1
	v_or_b32_e32 v114, 16, v150
	v_ashrrev_i32_e32 v115, 31, v114
	v_lshl_add_u64 v[112:113], v[114:115], 2, s[46:47]
	s_nop 1
	s_andn2_b64 vcc, exec, s[66:67]
	v_fmamk_f32 v112, v201, 0x3a800000, v166
	v_mul_f32_e32 v113, 0x4b800000, v112
	v_cmp_gt_f32_e64 s[10:11], s84, v112
	s_nop 1
	v_cndmask_b32_e64 v112, v112, v113, s[10:11]
	v_rsq_f32_e32 v112, v112
	v_cndmask_b32_e64 v113, 0, 1, s[66:67]
	v_cmp_ne_u32_e64 s[8:9], 1, v113
	v_mul_f32_e32 v113, 0x45800000, v112
	v_cndmask_b32_e64 v112, v112, v113, s[10:11]
	v_pk_mul_f32 v[110:111], v[110:111], v[112:113] op_sel_hi:[1,0]
	v_pk_mul_f32 v[108:109], v[108:109], v[112:113] op_sel_hi:[1,0]
	v_pk_mul_f32 v[106:107], v[106:107], v[112:113] op_sel_hi:[1,0]
	v_pk_mul_f32 v[104:105], v[104:105], v[112:113] op_sel_hi:[1,0]
	s_mov_b64 s[10:11], -1
	s_cbranch_vccz .LBB0_593
	v_mad_i64_i32 v[116:117], s[66:67], v114, s85, 0
	s_andn2_b64 vcc, exec, s[10:11]
	v_lshlrev_b64 v[114:115], 12, v[114:115]
	s_cbranch_vccz .LBB0_596

.LBB0_606:
	s_nop 1
	v_or_b32_e32 v98, 32, v150
	v_ashrrev_i32_e32 v99, 31, v98
	v_lshl_add_u64 v[96:97], v[98:99], 2, s[46:47]
	s_nop 1
	s_and_b64 vcc, exec, s[8:9]
	v_fmamk_f32 v96, v202, 0x3a800000, v166
	v_mul_f32_e32 v97, 0x4b800000, v96
	v_cmp_gt_f32_e64 s[10:11], s84, v96
	s_nop 1
	v_cndmask_b32_e64 v96, v96, v97, s[10:11]
	v_rsq_f32_e32 v96, v96
	s_nop 0
	v_mul_f32_e32 v97, 0x45800000, v96
	v_cndmask_b32_e64 v96, v96, v97, s[10:11]
	v_pk_mul_f32 v[94:95], v[94:95], v[96:97] op_sel_hi:[1,0]
	v_pk_mul_f32 v[92:93], v[92:93], v[96:97] op_sel_hi:[1,0]
	v_pk_mul_f32 v[90:91], v[90:91], v[96:97] op_sel_hi:[1,0]
	v_pk_mul_f32 v[88:89], v[88:89], v[96:97] op_sel_hi:[1,0]
	s_mov_b64 s[10:11], -1
	s_cbranch_vccz .LBB0_609
	v_mad_i64_i32 v[100:101], s[66:67], v98, s85, 0
	s_andn2_b64 vcc, exec, s[10:11]
	v_lshlrev_b64 v[98:99], 12, v[98:99]
	s_cbranch_vccz .LBB0_612

.LBB0_622:
	s_nop 1
	v_or_b32_e32 v82, 48, v150
	v_ashrrev_i32_e32 v83, 31, v82
	v_lshl_add_u64 v[80:81], v[82:83], 2, s[46:47]
	s_nop 1
	s_and_b64 vcc, exec, s[8:9]
	v_fmamk_f32 v80, v203, 0x3a800000, v166
	v_mul_f32_e32 v81, 0x4b800000, v80
	v_cmp_gt_f32_e64 s[10:11], s84, v80
	s_nop 1
	v_cndmask_b32_e64 v80, v80, v81, s[10:11]
	v_rsq_f32_e32 v80, v80
	s_nop 0
	v_mul_f32_e32 v81, 0x45800000, v80
	v_cndmask_b32_e64 v80, v80, v81, s[10:11]
	v_pk_mul_f32 v[78:79], v[78:79], v[80:81] op_sel_hi:[1,0]
	v_pk_mul_f32 v[76:77], v[76:77], v[80:81] op_sel_hi:[1,0]
	v_pk_mul_f32 v[74:75], v[74:75], v[80:81] op_sel_hi:[1,0]
	v_pk_mul_f32 v[72:73], v[72:73], v[80:81] op_sel_hi:[1,0]
	s_mov_b64 s[10:11], -1
	s_cbranch_vccz .LBB0_625
	v_mad_i64_i32 v[84:85], s[66:67], v82, s85, 0
	s_andn2_b64 vcc, exec, s[10:11]
	v_lshlrev_b64 v[82:83], 12, v[82:83]
	s_cbranch_vccz .LBB0_628

.LBB0_638:
	s_nop 1
	s_nop 0
	v_add_u32_e32 v66, 0x80, v150
	s_and_b64 vcc, exec, s[8:9]
	v_ashrrev_i32_e32 v67, 31, v66
	v_fmamk_f32 v64, v204, 0x3a800000, v166
	v_mul_f32_e32 v65, 0x4b800000, v64
	v_cmp_gt_f32_e64 s[10:11], s84, v64
	s_nop 1
	v_cndmask_b32_e64 v64, v64, v65, s[10:11]
	v_rsq_f32_e32 v64, v64
	s_nop 0
	v_mul_f32_e32 v65, 0x45800000, v64
	v_cndmask_b32_e64 v64, v64, v65, s[10:11]
	v_pk_mul_f32 v[62:63], v[62:63], v[64:65] op_sel_hi:[1,0]
	v_pk_mul_f32 v[60:61], v[60:61], v[64:65] op_sel_hi:[1,0]
	v_pk_mul_f32 v[58:59], v[58:59], v[64:65] op_sel_hi:[1,0]
	v_pk_mul_f32 v[56:57], v[56:57], v[64:65] op_sel_hi:[1,0]
	s_mov_b64 s[10:11], -1
	s_cbranch_vccz .LBB0_641
	v_mad_i64_i32 v[68:69], s[66:67], v66, s85, 0
	s_andn2_b64 vcc, exec, s[10:11]
	v_lshlrev_b64 v[66:67], 12, v[66:67]
	s_cbranch_vccz .LBB0_644

.LBB0_654:
	s_nop 1
	s_nop 0
	v_add_u32_e32 v50, 0x90, v150
	s_and_b64 vcc, exec, s[8:9]
	v_ashrrev_i32_e32 v51, 31, v50
	v_fmamk_f32 v48, v205, 0x3a800000, v166
	v_mul_f32_e32 v49, 0x4b800000, v48
	v_cmp_gt_f32_e64 s[10:11], s84, v48
	s_nop 1
	v_cndmask_b32_e64 v48, v48, v49, s[10:11]
	v_rsq_f32_e32 v48, v48
	s_nop 0
	v_mul_f32_e32 v49, 0x45800000, v48
	v_cndmask_b32_e64 v48, v48, v49, s[10:11]
	v_pk_mul_f32 v[46:47], v[46:47], v[48:49] op_sel_hi:[1,0]
	v_pk_mul_f32 v[44:45], v[44:45], v[48:49] op_sel_hi:[1,0]
	v_pk_mul_f32 v[42:43], v[42:43], v[48:49] op_sel_hi:[1,0]
	v_pk_mul_f32 v[40:41], v[40:41], v[48:49] op_sel_hi:[1,0]
	s_mov_b64 s[10:11], -1
	s_cbranch_vccz .LBB0_657
	v_mad_i64_i32 v[52:53], s[66:67], v50, s85, 0
	s_andn2_b64 vcc, exec, s[10:11]
	v_lshlrev_b64 v[50:51], 12, v[50:51]
	s_cbranch_vccz .LBB0_660

.LBB0_670:
	s_nop 1
	s_nop 0
	v_add_u32_e32 v34, 0xa0, v150
	s_and_b64 vcc, exec, s[8:9]
	v_ashrrev_i32_e32 v35, 31, v34
	v_fmamk_f32 v32, v206, 0x3a800000, v166
	v_mul_f32_e32 v33, 0x4b800000, v32
	v_cmp_gt_f32_e64 s[10:11], s84, v32
	s_nop 1
	v_cndmask_b32_e64 v32, v32, v33, s[10:11]
	v_rsq_f32_e32 v32, v32
	s_nop 0
	v_mul_f32_e32 v33, 0x45800000, v32
	v_cndmask_b32_e64 v32, v32, v33, s[10:11]
	v_pk_mul_f32 v[30:31], v[30:31], v[32:33] op_sel_hi:[1,0]
	v_pk_mul_f32 v[28:29], v[28:29], v[32:33] op_sel_hi:[1,0]
	v_pk_mul_f32 v[26:27], v[26:27], v[32:33] op_sel_hi:[1,0]
	v_pk_mul_f32 v[24:25], v[24:25], v[32:33] op_sel_hi:[1,0]
	s_mov_b64 s[10:11], -1
	s_cbranch_vccz .LBB0_673
	v_mad_i64_i32 v[36:37], s[66:67], v34, s85, 0
	s_andn2_b64 vcc, exec, s[10:11]
	v_lshlrev_b64 v[34:35], 12, v[34:35]
	s_cbranch_vccz .LBB0_676

.LBB0_686:
	s_nop 1
	s_nop 0
	v_add_u32_e32 v18, 0xb0, v150
	s_and_b64 vcc, exec, s[8:9]
	v_ashrrev_i32_e32 v19, 31, v18
	s_mov_b64 s[8:9], -1
	v_fmamk_f32 v16, v207, 0x3a800000, v166
	v_mul_f32_e32 v17, 0x4b800000, v16
	v_cmp_gt_f32_e64 s[10:11], s84, v16
	s_nop 1
	v_cndmask_b32_e64 v16, v16, v17, s[10:11]
	v_rsq_f32_e32 v16, v16
	s_nop 0
	v_mul_f32_e32 v17, 0x45800000, v16
	v_cndmask_b32_e64 v16, v16, v17, s[10:11]
	v_pk_mul_f32 v[14:15], v[14:15], v[16:17] op_sel_hi:[1,0]
	v_pk_mul_f32 v[12:13], v[12:13], v[16:17] op_sel_hi:[1,0]
	v_pk_mul_f32 v[10:11], v[10:11], v[16:17] op_sel_hi:[1,0]
	v_pk_mul_f32 v[8:9], v[8:9], v[16:17] op_sel_hi:[1,0]
	s_cbranch_vccz .LBB0_690
	v_mad_i64_i32 v[20:21], s[2:3], v18, s85, 0
	s_andn2_b64 vcc, exec, s[8:9]
	v_lshlrev_b64 v[18:19], 12, v[18:19]
	s_cbranch_vccz .LBB0_693

.LBB0_1106:
	ds_read_b128 v[150:153], v163
	ds_read_b128 v[154:157], v163 offset:1024
	ds_read_b128 v[158:161], v163 offset:2048
	ds_read_b128 v[168:171], v163 offset:3072
	ds_read_b128 v[172:175], v164
	ds_read_b128 v[176:179], v164 offset:1024
	ds_read_b128 v[180:183], v164 offset:2048
	ds_read_b128 v[184:187], v164 offset:3072
	s_add_u32 s36, s34, 0xfffc0080
	s_addc_u32 s37, s35, -1
	s_cmp_eq_u32 s63, 12
	s_cselect_b32 s39, s19, s37
	s_cselect_b32 s38, s23, s36
	s_cselect_b32 s37, s21, s62
	s_cselect_b32 s36, s31, s33
	v_lshl_add_u64 v[188:189], s[34:35], 0, v[142:143]
	s_add_i32 m0, s47, 0xc000
	ds_read_b128 v[192:195], v165
	ds_read_b128 v[196:199], v165 offset:1024
	ds_read_b128 v[200:203], v165 offset:2048
	ds_read_b128 v[204:207], v165 offset:3072
	ds_read_b128 v[208:211], v165 offset:4096
	ds_read_b128 v[212:215], v165 offset:5120
	ds_read_b128 v[216:219], v165 offset:6144
	ds_read_b128 v[220:223], v165 offset:7168
	global_load_lds_dwordx4 v[188:189], off
	v_lshl_add_u64 v[188:189], s[34:35], 0, v[140:141]
	s_add_i32 m0, s47, 0xe000
	s_nop 0
	global_load_lds_dwordx4 v[188:189], off
	s_waitcnt vmcnt(8)
	s_waitcnt lgkmcnt(0)
	s_barrier
	s_setprio 1
	s_waitcnt lgkmcnt(0)
	v_mfma_f32_16x16x32_bf16 v[124:127], v[150:153], v[192:195], v[124:127]
	v_mfma_f32_16x16x32_bf16 v[120:123], v[158:161], v[192:195], v[120:123]
	v_mfma_f32_16x16x32_bf16 v[108:111], v[150:153], v[200:203], v[108:111]
	v_mfma_f32_16x16x32_bf16 v[104:107], v[158:161], v[200:203], v[104:107]
	v_mfma_f32_16x16x32_bf16 v[92:95], v[150:153], v[208:211], v[92:95]
	v_mfma_f32_16x16x32_bf16 v[88:91], v[158:161], v[208:211], v[88:91]
	v_mfma_f32_16x16x32_bf16 v[76:79], v[150:153], v[216:219], v[76:79]
	v_mfma_f32_16x16x32_bf16 v[72:75], v[158:161], v[216:219], v[72:75]
	v_mfma_f32_16x16x32_bf16 v[124:127], v[154:157], v[196:199], v[124:127]
	v_mfma_f32_16x16x32_bf16 v[120:123], v[168:171], v[196:199], v[120:123]
	v_mfma_f32_16x16x32_bf16 v[108:111], v[154:157], v[204:207], v[108:111]
	v_mfma_f32_16x16x32_bf16 v[104:107], v[168:171], v[204:207], v[104:107]
	v_mfma_f32_16x16x32_bf16 v[92:95], v[154:157], v[212:215], v[92:95]
	v_mfma_f32_16x16x32_bf16 v[88:91], v[168:171], v[212:215], v[88:91]
	v_mfma_f32_16x16x32_bf16 v[76:79], v[154:157], v[220:223], v[76:79]
	v_mfma_f32_16x16x32_bf16 v[72:75], v[168:171], v[220:223], v[72:75]
	s_setprio 0
	s_setprio 1
	v_mfma_f32_16x16x32_bf16 v[116:119], v[172:175], v[192:195], v[116:119]
	v_mfma_f32_16x16x32_bf16 v[112:115], v[180:183], v[192:195], v[112:115]
	v_mfma_f32_16x16x32_bf16 v[100:103], v[172:175], v[200:203], v[100:103]
	v_mfma_f32_16x16x32_bf16 v[96:99], v[180:183], v[200:203], v[96:99]
	v_mfma_f32_16x16x32_bf16 v[84:87], v[172:175], v[208:211], v[84:87]
	v_mfma_f32_16x16x32_bf16 v[80:83], v[180:183], v[208:211], v[80:83]
	v_mfma_f32_16x16x32_bf16 v[68:71], v[172:175], v[216:219], v[68:71]
	v_mfma_f32_16x16x32_bf16 v[64:67], v[180:183], v[216:219], v[64:67]
	v_mfma_f32_16x16x32_bf16 v[116:119], v[176:179], v[196:199], v[116:119]
	v_mfma_f32_16x16x32_bf16 v[112:115], v[184:187], v[196:199], v[112:115]
	v_mfma_f32_16x16x32_bf16 v[100:103], v[176:179], v[204:207], v[100:103]
	v_mfma_f32_16x16x32_bf16 v[96:99], v[184:187], v[204:207], v[96:99]
	v_mfma_f32_16x16x32_bf16 v[84:87], v[176:179], v[212:215], v[84:87]
	v_mfma_f32_16x16x32_bf16 v[80:83], v[184:187], v[212:215], v[80:83]
	v_mfma_f32_16x16x32_bf16 v[68:71], v[176:179], v[220:223], v[68:71]
	v_mfma_f32_16x16x32_bf16 v[64:67], v[184:187], v[220:223], v[64:67]
	s_setprio 0
	s_barrier
	s_add_i32 s64, s55, s44
	v_lshl_add_u64 v[188:189], s[36:37], 0, v[132:133]
	s_mov_b32 m0, s64
	ds_read_b128 v[192:195], v165 offset:16384
	ds_read_b128 v[196:199], v165 offset:17408
	ds_read_b128 v[200:203], v165 offset:18432
	ds_read_b128 v[204:207], v165 offset:19456
	ds_read_b128 v[208:211], v165 offset:20480
	ds_read_b128 v[212:215], v165 offset:21504
	ds_read_b128 v[216:219], v165 offset:22528
	ds_read_b128 v[220:223], v165 offset:23552
	global_load_lds_dwordx4 v[188:189], off
	s_add_i32 m0, s64, 0x2000
	s_add_u32 s64, s36, 0x40000
	v_lshl_add_u64 v[224:225], s[36:37], 0, v[128:129]
	s_addc_u32 s65, s37, 0
	s_add_i32 s66, s56, s44
	global_load_lds_dwordx4 v[224:225], off
	v_lshl_add_u64 v[226:227], s[64:65], 0, v[132:133]
	s_mov_b32 m0, s66
	v_lshl_add_u64 v[228:229], s[38:39], 0, v[130:131]
	global_load_lds_dwordx4 v[226:227], off
	v_lshl_add_u64 v[226:227], s[64:65], 0, v[128:129]
	s_add_i32 m0, s66, 0x2000
	s_nop 0
	global_load_lds_dwordx4 v[226:227], off
	v_lshl_add_u64 v[226:227], s[38:39], 0, v[134:135]
	s_mov_b32 m0, s47
	s_nop 0
	global_load_lds_dwordx4 v[226:227], off
	s_mov_b32 m0, s48
	s_nop 0
	global_load_lds_dwordx4 v[228:229], off
	s_waitcnt vmcnt(8)
	s_waitcnt lgkmcnt(0)
	s_barrier
	s_setprio 1
	s_waitcnt lgkmcnt(0)
	v_mfma_f32_16x16x32_bf16 v[60:63], v[150:153], v[192:195], v[60:63]
	v_mfma_f32_16x16x32_bf16 v[56:59], v[158:161], v[192:195], v[56:59]
	v_mfma_f32_16x16x32_bf16 v[44:47], v[150:153], v[200:203], v[44:47]
	v_mfma_f32_16x16x32_bf16 v[40:43], v[158:161], v[200:203], v[40:43]
	v_mfma_f32_16x16x32_bf16 v[28:31], v[150:153], v[208:211], v[28:31]
	v_mfma_f32_16x16x32_bf16 v[24:27], v[158:161], v[208:211], v[24:27]
	v_mfma_f32_16x16x32_bf16 v[12:15], v[150:153], v[216:219], v[12:15]
	v_mfma_f32_16x16x32_bf16 v[8:11], v[158:161], v[216:219], v[8:11]
	v_mfma_f32_16x16x32_bf16 v[60:63], v[154:157], v[196:199], v[60:63]
	v_mfma_f32_16x16x32_bf16 v[56:59], v[168:171], v[196:199], v[56:59]
	v_mfma_f32_16x16x32_bf16 v[44:47], v[154:157], v[204:207], v[44:47]
	v_mfma_f32_16x16x32_bf16 v[40:43], v[168:171], v[204:207], v[40:43]
	v_mfma_f32_16x16x32_bf16 v[28:31], v[154:157], v[212:215], v[28:31]
	v_mfma_f32_16x16x32_bf16 v[24:27], v[168:171], v[212:215], v[24:27]
	v_mfma_f32_16x16x32_bf16 v[12:15], v[154:157], v[220:223], v[12:15]
	v_mfma_f32_16x16x32_bf16 v[8:11], v[168:171], v[220:223], v[8:11]
	s_setprio 0
	s_setprio 1
	v_mfma_f32_16x16x32_bf16 v[52:55], v[172:175], v[192:195], v[52:55]
	v_mfma_f32_16x16x32_bf16 v[48:51], v[180:183], v[192:195], v[48:51]
	v_mfma_f32_16x16x32_bf16 v[36:39], v[172:175], v[200:203], v[36:39]
	v_mfma_f32_16x16x32_bf16 v[32:35], v[180:183], v[200:203], v[32:35]
	v_mfma_f32_16x16x32_bf16 v[20:23], v[172:175], v[208:211], v[20:23]
	v_mfma_f32_16x16x32_bf16 v[16:19], v[180:183], v[208:211], v[16:19]
	v_mfma_f32_16x16x32_bf16 v[4:7], v[172:175], v[216:219], v[4:7]
	v_mfma_f32_16x16x32_bf16 v[0:3], v[180:183], v[216:219], v[0:3]
	v_mfma_f32_16x16x32_bf16 v[52:55], v[176:179], v[196:199], v[52:55]
	v_mfma_f32_16x16x32_bf16 v[48:51], v[184:187], v[196:199], v[48:51]
	v_mfma_f32_16x16x32_bf16 v[36:39], v[176:179], v[204:207], v[36:39]
	v_mfma_f32_16x16x32_bf16 v[32:35], v[184:187], v[204:207], v[32:35]
	v_mfma_f32_16x16x32_bf16 v[20:23], v[176:179], v[212:215], v[20:23]
	v_mfma_f32_16x16x32_bf16 v[16:19], v[184:187], v[212:215], v[16:19]
	v_mfma_f32_16x16x32_bf16 v[4:7], v[176:179], v[220:223], v[4:7]
	v_mfma_f32_16x16x32_bf16 v[0:3], v[184:187], v[220:223], v[0:3]
	s_setprio 0
	s_barrier
	s_add_i32 s64, 0, 0x18000
	v_add_u32_e32 v136, s64, v162
	s_add_i32 s65, 0, 0x1c000
	ds_read_b128 v[150:153], v136
	ds_read_b128 v[154:157], v136 offset:1024
	ds_read_b128 v[158:161], v136 offset:2048
	ds_read_b128 v[168:171], v136 offset:3072
	v_add_u32_e32 v136, s65, v162
	ds_read_b128 v[172:175], v136
	ds_read_b128 v[176:179], v136 offset:1024
	ds_read_b128 v[180:183], v136 offset:2048
	ds_read_b128 v[184:187], v136 offset:3072
	s_add_u32 s38, s38, 0x40000
	s_addc_u32 s39, s39, 0
	s_mov_b32 m0, s49
	v_lshl_add_u64 v[230:231], s[38:39], 0, v[134:135]
	ds_read_b128 v[192:195], v165 offset:32768
	ds_read_b128 v[196:199], v165 offset:33792
	ds_read_b128 v[200:203], v165 offset:34816
	ds_read_b128 v[204:207], v165 offset:35840
	ds_read_b128 v[208:211], v165 offset:36864
	ds_read_b128 v[212:215], v165 offset:37888
	ds_read_b128 v[216:219], v165 offset:38912
	ds_read_b128 v[220:223], v165 offset:39936
	global_load_lds_dwordx4 v[230:231], off
	v_lshl_add_u64 v[230:231], s[38:39], 0, v[130:131]
	s_mov_b32 m0, s50
	s_nop 0
	global_load_lds_dwordx4 v[230:231], off
	s_waitcnt vmcnt(8)
	s_waitcnt lgkmcnt(0)
	s_barrier
	s_setprio 1
	s_waitcnt lgkmcnt(0)
	v_mfma_f32_16x16x32_bf16 v[124:127], v[150:153], v[192:195], v[124:127]
	v_mfma_f32_16x16x32_bf16 v[120:123], v[158:161], v[192:195], v[120:123]
	v_mfma_f32_16x16x32_bf16 v[108:111], v[150:153], v[200:203], v[108:111]
	v_mfma_f32_16x16x32_bf16 v[104:107], v[158:161], v[200:203], v[104:107]
	v_mfma_f32_16x16x32_bf16 v[92:95], v[150:153], v[208:211], v[92:95]
	v_mfma_f32_16x16x32_bf16 v[88:91], v[158:161], v[208:211], v[88:91]
	v_mfma_f32_16x16x32_bf16 v[76:79], v[150:153], v[216:219], v[76:79]
	v_mfma_f32_16x16x32_bf16 v[72:75], v[158:161], v[216:219], v[72:75]
	v_mfma_f32_16x16x32_bf16 v[124:127], v[154:157], v[196:199], v[124:127]
	v_mfma_f32_16x16x32_bf16 v[120:123], v[168:171], v[196:199], v[120:123]
	v_mfma_f32_16x16x32_bf16 v[108:111], v[154:157], v[204:207], v[108:111]
	v_mfma_f32_16x16x32_bf16 v[104:107], v[168:171], v[204:207], v[104:107]
	v_mfma_f32_16x16x32_bf16 v[92:95], v[154:157], v[212:215], v[92:95]
	v_mfma_f32_16x16x32_bf16 v[88:91], v[168:171], v[212:215], v[88:91]
	v_mfma_f32_16x16x32_bf16 v[76:79], v[154:157], v[220:223], v[76:79]
	v_mfma_f32_16x16x32_bf16 v[72:75], v[168:171], v[220:223], v[72:75]
	s_setprio 0
	s_setprio 1
	v_mfma_f32_16x16x32_bf16 v[116:119], v[172:175], v[192:195], v[116:119]
	v_mfma_f32_16x16x32_bf16 v[112:115], v[180:183], v[192:195], v[112:115]
	v_mfma_f32_16x16x32_bf16 v[100:103], v[172:175], v[200:203], v[100:103]
	v_mfma_f32_16x16x32_bf16 v[96:99], v[180:183], v[200:203], v[96:99]
	v_mfma_f32_16x16x32_bf16 v[84:87], v[172:175], v[208:211], v[84:87]
	v_mfma_f32_16x16x32_bf16 v[80:83], v[180:183], v[208:211], v[80:83]
	v_mfma_f32_16x16x32_bf16 v[68:71], v[172:175], v[216:219], v[68:71]
	v_mfma_f32_16x16x32_bf16 v[64:67], v[180:183], v[216:219], v[64:67]
	v_mfma_f32_16x16x32_bf16 v[116:119], v[176:179], v[196:199], v[116:119]
	v_mfma_f32_16x16x32_bf16 v[112:115], v[184:187], v[196:199], v[112:115]
	v_mfma_f32_16x16x32_bf16 v[100:103], v[176:179], v[204:207], v[100:103]
	v_mfma_f32_16x16x32_bf16 v[96:99], v[184:187], v[204:207], v[96:99]
	v_mfma_f32_16x16x32_bf16 v[84:87], v[176:179], v[212:215], v[84:87]
	v_mfma_f32_16x16x32_bf16 v[80:83], v[184:187], v[212:215], v[80:83]
	v_mfma_f32_16x16x32_bf16 v[68:71], v[176:179], v[220:223], v[68:71]
	v_mfma_f32_16x16x32_bf16 v[64:67], v[184:187], v[220:223], v[64:67]
	s_setprio 0
	s_barrier
	s_add_i32 s38, s64, s44
	v_lshl_add_u64 v[188:189], v[188:189], 0, s[14:15]
	s_mov_b32 m0, s38
	ds_read_b128 v[192:195], v165 offset:49152
	ds_read_b128 v[196:199], v165 offset:50176
	ds_read_b128 v[200:203], v165 offset:51200
	ds_read_b128 v[204:207], v165 offset:52224
	ds_read_b128 v[208:211], v165 offset:53248
	ds_read_b128 v[212:215], v165 offset:54272
	ds_read_b128 v[216:219], v165 offset:55296
	ds_read_b128 v[220:223], v165 offset:56320
	global_load_lds_dwordx4 v[188:189], off
	s_add_i32 m0, s38, 0x2000
	s_add_u32 s36, s36, 0x40080
	v_lshl_add_u64 v[188:189], v[224:225], 0, s[14:15]
	s_addc_u32 s37, s37, 0
	s_add_i32 s38, s65, s44
	global_load_lds_dwordx4 v[188:189], off
	v_lshl_add_u64 v[188:189], s[36:37], 0, v[132:133]
	s_mov_b32 m0, s38
	s_nop 0
	global_load_lds_dwordx4 v[188:189], off
	v_lshl_add_u64 v[188:189], s[36:37], 0, v[128:129]
	s_add_i32 m0, s38, 0x2000
	s_nop 0
	global_load_lds_dwordx4 v[188:189], off
	v_lshl_add_u64 v[188:189], v[226:227], 0, s[14:15]
	s_mov_b32 m0, s51
	s_nop 0
	global_load_lds_dwordx4 v[188:189], off
	v_lshl_add_u64 v[188:189], v[228:229], 0, s[14:15]
	s_mov_b32 m0, s52
	s_nop 0
	global_load_lds_dwordx4 v[188:189], off
	s_waitcnt vmcnt(8)
	s_waitcnt lgkmcnt(0)
	s_barrier
	s_setprio 1
	s_waitcnt lgkmcnt(0)
	v_mfma_f32_16x16x32_bf16 v[60:63], v[150:153], v[192:195], v[60:63]
	v_mfma_f32_16x16x32_bf16 v[56:59], v[158:161], v[192:195], v[56:59]
	v_mfma_f32_16x16x32_bf16 v[44:47], v[150:153], v[200:203], v[44:47]
	v_mfma_f32_16x16x32_bf16 v[40:43], v[158:161], v[200:203], v[40:43]
	v_mfma_f32_16x16x32_bf16 v[28:31], v[150:153], v[208:211], v[28:31]
	v_mfma_f32_16x16x32_bf16 v[24:27], v[158:161], v[208:211], v[24:27]
	v_mfma_f32_16x16x32_bf16 v[12:15], v[150:153], v[216:219], v[12:15]
	v_mfma_f32_16x16x32_bf16 v[8:11], v[158:161], v[216:219], v[8:11]
	v_mfma_f32_16x16x32_bf16 v[60:63], v[154:157], v[196:199], v[60:63]
	v_mfma_f32_16x16x32_bf16 v[56:59], v[168:171], v[196:199], v[56:59]
	v_mfma_f32_16x16x32_bf16 v[44:47], v[154:157], v[204:207], v[44:47]
	v_mfma_f32_16x16x32_bf16 v[40:43], v[168:171], v[204:207], v[40:43]
	v_mfma_f32_16x16x32_bf16 v[28:31], v[154:157], v[212:215], v[28:31]
	v_mfma_f32_16x16x32_bf16 v[24:27], v[168:171], v[212:215], v[24:27]
	v_mfma_f32_16x16x32_bf16 v[12:15], v[154:157], v[220:223], v[12:15]
	v_mfma_f32_16x16x32_bf16 v[8:11], v[168:171], v[220:223], v[8:11]
	s_setprio 0
	s_setprio 1
	v_mfma_f32_16x16x32_bf16 v[52:55], v[172:175], v[192:195], v[52:55]
	v_mfma_f32_16x16x32_bf16 v[48:51], v[180:183], v[192:195], v[48:51]
	v_mfma_f32_16x16x32_bf16 v[36:39], v[172:175], v[200:203], v[36:39]
	v_mfma_f32_16x16x32_bf16 v[32:35], v[180:183], v[200:203], v[32:35]
	v_mfma_f32_16x16x32_bf16 v[20:23], v[172:175], v[208:211], v[20:23]
	v_mfma_f32_16x16x32_bf16 v[16:19], v[180:183], v[208:211], v[16:19]
	v_mfma_f32_16x16x32_bf16 v[4:7], v[172:175], v[216:219], v[4:7]
	v_mfma_f32_16x16x32_bf16 v[0:3], v[180:183], v[216:219], v[0:3]
	v_mfma_f32_16x16x32_bf16 v[52:55], v[176:179], v[196:199], v[52:55]
	v_mfma_f32_16x16x32_bf16 v[48:51], v[184:187], v[196:199], v[48:51]
	v_mfma_f32_16x16x32_bf16 v[36:39], v[176:179], v[204:207], v[36:39]
	v_mfma_f32_16x16x32_bf16 v[32:35], v[184:187], v[204:207], v[32:35]
	v_mfma_f32_16x16x32_bf16 v[20:23], v[176:179], v[212:215], v[20:23]
	v_mfma_f32_16x16x32_bf16 v[16:19], v[184:187], v[212:215], v[16:19]
	v_mfma_f32_16x16x32_bf16 v[4:7], v[176:179], v[220:223], v[4:7]
	v_mfma_f32_16x16x32_bf16 v[0:3], v[184:187], v[220:223], v[0:3]
	s_setprio 0
	s_barrier
	s_add_i32 s63, s63, 2
	s_add_u32 s33, s33, 0x100
	s_addc_u32 s62, s62, 0
	s_add_u32 s34, s34, 0x100
	s_addc_u32 s35, s35, 0
	s_cmp_gt_u32 s63, 13
	s_cbranch_scc0 .LBB0_1106
	v_lshl_add_u32 v214, s30, 8, v139
	v_ashrrev_i32_e32 v215, 31, v214
	v_lshl_add_u64 v[212:213], v[214:215], 2, s[12:13]
	global_load_dword v204, v[212:213], off
	global_load_dword v205, v[212:213], off offset:64
	global_load_dword v206, v[212:213], off offset:128
	global_load_dword v207, v[212:213], off offset:192
	global_load_dword v208, v[212:213], off offset:512
	global_load_dword v209, v[212:213], off offset:576
	global_load_dword v210, v[212:213], off offset:640
	global_load_dword v211, v[212:213], off offset:704
	s_and_b64 vcc, exec, s[16:17]
	s_cbranch_vccz .LBB0_1109
	s_barrier

.LBB0_1112:
	v_lshl_add_u64 v[158:159], v[156:157], 2, s[12:13]
	v_mov_b64_e32 v[160:161], s[10:11]
	s_lshl_b32 s6, s6, 8
	v_mad_i64_i32 v[168:169], s[34:35], v156, s58, v[160:161]
	s_mov_b32 s19, s7
	v_lshl_add_u64 v[168:169], v[168:169], 0, s[6:7]
	v_mov_b32_e32 v149, v137
	v_lshl_add_u64 v[168:169], v[168:169], 0, s[18:19]
	v_lshl_add_u64 v[174:175], v[168:169], 0, v[148:149]
	v_lshl_add_u64 v[172:173], v[154:155], 2, s[12:13]
	s_waitcnt vmcnt(0) lgkmcnt(0)
	v_fmamk_f32 v136, v204, 0x3a800000, v166
	v_mul_f32_e32 v167, 0x4b800000, v136
	v_cmp_gt_f32_e32 vcc, s57, v136
	s_nop 1
	v_cndmask_b32_e32 v136, v136, v167, vcc
	v_rsq_f32_e32 v136, v136
	s_nop 0
	v_mul_f32_e32 v167, 0x45800000, v136
	v_cndmask_b32_e32 v136, v136, v167, vcc
	v_pk_mul_f32 v[168:169], v[126:127], v[136:137] op_sel_hi:[1,0]
	v_pk_mul_f32 v[170:171], v[124:125], v[136:137] op_sel_hi:[1,0]
	v_pk_mul_f32 v[176:177], v[122:123], v[136:137] op_sel_hi:[1,0]
	v_pk_mul_f32 v[178:179], v[120:121], v[136:137] op_sel_hi:[1,0]
	v_pk_mul_f32 v[180:181], v[118:119], v[136:137] op_sel_hi:[1,0]
	v_pk_mul_f32 v[182:183], v[116:117], v[136:137] op_sel_hi:[1,0]
	v_pk_mul_f32 v[184:185], v[114:115], v[136:137] op_sel_hi:[1,0]
	v_pk_mul_f32 v[186:187], v[112:113], v[136:137] op_sel_hi:[1,0]
	v_mul_f32_e32 v136, 0xbfb8aa3b, v170
	v_mul_f32_e32 v167, 0xbfb8aa3b, v171
	v_mul_f32_e32 v188, 0xbfb8aa3b, v168
	v_mul_f32_e32 v189, 0xbfb8aa3b, v169
	v_mul_f32_e32 v191, 0xbfb8aa3b, v178
	v_mul_f32_e32 v192, 0xbfb8aa3b, v179
	v_mul_f32_e32 v193, 0xbfb8aa3b, v176
	v_mul_f32_e32 v194, 0xbfb8aa3b, v177
	v_exp_f32_e32 v136, v136
	v_exp_f32_e32 v167, v167
	v_exp_f32_e32 v188, v188
	v_exp_f32_e32 v189, v189
	v_exp_f32_e32 v191, v191
	v_exp_f32_e32 v192, v192
	v_exp_f32_e32 v193, v193
	v_exp_f32_e32 v194, v194
	v_add_f32_e32 v136, 1.0, v136
	v_add_f32_e32 v167, 1.0, v167
	v_add_f32_e32 v195, 1.0, v188
	v_add_f32_e32 v196, 1.0, v189
	v_add_f32_e32 v191, 1.0, v191
	v_add_f32_e32 v197, 1.0, v192
	v_add_f32_e32 v198, 1.0, v193
	v_add_f32_e32 v199, 1.0, v194
	v_rcp_f32_e32 v188, v136
	v_rcp_f32_e32 v189, v167
	v_rcp_f32_e32 v192, v195
	v_rcp_f32_e32 v193, v196
	v_rcp_f32_e32 v194, v191
	v_rcp_f32_e32 v195, v197
	v_rcp_f32_e32 v196, v198
	v_rcp_f32_e32 v197, v199
	v_pk_mul_f32 v[170:171], v[170:171], v[188:189]
	v_pk_mul_f32 v[168:169], v[168:169], v[192:193]
	v_pk_mul_f32 v[178:179], v[178:179], v[194:195]
	v_pk_mul_f32 v[176:177], v[176:177], v[196:197]
	v_pk_mul_f32 v[170:171], v[182:183], v[170:171]
	v_pk_mul_f32 v[180:181], v[180:181], v[168:169]
	v_pk_mul_f32 v[178:179], v[186:187], v[178:179]
	v_pk_mul_f32 v[176:177], v[184:185], v[176:177]
	v_cvt_pk_bf16_f32 v168, v170, v171
	v_cvt_pk_bf16_f32 v169, v180, v181
	v_cvt_pk_bf16_f32 v170, v178, v179
	v_cvt_pk_bf16_f32 v171, v176, v177
	global_store_dwordx4 v[174:175], v[168:171], off
	s_nop 1
	v_lshl_add_u64 v[172:173], v[152:153], 2, s[12:13]
	v_mad_i64_i32 v[168:169], s[34:35], v154, s58, v[160:161]
	v_lshl_add_u64 v[168:169], v[168:169], 0, s[6:7]
	v_lshl_add_u64 v[168:169], v[168:169], 0, s[18:19]
	v_lshl_add_u64 v[174:175], v[168:169], 0, v[148:149]
	v_fmamk_f32 v136, v205, 0x3a800000, v166
	v_mul_f32_e32 v167, 0x4b800000, v136
	v_cmp_gt_f32_e32 vcc, s57, v136
	s_nop 1
	v_cndmask_b32_e32 v136, v136, v167, vcc
	v_rsq_f32_e32 v136, v136
	s_nop 0
	v_mul_f32_e32 v167, 0x45800000, v136
	v_cndmask_b32_e32 v136, v136, v167, vcc
	v_pk_mul_f32 v[168:169], v[110:111], v[136:137] op_sel_hi:[1,0]
	v_pk_mul_f32 v[170:171], v[108:109], v[136:137] op_sel_hi:[1,0]
	v_pk_mul_f32 v[176:177], v[106:107], v[136:137] op_sel_hi:[1,0]
	v_pk_mul_f32 v[178:179], v[104:105], v[136:137] op_sel_hi:[1,0]
	v_pk_mul_f32 v[180:181], v[102:103], v[136:137] op_sel_hi:[1,0]
	v_pk_mul_f32 v[182:183], v[100:101], v[136:137] op_sel_hi:[1,0]
	v_pk_mul_f32 v[184:185], v[98:99], v[136:137] op_sel_hi:[1,0]
	v_pk_mul_f32 v[186:187], v[96:97], v[136:137] op_sel_hi:[1,0]
	v_mul_f32_e32 v136, 0xbfb8aa3b, v170
	v_mul_f32_e32 v167, 0xbfb8aa3b, v171
	v_mul_f32_e32 v188, 0xbfb8aa3b, v168
	v_mul_f32_e32 v189, 0xbfb8aa3b, v169
	v_mul_f32_e32 v191, 0xbfb8aa3b, v178
	v_mul_f32_e32 v192, 0xbfb8aa3b, v179
	v_mul_f32_e32 v193, 0xbfb8aa3b, v176
	v_mul_f32_e32 v194, 0xbfb8aa3b, v177
	v_exp_f32_e32 v136, v136
	v_exp_f32_e32 v167, v167
	v_exp_f32_e32 v188, v188
	v_exp_f32_e32 v189, v189
	v_exp_f32_e32 v191, v191
	v_exp_f32_e32 v192, v192
	v_exp_f32_e32 v193, v193
	v_exp_f32_e32 v194, v194
	v_add_f32_e32 v136, 1.0, v136
	v_add_f32_e32 v167, 1.0, v167
	v_add_f32_e32 v195, 1.0, v188
	v_add_f32_e32 v196, 1.0, v189
	v_add_f32_e32 v191, 1.0, v191
	v_add_f32_e32 v197, 1.0, v192
	v_add_f32_e32 v198, 1.0, v193
	v_add_f32_e32 v199, 1.0, v194
	v_rcp_f32_e32 v188, v136
	v_rcp_f32_e32 v189, v167
	v_rcp_f32_e32 v192, v195
	v_rcp_f32_e32 v193, v196
	v_rcp_f32_e32 v194, v191
	v_rcp_f32_e32 v195, v197
	v_rcp_f32_e32 v196, v198
	v_rcp_f32_e32 v197, v199
	v_pk_mul_f32 v[170:171], v[170:171], v[188:189]
	v_pk_mul_f32 v[168:169], v[168:169], v[192:193]
	v_pk_mul_f32 v[178:179], v[178:179], v[194:195]
	v_pk_mul_f32 v[176:177], v[176:177], v[196:197]
	v_pk_mul_f32 v[170:171], v[182:183], v[170:171]
	v_pk_mul_f32 v[180:181], v[180:181], v[168:169]
	v_pk_mul_f32 v[178:179], v[186:187], v[178:179]
	v_pk_mul_f32 v[176:177], v[184:185], v[176:177]
	v_cvt_pk_bf16_f32 v168, v170, v171
	v_cvt_pk_bf16_f32 v169, v180, v181
	v_cvt_pk_bf16_f32 v170, v178, v179
	v_cvt_pk_bf16_f32 v171, v176, v177
	global_store_dwordx4 v[174:175], v[168:171], off
	s_nop 1
	v_lshl_add_u64 v[172:173], v[150:151], 2, s[12:13]
	v_mad_i64_i32 v[168:169], s[34:35], v152, s58, v[160:161]
	v_lshl_add_u64 v[168:169], v[168:169], 0, s[6:7]
	v_lshl_add_u64 v[168:169], v[168:169], 0, s[18:19]
	v_lshl_add_u64 v[174:175], v[168:169], 0, v[148:149]
	v_fmamk_f32 v136, v206, 0x3a800000, v166
	v_mul_f32_e32 v167, 0x4b800000, v136
	v_cmp_gt_f32_e32 vcc, s57, v136
	s_nop 1
	v_cndmask_b32_e32 v136, v136, v167, vcc
	v_rsq_f32_e32 v136, v136
	s_nop 0
	v_mul_f32_e32 v167, 0x45800000, v136
	v_cndmask_b32_e32 v136, v136, v167, vcc
	v_pk_mul_f32 v[168:169], v[94:95], v[136:137] op_sel_hi:[1,0]
	v_pk_mul_f32 v[170:171], v[92:93], v[136:137] op_sel_hi:[1,0]
	v_pk_mul_f32 v[176:177], v[90:91], v[136:137] op_sel_hi:[1,0]
	v_pk_mul_f32 v[178:179], v[88:89], v[136:137] op_sel_hi:[1,0]
	v_pk_mul_f32 v[180:181], v[86:87], v[136:137] op_sel_hi:[1,0]
	v_pk_mul_f32 v[182:183], v[84:85], v[136:137] op_sel_hi:[1,0]
	v_pk_mul_f32 v[184:185], v[82:83], v[136:137] op_sel_hi:[1,0]
	v_pk_mul_f32 v[186:187], v[80:81], v[136:137] op_sel_hi:[1,0]
	v_mul_f32_e32 v136, 0xbfb8aa3b, v170
	v_mul_f32_e32 v167, 0xbfb8aa3b, v171
	v_mul_f32_e32 v188, 0xbfb8aa3b, v168
	v_mul_f32_e32 v189, 0xbfb8aa3b, v169
	v_mul_f32_e32 v191, 0xbfb8aa3b, v178
	v_mul_f32_e32 v192, 0xbfb8aa3b, v179
	v_mul_f32_e32 v193, 0xbfb8aa3b, v176
	v_mul_f32_e32 v194, 0xbfb8aa3b, v177
	v_exp_f32_e32 v136, v136
	v_exp_f32_e32 v167, v167
	v_exp_f32_e32 v188, v188
	v_exp_f32_e32 v189, v189
	v_exp_f32_e32 v191, v191
	v_exp_f32_e32 v192, v192
	v_exp_f32_e32 v193, v193
	v_exp_f32_e32 v194, v194
	v_add_f32_e32 v136, 1.0, v136
	v_add_f32_e32 v167, 1.0, v167
	v_add_f32_e32 v195, 1.0, v188
	v_add_f32_e32 v196, 1.0, v189
	v_add_f32_e32 v191, 1.0, v191
	v_add_f32_e32 v197, 1.0, v192
	v_add_f32_e32 v198, 1.0, v193
	v_add_f32_e32 v199, 1.0, v194
	v_rcp_f32_e32 v188, v136
	v_rcp_f32_e32 v189, v167
	v_rcp_f32_e32 v192, v195
	v_rcp_f32_e32 v193, v196
	v_rcp_f32_e32 v194, v191
	v_rcp_f32_e32 v195, v197
	v_rcp_f32_e32 v196, v198
	v_rcp_f32_e32 v197, v199
	v_pk_mul_f32 v[170:171], v[170:171], v[188:189]
	v_pk_mul_f32 v[168:169], v[168:169], v[192:193]
	v_pk_mul_f32 v[178:179], v[178:179], v[194:195]
	v_pk_mul_f32 v[176:177], v[176:177], v[196:197]
	v_pk_mul_f32 v[170:171], v[182:183], v[170:171]
	v_pk_mul_f32 v[180:181], v[180:181], v[168:169]
	v_pk_mul_f32 v[178:179], v[186:187], v[178:179]
	v_pk_mul_f32 v[176:177], v[184:185], v[176:177]
	v_cvt_pk_bf16_f32 v168, v170, v171
	v_cvt_pk_bf16_f32 v169, v180, v181
	v_cvt_pk_bf16_f32 v170, v178, v179
	v_cvt_pk_bf16_f32 v171, v176, v177
	global_store_dwordx4 v[174:175], v[168:171], off
	s_nop 1
	v_fmamk_f32 v136, v207, 0x3a800000, v166
	v_mul_f32_e32 v167, 0x4b800000, v136
	v_cmp_gt_f32_e32 vcc, s57, v136
	v_mad_i64_i32 v[168:169], s[34:35], v150, s58, v[160:161]
	s_nop 0
	v_cndmask_b32_e32 v136, v136, v167, vcc
	v_rsq_f32_e32 v136, v136
	v_lshl_add_u64 v[168:169], v[168:169], 0, s[6:7]
	v_lshl_add_u64 v[168:169], v[168:169], 0, s[18:19]
	v_lshl_add_u64 v[172:173], v[168:169], 0, v[148:149]
	v_mul_f32_e32 v167, 0x45800000, v136
	v_cndmask_b32_e32 v136, v136, v167, vcc
	v_pk_mul_f32 v[168:169], v[78:79], v[136:137] op_sel_hi:[1,0]
	v_pk_mul_f32 v[170:171], v[76:77], v[136:137] op_sel_hi:[1,0]
	v_pk_mul_f32 v[174:175], v[74:75], v[136:137] op_sel_hi:[1,0]
	v_pk_mul_f32 v[176:177], v[72:73], v[136:137] op_sel_hi:[1,0]
	v_pk_mul_f32 v[178:179], v[70:71], v[136:137] op_sel_hi:[1,0]
	v_pk_mul_f32 v[180:181], v[68:69], v[136:137] op_sel_hi:[1,0]
	v_pk_mul_f32 v[182:183], v[66:67], v[136:137] op_sel_hi:[1,0]
	v_pk_mul_f32 v[184:185], v[64:65], v[136:137] op_sel_hi:[1,0]
	v_mul_f32_e32 v136, 0xbfb8aa3b, v170
	v_mul_f32_e32 v167, 0xbfb8aa3b, v171
	v_mul_f32_e32 v186, 0xbfb8aa3b, v168
	v_mul_f32_e32 v187, 0xbfb8aa3b, v169
	v_mul_f32_e32 v188, 0xbfb8aa3b, v176
	v_mul_f32_e32 v189, 0xbfb8aa3b, v177
	v_mul_f32_e32 v191, 0xbfb8aa3b, v174
	v_mul_f32_e32 v192, 0xbfb8aa3b, v175
	v_exp_f32_e32 v136, v136
	v_exp_f32_e32 v167, v167
	v_exp_f32_e32 v186, v186
	v_exp_f32_e32 v187, v187
	v_exp_f32_e32 v188, v188
	v_exp_f32_e32 v189, v189
	v_exp_f32_e32 v191, v191
	v_exp_f32_e32 v192, v192
	v_add_f32_e32 v136, 1.0, v136
	v_add_f32_e32 v167, 1.0, v167
	v_add_f32_e32 v193, 1.0, v186
	v_add_f32_e32 v194, 1.0, v187
	v_add_f32_e32 v195, 1.0, v188
	v_add_f32_e32 v196, 1.0, v189
	v_add_f32_e32 v191, 1.0, v191
	v_add_f32_e32 v197, 1.0, v192
	v_rcp_f32_e32 v186, v136
	v_rcp_f32_e32 v187, v167
	v_rcp_f32_e32 v188, v193
	v_rcp_f32_e32 v189, v194
	v_rcp_f32_e32 v192, v195
	v_rcp_f32_e32 v193, v196
	v_rcp_f32_e32 v194, v191
	v_rcp_f32_e32 v195, v197
	v_pk_mul_f32 v[170:171], v[170:171], v[186:187]
	v_pk_mul_f32 v[168:169], v[168:169], v[188:189]
	v_pk_mul_f32 v[176:177], v[176:177], v[192:193]
	v_pk_mul_f32 v[174:175], v[174:175], v[194:195]
	v_pk_mul_f32 v[170:171], v[180:181], v[170:171]
	v_pk_mul_f32 v[178:179], v[178:179], v[168:169]
	v_pk_mul_f32 v[176:177], v[184:185], v[176:177]
	v_pk_mul_f32 v[174:175], v[182:183], v[174:175]
	v_cvt_pk_bf16_f32 v168, v170, v171
	v_cvt_pk_bf16_f32 v169, v178, v179
	v_cvt_pk_bf16_f32 v170, v176, v177
	v_cvt_pk_bf16_f32 v171, v174, v175
	global_store_dwordx4 v[172:173], v[168:171], off
	s_nop 1
	v_add_u32_e32 v167, 0x80, v156
	v_mad_i64_i32 v[168:169], s[34:35], v167, s58, v[160:161]
	v_lshl_add_u64 v[168:169], v[168:169], 0, s[6:7]
	v_lshl_add_u64 v[168:169], v[168:169], 0, s[18:19]
	v_lshl_add_u64 v[172:173], v[168:169], 0, v[148:149]
	v_fmamk_f32 v136, v208, 0x3a800000, v166
	v_mul_f32_e32 v167, 0x4b800000, v136
	v_cmp_gt_f32_e32 vcc, s57, v136
	s_nop 1
	v_cndmask_b32_e32 v136, v136, v167, vcc
	v_rsq_f32_e32 v136, v136
	s_nop 0
	v_mul_f32_e32 v167, 0x45800000, v136
	v_cndmask_b32_e32 v136, v136, v167, vcc
	v_pk_mul_f32 v[168:169], v[62:63], v[136:137] op_sel_hi:[1,0]
	v_pk_mul_f32 v[170:171], v[60:61], v[136:137] op_sel_hi:[1,0]
	v_pk_mul_f32 v[174:175], v[58:59], v[136:137] op_sel_hi:[1,0]
	v_pk_mul_f32 v[176:177], v[56:57], v[136:137] op_sel_hi:[1,0]
	v_pk_mul_f32 v[178:179], v[54:55], v[136:137] op_sel_hi:[1,0]
	v_pk_mul_f32 v[180:181], v[52:53], v[136:137] op_sel_hi:[1,0]
	v_pk_mul_f32 v[182:183], v[50:51], v[136:137] op_sel_hi:[1,0]
	v_pk_mul_f32 v[184:185], v[48:49], v[136:137] op_sel_hi:[1,0]
	v_mul_f32_e32 v136, 0xbfb8aa3b, v170
	v_mul_f32_e32 v167, 0xbfb8aa3b, v171
	v_mul_f32_e32 v186, 0xbfb8aa3b, v168
	v_mul_f32_e32 v187, 0xbfb8aa3b, v169
	v_mul_f32_e32 v188, 0xbfb8aa3b, v176
	v_mul_f32_e32 v189, 0xbfb8aa3b, v177
	v_mul_f32_e32 v191, 0xbfb8aa3b, v174
	v_mul_f32_e32 v192, 0xbfb8aa3b, v175
	v_exp_f32_e32 v136, v136
	v_exp_f32_e32 v167, v167
	v_exp_f32_e32 v186, v186
	v_exp_f32_e32 v187, v187
	v_exp_f32_e32 v188, v188
	v_exp_f32_e32 v189, v189
	v_exp_f32_e32 v191, v191
	v_exp_f32_e32 v192, v192
	v_add_f32_e32 v136, 1.0, v136
	v_add_f32_e32 v167, 1.0, v167
	v_add_f32_e32 v193, 1.0, v186
	v_add_f32_e32 v194, 1.0, v187
	v_add_f32_e32 v195, 1.0, v188
	v_add_f32_e32 v196, 1.0, v189
	v_add_f32_e32 v191, 1.0, v191
	v_add_f32_e32 v197, 1.0, v192
	v_rcp_f32_e32 v186, v136
	v_rcp_f32_e32 v187, v167
	v_rcp_f32_e32 v188, v193
	v_rcp_f32_e32 v189, v194
	v_rcp_f32_e32 v192, v195
	v_rcp_f32_e32 v193, v196
	v_rcp_f32_e32 v194, v191
	v_rcp_f32_e32 v195, v197
	v_pk_mul_f32 v[170:171], v[170:171], v[186:187]
	v_pk_mul_f32 v[168:169], v[168:169], v[188:189]
	v_pk_mul_f32 v[176:177], v[176:177], v[192:193]
	v_pk_mul_f32 v[174:175], v[174:175], v[194:195]
	v_pk_mul_f32 v[170:171], v[180:181], v[170:171]
	v_pk_mul_f32 v[178:179], v[178:179], v[168:169]
	v_pk_mul_f32 v[176:177], v[184:185], v[176:177]
	v_pk_mul_f32 v[174:175], v[182:183], v[174:175]
	v_cvt_pk_bf16_f32 v168, v170, v171
	v_cvt_pk_bf16_f32 v169, v178, v179
	v_cvt_pk_bf16_f32 v170, v176, v177
	v_cvt_pk_bf16_f32 v171, v174, v175
	global_store_dwordx4 v[172:173], v[168:171], off
	s_nop 1
	v_add_u32_e32 v167, 0x90, v156
	v_mad_i64_i32 v[168:169], s[34:35], v167, s58, v[160:161]
	v_lshl_add_u64 v[168:169], v[168:169], 0, s[6:7]
	v_lshl_add_u64 v[168:169], v[168:169], 0, s[18:19]
	v_lshl_add_u64 v[172:173], v[168:169], 0, v[148:149]
	v_fmamk_f32 v136, v209, 0x3a800000, v166
	v_mul_f32_e32 v167, 0x4b800000, v136
	v_cmp_gt_f32_e32 vcc, s57, v136
	s_nop 1
	v_cndmask_b32_e32 v136, v136, v167, vcc
	v_rsq_f32_e32 v136, v136
	s_nop 0
	v_mul_f32_e32 v167, 0x45800000, v136
	v_cndmask_b32_e32 v136, v136, v167, vcc
	v_pk_mul_f32 v[168:169], v[46:47], v[136:137] op_sel_hi:[1,0]
	v_pk_mul_f32 v[170:171], v[44:45], v[136:137] op_sel_hi:[1,0]
	v_pk_mul_f32 v[174:175], v[42:43], v[136:137] op_sel_hi:[1,0]
	v_pk_mul_f32 v[176:177], v[40:41], v[136:137] op_sel_hi:[1,0]
	v_pk_mul_f32 v[178:179], v[38:39], v[136:137] op_sel_hi:[1,0]
	v_pk_mul_f32 v[180:181], v[36:37], v[136:137] op_sel_hi:[1,0]
	v_pk_mul_f32 v[182:183], v[34:35], v[136:137] op_sel_hi:[1,0]
	v_pk_mul_f32 v[184:185], v[32:33], v[136:137] op_sel_hi:[1,0]
	v_mul_f32_e32 v136, 0xbfb8aa3b, v170
	v_mul_f32_e32 v167, 0xbfb8aa3b, v171
	v_mul_f32_e32 v186, 0xbfb8aa3b, v168
	v_mul_f32_e32 v187, 0xbfb8aa3b, v169
	v_mul_f32_e32 v188, 0xbfb8aa3b, v176
	v_mul_f32_e32 v189, 0xbfb8aa3b, v177
	v_mul_f32_e32 v191, 0xbfb8aa3b, v174
	v_mul_f32_e32 v192, 0xbfb8aa3b, v175
	v_exp_f32_e32 v136, v136
	v_exp_f32_e32 v167, v167
	v_exp_f32_e32 v186, v186
	v_exp_f32_e32 v187, v187
	v_exp_f32_e32 v188, v188
	v_exp_f32_e32 v189, v189
	v_exp_f32_e32 v191, v191
	v_exp_f32_e32 v192, v192
	v_add_f32_e32 v136, 1.0, v136
	v_add_f32_e32 v167, 1.0, v167
	v_add_f32_e32 v193, 1.0, v186
	v_add_f32_e32 v194, 1.0, v187
	v_add_f32_e32 v195, 1.0, v188
	v_add_f32_e32 v196, 1.0, v189
	v_add_f32_e32 v191, 1.0, v191
	v_add_f32_e32 v197, 1.0, v192
	v_rcp_f32_e32 v186, v136
	v_rcp_f32_e32 v187, v167
	v_rcp_f32_e32 v188, v193
	v_rcp_f32_e32 v189, v194
	v_rcp_f32_e32 v192, v195
	v_rcp_f32_e32 v193, v196
	v_rcp_f32_e32 v194, v191
	v_rcp_f32_e32 v195, v197
	v_pk_mul_f32 v[170:171], v[170:171], v[186:187]
	v_pk_mul_f32 v[168:169], v[168:169], v[188:189]
	v_pk_mul_f32 v[176:177], v[176:177], v[192:193]
	v_pk_mul_f32 v[174:175], v[174:175], v[194:195]
	v_pk_mul_f32 v[170:171], v[180:181], v[170:171]
	v_pk_mul_f32 v[178:179], v[178:179], v[168:169]
	v_pk_mul_f32 v[176:177], v[184:185], v[176:177]
	v_pk_mul_f32 v[174:175], v[182:183], v[174:175]
	v_cvt_pk_bf16_f32 v168, v170, v171
	v_cvt_pk_bf16_f32 v169, v178, v179
	v_cvt_pk_bf16_f32 v170, v176, v177
	v_cvt_pk_bf16_f32 v171, v174, v175
	global_store_dwordx4 v[172:173], v[168:171], off
	s_nop 1
	v_add_u32_e32 v167, 0xa0, v156
	v_mad_i64_i32 v[168:169], s[34:35], v167, s58, v[160:161]
	v_lshl_add_u64 v[168:169], v[168:169], 0, s[6:7]
	v_lshl_add_u64 v[168:169], v[168:169], 0, s[18:19]
	v_lshl_add_u64 v[172:173], v[168:169], 0, v[148:149]
	v_fmamk_f32 v136, v210, 0x3a800000, v166
	v_mul_f32_e32 v167, 0x4b800000, v136
	v_cmp_gt_f32_e32 vcc, s57, v136
	s_nop 1
	v_cndmask_b32_e32 v136, v136, v167, vcc
	v_rsq_f32_e32 v136, v136
	s_nop 0
	v_mul_f32_e32 v167, 0x45800000, v136
	v_cndmask_b32_e32 v136, v136, v167, vcc
	v_pk_mul_f32 v[168:169], v[30:31], v[136:137] op_sel_hi:[1,0]
	v_pk_mul_f32 v[170:171], v[28:29], v[136:137] op_sel_hi:[1,0]
	v_pk_mul_f32 v[174:175], v[26:27], v[136:137] op_sel_hi:[1,0]
	v_pk_mul_f32 v[176:177], v[24:25], v[136:137] op_sel_hi:[1,0]
	v_pk_mul_f32 v[178:179], v[22:23], v[136:137] op_sel_hi:[1,0]
	v_pk_mul_f32 v[180:181], v[20:21], v[136:137] op_sel_hi:[1,0]
	v_pk_mul_f32 v[182:183], v[18:19], v[136:137] op_sel_hi:[1,0]
	v_pk_mul_f32 v[184:185], v[16:17], v[136:137] op_sel_hi:[1,0]
	v_mul_f32_e32 v136, 0xbfb8aa3b, v170
	v_mul_f32_e32 v167, 0xbfb8aa3b, v171
	v_mul_f32_e32 v186, 0xbfb8aa3b, v168
	v_mul_f32_e32 v187, 0xbfb8aa3b, v169
	v_mul_f32_e32 v188, 0xbfb8aa3b, v176
	v_mul_f32_e32 v189, 0xbfb8aa3b, v177
	v_mul_f32_e32 v191, 0xbfb8aa3b, v174
	v_mul_f32_e32 v192, 0xbfb8aa3b, v175
	v_exp_f32_e32 v136, v136
	v_exp_f32_e32 v167, v167
	v_exp_f32_e32 v186, v186
	v_exp_f32_e32 v187, v187
	v_exp_f32_e32 v188, v188
	v_exp_f32_e32 v189, v189
	v_exp_f32_e32 v191, v191
	v_exp_f32_e32 v192, v192
	v_add_f32_e32 v136, 1.0, v136
	v_add_f32_e32 v167, 1.0, v167
	v_add_f32_e32 v193, 1.0, v186
	v_add_f32_e32 v194, 1.0, v187
	v_add_f32_e32 v195, 1.0, v188
	v_add_f32_e32 v196, 1.0, v189
	v_add_f32_e32 v191, 1.0, v191
	v_add_f32_e32 v197, 1.0, v192
	v_rcp_f32_e32 v186, v136
	v_rcp_f32_e32 v187, v167
	v_rcp_f32_e32 v188, v193
	v_rcp_f32_e32 v189, v194
	v_rcp_f32_e32 v192, v195
	v_rcp_f32_e32 v193, v196
	v_rcp_f32_e32 v194, v191
	v_rcp_f32_e32 v195, v197
	v_pk_mul_f32 v[170:171], v[170:171], v[186:187]
	v_pk_mul_f32 v[168:169], v[168:169], v[188:189]
	v_pk_mul_f32 v[176:177], v[176:177], v[192:193]
	v_pk_mul_f32 v[174:175], v[174:175], v[194:195]
	v_pk_mul_f32 v[170:171], v[180:181], v[170:171]
	v_pk_mul_f32 v[178:179], v[178:179], v[168:169]
	v_pk_mul_f32 v[176:177], v[184:185], v[176:177]
	v_pk_mul_f32 v[174:175], v[182:183], v[174:175]
	v_cvt_pk_bf16_f32 v168, v170, v171
	v_cvt_pk_bf16_f32 v169, v178, v179
	v_cvt_pk_bf16_f32 v170, v176, v177
	v_cvt_pk_bf16_f32 v171, v174, v175
	global_store_dwordx4 v[172:173], v[168:171], off
	s_nop 1
	v_add_u32_e32 v158, 0xb0, v156
	v_mad_i64_i32 v[158:159], s[34:35], v158, s58, v[160:161]
	v_lshl_add_u64 v[158:159], v[158:159], 0, s[6:7]
	v_lshl_add_u64 v[158:159], v[158:159], 0, s[18:19]
	v_lshl_add_u64 v[168:169], v[158:159], 0, v[148:149]
	v_fmamk_f32 v136, v211, 0x3a800000, v166
	v_mul_f32_e32 v160, 0x4b800000, v136
	v_cmp_gt_f32_e32 vcc, s57, v136
	s_nop 1
	v_cndmask_b32_e32 v136, v136, v160, vcc
	v_rsq_f32_e32 v136, v136
	s_nop 0
	v_mul_f32_e32 v149, 0x45800000, v136
	v_cndmask_b32_e32 v136, v136, v149, vcc
	v_pk_mul_f32 v[158:159], v[14:15], v[136:137] op_sel_hi:[1,0]
	v_pk_mul_f32 v[160:161], v[12:13], v[136:137] op_sel_hi:[1,0]
	v_pk_mul_f32 v[170:171], v[10:11], v[136:137] op_sel_hi:[1,0]
	v_pk_mul_f32 v[172:173], v[8:9], v[136:137] op_sel_hi:[1,0]
	v_pk_mul_f32 v[174:175], v[6:7], v[136:137] op_sel_hi:[1,0]
	v_pk_mul_f32 v[176:177], v[4:5], v[136:137] op_sel_hi:[1,0]
	v_pk_mul_f32 v[178:179], v[2:3], v[136:137] op_sel_hi:[1,0]
	v_pk_mul_f32 v[180:181], v[0:1], v[136:137] op_sel_hi:[1,0]
	v_mul_f32_e32 v136, 0xbfb8aa3b, v160
	v_mul_f32_e32 v149, 0xbfb8aa3b, v161
	v_mul_f32_e32 v167, 0xbfb8aa3b, v158
	v_mul_f32_e32 v182, 0xbfb8aa3b, v159
	v_mul_f32_e32 v183, 0xbfb8aa3b, v172
	v_mul_f32_e32 v184, 0xbfb8aa3b, v173
	v_mul_f32_e32 v185, 0xbfb8aa3b, v170
	v_mul_f32_e32 v186, 0xbfb8aa3b, v171
	v_exp_f32_e32 v136, v136
	v_exp_f32_e32 v149, v149
	v_exp_f32_e32 v167, v167
	v_exp_f32_e32 v182, v182
	v_exp_f32_e32 v183, v183
	v_exp_f32_e32 v184, v184
	v_exp_f32_e32 v185, v185
	v_exp_f32_e32 v186, v186
	v_add_f32_e32 v136, 1.0, v136
	v_add_f32_e32 v149, 1.0, v149
	v_add_f32_e32 v167, 1.0, v167
	v_add_f32_e32 v187, 1.0, v182
	v_add_f32_e32 v188, 1.0, v183
	v_add_f32_e32 v189, 1.0, v184
	v_add_f32_e32 v191, 1.0, v185
	v_add_f32_e32 v192, 1.0, v186
	v_rcp_f32_e32 v182, v136
	v_rcp_f32_e32 v183, v149
	v_rcp_f32_e32 v184, v167
	v_rcp_f32_e32 v185, v187
	v_rcp_f32_e32 v186, v188
	v_rcp_f32_e32 v187, v189
	v_rcp_f32_e32 v188, v191
	v_rcp_f32_e32 v189, v192
	v_pk_mul_f32 v[160:161], v[160:161], v[182:183]
	v_pk_mul_f32 v[158:159], v[158:159], v[184:185]
	v_pk_mul_f32 v[172:173], v[172:173], v[186:187]
	v_pk_mul_f32 v[170:171], v[170:171], v[188:189]
	v_pk_mul_f32 v[160:161], v[176:177], v[160:161]
	v_pk_mul_f32 v[174:175], v[174:175], v[158:159]
	v_pk_mul_f32 v[172:173], v[180:181], v[172:173]
	v_pk_mul_f32 v[170:171], v[178:179], v[170:171]
	v_cvt_pk_bf16_f32 v158, v160, v161
	v_cvt_pk_bf16_f32 v159, v174, v175
	v_cvt_pk_bf16_f32 v160, v172, v173
	v_cvt_pk_bf16_f32 v161, v170, v171
	global_store_dwordx4 v[168:169], v[158:161], off
	s_cbranch_execnz .LBB0_1111

.LBB0_1190:
	v_mbcnt_lo_u32_b32 v235, -1, 0
	v_mbcnt_hi_u32_b32 v235, -1, v235
	v_lshrrev_b32_e32 v236, 2, v235
	v_and_b32_e32 v237, 3, v235
	v_lshl_add_u32 v232, v237, 4, v236
	v_lshlrev_b32_e32 v232, 2, v232
	v_and_b32_e32 v233, -16, v168
	v_or_b32_e32 v233, v233, v236
	v_lshlrev_b32_e32 v237, 2, v237
	v_and_b32_e32 v234, -13, v170
	v_or_b32_e32 v234, v234, v237
	ds_bpermute_b32 v127, v232, v127
	ds_bpermute_b32 v126, v232, v126
	ds_bpermute_b32 v125, v232, v125
	ds_bpermute_b32 v124, v232, v124
	ds_bpermute_b32 v123, v232, v123
	ds_bpermute_b32 v122, v232, v122
	ds_bpermute_b32 v121, v232, v121
	ds_bpermute_b32 v120, v232, v120
	ds_bpermute_b32 v119, v232, v119
	ds_bpermute_b32 v118, v232, v118
	ds_bpermute_b32 v117, v232, v117
	ds_bpermute_b32 v116, v232, v116
	ds_bpermute_b32 v115, v232, v115
	ds_bpermute_b32 v114, v232, v114
	ds_bpermute_b32 v113, v232, v113
	ds_bpermute_b32 v112, v232, v112
	ds_bpermute_b32 v111, v232, v111
	ds_bpermute_b32 v110, v232, v110
	ds_bpermute_b32 v109, v232, v109
	ds_bpermute_b32 v108, v232, v108
	ds_bpermute_b32 v107, v232, v107
	ds_bpermute_b32 v106, v232, v106
	ds_bpermute_b32 v105, v232, v105
	ds_bpermute_b32 v104, v232, v104
	ds_bpermute_b32 v103, v232, v103
	ds_bpermute_b32 v102, v232, v102
	ds_bpermute_b32 v101, v232, v101
	ds_bpermute_b32 v100, v232, v100
	ds_bpermute_b32 v99, v232, v99
	ds_bpermute_b32 v98, v232, v98
	ds_bpermute_b32 v97, v232, v97
	ds_bpermute_b32 v96, v232, v96
	ds_bpermute_b32 v95, v232, v95
	ds_bpermute_b32 v94, v232, v94
	ds_bpermute_b32 v93, v232, v93
	ds_bpermute_b32 v92, v232, v92
	ds_bpermute_b32 v91, v232, v91
	ds_bpermute_b32 v90, v232, v90
	ds_bpermute_b32 v89, v232, v89
	ds_bpermute_b32 v88, v232, v88
	ds_bpermute_b32 v87, v232, v87
	ds_bpermute_b32 v86, v232, v86
	ds_bpermute_b32 v85, v232, v85
	ds_bpermute_b32 v84, v232, v84
	ds_bpermute_b32 v83, v232, v83
	ds_bpermute_b32 v82, v232, v82
	ds_bpermute_b32 v81, v232, v81
	ds_bpermute_b32 v80, v232, v80
	ds_bpermute_b32 v79, v232, v79
	ds_bpermute_b32 v78, v232, v78
	ds_bpermute_b32 v77, v232, v77
	ds_bpermute_b32 v76, v232, v76
	ds_bpermute_b32 v75, v232, v75
	ds_bpermute_b32 v74, v232, v74
	ds_bpermute_b32 v73, v232, v73
	ds_bpermute_b32 v72, v232, v72
	ds_bpermute_b32 v71, v232, v71
	ds_bpermute_b32 v70, v232, v70
	ds_bpermute_b32 v69, v232, v69
	ds_bpermute_b32 v68, v232, v68
	ds_bpermute_b32 v67, v232, v67
	ds_bpermute_b32 v66, v232, v66
	ds_bpermute_b32 v65, v232, v65
	ds_bpermute_b32 v64, v232, v64
	ds_bpermute_b32 v63, v232, v63
	ds_bpermute_b32 v62, v232, v62
	ds_bpermute_b32 v61, v232, v61
	ds_bpermute_b32 v60, v232, v60
	ds_bpermute_b32 v59, v232, v59
	ds_bpermute_b32 v58, v232, v58
	ds_bpermute_b32 v57, v232, v57
	ds_bpermute_b32 v56, v232, v56
	ds_bpermute_b32 v55, v232, v55
	ds_bpermute_b32 v54, v232, v54
	ds_bpermute_b32 v53, v232, v53
	ds_bpermute_b32 v52, v232, v52
	ds_bpermute_b32 v51, v232, v51
	ds_bpermute_b32 v50, v232, v50
	ds_bpermute_b32 v49, v232, v49
	ds_bpermute_b32 v48, v232, v48
	ds_bpermute_b32 v47, v232, v47
	ds_bpermute_b32 v46, v232, v46
	ds_bpermute_b32 v45, v232, v45
	ds_bpermute_b32 v44, v232, v44
	ds_bpermute_b32 v43, v232, v43
	ds_bpermute_b32 v42, v232, v42
	ds_bpermute_b32 v41, v232, v41
	ds_bpermute_b32 v40, v232, v40
	ds_bpermute_b32 v39, v232, v39
	ds_bpermute_b32 v38, v232, v38
	ds_bpermute_b32 v37, v232, v37
	ds_bpermute_b32 v36, v232, v36
	ds_bpermute_b32 v35, v232, v35
	ds_bpermute_b32 v34, v232, v34
	ds_bpermute_b32 v33, v232, v33
	ds_bpermute_b32 v32, v232, v32
	ds_bpermute_b32 v31, v232, v31
	ds_bpermute_b32 v30, v232, v30
	ds_bpermute_b32 v29, v232, v29
	ds_bpermute_b32 v28, v232, v28
	ds_bpermute_b32 v27, v232, v27
	ds_bpermute_b32 v26, v232, v26
	ds_bpermute_b32 v25, v232, v25
	ds_bpermute_b32 v24, v232, v24
	ds_bpermute_b32 v23, v232, v23
	ds_bpermute_b32 v22, v232, v22
	ds_bpermute_b32 v21, v232, v21
	ds_bpermute_b32 v20, v232, v20
	ds_bpermute_b32 v19, v232, v19
	ds_bpermute_b32 v18, v232, v18
	ds_bpermute_b32 v17, v232, v17
	ds_bpermute_b32 v16, v232, v16
	ds_bpermute_b32 v15, v232, v15
	ds_bpermute_b32 v14, v232, v14
	ds_bpermute_b32 v13, v232, v13
	ds_bpermute_b32 v12, v232, v12
	ds_bpermute_b32 v11, v232, v11
	ds_bpermute_b32 v10, v232, v10
	ds_bpermute_b32 v9, v232, v9
	ds_bpermute_b32 v8, v232, v8
	ds_bpermute_b32 v7, v232, v7
	ds_bpermute_b32 v6, v232, v6
	ds_bpermute_b32 v5, v232, v5
	ds_bpermute_b32 v4, v232, v4
	ds_bpermute_b32 v3, v232, v3
	ds_bpermute_b32 v2, v232, v2
	ds_bpermute_b32 v1, v232, v1
	ds_bpermute_b32 v0, v232, v0
	s_waitcnt lgkmcnt(0)
	v_lshl_add_u32 v158, s54, 8, v233
	v_lshl_or_b32 v156, s53, 8, v234
	v_ashrrev_i32_e32 v159, 31, v158
	v_lshlrev_b64 v[128:129], 12, v[158:159]
	v_ashrrev_i32_e32 v157, 31, v156
	v_lshl_add_u64 v[128:129], s[8:9], 0, v[128:129]
	v_lshlrev_b64 v[130:131], 2, v[156:157]
	v_lshl_add_u64 v[188:189], v[128:129], 0, v[130:131]
	global_load_dwordx4 v[164:167], v[188:189], off
	global_load_dwordx4 v[176:179], v[188:189], off offset:64
	global_load_dwordx4 v[180:183], v[188:189], off offset:512
	global_load_dwordx4 v[184:187], v[188:189], off offset:576
	v_or_b32_e32 v160, 16, v158
	v_ashrrev_i32_e32 v161, 31, v160
	v_lshlrev_b64 v[128:129], 12, v[160:161]
	v_lshl_add_u64 v[128:129], s[8:9], 0, v[128:129]
	v_lshl_add_u64 v[162:163], v[128:129], 0, v[130:131]
	global_load_dwordx4 v[140:143], v[162:163], off
	global_load_dwordx4 v[136:139], v[162:163], off offset:64
	global_load_dwordx4 v[132:135], v[162:163], off offset:512
	global_load_dwordx4 v[128:131], v[162:163], off offset:576
	v_lshlrev_b64 v[192:193], 11, v[158:159]
	v_lshl_add_u64 v[192:193], s[12:13], 0, v[192:193]
	v_and_b32_e32 v191, 64, v174
	v_lshl_add_u64 v[192:193], v[156:157], 1, v[192:193]
	v_xor_b32_e32 v175, 1, v174
	v_add_u32_e32 v191, 64, v191
	v_cmp_lt_i32_e32 vcc, v175, v191
	v_xor_b32_e32 v194, 2, v174
	s_waitcnt vmcnt(0) lgkmcnt(0)
	v_pk_fma_f32 v[126:127], v[126:127], 0.5, v[166:167] op_sel_hi:[1,0,1]
	v_pk_fma_f32 v[124:125], v[124:125], 0.5, v[164:165] op_sel_hi:[1,0,1]
	v_pk_fma_f32 v[122:123], v[122:123], 0.5, v[178:179] op_sel_hi:[1,0,1]
	v_pk_fma_f32 v[120:121], v[120:121], 0.5, v[176:177] op_sel_hi:[1,0,1]
	v_pk_fma_f32 v[118:119], v[118:119], 0.5, v[182:183] op_sel_hi:[1,0,1]
	v_pk_fma_f32 v[116:117], v[116:117], 0.5, v[180:181] op_sel_hi:[1,0,1]
	v_pk_fma_f32 v[164:165], v[112:113], 0.5, v[184:185] op_sel_hi:[1,0,1]
	v_mul_f32_e32 v178, v125, v125
	v_mul_f32_e32 v179, v127, v127
	global_store_dwordx4 v[188:189], v[124:127], off
	v_cvt_pk_bf16_f32 v112, v124, v125
	v_cvt_pk_bf16_f32 v113, v126, v127
	v_mul_f32_e32 v125, v121, v121
	v_mul_f32_e32 v127, v123, v123
	v_pk_fma_f32 v[166:167], v[114:115], 0.5, v[186:187] op_sel_hi:[1,0,1]
	v_mul_f32_e32 v180, v117, v117
	v_mul_f32_e32 v181, v119, v119
	v_fmac_f32_e32 v178, v124, v124
	v_fmac_f32_e32 v179, v126, v126
	v_fmac_f32_e32 v125, v120, v120
	v_fmac_f32_e32 v127, v122, v122
	v_mul_f32_e32 v182, v165, v165
	v_mul_f32_e32 v183, v167, v167
	global_store_dwordx2 v[192:193], v[112:113], off
	v_fmac_f32_e32 v180, v116, v116
	v_fmac_f32_e32 v181, v118, v118
	v_add_f32_e32 v112, v178, v179
	v_add_f32_e32 v113, v125, v127
	v_fmac_f32_e32 v182, v164, v164
	v_fmac_f32_e32 v183, v166, v166
	v_add_f32_e32 v124, v180, v181
	v_add_f32_e32 v112, v112, v113
	v_cndmask_b32_e32 v175, v174, v175, vcc
	v_add_f32_e32 v125, v182, v183
	v_add_f32_e32 v112, v112, v124
	v_lshlrev_b32_e32 v175, 2, v175
	v_add_f32_e32 v112, v112, v125
	ds_bpermute_b32 v113, v175, v112
	v_cmp_lt_i32_e32 vcc, v194, v191
	v_cvt_pk_bf16_f32 v176, v116, v117
	v_cvt_pk_bf16_f32 v114, v120, v121
	v_cndmask_b32_e32 v191, v174, v194, vcc
	v_cvt_pk_bf16_f32 v115, v122, v123
	v_cvt_pk_bf16_f32 v177, v118, v119
	global_store_dwordx4 v[188:189], v[120:123], off offset:64
	global_store_dwordx2 v[192:193], v[114:115], off offset:32
	global_store_dwordx4 v[188:189], v[116:119], off offset:512
	global_store_dwordx2 v[192:193], v[176:177], off offset:256
	s_waitcnt lgkmcnt(0)
	v_add_f32_e32 v112, v112, v113
	v_lshlrev_b32_e32 v176, 2, v191
	ds_bpermute_b32 v113, v176, v112
	v_cvt_pk_bf16_f32 v114, v164, v165
	v_cvt_pk_bf16_f32 v115, v166, v167
	global_store_dwordx4 v[188:189], v[164:167], off offset:576
	global_store_dwordx2 v[192:193], v[114:115], off offset:288
	s_mov_b32 vcc_lo, 0x11111111
	s_mov_b32 vcc_hi, 0x11111111
	s_and_saveexec_b64 s[22:23], vcc
	s_cbranch_execz .LBB0_1192
	v_lshl_add_u64 v[114:115], v[158:159], 2, s[14:15]
	s_waitcnt lgkmcnt(0)
	v_add_f32_e32 v112, v112, v113
	global_atomic_add_f32 v[114:115], v112, off
.LBB0_1192:
	s_or_b64 exec, exec, s[22:23]
	v_or_b32_e32 v164, 32, v158
	v_ashrrev_i32_e32 v165, 31, v164
	s_waitcnt lgkmcnt(0)
	v_lshlrev_b64 v[112:113], 12, v[164:165]
	v_lshl_add_u64 v[112:113], s[8:9], 0, v[112:113]
	v_lshl_add_u64 v[166:167], v[156:157], 2, v[112:113]
	global_load_dwordx4 v[124:127], v[166:167], off
	global_load_dwordx4 v[120:123], v[166:167], off offset:64
	global_load_dwordx4 v[116:119], v[166:167], off offset:512
	global_load_dwordx4 v[112:115], v[166:167], off offset:576
	v_pk_fma_f32 v[110:111], v[110:111], 0.5, v[142:143] op_sel_hi:[1,0,1]
	v_pk_fma_f32 v[108:109], v[108:109], 0.5, v[140:141] op_sel_hi:[1,0,1]
	v_mul_f32_e32 v141, v111, v111
	v_mul_f32_e32 v140, v109, v109
	v_fmac_f32_e32 v140, v108, v108
	v_fmac_f32_e32 v141, v110, v110
	v_add_f32_e32 v142, v140, v141
	v_lshlrev_b64 v[140:141], 11, v[160:161]
	v_lshl_add_u64 v[140:141], s[12:13], 0, v[140:141]
	global_store_dwordx4 v[162:163], v[108:111], off
	v_lshl_add_u64 v[140:141], v[156:157], 1, v[140:141]
	v_pk_fma_f32 v[104:105], v[104:105], 0.5, v[136:137] op_sel_hi:[1,0,1]
	v_cvt_pk_bf16_f32 v108, v108, v109
	v_cvt_pk_bf16_f32 v109, v110, v111
	global_store_dwordx2 v[140:141], v[108:109], off
	v_pk_fma_f32 v[106:107], v[106:107], 0.5, v[138:139] op_sel_hi:[1,0,1]
	v_mul_f32_e32 v108, v105, v105
	v_fmac_f32_e32 v108, v104, v104
	v_mul_f32_e32 v109, v107, v107
	global_store_dwordx4 v[162:163], v[104:107], off offset:64
	v_pk_fma_f32 v[102:103], v[102:103], 0.5, v[134:135] op_sel_hi:[1,0,1]
	v_pk_fma_f32 v[100:101], v[100:101], 0.5, v[132:133] op_sel_hi:[1,0,1]
	v_cvt_pk_bf16_f32 v104, v104, v105
	v_cvt_pk_bf16_f32 v105, v106, v107
	v_fmac_f32_e32 v109, v106, v106
	global_store_dwordx2 v[140:141], v[104:105], off offset:32
	v_mul_f32_e32 v104, v101, v101
	v_mul_f32_e32 v105, v103, v103
	v_add_f32_e32 v108, v108, v109
	v_fmac_f32_e32 v104, v100, v100
	v_fmac_f32_e32 v105, v102, v102
	v_add_f32_e32 v108, v142, v108
	v_add_f32_e32 v104, v104, v105
	v_add_f32_e32 v108, v108, v104
	v_pk_fma_f32 v[106:107], v[98:99], 0.5, v[130:131] op_sel_hi:[1,0,1]
	v_pk_fma_f32 v[104:105], v[96:97], 0.5, v[128:129] op_sel_hi:[1,0,1]
	v_mul_f32_e32 v97, v107, v107
	v_mul_f32_e32 v96, v105, v105
	v_fmac_f32_e32 v96, v104, v104
	v_fmac_f32_e32 v97, v106, v106
	v_add_f32_e32 v96, v96, v97
	v_add_f32_e32 v98, v108, v96
	ds_bpermute_b32 v99, v175, v98
	v_cvt_pk_bf16_f32 v96, v100, v101
	v_cvt_pk_bf16_f32 v97, v102, v103
	global_store_dwordx4 v[162:163], v[100:103], off offset:512
	global_store_dwordx2 v[140:141], v[96:97], off offset:256
	s_waitcnt lgkmcnt(0)
	v_add_f32_e32 v96, v98, v99
	ds_bpermute_b32 v97, v176, v96
	v_cvt_pk_bf16_f32 v98, v104, v105
	v_cvt_pk_bf16_f32 v99, v106, v107
	global_store_dwordx4 v[162:163], v[104:107], off offset:576
	global_store_dwordx2 v[140:141], v[98:99], off offset:288
	s_mov_b32 vcc_lo, 0x11111111
	s_mov_b32 vcc_hi, 0x11111111
	s_and_saveexec_b64 s[22:23], vcc
	s_cbranch_execz .LBB0_1194
	v_lshl_add_u64 v[98:99], v[160:161], 2, s[14:15]
	s_waitcnt lgkmcnt(0)
	v_add_f32_e32 v96, v96, v97
	global_atomic_add_f32 v[98:99], v96, off
.LBB0_1194:
	s_or_b64 exec, exec, s[22:23]
	v_or_b32_e32 v128, 48, v158
	v_ashrrev_i32_e32 v129, 31, v128
	s_waitcnt lgkmcnt(0)
	v_lshlrev_b64 v[96:97], 12, v[128:129]
	v_lshl_add_u64 v[96:97], s[8:9], 0, v[96:97]
	v_lshl_add_u64 v[130:131], v[156:157], 2, v[96:97]
	global_load_dwordx4 v[108:111], v[130:131], off
	global_load_dwordx4 v[104:107], v[130:131], off offset:64
	global_load_dwordx4 v[100:103], v[130:131], off offset:512
	global_load_dwordx4 v[96:99], v[130:131], off offset:576
	s_waitcnt vmcnt(0)
	v_pk_fma_f32 v[94:95], v[94:95], 0.5, v[126:127] op_sel_hi:[1,0,1]
	v_pk_fma_f32 v[92:93], v[92:93], 0.5, v[124:125] op_sel_hi:[1,0,1]
	v_mul_f32_e32 v125, v95, v95
	v_mul_f32_e32 v124, v93, v93
	v_fmac_f32_e32 v124, v92, v92
	v_fmac_f32_e32 v125, v94, v94
	v_add_f32_e32 v126, v124, v125
	v_lshlrev_b64 v[124:125], 11, v[164:165]
	v_lshl_add_u64 v[124:125], s[12:13], 0, v[124:125]
	global_store_dwordx4 v[166:167], v[92:95], off
	v_lshl_add_u64 v[124:125], v[156:157], 1, v[124:125]
	v_pk_fma_f32 v[88:89], v[88:89], 0.5, v[120:121] op_sel_hi:[1,0,1]
	v_cvt_pk_bf16_f32 v92, v92, v93
	v_cvt_pk_bf16_f32 v93, v94, v95
	global_store_dwordx2 v[124:125], v[92:93], off
	v_pk_fma_f32 v[90:91], v[90:91], 0.5, v[122:123] op_sel_hi:[1,0,1]
	v_mul_f32_e32 v92, v89, v89
	v_fmac_f32_e32 v92, v88, v88
	v_mul_f32_e32 v93, v91, v91
	global_store_dwordx4 v[166:167], v[88:91], off offset:64
	v_pk_fma_f32 v[86:87], v[86:87], 0.5, v[118:119] op_sel_hi:[1,0,1]
	v_pk_fma_f32 v[84:85], v[84:85], 0.5, v[116:117] op_sel_hi:[1,0,1]
	v_cvt_pk_bf16_f32 v88, v88, v89
	v_cvt_pk_bf16_f32 v89, v90, v91
	v_fmac_f32_e32 v93, v90, v90
	global_store_dwordx2 v[124:125], v[88:89], off offset:32
	v_mul_f32_e32 v88, v85, v85
	v_mul_f32_e32 v89, v87, v87
	v_add_f32_e32 v92, v92, v93
	v_fmac_f32_e32 v88, v84, v84
	v_fmac_f32_e32 v89, v86, v86
	v_add_f32_e32 v92, v126, v92
	v_add_f32_e32 v88, v88, v89
	v_add_f32_e32 v92, v92, v88
	v_pk_fma_f32 v[90:91], v[82:83], 0.5, v[114:115] op_sel_hi:[1,0,1]
	v_pk_fma_f32 v[88:89], v[80:81], 0.5, v[112:113] op_sel_hi:[1,0,1]
	v_mul_f32_e32 v81, v91, v91
	v_mul_f32_e32 v80, v89, v89
	v_fmac_f32_e32 v80, v88, v88
	v_fmac_f32_e32 v81, v90, v90
	v_add_f32_e32 v80, v80, v81
	v_add_f32_e32 v82, v92, v80
	ds_bpermute_b32 v83, v175, v82
	v_cvt_pk_bf16_f32 v80, v84, v85
	v_cvt_pk_bf16_f32 v81, v86, v87
	global_store_dwordx4 v[166:167], v[84:87], off offset:512
	global_store_dwordx2 v[124:125], v[80:81], off offset:256
	s_waitcnt lgkmcnt(0)
	v_add_f32_e32 v80, v82, v83
	ds_bpermute_b32 v81, v176, v80
	v_cvt_pk_bf16_f32 v82, v88, v89
	v_cvt_pk_bf16_f32 v83, v90, v91
	global_store_dwordx4 v[166:167], v[88:91], off offset:576
	global_store_dwordx2 v[124:125], v[82:83], off offset:288
	s_mov_b32 vcc_lo, 0x11111111
	s_mov_b32 vcc_hi, 0x11111111
	s_and_saveexec_b64 s[22:23], vcc
	s_cbranch_execz .LBB0_1196
	v_lshl_add_u64 v[82:83], v[164:165], 2, s[14:15]
	s_waitcnt lgkmcnt(0)
	v_add_f32_e32 v80, v80, v81
	global_atomic_add_f32 v[82:83], v80, off
.LBB0_1196:
	s_or_b64 exec, exec, s[22:23]
	v_add_u32_e32 v112, 0x80, v158
	v_ashrrev_i32_e32 v113, 31, v112
	s_waitcnt lgkmcnt(0)
	v_lshlrev_b64 v[80:81], 12, v[112:113]
	v_lshl_add_u64 v[80:81], s[8:9], 0, v[80:81]
	v_lshl_add_u64 v[114:115], v[156:157], 2, v[80:81]
	global_load_dwordx4 v[92:95], v[114:115], off
	global_load_dwordx4 v[88:91], v[114:115], off offset:64
	global_load_dwordx4 v[84:87], v[114:115], off offset:512
	global_load_dwordx4 v[80:83], v[114:115], off offset:576
	v_pk_fma_f32 v[78:79], v[78:79], 0.5, v[110:111] op_sel_hi:[1,0,1]
	v_pk_fma_f32 v[76:77], v[76:77], 0.5, v[108:109] op_sel_hi:[1,0,1]
	v_mul_f32_e32 v109, v79, v79
	v_mul_f32_e32 v108, v77, v77
	v_fmac_f32_e32 v108, v76, v76
	v_fmac_f32_e32 v109, v78, v78
	v_add_f32_e32 v110, v108, v109
	v_lshlrev_b64 v[108:109], 11, v[128:129]
	v_lshl_add_u64 v[108:109], s[12:13], 0, v[108:109]
	global_store_dwordx4 v[130:131], v[76:79], off
	v_lshl_add_u64 v[108:109], v[156:157], 1, v[108:109]
	v_pk_fma_f32 v[72:73], v[72:73], 0.5, v[104:105] op_sel_hi:[1,0,1]
	v_cvt_pk_bf16_f32 v76, v76, v77
	v_cvt_pk_bf16_f32 v77, v78, v79
	global_store_dwordx2 v[108:109], v[76:77], off
	v_pk_fma_f32 v[74:75], v[74:75], 0.5, v[106:107] op_sel_hi:[1,0,1]
	v_mul_f32_e32 v76, v73, v73
	v_fmac_f32_e32 v76, v72, v72
	v_mul_f32_e32 v77, v75, v75
	global_store_dwordx4 v[130:131], v[72:75], off offset:64
	v_pk_fma_f32 v[70:71], v[70:71], 0.5, v[102:103] op_sel_hi:[1,0,1]
	v_pk_fma_f32 v[68:69], v[68:69], 0.5, v[100:101] op_sel_hi:[1,0,1]
	v_cvt_pk_bf16_f32 v72, v72, v73
	v_cvt_pk_bf16_f32 v73, v74, v75
	v_fmac_f32_e32 v77, v74, v74
	global_store_dwordx2 v[108:109], v[72:73], off offset:32
	v_mul_f32_e32 v72, v69, v69
	v_mul_f32_e32 v73, v71, v71
	v_add_f32_e32 v76, v76, v77
	v_fmac_f32_e32 v72, v68, v68
	v_fmac_f32_e32 v73, v70, v70
	v_add_f32_e32 v76, v110, v76
	v_add_f32_e32 v72, v72, v73
	v_add_f32_e32 v76, v76, v72
	v_pk_fma_f32 v[74:75], v[66:67], 0.5, v[98:99] op_sel_hi:[1,0,1]
	v_pk_fma_f32 v[72:73], v[64:65], 0.5, v[96:97] op_sel_hi:[1,0,1]
	v_mul_f32_e32 v65, v75, v75
	v_mul_f32_e32 v64, v73, v73
	v_fmac_f32_e32 v64, v72, v72
	v_fmac_f32_e32 v65, v74, v74
	v_add_f32_e32 v64, v64, v65
	v_add_f32_e32 v66, v76, v64
	ds_bpermute_b32 v67, v175, v66
	v_cvt_pk_bf16_f32 v64, v68, v69
	v_cvt_pk_bf16_f32 v65, v70, v71
	global_store_dwordx4 v[130:131], v[68:71], off offset:512
	global_store_dwordx2 v[108:109], v[64:65], off offset:256
	s_waitcnt lgkmcnt(0)
	v_add_f32_e32 v64, v66, v67
	ds_bpermute_b32 v65, v176, v64
	v_cvt_pk_bf16_f32 v66, v72, v73
	v_cvt_pk_bf16_f32 v67, v74, v75
	global_store_dwordx4 v[130:131], v[72:75], off offset:576
	global_store_dwordx2 v[108:109], v[66:67], off offset:288
	s_mov_b32 vcc_lo, 0x11111111
	s_mov_b32 vcc_hi, 0x11111111
	s_and_saveexec_b64 s[22:23], vcc
	s_cbranch_execz .LBB0_1198
	v_lshl_add_u64 v[66:67], v[128:129], 2, s[14:15]
	s_waitcnt lgkmcnt(0)
	v_add_f32_e32 v64, v64, v65
	global_atomic_add_f32 v[66:67], v64, off
.LBB0_1198:
	s_or_b64 exec, exec, s[22:23]
	v_or_b32_e32 v96, 16, v112
	v_ashrrev_i32_e32 v97, 31, v96
	s_waitcnt lgkmcnt(0)
	v_lshlrev_b64 v[64:65], 12, v[96:97]
	v_lshl_add_u64 v[64:65], s[8:9], 0, v[64:65]
	v_lshl_add_u64 v[98:99], v[156:157], 2, v[64:65]
	global_load_dwordx4 v[76:79], v[98:99], off
	global_load_dwordx4 v[72:75], v[98:99], off offset:64
	global_load_dwordx4 v[68:71], v[98:99], off offset:512
	global_load_dwordx4 v[64:67], v[98:99], off offset:576
	s_waitcnt vmcnt(0)
	v_pk_fma_f32 v[62:63], v[62:63], 0.5, v[94:95] op_sel_hi:[1,0,1]
	v_pk_fma_f32 v[60:61], v[60:61], 0.5, v[92:93] op_sel_hi:[1,0,1]
	v_mul_f32_e32 v93, v63, v63
	v_mul_f32_e32 v92, v61, v61
	v_fmac_f32_e32 v92, v60, v60
	v_fmac_f32_e32 v93, v62, v62
	v_add_f32_e32 v94, v92, v93
	v_lshlrev_b64 v[92:93], 11, v[112:113]
	v_lshl_add_u64 v[92:93], s[12:13], 0, v[92:93]
	global_store_dwordx4 v[114:115], v[60:63], off
	v_lshl_add_u64 v[92:93], v[156:157], 1, v[92:93]
	v_pk_fma_f32 v[56:57], v[56:57], 0.5, v[88:89] op_sel_hi:[1,0,1]
	v_cvt_pk_bf16_f32 v60, v60, v61
	v_cvt_pk_bf16_f32 v61, v62, v63
	global_store_dwordx2 v[92:93], v[60:61], off
	v_pk_fma_f32 v[58:59], v[58:59], 0.5, v[90:91] op_sel_hi:[1,0,1]
	v_mul_f32_e32 v60, v57, v57
	v_fmac_f32_e32 v60, v56, v56
	v_mul_f32_e32 v61, v59, v59
	global_store_dwordx4 v[114:115], v[56:59], off offset:64
	v_pk_fma_f32 v[54:55], v[54:55], 0.5, v[86:87] op_sel_hi:[1,0,1]
	v_pk_fma_f32 v[52:53], v[52:53], 0.5, v[84:85] op_sel_hi:[1,0,1]
	v_cvt_pk_bf16_f32 v56, v56, v57
	v_cvt_pk_bf16_f32 v57, v58, v59
	v_fmac_f32_e32 v61, v58, v58
	global_store_dwordx2 v[92:93], v[56:57], off offset:32
	v_mul_f32_e32 v56, v53, v53
	v_mul_f32_e32 v57, v55, v55
	v_add_f32_e32 v60, v60, v61
	v_fmac_f32_e32 v56, v52, v52
	v_fmac_f32_e32 v57, v54, v54
	v_add_f32_e32 v60, v94, v60
	v_add_f32_e32 v56, v56, v57
	v_add_f32_e32 v60, v60, v56
	v_pk_fma_f32 v[58:59], v[50:51], 0.5, v[82:83] op_sel_hi:[1,0,1]
	v_pk_fma_f32 v[56:57], v[48:49], 0.5, v[80:81] op_sel_hi:[1,0,1]
	v_mul_f32_e32 v49, v59, v59
	v_mul_f32_e32 v48, v57, v57
	v_fmac_f32_e32 v48, v56, v56
	v_fmac_f32_e32 v49, v58, v58
	v_add_f32_e32 v48, v48, v49
	v_add_f32_e32 v50, v60, v48
	ds_bpermute_b32 v51, v175, v50
	v_cvt_pk_bf16_f32 v48, v52, v53
	v_cvt_pk_bf16_f32 v49, v54, v55
	global_store_dwordx4 v[114:115], v[52:55], off offset:512
	global_store_dwordx2 v[92:93], v[48:49], off offset:256
	s_waitcnt lgkmcnt(0)
	v_add_f32_e32 v48, v50, v51
	ds_bpermute_b32 v49, v176, v48
	v_cvt_pk_bf16_f32 v50, v56, v57
	v_cvt_pk_bf16_f32 v51, v58, v59
	global_store_dwordx4 v[114:115], v[56:59], off offset:576
	global_store_dwordx2 v[92:93], v[50:51], off offset:288
	s_mov_b32 vcc_lo, 0x11111111
	s_mov_b32 vcc_hi, 0x11111111
	s_and_saveexec_b64 s[22:23], vcc
	s_cbranch_execz .LBB0_1200
	v_lshl_add_u64 v[50:51], v[112:113], 2, s[14:15]
	s_waitcnt lgkmcnt(0)
	v_add_f32_e32 v48, v48, v49
	global_atomic_add_f32 v[50:51], v48, off
.LBB0_1200:
	s_or_b64 exec, exec, s[22:23]
	v_or_b32_e32 v80, 32, v112
	v_ashrrev_i32_e32 v81, 31, v80
	s_waitcnt lgkmcnt(0)
	v_lshlrev_b64 v[48:49], 12, v[80:81]
	v_lshl_add_u64 v[48:49], s[8:9], 0, v[48:49]
	v_lshl_add_u64 v[82:83], v[156:157], 2, v[48:49]
	global_load_dwordx4 v[60:63], v[82:83], off
	global_load_dwordx4 v[56:59], v[82:83], off offset:64
	global_load_dwordx4 v[52:55], v[82:83], off offset:512
	global_load_dwordx4 v[48:51], v[82:83], off offset:576
	v_pk_fma_f32 v[46:47], v[46:47], 0.5, v[78:79] op_sel_hi:[1,0,1]
	v_pk_fma_f32 v[44:45], v[44:45], 0.5, v[76:77] op_sel_hi:[1,0,1]
	v_mul_f32_e32 v77, v47, v47
	v_mul_f32_e32 v76, v45, v45
	v_fmac_f32_e32 v76, v44, v44
	v_fmac_f32_e32 v77, v46, v46
	v_add_f32_e32 v78, v76, v77
	v_lshlrev_b64 v[76:77], 11, v[96:97]
	v_lshl_add_u64 v[76:77], s[12:13], 0, v[76:77]
	global_store_dwordx4 v[98:99], v[44:47], off
	v_lshl_add_u64 v[76:77], v[156:157], 1, v[76:77]
	v_pk_fma_f32 v[40:41], v[40:41], 0.5, v[72:73] op_sel_hi:[1,0,1]
	v_cvt_pk_bf16_f32 v44, v44, v45
	v_cvt_pk_bf16_f32 v45, v46, v47
	global_store_dwordx2 v[76:77], v[44:45], off
	v_pk_fma_f32 v[42:43], v[42:43], 0.5, v[74:75] op_sel_hi:[1,0,1]
	v_mul_f32_e32 v44, v41, v41
	v_fmac_f32_e32 v44, v40, v40
	v_mul_f32_e32 v45, v43, v43
	global_store_dwordx4 v[98:99], v[40:43], off offset:64
	v_pk_fma_f32 v[38:39], v[38:39], 0.5, v[70:71] op_sel_hi:[1,0,1]
	v_pk_fma_f32 v[36:37], v[36:37], 0.5, v[68:69] op_sel_hi:[1,0,1]
	v_cvt_pk_bf16_f32 v40, v40, v41
	v_cvt_pk_bf16_f32 v41, v42, v43
	v_fmac_f32_e32 v45, v42, v42
	global_store_dwordx2 v[76:77], v[40:41], off offset:32
	v_mul_f32_e32 v40, v37, v37
	v_mul_f32_e32 v41, v39, v39
	v_add_f32_e32 v44, v44, v45
	v_fmac_f32_e32 v40, v36, v36
	v_fmac_f32_e32 v41, v38, v38
	v_add_f32_e32 v44, v78, v44
	v_add_f32_e32 v40, v40, v41
	v_add_f32_e32 v44, v44, v40
	v_pk_fma_f32 v[42:43], v[34:35], 0.5, v[66:67] op_sel_hi:[1,0,1]
	v_pk_fma_f32 v[40:41], v[32:33], 0.5, v[64:65] op_sel_hi:[1,0,1]
	v_mul_f32_e32 v33, v43, v43
	v_mul_f32_e32 v32, v41, v41
	v_fmac_f32_e32 v32, v40, v40
	v_fmac_f32_e32 v33, v42, v42
	v_add_f32_e32 v32, v32, v33
	v_add_f32_e32 v34, v44, v32
	ds_bpermute_b32 v35, v175, v34
	v_cvt_pk_bf16_f32 v32, v36, v37
	v_cvt_pk_bf16_f32 v33, v38, v39
	global_store_dwordx4 v[98:99], v[36:39], off offset:512
	global_store_dwordx2 v[76:77], v[32:33], off offset:256
	s_waitcnt lgkmcnt(0)
	v_add_f32_e32 v32, v34, v35
	ds_bpermute_b32 v33, v176, v32
	v_cvt_pk_bf16_f32 v34, v40, v41
	v_cvt_pk_bf16_f32 v35, v42, v43
	global_store_dwordx4 v[98:99], v[40:43], off offset:576
	global_store_dwordx2 v[76:77], v[34:35], off offset:288
	s_mov_b32 vcc_lo, 0x11111111
	s_mov_b32 vcc_hi, 0x11111111
	s_and_saveexec_b64 s[22:23], vcc
	s_cbranch_execz .LBB0_1202
	v_lshl_add_u64 v[34:35], v[96:97], 2, s[14:15]
	s_waitcnt lgkmcnt(0)
	v_add_f32_e32 v32, v32, v33
	global_atomic_add_f32 v[34:35], v32, off
.LBB0_1202:
	s_or_b64 exec, exec, s[22:23]
	v_or_b32_e32 v64, 48, v112
	v_ashrrev_i32_e32 v65, 31, v64
	s_waitcnt lgkmcnt(0)
	v_lshlrev_b64 v[32:33], 12, v[64:65]
	v_lshl_add_u64 v[32:33], s[8:9], 0, v[32:33]
	v_lshl_add_u64 v[66:67], v[156:157], 2, v[32:33]
	global_load_dwordx4 v[44:47], v[66:67], off
	global_load_dwordx4 v[40:43], v[66:67], off offset:64
	global_load_dwordx4 v[36:39], v[66:67], off offset:512
	global_load_dwordx4 v[32:35], v[66:67], off offset:576
	s_waitcnt vmcnt(0)
	v_pk_fma_f32 v[30:31], v[30:31], 0.5, v[62:63] op_sel_hi:[1,0,1]
	v_pk_fma_f32 v[28:29], v[28:29], 0.5, v[60:61] op_sel_hi:[1,0,1]
	v_mul_f32_e32 v61, v31, v31
	v_mul_f32_e32 v60, v29, v29
	v_fmac_f32_e32 v60, v28, v28
	v_fmac_f32_e32 v61, v30, v30
	v_add_f32_e32 v62, v60, v61
	v_lshlrev_b64 v[60:61], 11, v[80:81]
	v_lshl_add_u64 v[60:61], s[12:13], 0, v[60:61]
	global_store_dwordx4 v[82:83], v[28:31], off
	v_lshl_add_u64 v[60:61], v[156:157], 1, v[60:61]
	v_pk_fma_f32 v[24:25], v[24:25], 0.5, v[56:57] op_sel_hi:[1,0,1]
	v_cvt_pk_bf16_f32 v28, v28, v29
	v_cvt_pk_bf16_f32 v29, v30, v31
	global_store_dwordx2 v[60:61], v[28:29], off
	v_pk_fma_f32 v[26:27], v[26:27], 0.5, v[58:59] op_sel_hi:[1,0,1]
	v_mul_f32_e32 v28, v25, v25
	v_fmac_f32_e32 v28, v24, v24
	v_mul_f32_e32 v29, v27, v27
	global_store_dwordx4 v[82:83], v[24:27], off offset:64
	v_pk_fma_f32 v[22:23], v[22:23], 0.5, v[54:55] op_sel_hi:[1,0,1]
	v_pk_fma_f32 v[20:21], v[20:21], 0.5, v[52:53] op_sel_hi:[1,0,1]
	v_cvt_pk_bf16_f32 v24, v24, v25
	v_cvt_pk_bf16_f32 v25, v26, v27
	v_fmac_f32_e32 v29, v26, v26
	global_store_dwordx2 v[60:61], v[24:25], off offset:32
	v_mul_f32_e32 v24, v21, v21
	v_mul_f32_e32 v25, v23, v23
	v_add_f32_e32 v28, v28, v29
	v_fmac_f32_e32 v24, v20, v20
	v_fmac_f32_e32 v25, v22, v22
	v_add_f32_e32 v28, v62, v28
	v_add_f32_e32 v24, v24, v25
	v_add_f32_e32 v28, v28, v24
	v_pk_fma_f32 v[26:27], v[18:19], 0.5, v[50:51] op_sel_hi:[1,0,1]
	v_pk_fma_f32 v[24:25], v[16:17], 0.5, v[48:49] op_sel_hi:[1,0,1]
	v_mul_f32_e32 v17, v27, v27
	v_mul_f32_e32 v16, v25, v25
	v_fmac_f32_e32 v16, v24, v24
	v_fmac_f32_e32 v17, v26, v26
	v_add_f32_e32 v16, v16, v17
	v_add_f32_e32 v18, v28, v16
	ds_bpermute_b32 v19, v175, v18
	v_cvt_pk_bf16_f32 v16, v20, v21
	v_cvt_pk_bf16_f32 v17, v22, v23
	global_store_dwordx4 v[82:83], v[20:23], off offset:512
	global_store_dwordx2 v[60:61], v[16:17], off offset:256
	s_waitcnt lgkmcnt(0)
	v_add_f32_e32 v16, v18, v19
	ds_bpermute_b32 v17, v176, v16
	v_cvt_pk_bf16_f32 v18, v24, v25
	v_cvt_pk_bf16_f32 v19, v26, v27
	global_store_dwordx4 v[82:83], v[24:27], off offset:576
	global_store_dwordx2 v[60:61], v[18:19], off offset:288
	s_mov_b32 vcc_lo, 0x11111111
	s_mov_b32 vcc_hi, 0x11111111
	s_and_saveexec_b64 s[22:23], vcc
	s_cbranch_execz .LBB0_1204
	v_lshl_add_u64 v[18:19], v[80:81], 2, s[14:15]
	s_waitcnt lgkmcnt(0)
	v_add_f32_e32 v16, v16, v17
	global_atomic_add_f32 v[18:19], v16, off
.LBB0_1204:
	s_or_b64 exec, exec, s[22:23]
	v_pk_fma_f32 v[14:15], v[14:15], 0.5, v[46:47] op_sel_hi:[1,0,1]
	v_pk_fma_f32 v[12:13], v[12:13], 0.5, v[44:45] op_sel_hi:[1,0,1]
	s_waitcnt lgkmcnt(0)
	v_mul_f32_e32 v17, v15, v15
	v_mul_f32_e32 v16, v13, v13
	v_fmac_f32_e32 v16, v12, v12
	v_fmac_f32_e32 v17, v14, v14
	v_add_f32_e32 v18, v16, v17
	v_lshlrev_b64 v[16:17], 11, v[64:65]
	v_lshl_add_u64 v[16:17], s[12:13], 0, v[16:17]
	global_store_dwordx4 v[66:67], v[12:15], off
	v_lshl_add_u64 v[16:17], v[156:157], 1, v[16:17]
	v_pk_fma_f32 v[8:9], v[8:9], 0.5, v[40:41] op_sel_hi:[1,0,1]
	v_cvt_pk_bf16_f32 v12, v12, v13
	v_cvt_pk_bf16_f32 v13, v14, v15
	global_store_dwordx2 v[16:17], v[12:13], off
	v_pk_fma_f32 v[10:11], v[10:11], 0.5, v[42:43] op_sel_hi:[1,0,1]
	v_mul_f32_e32 v12, v9, v9
	v_fmac_f32_e32 v12, v8, v8
	v_mul_f32_e32 v13, v11, v11
	global_store_dwordx4 v[66:67], v[8:11], off offset:64
	v_pk_fma_f32 v[6:7], v[6:7], 0.5, v[38:39] op_sel_hi:[1,0,1]
	v_pk_fma_f32 v[4:5], v[4:5], 0.5, v[36:37] op_sel_hi:[1,0,1]
	v_cvt_pk_bf16_f32 v8, v8, v9
	v_cvt_pk_bf16_f32 v9, v10, v11
	v_fmac_f32_e32 v13, v10, v10
	global_store_dwordx2 v[16:17], v[8:9], off offset:32
	v_mul_f32_e32 v8, v5, v5
	v_mul_f32_e32 v9, v7, v7
	v_add_f32_e32 v12, v12, v13
	v_fmac_f32_e32 v8, v4, v4
	v_fmac_f32_e32 v9, v6, v6
	v_add_f32_e32 v12, v18, v12
	v_add_f32_e32 v8, v8, v9
	v_add_f32_e32 v12, v12, v8
	v_pk_fma_f32 v[10:11], v[2:3], 0.5, v[34:35] op_sel_hi:[1,0,1]
	v_pk_fma_f32 v[8:9], v[0:1], 0.5, v[32:33] op_sel_hi:[1,0,1]
	v_mul_f32_e32 v1, v11, v11
	v_mul_f32_e32 v0, v9, v9
	v_fmac_f32_e32 v0, v8, v8
	v_fmac_f32_e32 v1, v10, v10
	v_add_f32_e32 v0, v0, v1
	v_add_f32_e32 v2, v12, v0
	ds_bpermute_b32 v3, v175, v2
	v_cvt_pk_bf16_f32 v0, v4, v5
	v_cvt_pk_bf16_f32 v1, v6, v7
	global_store_dwordx4 v[66:67], v[4:7], off offset:512
	global_store_dwordx2 v[16:17], v[0:1], off offset:256
	s_waitcnt lgkmcnt(0)
	v_add_f32_e32 v0, v2, v3
	ds_bpermute_b32 v1, v176, v0
	v_cvt_pk_bf16_f32 v2, v8, v9
	v_cvt_pk_bf16_f32 v3, v10, v11
	global_store_dwordx4 v[66:67], v[8:11], off offset:576
	global_store_dwordx2 v[16:17], v[2:3], off offset:288
	s_mov_b32 vcc_lo, 0x11111111
	s_mov_b32 vcc_hi, 0x11111111
	s_and_saveexec_b64 s[22:23], vcc
	s_cbranch_execz .LBB0_1206
	v_lshl_add_u64 v[2:3], v[64:65], 2, s[14:15]
	s_waitcnt lgkmcnt(0)
	v_add_f32_e32 v0, v0, v1
	global_atomic_add_f32 v[2:3], v0, off

.LBB0_1416:
	ds_read_b128 v[150:153], v163
	ds_read_b128 v[154:157], v163 offset:1024
	ds_read_b128 v[158:161], v163 offset:2048
	ds_read_b128 v[168:171], v163 offset:3072
	ds_read_b128 v[172:175], v164
	ds_read_b128 v[176:179], v164 offset:1024
	ds_read_b128 v[180:183], v164 offset:2048
	ds_read_b128 v[184:187], v164 offset:3072
	s_add_u32 s34, s30, 0xfffc0080
	s_addc_u32 s35, s31, -1
	s_cmp_eq_u32 s59, 12
	s_cselect_b32 s37, s21, s35
	s_cselect_b32 s36, s23, s34
	s_cselect_b32 s35, s25, s58
	s_cselect_b32 s34, s33, s57
	v_lshl_add_u64 v[188:189], s[30:31], 0, v[142:143]
	s_add_i32 m0, s45, 0xc000
	ds_read_b128 v[192:195], v165
	ds_read_b128 v[196:199], v165 offset:1024
	ds_read_b128 v[200:203], v165 offset:2048
	ds_read_b128 v[204:207], v165 offset:3072
	ds_read_b128 v[208:211], v165 offset:4096
	ds_read_b128 v[212:215], v165 offset:5120
	ds_read_b128 v[216:219], v165 offset:6144
	ds_read_b128 v[220:223], v165 offset:7168
	global_load_lds_dwordx4 v[188:189], off
	v_lshl_add_u64 v[188:189], s[30:31], 0, v[140:141]
	s_add_i32 m0, s45, 0xe000
	s_nop 0
	global_load_lds_dwordx4 v[188:189], off
	s_waitcnt vmcnt(8)
	s_waitcnt lgkmcnt(0)
	s_barrier
	s_setprio 1
	s_waitcnt lgkmcnt(0)
	v_mfma_f32_16x16x32_bf16 v[124:127], v[150:153], v[192:195], v[124:127]
	v_mfma_f32_16x16x32_bf16 v[120:123], v[158:161], v[192:195], v[120:123]
	v_mfma_f32_16x16x32_bf16 v[108:111], v[150:153], v[200:203], v[108:111]
	v_mfma_f32_16x16x32_bf16 v[104:107], v[158:161], v[200:203], v[104:107]
	v_mfma_f32_16x16x32_bf16 v[92:95], v[150:153], v[208:211], v[92:95]
	v_mfma_f32_16x16x32_bf16 v[88:91], v[158:161], v[208:211], v[88:91]
	v_mfma_f32_16x16x32_bf16 v[76:79], v[150:153], v[216:219], v[76:79]
	v_mfma_f32_16x16x32_bf16 v[72:75], v[158:161], v[216:219], v[72:75]
	v_mfma_f32_16x16x32_bf16 v[124:127], v[154:157], v[196:199], v[124:127]
	v_mfma_f32_16x16x32_bf16 v[120:123], v[168:171], v[196:199], v[120:123]
	v_mfma_f32_16x16x32_bf16 v[108:111], v[154:157], v[204:207], v[108:111]
	v_mfma_f32_16x16x32_bf16 v[104:107], v[168:171], v[204:207], v[104:107]
	v_mfma_f32_16x16x32_bf16 v[92:95], v[154:157], v[212:215], v[92:95]
	v_mfma_f32_16x16x32_bf16 v[88:91], v[168:171], v[212:215], v[88:91]
	v_mfma_f32_16x16x32_bf16 v[76:79], v[154:157], v[220:223], v[76:79]
	v_mfma_f32_16x16x32_bf16 v[72:75], v[168:171], v[220:223], v[72:75]
	s_setprio 0
	s_setprio 1
	v_mfma_f32_16x16x32_bf16 v[116:119], v[172:175], v[192:195], v[116:119]
	v_mfma_f32_16x16x32_bf16 v[112:115], v[180:183], v[192:195], v[112:115]
	v_mfma_f32_16x16x32_bf16 v[100:103], v[172:175], v[200:203], v[100:103]
	v_mfma_f32_16x16x32_bf16 v[96:99], v[180:183], v[200:203], v[96:99]
	v_mfma_f32_16x16x32_bf16 v[84:87], v[172:175], v[208:211], v[84:87]
	v_mfma_f32_16x16x32_bf16 v[80:83], v[180:183], v[208:211], v[80:83]
	v_mfma_f32_16x16x32_bf16 v[68:71], v[172:175], v[216:219], v[68:71]
	v_mfma_f32_16x16x32_bf16 v[64:67], v[180:183], v[216:219], v[64:67]
	v_mfma_f32_16x16x32_bf16 v[116:119], v[176:179], v[196:199], v[116:119]
	v_mfma_f32_16x16x32_bf16 v[112:115], v[184:187], v[196:199], v[112:115]
	v_mfma_f32_16x16x32_bf16 v[100:103], v[176:179], v[204:207], v[100:103]
	v_mfma_f32_16x16x32_bf16 v[96:99], v[184:187], v[204:207], v[96:99]
	v_mfma_f32_16x16x32_bf16 v[84:87], v[176:179], v[212:215], v[84:87]
	v_mfma_f32_16x16x32_bf16 v[80:83], v[184:187], v[212:215], v[80:83]
	v_mfma_f32_16x16x32_bf16 v[68:71], v[176:179], v[220:223], v[68:71]
	v_mfma_f32_16x16x32_bf16 v[64:67], v[184:187], v[220:223], v[64:67]
	s_setprio 0
	s_barrier
	s_add_i32 s60, s51, s42
	v_lshl_add_u64 v[188:189], s[34:35], 0, v[132:133]
	s_mov_b32 m0, s60
	ds_read_b128 v[192:195], v165 offset:16384
	ds_read_b128 v[196:199], v165 offset:17408
	ds_read_b128 v[200:203], v165 offset:18432
	ds_read_b128 v[204:207], v165 offset:19456
	ds_read_b128 v[208:211], v165 offset:20480
	ds_read_b128 v[212:215], v165 offset:21504
	ds_read_b128 v[216:219], v165 offset:22528
	ds_read_b128 v[220:223], v165 offset:23552
	global_load_lds_dwordx4 v[188:189], off
	s_add_i32 m0, s60, 0x2000
	s_add_u32 s60, s34, 0x40000
	v_lshl_add_u64 v[224:225], s[34:35], 0, v[128:129]
	s_addc_u32 s61, s35, 0
	s_add_i32 s62, s52, s42
	global_load_lds_dwordx4 v[224:225], off
	v_lshl_add_u64 v[226:227], s[60:61], 0, v[132:133]
	s_mov_b32 m0, s62
	v_lshl_add_u64 v[228:229], s[36:37], 0, v[130:131]
	global_load_lds_dwordx4 v[226:227], off
	v_lshl_add_u64 v[226:227], s[60:61], 0, v[128:129]
	s_add_i32 m0, s62, 0x2000
	s_nop 0
	global_load_lds_dwordx4 v[226:227], off
	v_lshl_add_u64 v[226:227], s[36:37], 0, v[134:135]
	s_mov_b32 m0, s45
	s_nop 0
	global_load_lds_dwordx4 v[226:227], off
	s_mov_b32 m0, s46
	s_nop 0
	global_load_lds_dwordx4 v[228:229], off
	s_waitcnt vmcnt(8)
	s_waitcnt lgkmcnt(0)
	s_barrier
	s_setprio 1
	s_waitcnt lgkmcnt(0)
	v_mfma_f32_16x16x32_bf16 v[60:63], v[150:153], v[192:195], v[60:63]
	v_mfma_f32_16x16x32_bf16 v[56:59], v[158:161], v[192:195], v[56:59]
	v_mfma_f32_16x16x32_bf16 v[44:47], v[150:153], v[200:203], v[44:47]
	v_mfma_f32_16x16x32_bf16 v[40:43], v[158:161], v[200:203], v[40:43]
	v_mfma_f32_16x16x32_bf16 v[28:31], v[150:153], v[208:211], v[28:31]
	v_mfma_f32_16x16x32_bf16 v[24:27], v[158:161], v[208:211], v[24:27]
	v_mfma_f32_16x16x32_bf16 v[12:15], v[150:153], v[216:219], v[12:15]
	v_mfma_f32_16x16x32_bf16 v[8:11], v[158:161], v[216:219], v[8:11]
	v_mfma_f32_16x16x32_bf16 v[60:63], v[154:157], v[196:199], v[60:63]
	v_mfma_f32_16x16x32_bf16 v[56:59], v[168:171], v[196:199], v[56:59]
	v_mfma_f32_16x16x32_bf16 v[44:47], v[154:157], v[204:207], v[44:47]
	v_mfma_f32_16x16x32_bf16 v[40:43], v[168:171], v[204:207], v[40:43]
	v_mfma_f32_16x16x32_bf16 v[28:31], v[154:157], v[212:215], v[28:31]
	v_mfma_f32_16x16x32_bf16 v[24:27], v[168:171], v[212:215], v[24:27]
	v_mfma_f32_16x16x32_bf16 v[12:15], v[154:157], v[220:223], v[12:15]
	v_mfma_f32_16x16x32_bf16 v[8:11], v[168:171], v[220:223], v[8:11]
	s_setprio 0
	s_setprio 1
	v_mfma_f32_16x16x32_bf16 v[52:55], v[172:175], v[192:195], v[52:55]
	v_mfma_f32_16x16x32_bf16 v[48:51], v[180:183], v[192:195], v[48:51]
	v_mfma_f32_16x16x32_bf16 v[36:39], v[172:175], v[200:203], v[36:39]
	v_mfma_f32_16x16x32_bf16 v[32:35], v[180:183], v[200:203], v[32:35]
	v_mfma_f32_16x16x32_bf16 v[20:23], v[172:175], v[208:211], v[20:23]
	v_mfma_f32_16x16x32_bf16 v[16:19], v[180:183], v[208:211], v[16:19]
	v_mfma_f32_16x16x32_bf16 v[4:7], v[172:175], v[216:219], v[4:7]
	v_mfma_f32_16x16x32_bf16 v[0:3], v[180:183], v[216:219], v[0:3]
	v_mfma_f32_16x16x32_bf16 v[52:55], v[176:179], v[196:199], v[52:55]
	v_mfma_f32_16x16x32_bf16 v[48:51], v[184:187], v[196:199], v[48:51]
	v_mfma_f32_16x16x32_bf16 v[36:39], v[176:179], v[204:207], v[36:39]
	v_mfma_f32_16x16x32_bf16 v[32:35], v[184:187], v[204:207], v[32:35]
	v_mfma_f32_16x16x32_bf16 v[20:23], v[176:179], v[212:215], v[20:23]
	v_mfma_f32_16x16x32_bf16 v[16:19], v[184:187], v[212:215], v[16:19]
	v_mfma_f32_16x16x32_bf16 v[4:7], v[176:179], v[220:223], v[4:7]
	v_mfma_f32_16x16x32_bf16 v[0:3], v[184:187], v[220:223], v[0:3]
	s_setprio 0
	s_barrier
	s_add_i32 s60, 0, 0x18000
	v_add_u32_e32 v136, s60, v162
	s_add_i32 s61, 0, 0x1c000
	ds_read_b128 v[150:153], v136
	ds_read_b128 v[154:157], v136 offset:1024
	ds_read_b128 v[158:161], v136 offset:2048
	ds_read_b128 v[168:171], v136 offset:3072
	v_add_u32_e32 v136, s61, v162
	ds_read_b128 v[172:175], v136
	ds_read_b128 v[176:179], v136 offset:1024
	ds_read_b128 v[180:183], v136 offset:2048
	ds_read_b128 v[184:187], v136 offset:3072
	s_add_u32 s36, s36, 0x40000
	s_addc_u32 s37, s37, 0
	s_mov_b32 m0, s47
	v_lshl_add_u64 v[230:231], s[36:37], 0, v[134:135]
	ds_read_b128 v[192:195], v165 offset:32768
	ds_read_b128 v[196:199], v165 offset:33792
	ds_read_b128 v[200:203], v165 offset:34816
	ds_read_b128 v[204:207], v165 offset:35840
	ds_read_b128 v[208:211], v165 offset:36864
	ds_read_b128 v[212:215], v165 offset:37888
	ds_read_b128 v[216:219], v165 offset:38912
	ds_read_b128 v[220:223], v165 offset:39936
	global_load_lds_dwordx4 v[230:231], off
	v_lshl_add_u64 v[230:231], s[36:37], 0, v[130:131]
	s_mov_b32 m0, s48
	s_nop 0
	global_load_lds_dwordx4 v[230:231], off
	s_waitcnt vmcnt(8)
	s_waitcnt lgkmcnt(0)
	s_barrier
	s_setprio 1
	s_waitcnt lgkmcnt(0)
	v_mfma_f32_16x16x32_bf16 v[124:127], v[150:153], v[192:195], v[124:127]
	v_mfma_f32_16x16x32_bf16 v[120:123], v[158:161], v[192:195], v[120:123]
	v_mfma_f32_16x16x32_bf16 v[108:111], v[150:153], v[200:203], v[108:111]
	v_mfma_f32_16x16x32_bf16 v[104:107], v[158:161], v[200:203], v[104:107]
	v_mfma_f32_16x16x32_bf16 v[92:95], v[150:153], v[208:211], v[92:95]
	v_mfma_f32_16x16x32_bf16 v[88:91], v[158:161], v[208:211], v[88:91]
	v_mfma_f32_16x16x32_bf16 v[76:79], v[150:153], v[216:219], v[76:79]
	v_mfma_f32_16x16x32_bf16 v[72:75], v[158:161], v[216:219], v[72:75]
	v_mfma_f32_16x16x32_bf16 v[124:127], v[154:157], v[196:199], v[124:127]
	v_mfma_f32_16x16x32_bf16 v[120:123], v[168:171], v[196:199], v[120:123]
	v_mfma_f32_16x16x32_bf16 v[108:111], v[154:157], v[204:207], v[108:111]
	v_mfma_f32_16x16x32_bf16 v[104:107], v[168:171], v[204:207], v[104:107]
	v_mfma_f32_16x16x32_bf16 v[92:95], v[154:157], v[212:215], v[92:95]
	v_mfma_f32_16x16x32_bf16 v[88:91], v[168:171], v[212:215], v[88:91]
	v_mfma_f32_16x16x32_bf16 v[76:79], v[154:157], v[220:223], v[76:79]
	v_mfma_f32_16x16x32_bf16 v[72:75], v[168:171], v[220:223], v[72:75]
	s_setprio 0
	s_setprio 1
	v_mfma_f32_16x16x32_bf16 v[116:119], v[172:175], v[192:195], v[116:119]
	v_mfma_f32_16x16x32_bf16 v[112:115], v[180:183], v[192:195], v[112:115]
	v_mfma_f32_16x16x32_bf16 v[100:103], v[172:175], v[200:203], v[100:103]
	v_mfma_f32_16x16x32_bf16 v[96:99], v[180:183], v[200:203], v[96:99]
	v_mfma_f32_16x16x32_bf16 v[84:87], v[172:175], v[208:211], v[84:87]
	v_mfma_f32_16x16x32_bf16 v[80:83], v[180:183], v[208:211], v[80:83]
	v_mfma_f32_16x16x32_bf16 v[68:71], v[172:175], v[216:219], v[68:71]
	v_mfma_f32_16x16x32_bf16 v[64:67], v[180:183], v[216:219], v[64:67]
	v_mfma_f32_16x16x32_bf16 v[116:119], v[176:179], v[196:199], v[116:119]
	v_mfma_f32_16x16x32_bf16 v[112:115], v[184:187], v[196:199], v[112:115]
	v_mfma_f32_16x16x32_bf16 v[100:103], v[176:179], v[204:207], v[100:103]
	v_mfma_f32_16x16x32_bf16 v[96:99], v[184:187], v[204:207], v[96:99]
	v_mfma_f32_16x16x32_bf16 v[84:87], v[176:179], v[212:215], v[84:87]
	v_mfma_f32_16x16x32_bf16 v[80:83], v[184:187], v[212:215], v[80:83]
	v_mfma_f32_16x16x32_bf16 v[68:71], v[176:179], v[220:223], v[68:71]
	v_mfma_f32_16x16x32_bf16 v[64:67], v[184:187], v[220:223], v[64:67]
	s_setprio 0
	s_barrier
	s_add_i32 s36, s60, s42
	v_lshl_add_u64 v[188:189], v[188:189], 0, s[16:17]
	s_mov_b32 m0, s36
	ds_read_b128 v[192:195], v165 offset:49152
	ds_read_b128 v[196:199], v165 offset:50176
	ds_read_b128 v[200:203], v165 offset:51200
	ds_read_b128 v[204:207], v165 offset:52224
	ds_read_b128 v[208:211], v165 offset:53248
	ds_read_b128 v[212:215], v165 offset:54272
	ds_read_b128 v[216:219], v165 offset:55296
	ds_read_b128 v[220:223], v165 offset:56320
	global_load_lds_dwordx4 v[188:189], off
	s_add_i32 m0, s36, 0x2000
	s_add_u32 s34, s34, 0x40080
	v_lshl_add_u64 v[188:189], v[224:225], 0, s[16:17]
	s_addc_u32 s35, s35, 0
	s_add_i32 s36, s61, s42
	global_load_lds_dwordx4 v[188:189], off
	v_lshl_add_u64 v[188:189], s[34:35], 0, v[132:133]
	s_mov_b32 m0, s36
	s_nop 0
	global_load_lds_dwordx4 v[188:189], off
	v_lshl_add_u64 v[188:189], s[34:35], 0, v[128:129]
	s_add_i32 m0, s36, 0x2000
	s_nop 0
	global_load_lds_dwordx4 v[188:189], off
	v_lshl_add_u64 v[188:189], v[226:227], 0, s[16:17]
	s_mov_b32 m0, s49
	s_nop 0
	global_load_lds_dwordx4 v[188:189], off
	v_lshl_add_u64 v[188:189], v[228:229], 0, s[16:17]
	s_mov_b32 m0, s50
	s_nop 0
	global_load_lds_dwordx4 v[188:189], off
	s_waitcnt vmcnt(8)
	s_waitcnt lgkmcnt(0)
	s_barrier
	s_setprio 1
	s_waitcnt lgkmcnt(0)
	v_mfma_f32_16x16x32_bf16 v[60:63], v[150:153], v[192:195], v[60:63]
	v_mfma_f32_16x16x32_bf16 v[56:59], v[158:161], v[192:195], v[56:59]
	v_mfma_f32_16x16x32_bf16 v[44:47], v[150:153], v[200:203], v[44:47]
	v_mfma_f32_16x16x32_bf16 v[40:43], v[158:161], v[200:203], v[40:43]
	v_mfma_f32_16x16x32_bf16 v[28:31], v[150:153], v[208:211], v[28:31]
	v_mfma_f32_16x16x32_bf16 v[24:27], v[158:161], v[208:211], v[24:27]
	v_mfma_f32_16x16x32_bf16 v[12:15], v[150:153], v[216:219], v[12:15]
	v_mfma_f32_16x16x32_bf16 v[8:11], v[158:161], v[216:219], v[8:11]
	v_mfma_f32_16x16x32_bf16 v[60:63], v[154:157], v[196:199], v[60:63]
	v_mfma_f32_16x16x32_bf16 v[56:59], v[168:171], v[196:199], v[56:59]
	v_mfma_f32_16x16x32_bf16 v[44:47], v[154:157], v[204:207], v[44:47]
	v_mfma_f32_16x16x32_bf16 v[40:43], v[168:171], v[204:207], v[40:43]
	v_mfma_f32_16x16x32_bf16 v[28:31], v[154:157], v[212:215], v[28:31]
	v_mfma_f32_16x16x32_bf16 v[24:27], v[168:171], v[212:215], v[24:27]
	v_mfma_f32_16x16x32_bf16 v[12:15], v[154:157], v[220:223], v[12:15]
	v_mfma_f32_16x16x32_bf16 v[8:11], v[168:171], v[220:223], v[8:11]
	s_setprio 0
	s_setprio 1
	v_mfma_f32_16x16x32_bf16 v[52:55], v[172:175], v[192:195], v[52:55]
	v_mfma_f32_16x16x32_bf16 v[48:51], v[180:183], v[192:195], v[48:51]
	v_mfma_f32_16x16x32_bf16 v[36:39], v[172:175], v[200:203], v[36:39]
	v_mfma_f32_16x16x32_bf16 v[32:35], v[180:183], v[200:203], v[32:35]
	v_mfma_f32_16x16x32_bf16 v[20:23], v[172:175], v[208:211], v[20:23]
	v_mfma_f32_16x16x32_bf16 v[16:19], v[180:183], v[208:211], v[16:19]
	v_mfma_f32_16x16x32_bf16 v[4:7], v[172:175], v[216:219], v[4:7]
	v_mfma_f32_16x16x32_bf16 v[0:3], v[180:183], v[216:219], v[0:3]
	v_mfma_f32_16x16x32_bf16 v[52:55], v[176:179], v[196:199], v[52:55]
	v_mfma_f32_16x16x32_bf16 v[48:51], v[184:187], v[196:199], v[48:51]
	v_mfma_f32_16x16x32_bf16 v[36:39], v[176:179], v[204:207], v[36:39]
	v_mfma_f32_16x16x32_bf16 v[32:35], v[184:187], v[204:207], v[32:35]
	v_mfma_f32_16x16x32_bf16 v[20:23], v[176:179], v[212:215], v[20:23]
	v_mfma_f32_16x16x32_bf16 v[16:19], v[184:187], v[212:215], v[16:19]
	v_mfma_f32_16x16x32_bf16 v[4:7], v[176:179], v[220:223], v[4:7]
	v_mfma_f32_16x16x32_bf16 v[0:3], v[184:187], v[220:223], v[0:3]
	s_setprio 0
	s_barrier
	s_add_i32 s59, s59, 2
	s_add_u32 s57, s57, 0x100
	s_addc_u32 s58, s58, 0
	s_add_u32 s30, s30, 0x100
	s_addc_u32 s31, s31, 0
	s_cmp_gt_u32 s59, 13
	s_cbranch_scc0 .LBB0_1416
	v_lshl_add_u32 v214, s0, 8, v139
	v_ashrrev_i32_e32 v215, 31, v214
	v_lshl_add_u64 v[212:213], v[214:215], 2, s[10:11]
	global_load_dword v204, v[212:213], off
	global_load_dword v205, v[212:213], off offset:64
	global_load_dword v206, v[212:213], off offset:128
	global_load_dword v207, v[212:213], off offset:192
	global_load_dword v208, v[212:213], off offset:512
	global_load_dword v209, v[212:213], off offset:576
	global_load_dword v210, v[212:213], off offset:640
	global_load_dword v211, v[212:213], off offset:704
	s_and_b64 vcc, exec, s[18:19]
	s_cbranch_vccz .LBB0_1419
	s_barrier

.LBB0_1422:
	v_lshl_add_u64 v[158:159], v[156:157], 2, s[10:11]
	v_mov_b64_e32 v[160:161], s[8:9]
	s_lshl_b32 s30, s1, 8
	s_mov_b32 s31, s13
	v_mad_i64_i32 v[168:169], s[34:35], v156, s54, v[160:161]
	s_mov_b32 s21, s13
	v_lshl_add_u64 v[168:169], v[168:169], 0, s[30:31]
	v_mov_b32_e32 v149, v137
	v_lshl_add_u64 v[168:169], v[168:169], 0, s[20:21]
	v_lshl_add_u64 v[174:175], v[168:169], 0, v[148:149]
	v_lshl_add_u64 v[172:173], v[154:155], 2, s[10:11]
	s_waitcnt vmcnt(0) lgkmcnt(0)
	v_fmamk_f32 v136, v204, 0x3a800000, v166
	v_mul_f32_e32 v167, 0x4b800000, v136
	v_cmp_gt_f32_e32 vcc, s53, v136
	s_nop 1
	v_cndmask_b32_e32 v136, v136, v167, vcc
	v_rsq_f32_e32 v136, v136
	s_nop 0
	v_mul_f32_e32 v167, 0x45800000, v136
	v_cndmask_b32_e32 v136, v136, v167, vcc
	v_pk_mul_f32 v[168:169], v[126:127], v[136:137] op_sel_hi:[1,0]
	v_pk_mul_f32 v[170:171], v[124:125], v[136:137] op_sel_hi:[1,0]
	v_pk_mul_f32 v[176:177], v[122:123], v[136:137] op_sel_hi:[1,0]
	v_pk_mul_f32 v[178:179], v[120:121], v[136:137] op_sel_hi:[1,0]
	v_pk_mul_f32 v[180:181], v[118:119], v[136:137] op_sel_hi:[1,0]
	v_pk_mul_f32 v[182:183], v[116:117], v[136:137] op_sel_hi:[1,0]
	v_pk_mul_f32 v[184:185], v[114:115], v[136:137] op_sel_hi:[1,0]
	v_pk_mul_f32 v[186:187], v[112:113], v[136:137] op_sel_hi:[1,0]
	v_mul_f32_e32 v136, 0xbfb8aa3b, v170
	v_mul_f32_e32 v167, 0xbfb8aa3b, v171
	v_mul_f32_e32 v188, 0xbfb8aa3b, v168
	v_mul_f32_e32 v189, 0xbfb8aa3b, v169
	v_mul_f32_e32 v191, 0xbfb8aa3b, v178
	v_mul_f32_e32 v192, 0xbfb8aa3b, v179
	v_mul_f32_e32 v193, 0xbfb8aa3b, v176
	v_mul_f32_e32 v194, 0xbfb8aa3b, v177
	v_exp_f32_e32 v136, v136
	v_exp_f32_e32 v167, v167
	v_exp_f32_e32 v188, v188
	v_exp_f32_e32 v189, v189
	v_exp_f32_e32 v191, v191
	v_exp_f32_e32 v192, v192
	v_exp_f32_e32 v193, v193
	v_exp_f32_e32 v194, v194
	v_add_f32_e32 v136, 1.0, v136
	v_add_f32_e32 v167, 1.0, v167
	v_add_f32_e32 v195, 1.0, v188
	v_add_f32_e32 v196, 1.0, v189
	v_add_f32_e32 v191, 1.0, v191
	v_add_f32_e32 v197, 1.0, v192
	v_add_f32_e32 v198, 1.0, v193
	v_add_f32_e32 v199, 1.0, v194
	v_rcp_f32_e32 v188, v136
	v_rcp_f32_e32 v189, v167
	v_rcp_f32_e32 v192, v195
	v_rcp_f32_e32 v193, v196
	v_rcp_f32_e32 v194, v191
	v_rcp_f32_e32 v195, v197
	v_rcp_f32_e32 v196, v198
	v_rcp_f32_e32 v197, v199
	v_pk_mul_f32 v[170:171], v[170:171], v[188:189]
	v_pk_mul_f32 v[168:169], v[168:169], v[192:193]
	v_pk_mul_f32 v[178:179], v[178:179], v[194:195]
	v_pk_mul_f32 v[176:177], v[176:177], v[196:197]
	v_pk_mul_f32 v[170:171], v[182:183], v[170:171]
	v_pk_mul_f32 v[180:181], v[180:181], v[168:169]
	v_pk_mul_f32 v[178:179], v[186:187], v[178:179]
	v_pk_mul_f32 v[176:177], v[184:185], v[176:177]
	v_cvt_pk_bf16_f32 v168, v170, v171
	v_cvt_pk_bf16_f32 v169, v180, v181
	v_cvt_pk_bf16_f32 v170, v178, v179
	v_cvt_pk_bf16_f32 v171, v176, v177
	global_store_dwordx4 v[174:175], v[168:171], off
	s_nop 1
	v_lshl_add_u64 v[172:173], v[152:153], 2, s[10:11]
	v_mad_i64_i32 v[168:169], s[34:35], v154, s54, v[160:161]
	v_lshl_add_u64 v[168:169], v[168:169], 0, s[30:31]
	v_lshl_add_u64 v[168:169], v[168:169], 0, s[20:21]
	v_lshl_add_u64 v[174:175], v[168:169], 0, v[148:149]
	v_fmamk_f32 v136, v205, 0x3a800000, v166
	v_mul_f32_e32 v167, 0x4b800000, v136
	v_cmp_gt_f32_e32 vcc, s53, v136
	s_nop 1
	v_cndmask_b32_e32 v136, v136, v167, vcc
	v_rsq_f32_e32 v136, v136
	s_nop 0
	v_mul_f32_e32 v167, 0x45800000, v136
	v_cndmask_b32_e32 v136, v136, v167, vcc
	v_pk_mul_f32 v[168:169], v[110:111], v[136:137] op_sel_hi:[1,0]
	v_pk_mul_f32 v[170:171], v[108:109], v[136:137] op_sel_hi:[1,0]
	v_pk_mul_f32 v[176:177], v[106:107], v[136:137] op_sel_hi:[1,0]
	v_pk_mul_f32 v[178:179], v[104:105], v[136:137] op_sel_hi:[1,0]
	v_pk_mul_f32 v[180:181], v[102:103], v[136:137] op_sel_hi:[1,0]
	v_pk_mul_f32 v[182:183], v[100:101], v[136:137] op_sel_hi:[1,0]
	v_pk_mul_f32 v[184:185], v[98:99], v[136:137] op_sel_hi:[1,0]
	v_pk_mul_f32 v[186:187], v[96:97], v[136:137] op_sel_hi:[1,0]
	v_mul_f32_e32 v136, 0xbfb8aa3b, v170
	v_mul_f32_e32 v167, 0xbfb8aa3b, v171
	v_mul_f32_e32 v188, 0xbfb8aa3b, v168
	v_mul_f32_e32 v189, 0xbfb8aa3b, v169
	v_mul_f32_e32 v191, 0xbfb8aa3b, v178
	v_mul_f32_e32 v192, 0xbfb8aa3b, v179
	v_mul_f32_e32 v193, 0xbfb8aa3b, v176
	v_mul_f32_e32 v194, 0xbfb8aa3b, v177
	v_exp_f32_e32 v136, v136
	v_exp_f32_e32 v167, v167
	v_exp_f32_e32 v188, v188
	v_exp_f32_e32 v189, v189
	v_exp_f32_e32 v191, v191
	v_exp_f32_e32 v192, v192
	v_exp_f32_e32 v193, v193
	v_exp_f32_e32 v194, v194
	v_add_f32_e32 v136, 1.0, v136
	v_add_f32_e32 v167, 1.0, v167
	v_add_f32_e32 v195, 1.0, v188
	v_add_f32_e32 v196, 1.0, v189
	v_add_f32_e32 v191, 1.0, v191
	v_add_f32_e32 v197, 1.0, v192
	v_add_f32_e32 v198, 1.0, v193
	v_add_f32_e32 v199, 1.0, v194
	v_rcp_f32_e32 v188, v136
	v_rcp_f32_e32 v189, v167
	v_rcp_f32_e32 v192, v195
	v_rcp_f32_e32 v193, v196
	v_rcp_f32_e32 v194, v191
	v_rcp_f32_e32 v195, v197
	v_rcp_f32_e32 v196, v198
	v_rcp_f32_e32 v197, v199
	v_pk_mul_f32 v[170:171], v[170:171], v[188:189]
	v_pk_mul_f32 v[168:169], v[168:169], v[192:193]
	v_pk_mul_f32 v[178:179], v[178:179], v[194:195]
	v_pk_mul_f32 v[176:177], v[176:177], v[196:197]
	v_pk_mul_f32 v[170:171], v[182:183], v[170:171]
	v_pk_mul_f32 v[180:181], v[180:181], v[168:169]
	v_pk_mul_f32 v[178:179], v[186:187], v[178:179]
	v_pk_mul_f32 v[176:177], v[184:185], v[176:177]
	v_cvt_pk_bf16_f32 v168, v170, v171
	v_cvt_pk_bf16_f32 v169, v180, v181
	v_cvt_pk_bf16_f32 v170, v178, v179
	v_cvt_pk_bf16_f32 v171, v176, v177
	global_store_dwordx4 v[174:175], v[168:171], off
	s_nop 1
	v_lshl_add_u64 v[172:173], v[150:151], 2, s[10:11]
	v_mad_i64_i32 v[168:169], s[34:35], v152, s54, v[160:161]
	v_lshl_add_u64 v[168:169], v[168:169], 0, s[30:31]
	v_lshl_add_u64 v[168:169], v[168:169], 0, s[20:21]
	v_lshl_add_u64 v[174:175], v[168:169], 0, v[148:149]
	v_fmamk_f32 v136, v206, 0x3a800000, v166
	v_mul_f32_e32 v167, 0x4b800000, v136
	v_cmp_gt_f32_e32 vcc, s53, v136
	s_nop 1
	v_cndmask_b32_e32 v136, v136, v167, vcc
	v_rsq_f32_e32 v136, v136
	s_nop 0
	v_mul_f32_e32 v167, 0x45800000, v136
	v_cndmask_b32_e32 v136, v136, v167, vcc
	v_pk_mul_f32 v[168:169], v[94:95], v[136:137] op_sel_hi:[1,0]
	v_pk_mul_f32 v[170:171], v[92:93], v[136:137] op_sel_hi:[1,0]
	v_pk_mul_f32 v[176:177], v[90:91], v[136:137] op_sel_hi:[1,0]
	v_pk_mul_f32 v[178:179], v[88:89], v[136:137] op_sel_hi:[1,0]
	v_pk_mul_f32 v[180:181], v[86:87], v[136:137] op_sel_hi:[1,0]
	v_pk_mul_f32 v[182:183], v[84:85], v[136:137] op_sel_hi:[1,0]
	v_pk_mul_f32 v[184:185], v[82:83], v[136:137] op_sel_hi:[1,0]
	v_pk_mul_f32 v[186:187], v[80:81], v[136:137] op_sel_hi:[1,0]
	v_mul_f32_e32 v136, 0xbfb8aa3b, v170
	v_mul_f32_e32 v167, 0xbfb8aa3b, v171
	v_mul_f32_e32 v188, 0xbfb8aa3b, v168
	v_mul_f32_e32 v189, 0xbfb8aa3b, v169
	v_mul_f32_e32 v191, 0xbfb8aa3b, v178
	v_mul_f32_e32 v192, 0xbfb8aa3b, v179
	v_mul_f32_e32 v193, 0xbfb8aa3b, v176
	v_mul_f32_e32 v194, 0xbfb8aa3b, v177
	v_exp_f32_e32 v136, v136
	v_exp_f32_e32 v167, v167
	v_exp_f32_e32 v188, v188
	v_exp_f32_e32 v189, v189
	v_exp_f32_e32 v191, v191
	v_exp_f32_e32 v192, v192
	v_exp_f32_e32 v193, v193
	v_exp_f32_e32 v194, v194
	v_add_f32_e32 v136, 1.0, v136
	v_add_f32_e32 v167, 1.0, v167
	v_add_f32_e32 v195, 1.0, v188
	v_add_f32_e32 v196, 1.0, v189
	v_add_f32_e32 v191, 1.0, v191
	v_add_f32_e32 v197, 1.0, v192
	v_add_f32_e32 v198, 1.0, v193
	v_add_f32_e32 v199, 1.0, v194
	v_rcp_f32_e32 v188, v136
	v_rcp_f32_e32 v189, v167
	v_rcp_f32_e32 v192, v195
	v_rcp_f32_e32 v193, v196
	v_rcp_f32_e32 v194, v191
	v_rcp_f32_e32 v195, v197
	v_rcp_f32_e32 v196, v198
	v_rcp_f32_e32 v197, v199
	v_pk_mul_f32 v[170:171], v[170:171], v[188:189]
	v_pk_mul_f32 v[168:169], v[168:169], v[192:193]
	v_pk_mul_f32 v[178:179], v[178:179], v[194:195]
	v_pk_mul_f32 v[176:177], v[176:177], v[196:197]
	v_pk_mul_f32 v[170:171], v[182:183], v[170:171]
	v_pk_mul_f32 v[180:181], v[180:181], v[168:169]
	v_pk_mul_f32 v[178:179], v[186:187], v[178:179]
	v_pk_mul_f32 v[176:177], v[184:185], v[176:177]
	v_cvt_pk_bf16_f32 v168, v170, v171
	v_cvt_pk_bf16_f32 v169, v180, v181
	v_cvt_pk_bf16_f32 v170, v178, v179
	v_cvt_pk_bf16_f32 v171, v176, v177
	global_store_dwordx4 v[174:175], v[168:171], off
	s_nop 1
	v_fmamk_f32 v136, v207, 0x3a800000, v166
	v_mul_f32_e32 v167, 0x4b800000, v136
	v_cmp_gt_f32_e32 vcc, s53, v136
	v_mad_i64_i32 v[168:169], s[34:35], v150, s54, v[160:161]
	s_nop 0
	v_cndmask_b32_e32 v136, v136, v167, vcc
	v_rsq_f32_e32 v136, v136
	v_lshl_add_u64 v[168:169], v[168:169], 0, s[30:31]
	v_lshl_add_u64 v[168:169], v[168:169], 0, s[20:21]
	v_lshl_add_u64 v[172:173], v[168:169], 0, v[148:149]
	v_mul_f32_e32 v167, 0x45800000, v136
	v_cndmask_b32_e32 v136, v136, v167, vcc
	v_pk_mul_f32 v[168:169], v[78:79], v[136:137] op_sel_hi:[1,0]
	v_pk_mul_f32 v[170:171], v[76:77], v[136:137] op_sel_hi:[1,0]
	v_pk_mul_f32 v[174:175], v[74:75], v[136:137] op_sel_hi:[1,0]
	v_pk_mul_f32 v[176:177], v[72:73], v[136:137] op_sel_hi:[1,0]
	v_pk_mul_f32 v[178:179], v[70:71], v[136:137] op_sel_hi:[1,0]
	v_pk_mul_f32 v[180:181], v[68:69], v[136:137] op_sel_hi:[1,0]
	v_pk_mul_f32 v[182:183], v[66:67], v[136:137] op_sel_hi:[1,0]
	v_pk_mul_f32 v[184:185], v[64:65], v[136:137] op_sel_hi:[1,0]
	v_mul_f32_e32 v136, 0xbfb8aa3b, v170
	v_mul_f32_e32 v167, 0xbfb8aa3b, v171
	v_mul_f32_e32 v186, 0xbfb8aa3b, v168
	v_mul_f32_e32 v187, 0xbfb8aa3b, v169
	v_mul_f32_e32 v188, 0xbfb8aa3b, v176
	v_mul_f32_e32 v189, 0xbfb8aa3b, v177
	v_mul_f32_e32 v191, 0xbfb8aa3b, v174
	v_mul_f32_e32 v192, 0xbfb8aa3b, v175
	v_exp_f32_e32 v136, v136
	v_exp_f32_e32 v167, v167
	v_exp_f32_e32 v186, v186
	v_exp_f32_e32 v187, v187
	v_exp_f32_e32 v188, v188
	v_exp_f32_e32 v189, v189
	v_exp_f32_e32 v191, v191
	v_exp_f32_e32 v192, v192
	v_add_f32_e32 v136, 1.0, v136
	v_add_f32_e32 v167, 1.0, v167
	v_add_f32_e32 v193, 1.0, v186
	v_add_f32_e32 v194, 1.0, v187
	v_add_f32_e32 v195, 1.0, v188
	v_add_f32_e32 v196, 1.0, v189
	v_add_f32_e32 v191, 1.0, v191
	v_add_f32_e32 v197, 1.0, v192
	v_rcp_f32_e32 v186, v136
	v_rcp_f32_e32 v187, v167
	v_rcp_f32_e32 v188, v193
	v_rcp_f32_e32 v189, v194
	v_rcp_f32_e32 v192, v195
	v_rcp_f32_e32 v193, v196
	v_rcp_f32_e32 v194, v191
	v_rcp_f32_e32 v195, v197
	v_pk_mul_f32 v[170:171], v[170:171], v[186:187]
	v_pk_mul_f32 v[168:169], v[168:169], v[188:189]
	v_pk_mul_f32 v[176:177], v[176:177], v[192:193]
	v_pk_mul_f32 v[174:175], v[174:175], v[194:195]
	v_pk_mul_f32 v[170:171], v[180:181], v[170:171]
	v_pk_mul_f32 v[178:179], v[178:179], v[168:169]
	v_pk_mul_f32 v[176:177], v[184:185], v[176:177]
	v_pk_mul_f32 v[174:175], v[182:183], v[174:175]
	v_cvt_pk_bf16_f32 v168, v170, v171
	v_cvt_pk_bf16_f32 v169, v178, v179
	v_cvt_pk_bf16_f32 v170, v176, v177
	v_cvt_pk_bf16_f32 v171, v174, v175
	global_store_dwordx4 v[172:173], v[168:171], off
	s_nop 1
	v_add_u32_e32 v167, 0x80, v156
	v_mad_i64_i32 v[168:169], s[34:35], v167, s54, v[160:161]
	v_lshl_add_u64 v[168:169], v[168:169], 0, s[30:31]
	v_lshl_add_u64 v[168:169], v[168:169], 0, s[20:21]
	v_lshl_add_u64 v[172:173], v[168:169], 0, v[148:149]
	v_fmamk_f32 v136, v208, 0x3a800000, v166
	v_mul_f32_e32 v167, 0x4b800000, v136
	v_cmp_gt_f32_e32 vcc, s53, v136
	s_nop 1
	v_cndmask_b32_e32 v136, v136, v167, vcc
	v_rsq_f32_e32 v136, v136
	s_nop 0
	v_mul_f32_e32 v167, 0x45800000, v136
	v_cndmask_b32_e32 v136, v136, v167, vcc
	v_pk_mul_f32 v[168:169], v[62:63], v[136:137] op_sel_hi:[1,0]
	v_pk_mul_f32 v[170:171], v[60:61], v[136:137] op_sel_hi:[1,0]
	v_pk_mul_f32 v[174:175], v[58:59], v[136:137] op_sel_hi:[1,0]
	v_pk_mul_f32 v[176:177], v[56:57], v[136:137] op_sel_hi:[1,0]
	v_pk_mul_f32 v[178:179], v[54:55], v[136:137] op_sel_hi:[1,0]
	v_pk_mul_f32 v[180:181], v[52:53], v[136:137] op_sel_hi:[1,0]
	v_pk_mul_f32 v[182:183], v[50:51], v[136:137] op_sel_hi:[1,0]
	v_pk_mul_f32 v[184:185], v[48:49], v[136:137] op_sel_hi:[1,0]
	v_mul_f32_e32 v136, 0xbfb8aa3b, v170
	v_mul_f32_e32 v167, 0xbfb8aa3b, v171
	v_mul_f32_e32 v186, 0xbfb8aa3b, v168
	v_mul_f32_e32 v187, 0xbfb8aa3b, v169
	v_mul_f32_e32 v188, 0xbfb8aa3b, v176
	v_mul_f32_e32 v189, 0xbfb8aa3b, v177
	v_mul_f32_e32 v191, 0xbfb8aa3b, v174
	v_mul_f32_e32 v192, 0xbfb8aa3b, v175
	v_exp_f32_e32 v136, v136
	v_exp_f32_e32 v167, v167
	v_exp_f32_e32 v186, v186
	v_exp_f32_e32 v187, v187
	v_exp_f32_e32 v188, v188
	v_exp_f32_e32 v189, v189
	v_exp_f32_e32 v191, v191
	v_exp_f32_e32 v192, v192
	v_add_f32_e32 v136, 1.0, v136
	v_add_f32_e32 v167, 1.0, v167
	v_add_f32_e32 v193, 1.0, v186
	v_add_f32_e32 v194, 1.0, v187
	v_add_f32_e32 v195, 1.0, v188
	v_add_f32_e32 v196, 1.0, v189
	v_add_f32_e32 v191, 1.0, v191
	v_add_f32_e32 v197, 1.0, v192
	v_rcp_f32_e32 v186, v136
	v_rcp_f32_e32 v187, v167
	v_rcp_f32_e32 v188, v193
	v_rcp_f32_e32 v189, v194
	v_rcp_f32_e32 v192, v195
	v_rcp_f32_e32 v193, v196
	v_rcp_f32_e32 v194, v191
	v_rcp_f32_e32 v195, v197
	v_pk_mul_f32 v[170:171], v[170:171], v[186:187]
	v_pk_mul_f32 v[168:169], v[168:169], v[188:189]
	v_pk_mul_f32 v[176:177], v[176:177], v[192:193]
	v_pk_mul_f32 v[174:175], v[174:175], v[194:195]
	v_pk_mul_f32 v[170:171], v[180:181], v[170:171]
	v_pk_mul_f32 v[178:179], v[178:179], v[168:169]
	v_pk_mul_f32 v[176:177], v[184:185], v[176:177]
	v_pk_mul_f32 v[174:175], v[182:183], v[174:175]
	v_cvt_pk_bf16_f32 v168, v170, v171
	v_cvt_pk_bf16_f32 v169, v178, v179
	v_cvt_pk_bf16_f32 v170, v176, v177
	v_cvt_pk_bf16_f32 v171, v174, v175
	global_store_dwordx4 v[172:173], v[168:171], off
	s_nop 1
	v_add_u32_e32 v167, 0x90, v156
	v_mad_i64_i32 v[168:169], s[34:35], v167, s54, v[160:161]
	v_lshl_add_u64 v[168:169], v[168:169], 0, s[30:31]
	v_lshl_add_u64 v[168:169], v[168:169], 0, s[20:21]
	v_lshl_add_u64 v[172:173], v[168:169], 0, v[148:149]
	v_fmamk_f32 v136, v209, 0x3a800000, v166
	v_mul_f32_e32 v167, 0x4b800000, v136
	v_cmp_gt_f32_e32 vcc, s53, v136
	s_nop 1
	v_cndmask_b32_e32 v136, v136, v167, vcc
	v_rsq_f32_e32 v136, v136
	s_nop 0
	v_mul_f32_e32 v167, 0x45800000, v136
	v_cndmask_b32_e32 v136, v136, v167, vcc
	v_pk_mul_f32 v[168:169], v[46:47], v[136:137] op_sel_hi:[1,0]
	v_pk_mul_f32 v[170:171], v[44:45], v[136:137] op_sel_hi:[1,0]
	v_pk_mul_f32 v[174:175], v[42:43], v[136:137] op_sel_hi:[1,0]
	v_pk_mul_f32 v[176:177], v[40:41], v[136:137] op_sel_hi:[1,0]
	v_pk_mul_f32 v[178:179], v[38:39], v[136:137] op_sel_hi:[1,0]
	v_pk_mul_f32 v[180:181], v[36:37], v[136:137] op_sel_hi:[1,0]
	v_pk_mul_f32 v[182:183], v[34:35], v[136:137] op_sel_hi:[1,0]
	v_pk_mul_f32 v[184:185], v[32:33], v[136:137] op_sel_hi:[1,0]
	v_mul_f32_e32 v136, 0xbfb8aa3b, v170
	v_mul_f32_e32 v167, 0xbfb8aa3b, v171
	v_mul_f32_e32 v186, 0xbfb8aa3b, v168
	v_mul_f32_e32 v187, 0xbfb8aa3b, v169
	v_mul_f32_e32 v188, 0xbfb8aa3b, v176
	v_mul_f32_e32 v189, 0xbfb8aa3b, v177
	v_mul_f32_e32 v191, 0xbfb8aa3b, v174
	v_mul_f32_e32 v192, 0xbfb8aa3b, v175
	v_exp_f32_e32 v136, v136
	v_exp_f32_e32 v167, v167
	v_exp_f32_e32 v186, v186
	v_exp_f32_e32 v187, v187
	v_exp_f32_e32 v188, v188
	v_exp_f32_e32 v189, v189
	v_exp_f32_e32 v191, v191
	v_exp_f32_e32 v192, v192
	v_add_f32_e32 v136, 1.0, v136
	v_add_f32_e32 v167, 1.0, v167
	v_add_f32_e32 v193, 1.0, v186
	v_add_f32_e32 v194, 1.0, v187
	v_add_f32_e32 v195, 1.0, v188
	v_add_f32_e32 v196, 1.0, v189
	v_add_f32_e32 v191, 1.0, v191
	v_add_f32_e32 v197, 1.0, v192
	v_rcp_f32_e32 v186, v136
	v_rcp_f32_e32 v187, v167
	v_rcp_f32_e32 v188, v193
	v_rcp_f32_e32 v189, v194
	v_rcp_f32_e32 v192, v195
	v_rcp_f32_e32 v193, v196
	v_rcp_f32_e32 v194, v191
	v_rcp_f32_e32 v195, v197
	v_pk_mul_f32 v[170:171], v[170:171], v[186:187]
	v_pk_mul_f32 v[168:169], v[168:169], v[188:189]
	v_pk_mul_f32 v[176:177], v[176:177], v[192:193]
	v_pk_mul_f32 v[174:175], v[174:175], v[194:195]
	v_pk_mul_f32 v[170:171], v[180:181], v[170:171]
	v_pk_mul_f32 v[178:179], v[178:179], v[168:169]
	v_pk_mul_f32 v[176:177], v[184:185], v[176:177]
	v_pk_mul_f32 v[174:175], v[182:183], v[174:175]
	v_cvt_pk_bf16_f32 v168, v170, v171
	v_cvt_pk_bf16_f32 v169, v178, v179
	v_cvt_pk_bf16_f32 v170, v176, v177
	v_cvt_pk_bf16_f32 v171, v174, v175
	global_store_dwordx4 v[172:173], v[168:171], off
	s_nop 1
	v_add_u32_e32 v167, 0xa0, v156
	v_mad_i64_i32 v[168:169], s[34:35], v167, s54, v[160:161]
	v_lshl_add_u64 v[168:169], v[168:169], 0, s[30:31]
	v_lshl_add_u64 v[168:169], v[168:169], 0, s[20:21]
	v_lshl_add_u64 v[172:173], v[168:169], 0, v[148:149]
	v_fmamk_f32 v136, v210, 0x3a800000, v166
	v_mul_f32_e32 v167, 0x4b800000, v136
	v_cmp_gt_f32_e32 vcc, s53, v136
	s_nop 1
	v_cndmask_b32_e32 v136, v136, v167, vcc
	v_rsq_f32_e32 v136, v136
	s_nop 0
	v_mul_f32_e32 v167, 0x45800000, v136
	v_cndmask_b32_e32 v136, v136, v167, vcc
	v_pk_mul_f32 v[168:169], v[30:31], v[136:137] op_sel_hi:[1,0]
	v_pk_mul_f32 v[170:171], v[28:29], v[136:137] op_sel_hi:[1,0]
	v_pk_mul_f32 v[174:175], v[26:27], v[136:137] op_sel_hi:[1,0]
	v_pk_mul_f32 v[176:177], v[24:25], v[136:137] op_sel_hi:[1,0]
	v_pk_mul_f32 v[178:179], v[22:23], v[136:137] op_sel_hi:[1,0]
	v_pk_mul_f32 v[180:181], v[20:21], v[136:137] op_sel_hi:[1,0]
	v_pk_mul_f32 v[182:183], v[18:19], v[136:137] op_sel_hi:[1,0]
	v_pk_mul_f32 v[184:185], v[16:17], v[136:137] op_sel_hi:[1,0]
	v_mul_f32_e32 v136, 0xbfb8aa3b, v170
	v_mul_f32_e32 v167, 0xbfb8aa3b, v171
	v_mul_f32_e32 v186, 0xbfb8aa3b, v168
	v_mul_f32_e32 v187, 0xbfb8aa3b, v169
	v_mul_f32_e32 v188, 0xbfb8aa3b, v176
	v_mul_f32_e32 v189, 0xbfb8aa3b, v177
	v_mul_f32_e32 v191, 0xbfb8aa3b, v174
	v_mul_f32_e32 v192, 0xbfb8aa3b, v175
	v_exp_f32_e32 v136, v136
	v_exp_f32_e32 v167, v167
	v_exp_f32_e32 v186, v186
	v_exp_f32_e32 v187, v187
	v_exp_f32_e32 v188, v188
	v_exp_f32_e32 v189, v189
	v_exp_f32_e32 v191, v191
	v_exp_f32_e32 v192, v192
	v_add_f32_e32 v136, 1.0, v136
	v_add_f32_e32 v167, 1.0, v167
	v_add_f32_e32 v193, 1.0, v186
	v_add_f32_e32 v194, 1.0, v187
	v_add_f32_e32 v195, 1.0, v188
	v_add_f32_e32 v196, 1.0, v189
	v_add_f32_e32 v191, 1.0, v191
	v_add_f32_e32 v197, 1.0, v192
	v_rcp_f32_e32 v186, v136
	v_rcp_f32_e32 v187, v167
	v_rcp_f32_e32 v188, v193
	v_rcp_f32_e32 v189, v194
	v_rcp_f32_e32 v192, v195
	v_rcp_f32_e32 v193, v196
	v_rcp_f32_e32 v194, v191
	v_rcp_f32_e32 v195, v197
	v_pk_mul_f32 v[170:171], v[170:171], v[186:187]
	v_pk_mul_f32 v[168:169], v[168:169], v[188:189]
	v_pk_mul_f32 v[176:177], v[176:177], v[192:193]
	v_pk_mul_f32 v[174:175], v[174:175], v[194:195]
	v_pk_mul_f32 v[170:171], v[180:181], v[170:171]
	v_pk_mul_f32 v[178:179], v[178:179], v[168:169]
	v_pk_mul_f32 v[176:177], v[184:185], v[176:177]
	v_pk_mul_f32 v[174:175], v[182:183], v[174:175]
	v_cvt_pk_bf16_f32 v168, v170, v171
	v_cvt_pk_bf16_f32 v169, v178, v179
	v_cvt_pk_bf16_f32 v170, v176, v177
	v_cvt_pk_bf16_f32 v171, v174, v175
	global_store_dwordx4 v[172:173], v[168:171], off
	s_nop 1
	v_add_u32_e32 v158, 0xb0, v156
	v_mad_i64_i32 v[158:159], s[34:35], v158, s54, v[160:161]
	v_lshl_add_u64 v[158:159], v[158:159], 0, s[30:31]
	v_lshl_add_u64 v[158:159], v[158:159], 0, s[20:21]
	v_lshl_add_u64 v[168:169], v[158:159], 0, v[148:149]
	v_fmamk_f32 v136, v211, 0x3a800000, v166
	v_mul_f32_e32 v160, 0x4b800000, v136
	v_cmp_gt_f32_e32 vcc, s53, v136
	s_nop 1
	v_cndmask_b32_e32 v136, v136, v160, vcc
	v_rsq_f32_e32 v136, v136
	s_nop 0
	v_mul_f32_e32 v149, 0x45800000, v136
	v_cndmask_b32_e32 v136, v136, v149, vcc
	v_pk_mul_f32 v[158:159], v[14:15], v[136:137] op_sel_hi:[1,0]
	v_pk_mul_f32 v[160:161], v[12:13], v[136:137] op_sel_hi:[1,0]
	v_pk_mul_f32 v[170:171], v[10:11], v[136:137] op_sel_hi:[1,0]
	v_pk_mul_f32 v[172:173], v[8:9], v[136:137] op_sel_hi:[1,0]
	v_pk_mul_f32 v[174:175], v[6:7], v[136:137] op_sel_hi:[1,0]
	v_pk_mul_f32 v[176:177], v[4:5], v[136:137] op_sel_hi:[1,0]
	v_pk_mul_f32 v[178:179], v[2:3], v[136:137] op_sel_hi:[1,0]
	v_pk_mul_f32 v[180:181], v[0:1], v[136:137] op_sel_hi:[1,0]
	v_mul_f32_e32 v136, 0xbfb8aa3b, v160
	v_mul_f32_e32 v149, 0xbfb8aa3b, v161
	v_mul_f32_e32 v167, 0xbfb8aa3b, v158
	v_mul_f32_e32 v182, 0xbfb8aa3b, v159
	v_mul_f32_e32 v183, 0xbfb8aa3b, v172
	v_mul_f32_e32 v184, 0xbfb8aa3b, v173
	v_mul_f32_e32 v185, 0xbfb8aa3b, v170
	v_mul_f32_e32 v186, 0xbfb8aa3b, v171
	v_exp_f32_e32 v136, v136
	v_exp_f32_e32 v149, v149
	v_exp_f32_e32 v167, v167
	v_exp_f32_e32 v182, v182
	v_exp_f32_e32 v183, v183
	v_exp_f32_e32 v184, v184
	v_exp_f32_e32 v185, v185
	v_exp_f32_e32 v186, v186
	v_add_f32_e32 v136, 1.0, v136
	v_add_f32_e32 v149, 1.0, v149
	v_add_f32_e32 v167, 1.0, v167
	v_add_f32_e32 v187, 1.0, v182
	v_add_f32_e32 v188, 1.0, v183
	v_add_f32_e32 v189, 1.0, v184
	v_add_f32_e32 v191, 1.0, v185
	v_add_f32_e32 v192, 1.0, v186
	v_rcp_f32_e32 v182, v136
	v_rcp_f32_e32 v183, v149
	v_rcp_f32_e32 v184, v167
	v_rcp_f32_e32 v185, v187
	v_rcp_f32_e32 v186, v188
	v_rcp_f32_e32 v187, v189
	v_rcp_f32_e32 v188, v191
	v_rcp_f32_e32 v189, v192
	v_pk_mul_f32 v[160:161], v[160:161], v[182:183]
	v_pk_mul_f32 v[158:159], v[158:159], v[184:185]
	v_pk_mul_f32 v[172:173], v[172:173], v[186:187]
	v_pk_mul_f32 v[170:171], v[170:171], v[188:189]
	v_pk_mul_f32 v[160:161], v[176:177], v[160:161]
	v_pk_mul_f32 v[174:175], v[174:175], v[158:159]
	v_pk_mul_f32 v[172:173], v[180:181], v[172:173]
	v_pk_mul_f32 v[170:171], v[178:179], v[170:171]
	v_cvt_pk_bf16_f32 v158, v160, v161
	v_cvt_pk_bf16_f32 v159, v174, v175
	v_cvt_pk_bf16_f32 v160, v172, v173
	v_cvt_pk_bf16_f32 v161, v170, v171
	global_store_dwordx4 v[168:169], v[158:161], off
	s_cbranch_execnz .LBB0_1421

.LBB0_1500:
	v_mbcnt_lo_u32_b32 v235, -1, 0
	v_mbcnt_hi_u32_b32 v235, -1, v235
	v_lshrrev_b32_e32 v236, 2, v235
	v_and_b32_e32 v237, 3, v235
	v_lshl_add_u32 v232, v237, 4, v236
	v_lshlrev_b32_e32 v232, 2, v232
	v_and_b32_e32 v233, -16, v168
	v_or_b32_e32 v233, v233, v236
	v_lshlrev_b32_e32 v237, 2, v237
	v_and_b32_e32 v234, -13, v170
	v_or_b32_e32 v234, v234, v237
	ds_bpermute_b32 v127, v232, v127
	ds_bpermute_b32 v126, v232, v126
	ds_bpermute_b32 v125, v232, v125
	ds_bpermute_b32 v124, v232, v124
	ds_bpermute_b32 v123, v232, v123
	ds_bpermute_b32 v122, v232, v122
	ds_bpermute_b32 v121, v232, v121
	ds_bpermute_b32 v120, v232, v120
	ds_bpermute_b32 v119, v232, v119
	ds_bpermute_b32 v118, v232, v118
	ds_bpermute_b32 v117, v232, v117
	ds_bpermute_b32 v116, v232, v116
	ds_bpermute_b32 v115, v232, v115
	ds_bpermute_b32 v114, v232, v114
	ds_bpermute_b32 v113, v232, v113
	ds_bpermute_b32 v112, v232, v112
	ds_bpermute_b32 v111, v232, v111
	ds_bpermute_b32 v110, v232, v110
	ds_bpermute_b32 v109, v232, v109
	ds_bpermute_b32 v108, v232, v108
	ds_bpermute_b32 v107, v232, v107
	ds_bpermute_b32 v106, v232, v106
	ds_bpermute_b32 v105, v232, v105
	ds_bpermute_b32 v104, v232, v104
	ds_bpermute_b32 v103, v232, v103
	ds_bpermute_b32 v102, v232, v102
	ds_bpermute_b32 v101, v232, v101
	ds_bpermute_b32 v100, v232, v100
	ds_bpermute_b32 v99, v232, v99
	ds_bpermute_b32 v98, v232, v98
	ds_bpermute_b32 v97, v232, v97
	ds_bpermute_b32 v96, v232, v96
	ds_bpermute_b32 v95, v232, v95
	ds_bpermute_b32 v94, v232, v94
	ds_bpermute_b32 v93, v232, v93
	ds_bpermute_b32 v92, v232, v92
	ds_bpermute_b32 v91, v232, v91
	ds_bpermute_b32 v90, v232, v90
	ds_bpermute_b32 v89, v232, v89
	ds_bpermute_b32 v88, v232, v88
	ds_bpermute_b32 v87, v232, v87
	ds_bpermute_b32 v86, v232, v86
	ds_bpermute_b32 v85, v232, v85
	ds_bpermute_b32 v84, v232, v84
	ds_bpermute_b32 v83, v232, v83
	ds_bpermute_b32 v82, v232, v82
	ds_bpermute_b32 v81, v232, v81
	ds_bpermute_b32 v80, v232, v80
	ds_bpermute_b32 v79, v232, v79
	ds_bpermute_b32 v78, v232, v78
	ds_bpermute_b32 v77, v232, v77
	ds_bpermute_b32 v76, v232, v76
	ds_bpermute_b32 v75, v232, v75
	ds_bpermute_b32 v74, v232, v74
	ds_bpermute_b32 v73, v232, v73
	ds_bpermute_b32 v72, v232, v72
	ds_bpermute_b32 v71, v232, v71
	ds_bpermute_b32 v70, v232, v70
	ds_bpermute_b32 v69, v232, v69
	ds_bpermute_b32 v68, v232, v68
	ds_bpermute_b32 v67, v232, v67
	ds_bpermute_b32 v66, v232, v66
	ds_bpermute_b32 v65, v232, v65
	ds_bpermute_b32 v64, v232, v64
	ds_bpermute_b32 v63, v232, v63
	ds_bpermute_b32 v62, v232, v62
	ds_bpermute_b32 v61, v232, v61
	ds_bpermute_b32 v60, v232, v60
	ds_bpermute_b32 v59, v232, v59
	ds_bpermute_b32 v58, v232, v58
	ds_bpermute_b32 v57, v232, v57
	ds_bpermute_b32 v56, v232, v56
	ds_bpermute_b32 v55, v232, v55
	ds_bpermute_b32 v54, v232, v54
	ds_bpermute_b32 v53, v232, v53
	ds_bpermute_b32 v52, v232, v52
	ds_bpermute_b32 v51, v232, v51
	ds_bpermute_b32 v50, v232, v50
	ds_bpermute_b32 v49, v232, v49
	ds_bpermute_b32 v48, v232, v48
	ds_bpermute_b32 v47, v232, v47
	ds_bpermute_b32 v46, v232, v46
	ds_bpermute_b32 v45, v232, v45
	ds_bpermute_b32 v44, v232, v44
	ds_bpermute_b32 v43, v232, v43
	ds_bpermute_b32 v42, v232, v42
	ds_bpermute_b32 v41, v232, v41
	ds_bpermute_b32 v40, v232, v40
	ds_bpermute_b32 v39, v232, v39
	ds_bpermute_b32 v38, v232, v38
	ds_bpermute_b32 v37, v232, v37
	ds_bpermute_b32 v36, v232, v36
	ds_bpermute_b32 v35, v232, v35
	ds_bpermute_b32 v34, v232, v34
	ds_bpermute_b32 v33, v232, v33
	ds_bpermute_b32 v32, v232, v32
	ds_bpermute_b32 v31, v232, v31
	ds_bpermute_b32 v30, v232, v30
	ds_bpermute_b32 v29, v232, v29
	ds_bpermute_b32 v28, v232, v28
	ds_bpermute_b32 v27, v232, v27
	ds_bpermute_b32 v26, v232, v26
	ds_bpermute_b32 v25, v232, v25
	ds_bpermute_b32 v24, v232, v24
	ds_bpermute_b32 v23, v232, v23
	ds_bpermute_b32 v22, v232, v22
	ds_bpermute_b32 v21, v232, v21
	ds_bpermute_b32 v20, v232, v20
	ds_bpermute_b32 v19, v232, v19
	ds_bpermute_b32 v18, v232, v18
	ds_bpermute_b32 v17, v232, v17
	ds_bpermute_b32 v16, v232, v16
	ds_bpermute_b32 v15, v232, v15
	ds_bpermute_b32 v14, v232, v14
	ds_bpermute_b32 v13, v232, v13
	ds_bpermute_b32 v12, v232, v12
	ds_bpermute_b32 v11, v232, v11
	ds_bpermute_b32 v10, v232, v10
	ds_bpermute_b32 v9, v232, v9
	ds_bpermute_b32 v8, v232, v8
	ds_bpermute_b32 v7, v232, v7
	ds_bpermute_b32 v6, v232, v6
	ds_bpermute_b32 v5, v232, v5
	ds_bpermute_b32 v4, v232, v4
	ds_bpermute_b32 v3, v232, v3
	ds_bpermute_b32 v2, v232, v2
	ds_bpermute_b32 v1, v232, v1
	ds_bpermute_b32 v0, v232, v0
	s_waitcnt lgkmcnt(0)
	v_lshl_add_u32 v158, s52, 8, v233
	v_lshl_or_b32 v156, s51, 8, v234
	v_ashrrev_i32_e32 v159, 31, v158
	v_lshlrev_b64 v[128:129], 12, v[158:159]
	v_ashrrev_i32_e32 v157, 31, v156
	v_lshl_add_u64 v[128:129], s[10:11], 0, v[128:129]
	v_lshlrev_b64 v[130:131], 2, v[156:157]
	v_lshl_add_u64 v[188:189], v[128:129], 0, v[130:131]
	global_load_dwordx4 v[164:167], v[188:189], off
	global_load_dwordx4 v[176:179], v[188:189], off offset:64
	global_load_dwordx4 v[180:183], v[188:189], off offset:512
	global_load_dwordx4 v[184:187], v[188:189], off offset:576
	v_or_b32_e32 v160, 16, v158
	v_ashrrev_i32_e32 v161, 31, v160
	v_lshlrev_b64 v[128:129], 12, v[160:161]
	v_lshl_add_u64 v[128:129], s[10:11], 0, v[128:129]
	v_lshl_add_u64 v[162:163], v[128:129], 0, v[130:131]
	global_load_dwordx4 v[140:143], v[162:163], off
	global_load_dwordx4 v[136:139], v[162:163], off offset:64
	global_load_dwordx4 v[132:135], v[162:163], off offset:512
	global_load_dwordx4 v[128:131], v[162:163], off offset:576
	v_lshlrev_b64 v[192:193], 11, v[158:159]
	v_lshl_add_u64 v[192:193], s[14:15], 0, v[192:193]
	v_and_b32_e32 v191, 64, v174
	v_lshl_add_u64 v[192:193], v[156:157], 1, v[192:193]
	v_xor_b32_e32 v175, 1, v174
	v_add_u32_e32 v191, 64, v191
	v_cmp_lt_i32_e32 vcc, v175, v191
	v_xor_b32_e32 v194, 2, v174
	s_waitcnt vmcnt(0) lgkmcnt(0)
	v_pk_fma_f32 v[126:127], v[126:127], 0.5, v[166:167] op_sel_hi:[1,0,1]
	v_pk_fma_f32 v[124:125], v[124:125], 0.5, v[164:165] op_sel_hi:[1,0,1]
	v_pk_fma_f32 v[122:123], v[122:123], 0.5, v[178:179] op_sel_hi:[1,0,1]
	v_pk_fma_f32 v[120:121], v[120:121], 0.5, v[176:177] op_sel_hi:[1,0,1]
	v_pk_fma_f32 v[118:119], v[118:119], 0.5, v[182:183] op_sel_hi:[1,0,1]
	v_pk_fma_f32 v[116:117], v[116:117], 0.5, v[180:181] op_sel_hi:[1,0,1]
	v_pk_fma_f32 v[164:165], v[112:113], 0.5, v[184:185] op_sel_hi:[1,0,1]
	v_mul_f32_e32 v178, v125, v125
	v_mul_f32_e32 v179, v127, v127
	global_store_dwordx4 v[188:189], v[124:127], off
	v_cvt_pk_bf16_f32 v112, v124, v125
	v_cvt_pk_bf16_f32 v113, v126, v127
	v_mul_f32_e32 v125, v121, v121
	v_mul_f32_e32 v127, v123, v123
	v_pk_fma_f32 v[166:167], v[114:115], 0.5, v[186:187] op_sel_hi:[1,0,1]
	v_mul_f32_e32 v180, v117, v117
	v_mul_f32_e32 v181, v119, v119
	v_fmac_f32_e32 v178, v124, v124
	v_fmac_f32_e32 v179, v126, v126
	v_fmac_f32_e32 v125, v120, v120
	v_fmac_f32_e32 v127, v122, v122
	v_mul_f32_e32 v182, v165, v165
	v_mul_f32_e32 v183, v167, v167
	global_store_dwordx2 v[192:193], v[112:113], off
	v_fmac_f32_e32 v180, v116, v116
	v_fmac_f32_e32 v181, v118, v118
	v_add_f32_e32 v112, v178, v179
	v_add_f32_e32 v113, v125, v127
	v_fmac_f32_e32 v182, v164, v164
	v_fmac_f32_e32 v183, v166, v166
	v_add_f32_e32 v124, v180, v181
	v_add_f32_e32 v112, v112, v113
	v_cndmask_b32_e32 v175, v174, v175, vcc
	v_add_f32_e32 v125, v182, v183
	v_add_f32_e32 v112, v112, v124
	v_lshlrev_b32_e32 v175, 2, v175
	v_add_f32_e32 v112, v112, v125
	ds_bpermute_b32 v113, v175, v112
	v_cmp_lt_i32_e32 vcc, v194, v191
	v_cvt_pk_bf16_f32 v176, v116, v117
	v_cvt_pk_bf16_f32 v114, v120, v121
	v_cndmask_b32_e32 v191, v174, v194, vcc
	v_cvt_pk_bf16_f32 v115, v122, v123
	v_cvt_pk_bf16_f32 v177, v118, v119
	global_store_dwordx4 v[188:189], v[120:123], off offset:64
	global_store_dwordx2 v[192:193], v[114:115], off offset:32
	global_store_dwordx4 v[188:189], v[116:119], off offset:512
	global_store_dwordx2 v[192:193], v[176:177], off offset:256
	s_waitcnt lgkmcnt(0)
	v_add_f32_e32 v112, v112, v113
	v_lshlrev_b32_e32 v176, 2, v191
	ds_bpermute_b32 v113, v176, v112
	v_cvt_pk_bf16_f32 v114, v164, v165
	v_cvt_pk_bf16_f32 v115, v166, v167
	global_store_dwordx4 v[188:189], v[164:167], off offset:576
	global_store_dwordx2 v[192:193], v[114:115], off offset:288
	s_mov_b32 vcc_lo, 0x11111111
	s_mov_b32 vcc_hi, 0x11111111
	s_and_saveexec_b64 s[24:25], vcc
	s_cbranch_execz .LBB0_1502
	v_lshl_add_u64 v[114:115], v[158:159], 2, s[16:17]
	s_waitcnt lgkmcnt(0)
	v_add_f32_e32 v112, v112, v113
	global_atomic_add_f32 v[114:115], v112, off
.LBB0_1502:
	s_or_b64 exec, exec, s[24:25]
	v_or_b32_e32 v164, 32, v158
	v_ashrrev_i32_e32 v165, 31, v164
	s_waitcnt lgkmcnt(0)
	v_lshlrev_b64 v[112:113], 12, v[164:165]
	v_lshl_add_u64 v[112:113], s[10:11], 0, v[112:113]
	v_lshl_add_u64 v[166:167], v[156:157], 2, v[112:113]
	global_load_dwordx4 v[124:127], v[166:167], off
	global_load_dwordx4 v[120:123], v[166:167], off offset:64
	global_load_dwordx4 v[116:119], v[166:167], off offset:512
	global_load_dwordx4 v[112:115], v[166:167], off offset:576
	v_pk_fma_f32 v[110:111], v[110:111], 0.5, v[142:143] op_sel_hi:[1,0,1]
	v_pk_fma_f32 v[108:109], v[108:109], 0.5, v[140:141] op_sel_hi:[1,0,1]
	v_mul_f32_e32 v141, v111, v111
	v_mul_f32_e32 v140, v109, v109
	v_fmac_f32_e32 v140, v108, v108
	v_fmac_f32_e32 v141, v110, v110
	v_add_f32_e32 v142, v140, v141
	v_lshlrev_b64 v[140:141], 11, v[160:161]
	v_lshl_add_u64 v[140:141], s[14:15], 0, v[140:141]
	global_store_dwordx4 v[162:163], v[108:111], off
	v_lshl_add_u64 v[140:141], v[156:157], 1, v[140:141]
	v_pk_fma_f32 v[104:105], v[104:105], 0.5, v[136:137] op_sel_hi:[1,0,1]
	v_cvt_pk_bf16_f32 v108, v108, v109
	v_cvt_pk_bf16_f32 v109, v110, v111
	global_store_dwordx2 v[140:141], v[108:109], off
	v_pk_fma_f32 v[106:107], v[106:107], 0.5, v[138:139] op_sel_hi:[1,0,1]
	v_mul_f32_e32 v108, v105, v105
	v_fmac_f32_e32 v108, v104, v104
	v_mul_f32_e32 v109, v107, v107
	global_store_dwordx4 v[162:163], v[104:107], off offset:64
	v_pk_fma_f32 v[102:103], v[102:103], 0.5, v[134:135] op_sel_hi:[1,0,1]
	v_pk_fma_f32 v[100:101], v[100:101], 0.5, v[132:133] op_sel_hi:[1,0,1]
	v_cvt_pk_bf16_f32 v104, v104, v105
	v_cvt_pk_bf16_f32 v105, v106, v107
	v_fmac_f32_e32 v109, v106, v106
	global_store_dwordx2 v[140:141], v[104:105], off offset:32
	v_mul_f32_e32 v104, v101, v101
	v_mul_f32_e32 v105, v103, v103
	v_add_f32_e32 v108, v108, v109
	v_fmac_f32_e32 v104, v100, v100
	v_fmac_f32_e32 v105, v102, v102
	v_add_f32_e32 v108, v142, v108
	v_add_f32_e32 v104, v104, v105
	v_add_f32_e32 v108, v108, v104
	v_pk_fma_f32 v[106:107], v[98:99], 0.5, v[130:131] op_sel_hi:[1,0,1]
	v_pk_fma_f32 v[104:105], v[96:97], 0.5, v[128:129] op_sel_hi:[1,0,1]
	v_mul_f32_e32 v97, v107, v107
	v_mul_f32_e32 v96, v105, v105
	v_fmac_f32_e32 v96, v104, v104
	v_fmac_f32_e32 v97, v106, v106
	v_add_f32_e32 v96, v96, v97
	v_add_f32_e32 v98, v108, v96
	ds_bpermute_b32 v99, v175, v98
	v_cvt_pk_bf16_f32 v96, v100, v101
	v_cvt_pk_bf16_f32 v97, v102, v103
	global_store_dwordx4 v[162:163], v[100:103], off offset:512
	global_store_dwordx2 v[140:141], v[96:97], off offset:256
	s_waitcnt lgkmcnt(0)
	v_add_f32_e32 v96, v98, v99
	ds_bpermute_b32 v97, v176, v96
	v_cvt_pk_bf16_f32 v98, v104, v105
	v_cvt_pk_bf16_f32 v99, v106, v107
	global_store_dwordx4 v[162:163], v[104:107], off offset:576
	global_store_dwordx2 v[140:141], v[98:99], off offset:288
	s_mov_b32 vcc_lo, 0x11111111
	s_mov_b32 vcc_hi, 0x11111111
	s_and_saveexec_b64 s[24:25], vcc
	s_cbranch_execz .LBB0_1504
	v_lshl_add_u64 v[98:99], v[160:161], 2, s[16:17]
	s_waitcnt lgkmcnt(0)
	v_add_f32_e32 v96, v96, v97
	global_atomic_add_f32 v[98:99], v96, off
.LBB0_1504:
	s_or_b64 exec, exec, s[24:25]
	v_or_b32_e32 v128, 48, v158
	v_ashrrev_i32_e32 v129, 31, v128
	s_waitcnt lgkmcnt(0)
	v_lshlrev_b64 v[96:97], 12, v[128:129]
	v_lshl_add_u64 v[96:97], s[10:11], 0, v[96:97]
	v_lshl_add_u64 v[130:131], v[156:157], 2, v[96:97]
	global_load_dwordx4 v[108:111], v[130:131], off
	global_load_dwordx4 v[104:107], v[130:131], off offset:64
	global_load_dwordx4 v[100:103], v[130:131], off offset:512
	global_load_dwordx4 v[96:99], v[130:131], off offset:576
	s_waitcnt vmcnt(0)
	v_pk_fma_f32 v[94:95], v[94:95], 0.5, v[126:127] op_sel_hi:[1,0,1]
	v_pk_fma_f32 v[92:93], v[92:93], 0.5, v[124:125] op_sel_hi:[1,0,1]
	v_mul_f32_e32 v125, v95, v95
	v_mul_f32_e32 v124, v93, v93
	v_fmac_f32_e32 v124, v92, v92
	v_fmac_f32_e32 v125, v94, v94
	v_add_f32_e32 v126, v124, v125
	v_lshlrev_b64 v[124:125], 11, v[164:165]
	v_lshl_add_u64 v[124:125], s[14:15], 0, v[124:125]
	global_store_dwordx4 v[166:167], v[92:95], off
	v_lshl_add_u64 v[124:125], v[156:157], 1, v[124:125]
	v_pk_fma_f32 v[88:89], v[88:89], 0.5, v[120:121] op_sel_hi:[1,0,1]
	v_cvt_pk_bf16_f32 v92, v92, v93
	v_cvt_pk_bf16_f32 v93, v94, v95
	global_store_dwordx2 v[124:125], v[92:93], off
	v_pk_fma_f32 v[90:91], v[90:91], 0.5, v[122:123] op_sel_hi:[1,0,1]
	v_mul_f32_e32 v92, v89, v89
	v_fmac_f32_e32 v92, v88, v88
	v_mul_f32_e32 v93, v91, v91
	global_store_dwordx4 v[166:167], v[88:91], off offset:64
	v_pk_fma_f32 v[86:87], v[86:87], 0.5, v[118:119] op_sel_hi:[1,0,1]
	v_pk_fma_f32 v[84:85], v[84:85], 0.5, v[116:117] op_sel_hi:[1,0,1]
	v_cvt_pk_bf16_f32 v88, v88, v89
	v_cvt_pk_bf16_f32 v89, v90, v91
	v_fmac_f32_e32 v93, v90, v90
	global_store_dwordx2 v[124:125], v[88:89], off offset:32
	v_mul_f32_e32 v88, v85, v85
	v_mul_f32_e32 v89, v87, v87
	v_add_f32_e32 v92, v92, v93
	v_fmac_f32_e32 v88, v84, v84
	v_fmac_f32_e32 v89, v86, v86
	v_add_f32_e32 v92, v126, v92
	v_add_f32_e32 v88, v88, v89
	v_add_f32_e32 v92, v92, v88
	v_pk_fma_f32 v[90:91], v[82:83], 0.5, v[114:115] op_sel_hi:[1,0,1]
	v_pk_fma_f32 v[88:89], v[80:81], 0.5, v[112:113] op_sel_hi:[1,0,1]
	v_mul_f32_e32 v81, v91, v91
	v_mul_f32_e32 v80, v89, v89
	v_fmac_f32_e32 v80, v88, v88
	v_fmac_f32_e32 v81, v90, v90
	v_add_f32_e32 v80, v80, v81
	v_add_f32_e32 v82, v92, v80
	ds_bpermute_b32 v83, v175, v82
	v_cvt_pk_bf16_f32 v80, v84, v85
	v_cvt_pk_bf16_f32 v81, v86, v87
	global_store_dwordx4 v[166:167], v[84:87], off offset:512
	global_store_dwordx2 v[124:125], v[80:81], off offset:256
	s_waitcnt lgkmcnt(0)
	v_add_f32_e32 v80, v82, v83
	ds_bpermute_b32 v81, v176, v80
	v_cvt_pk_bf16_f32 v82, v88, v89
	v_cvt_pk_bf16_f32 v83, v90, v91
	global_store_dwordx4 v[166:167], v[88:91], off offset:576
	global_store_dwordx2 v[124:125], v[82:83], off offset:288
	s_mov_b32 vcc_lo, 0x11111111
	s_mov_b32 vcc_hi, 0x11111111
	s_and_saveexec_b64 s[24:25], vcc
	s_cbranch_execz .LBB0_1506
	v_lshl_add_u64 v[82:83], v[164:165], 2, s[16:17]
	s_waitcnt lgkmcnt(0)
	v_add_f32_e32 v80, v80, v81
	global_atomic_add_f32 v[82:83], v80, off
.LBB0_1506:
	s_or_b64 exec, exec, s[24:25]
	v_add_u32_e32 v112, 0x80, v158
	v_ashrrev_i32_e32 v113, 31, v112
	s_waitcnt lgkmcnt(0)
	v_lshlrev_b64 v[80:81], 12, v[112:113]
	v_lshl_add_u64 v[80:81], s[10:11], 0, v[80:81]
	v_lshl_add_u64 v[114:115], v[156:157], 2, v[80:81]
	global_load_dwordx4 v[92:95], v[114:115], off
	global_load_dwordx4 v[88:91], v[114:115], off offset:64
	global_load_dwordx4 v[84:87], v[114:115], off offset:512
	global_load_dwordx4 v[80:83], v[114:115], off offset:576
	v_pk_fma_f32 v[78:79], v[78:79], 0.5, v[110:111] op_sel_hi:[1,0,1]
	v_pk_fma_f32 v[76:77], v[76:77], 0.5, v[108:109] op_sel_hi:[1,0,1]
	v_mul_f32_e32 v109, v79, v79
	v_mul_f32_e32 v108, v77, v77
	v_fmac_f32_e32 v108, v76, v76
	v_fmac_f32_e32 v109, v78, v78
	v_add_f32_e32 v110, v108, v109
	v_lshlrev_b64 v[108:109], 11, v[128:129]
	v_lshl_add_u64 v[108:109], s[14:15], 0, v[108:109]
	global_store_dwordx4 v[130:131], v[76:79], off
	v_lshl_add_u64 v[108:109], v[156:157], 1, v[108:109]
	v_pk_fma_f32 v[72:73], v[72:73], 0.5, v[104:105] op_sel_hi:[1,0,1]
	v_cvt_pk_bf16_f32 v76, v76, v77
	v_cvt_pk_bf16_f32 v77, v78, v79
	global_store_dwordx2 v[108:109], v[76:77], off
	v_pk_fma_f32 v[74:75], v[74:75], 0.5, v[106:107] op_sel_hi:[1,0,1]
	v_mul_f32_e32 v76, v73, v73
	v_fmac_f32_e32 v76, v72, v72
	v_mul_f32_e32 v77, v75, v75
	global_store_dwordx4 v[130:131], v[72:75], off offset:64
	v_pk_fma_f32 v[70:71], v[70:71], 0.5, v[102:103] op_sel_hi:[1,0,1]
	v_pk_fma_f32 v[68:69], v[68:69], 0.5, v[100:101] op_sel_hi:[1,0,1]
	v_cvt_pk_bf16_f32 v72, v72, v73
	v_cvt_pk_bf16_f32 v73, v74, v75
	v_fmac_f32_e32 v77, v74, v74
	global_store_dwordx2 v[108:109], v[72:73], off offset:32
	v_mul_f32_e32 v72, v69, v69
	v_mul_f32_e32 v73, v71, v71
	v_add_f32_e32 v76, v76, v77
	v_fmac_f32_e32 v72, v68, v68
	v_fmac_f32_e32 v73, v70, v70
	v_add_f32_e32 v76, v110, v76
	v_add_f32_e32 v72, v72, v73
	v_add_f32_e32 v76, v76, v72
	v_pk_fma_f32 v[74:75], v[66:67], 0.5, v[98:99] op_sel_hi:[1,0,1]
	v_pk_fma_f32 v[72:73], v[64:65], 0.5, v[96:97] op_sel_hi:[1,0,1]
	v_mul_f32_e32 v65, v75, v75
	v_mul_f32_e32 v64, v73, v73
	v_fmac_f32_e32 v64, v72, v72
	v_fmac_f32_e32 v65, v74, v74
	v_add_f32_e32 v64, v64, v65
	v_add_f32_e32 v66, v76, v64
	ds_bpermute_b32 v67, v175, v66
	v_cvt_pk_bf16_f32 v64, v68, v69
	v_cvt_pk_bf16_f32 v65, v70, v71
	global_store_dwordx4 v[130:131], v[68:71], off offset:512
	global_store_dwordx2 v[108:109], v[64:65], off offset:256
	s_waitcnt lgkmcnt(0)
	v_add_f32_e32 v64, v66, v67
	ds_bpermute_b32 v65, v176, v64
	v_cvt_pk_bf16_f32 v66, v72, v73
	v_cvt_pk_bf16_f32 v67, v74, v75
	global_store_dwordx4 v[130:131], v[72:75], off offset:576
	global_store_dwordx2 v[108:109], v[66:67], off offset:288
	s_mov_b32 vcc_lo, 0x11111111
	s_mov_b32 vcc_hi, 0x11111111
	s_and_saveexec_b64 s[24:25], vcc
	s_cbranch_execz .LBB0_1508
	v_lshl_add_u64 v[66:67], v[128:129], 2, s[16:17]
	s_waitcnt lgkmcnt(0)
	v_add_f32_e32 v64, v64, v65
	global_atomic_add_f32 v[66:67], v64, off
.LBB0_1508:
	s_or_b64 exec, exec, s[24:25]
	v_or_b32_e32 v96, 16, v112
	v_ashrrev_i32_e32 v97, 31, v96
	s_waitcnt lgkmcnt(0)
	v_lshlrev_b64 v[64:65], 12, v[96:97]
	v_lshl_add_u64 v[64:65], s[10:11], 0, v[64:65]
	v_lshl_add_u64 v[98:99], v[156:157], 2, v[64:65]
	global_load_dwordx4 v[76:79], v[98:99], off
	global_load_dwordx4 v[72:75], v[98:99], off offset:64
	global_load_dwordx4 v[68:71], v[98:99], off offset:512
	global_load_dwordx4 v[64:67], v[98:99], off offset:576
	s_waitcnt vmcnt(0)
	v_pk_fma_f32 v[62:63], v[62:63], 0.5, v[94:95] op_sel_hi:[1,0,1]
	v_pk_fma_f32 v[60:61], v[60:61], 0.5, v[92:93] op_sel_hi:[1,0,1]
	v_mul_f32_e32 v93, v63, v63
	v_mul_f32_e32 v92, v61, v61
	v_fmac_f32_e32 v92, v60, v60
	v_fmac_f32_e32 v93, v62, v62
	v_add_f32_e32 v94, v92, v93
	v_lshlrev_b64 v[92:93], 11, v[112:113]
	v_lshl_add_u64 v[92:93], s[14:15], 0, v[92:93]
	global_store_dwordx4 v[114:115], v[60:63], off
	v_lshl_add_u64 v[92:93], v[156:157], 1, v[92:93]
	v_pk_fma_f32 v[56:57], v[56:57], 0.5, v[88:89] op_sel_hi:[1,0,1]
	v_cvt_pk_bf16_f32 v60, v60, v61
	v_cvt_pk_bf16_f32 v61, v62, v63
	global_store_dwordx2 v[92:93], v[60:61], off
	v_pk_fma_f32 v[58:59], v[58:59], 0.5, v[90:91] op_sel_hi:[1,0,1]
	v_mul_f32_e32 v60, v57, v57
	v_fmac_f32_e32 v60, v56, v56
	v_mul_f32_e32 v61, v59, v59
	global_store_dwordx4 v[114:115], v[56:59], off offset:64
	v_pk_fma_f32 v[54:55], v[54:55], 0.5, v[86:87] op_sel_hi:[1,0,1]
	v_pk_fma_f32 v[52:53], v[52:53], 0.5, v[84:85] op_sel_hi:[1,0,1]
	v_cvt_pk_bf16_f32 v56, v56, v57
	v_cvt_pk_bf16_f32 v57, v58, v59
	v_fmac_f32_e32 v61, v58, v58
	global_store_dwordx2 v[92:93], v[56:57], off offset:32
	v_mul_f32_e32 v56, v53, v53
	v_mul_f32_e32 v57, v55, v55
	v_add_f32_e32 v60, v60, v61
	v_fmac_f32_e32 v56, v52, v52
	v_fmac_f32_e32 v57, v54, v54
	v_add_f32_e32 v60, v94, v60
	v_add_f32_e32 v56, v56, v57
	v_add_f32_e32 v60, v60, v56
	v_pk_fma_f32 v[58:59], v[50:51], 0.5, v[82:83] op_sel_hi:[1,0,1]
	v_pk_fma_f32 v[56:57], v[48:49], 0.5, v[80:81] op_sel_hi:[1,0,1]
	v_mul_f32_e32 v49, v59, v59
	v_mul_f32_e32 v48, v57, v57
	v_fmac_f32_e32 v48, v56, v56
	v_fmac_f32_e32 v49, v58, v58
	v_add_f32_e32 v48, v48, v49
	v_add_f32_e32 v50, v60, v48
	ds_bpermute_b32 v51, v175, v50
	v_cvt_pk_bf16_f32 v48, v52, v53
	v_cvt_pk_bf16_f32 v49, v54, v55
	global_store_dwordx4 v[114:115], v[52:55], off offset:512
	global_store_dwordx2 v[92:93], v[48:49], off offset:256
	s_waitcnt lgkmcnt(0)
	v_add_f32_e32 v48, v50, v51
	ds_bpermute_b32 v49, v176, v48
	v_cvt_pk_bf16_f32 v50, v56, v57
	v_cvt_pk_bf16_f32 v51, v58, v59
	global_store_dwordx4 v[114:115], v[56:59], off offset:576
	global_store_dwordx2 v[92:93], v[50:51], off offset:288
	s_mov_b32 vcc_lo, 0x11111111
	s_mov_b32 vcc_hi, 0x11111111
	s_and_saveexec_b64 s[24:25], vcc
	s_cbranch_execz .LBB0_1510
	v_lshl_add_u64 v[50:51], v[112:113], 2, s[16:17]
	s_waitcnt lgkmcnt(0)
	v_add_f32_e32 v48, v48, v49
	global_atomic_add_f32 v[50:51], v48, off
.LBB0_1510:
	s_or_b64 exec, exec, s[24:25]
	v_or_b32_e32 v80, 32, v112
	v_ashrrev_i32_e32 v81, 31, v80
	s_waitcnt lgkmcnt(0)
	v_lshlrev_b64 v[48:49], 12, v[80:81]
	v_lshl_add_u64 v[48:49], s[10:11], 0, v[48:49]
	v_lshl_add_u64 v[82:83], v[156:157], 2, v[48:49]
	global_load_dwordx4 v[60:63], v[82:83], off
	global_load_dwordx4 v[56:59], v[82:83], off offset:64
	global_load_dwordx4 v[52:55], v[82:83], off offset:512
	global_load_dwordx4 v[48:51], v[82:83], off offset:576
	v_pk_fma_f32 v[46:47], v[46:47], 0.5, v[78:79] op_sel_hi:[1,0,1]
	v_pk_fma_f32 v[44:45], v[44:45], 0.5, v[76:77] op_sel_hi:[1,0,1]
	v_mul_f32_e32 v77, v47, v47
	v_mul_f32_e32 v76, v45, v45
	v_fmac_f32_e32 v76, v44, v44
	v_fmac_f32_e32 v77, v46, v46
	v_add_f32_e32 v78, v76, v77
	v_lshlrev_b64 v[76:77], 11, v[96:97]
	v_lshl_add_u64 v[76:77], s[14:15], 0, v[76:77]
	global_store_dwordx4 v[98:99], v[44:47], off
	v_lshl_add_u64 v[76:77], v[156:157], 1, v[76:77]
	v_pk_fma_f32 v[40:41], v[40:41], 0.5, v[72:73] op_sel_hi:[1,0,1]
	v_cvt_pk_bf16_f32 v44, v44, v45
	v_cvt_pk_bf16_f32 v45, v46, v47
	global_store_dwordx2 v[76:77], v[44:45], off
	v_pk_fma_f32 v[42:43], v[42:43], 0.5, v[74:75] op_sel_hi:[1,0,1]
	v_mul_f32_e32 v44, v41, v41
	v_fmac_f32_e32 v44, v40, v40
	v_mul_f32_e32 v45, v43, v43
	global_store_dwordx4 v[98:99], v[40:43], off offset:64
	v_pk_fma_f32 v[38:39], v[38:39], 0.5, v[70:71] op_sel_hi:[1,0,1]
	v_pk_fma_f32 v[36:37], v[36:37], 0.5, v[68:69] op_sel_hi:[1,0,1]
	v_cvt_pk_bf16_f32 v40, v40, v41
	v_cvt_pk_bf16_f32 v41, v42, v43
	v_fmac_f32_e32 v45, v42, v42
	global_store_dwordx2 v[76:77], v[40:41], off offset:32
	v_mul_f32_e32 v40, v37, v37
	v_mul_f32_e32 v41, v39, v39
	v_add_f32_e32 v44, v44, v45
	v_fmac_f32_e32 v40, v36, v36
	v_fmac_f32_e32 v41, v38, v38
	v_add_f32_e32 v44, v78, v44
	v_add_f32_e32 v40, v40, v41
	v_add_f32_e32 v44, v44, v40
	v_pk_fma_f32 v[42:43], v[34:35], 0.5, v[66:67] op_sel_hi:[1,0,1]
	v_pk_fma_f32 v[40:41], v[32:33], 0.5, v[64:65] op_sel_hi:[1,0,1]
	v_mul_f32_e32 v33, v43, v43
	v_mul_f32_e32 v32, v41, v41
	v_fmac_f32_e32 v32, v40, v40
	v_fmac_f32_e32 v33, v42, v42
	v_add_f32_e32 v32, v32, v33
	v_add_f32_e32 v34, v44, v32
	ds_bpermute_b32 v35, v175, v34
	v_cvt_pk_bf16_f32 v32, v36, v37
	v_cvt_pk_bf16_f32 v33, v38, v39
	global_store_dwordx4 v[98:99], v[36:39], off offset:512
	global_store_dwordx2 v[76:77], v[32:33], off offset:256
	s_waitcnt lgkmcnt(0)
	v_add_f32_e32 v32, v34, v35
	ds_bpermute_b32 v33, v176, v32
	v_cvt_pk_bf16_f32 v34, v40, v41
	v_cvt_pk_bf16_f32 v35, v42, v43
	global_store_dwordx4 v[98:99], v[40:43], off offset:576
	global_store_dwordx2 v[76:77], v[34:35], off offset:288
	s_mov_b32 vcc_lo, 0x11111111
	s_mov_b32 vcc_hi, 0x11111111
	s_and_saveexec_b64 s[24:25], vcc
	s_cbranch_execz .LBB0_1512
	v_lshl_add_u64 v[34:35], v[96:97], 2, s[16:17]
	s_waitcnt lgkmcnt(0)
	v_add_f32_e32 v32, v32, v33
	global_atomic_add_f32 v[34:35], v32, off
.LBB0_1512:
	s_or_b64 exec, exec, s[24:25]
	v_or_b32_e32 v64, 48, v112
	v_ashrrev_i32_e32 v65, 31, v64
	s_waitcnt lgkmcnt(0)
	v_lshlrev_b64 v[32:33], 12, v[64:65]
	v_lshl_add_u64 v[32:33], s[10:11], 0, v[32:33]
	v_lshl_add_u64 v[66:67], v[156:157], 2, v[32:33]
	global_load_dwordx4 v[44:47], v[66:67], off
	global_load_dwordx4 v[40:43], v[66:67], off offset:64
	global_load_dwordx4 v[36:39], v[66:67], off offset:512
	global_load_dwordx4 v[32:35], v[66:67], off offset:576
	s_waitcnt vmcnt(0)
	v_pk_fma_f32 v[30:31], v[30:31], 0.5, v[62:63] op_sel_hi:[1,0,1]
	v_pk_fma_f32 v[28:29], v[28:29], 0.5, v[60:61] op_sel_hi:[1,0,1]
	v_mul_f32_e32 v61, v31, v31
	v_mul_f32_e32 v60, v29, v29
	v_fmac_f32_e32 v60, v28, v28
	v_fmac_f32_e32 v61, v30, v30
	v_add_f32_e32 v62, v60, v61
	v_lshlrev_b64 v[60:61], 11, v[80:81]
	v_lshl_add_u64 v[60:61], s[14:15], 0, v[60:61]
	global_store_dwordx4 v[82:83], v[28:31], off
	v_lshl_add_u64 v[60:61], v[156:157], 1, v[60:61]
	v_pk_fma_f32 v[24:25], v[24:25], 0.5, v[56:57] op_sel_hi:[1,0,1]
	v_cvt_pk_bf16_f32 v28, v28, v29
	v_cvt_pk_bf16_f32 v29, v30, v31
	global_store_dwordx2 v[60:61], v[28:29], off
	v_pk_fma_f32 v[26:27], v[26:27], 0.5, v[58:59] op_sel_hi:[1,0,1]
	v_mul_f32_e32 v28, v25, v25
	v_fmac_f32_e32 v28, v24, v24
	v_mul_f32_e32 v29, v27, v27
	global_store_dwordx4 v[82:83], v[24:27], off offset:64
	v_pk_fma_f32 v[22:23], v[22:23], 0.5, v[54:55] op_sel_hi:[1,0,1]
	v_pk_fma_f32 v[20:21], v[20:21], 0.5, v[52:53] op_sel_hi:[1,0,1]
	v_cvt_pk_bf16_f32 v24, v24, v25
	v_cvt_pk_bf16_f32 v25, v26, v27
	v_fmac_f32_e32 v29, v26, v26
	global_store_dwordx2 v[60:61], v[24:25], off offset:32
	v_mul_f32_e32 v24, v21, v21
	v_mul_f32_e32 v25, v23, v23
	v_add_f32_e32 v28, v28, v29
	v_fmac_f32_e32 v24, v20, v20
	v_fmac_f32_e32 v25, v22, v22
	v_add_f32_e32 v28, v62, v28
	v_add_f32_e32 v24, v24, v25
	v_add_f32_e32 v28, v28, v24
	v_pk_fma_f32 v[26:27], v[18:19], 0.5, v[50:51] op_sel_hi:[1,0,1]
	v_pk_fma_f32 v[24:25], v[16:17], 0.5, v[48:49] op_sel_hi:[1,0,1]
	v_mul_f32_e32 v17, v27, v27
	v_mul_f32_e32 v16, v25, v25
	v_fmac_f32_e32 v16, v24, v24
	v_fmac_f32_e32 v17, v26, v26
	v_add_f32_e32 v16, v16, v17
	v_add_f32_e32 v18, v28, v16
	ds_bpermute_b32 v19, v175, v18
	v_cvt_pk_bf16_f32 v16, v20, v21
	v_cvt_pk_bf16_f32 v17, v22, v23
	global_store_dwordx4 v[82:83], v[20:23], off offset:512
	global_store_dwordx2 v[60:61], v[16:17], off offset:256
	s_waitcnt lgkmcnt(0)
	v_add_f32_e32 v16, v18, v19
	ds_bpermute_b32 v17, v176, v16
	v_cvt_pk_bf16_f32 v18, v24, v25
	v_cvt_pk_bf16_f32 v19, v26, v27
	global_store_dwordx4 v[82:83], v[24:27], off offset:576
	global_store_dwordx2 v[60:61], v[18:19], off offset:288
	s_mov_b32 vcc_lo, 0x11111111
	s_mov_b32 vcc_hi, 0x11111111
	s_and_saveexec_b64 s[24:25], vcc
	s_cbranch_execz .LBB0_1514
	v_lshl_add_u64 v[18:19], v[80:81], 2, s[16:17]
	s_waitcnt lgkmcnt(0)
	v_add_f32_e32 v16, v16, v17
	global_atomic_add_f32 v[18:19], v16, off
.LBB0_1514:
	s_or_b64 exec, exec, s[24:25]
	v_pk_fma_f32 v[14:15], v[14:15], 0.5, v[46:47] op_sel_hi:[1,0,1]
	v_pk_fma_f32 v[12:13], v[12:13], 0.5, v[44:45] op_sel_hi:[1,0,1]
	s_waitcnt lgkmcnt(0)
	v_mul_f32_e32 v17, v15, v15
	v_mul_f32_e32 v16, v13, v13
	v_fmac_f32_e32 v16, v12, v12
	v_fmac_f32_e32 v17, v14, v14
	v_add_f32_e32 v18, v16, v17
	v_lshlrev_b64 v[16:17], 11, v[64:65]
	v_lshl_add_u64 v[16:17], s[14:15], 0, v[16:17]
	global_store_dwordx4 v[66:67], v[12:15], off
	v_lshl_add_u64 v[16:17], v[156:157], 1, v[16:17]
	v_pk_fma_f32 v[8:9], v[8:9], 0.5, v[40:41] op_sel_hi:[1,0,1]
	v_cvt_pk_bf16_f32 v12, v12, v13
	v_cvt_pk_bf16_f32 v13, v14, v15
	global_store_dwordx2 v[16:17], v[12:13], off
	v_pk_fma_f32 v[10:11], v[10:11], 0.5, v[42:43] op_sel_hi:[1,0,1]
	v_mul_f32_e32 v12, v9, v9
	v_fmac_f32_e32 v12, v8, v8
	v_mul_f32_e32 v13, v11, v11
	global_store_dwordx4 v[66:67], v[8:11], off offset:64
	v_pk_fma_f32 v[6:7], v[6:7], 0.5, v[38:39] op_sel_hi:[1,0,1]
	v_pk_fma_f32 v[4:5], v[4:5], 0.5, v[36:37] op_sel_hi:[1,0,1]
	v_cvt_pk_bf16_f32 v8, v8, v9
	v_cvt_pk_bf16_f32 v9, v10, v11
	v_fmac_f32_e32 v13, v10, v10
	global_store_dwordx2 v[16:17], v[8:9], off offset:32
	v_mul_f32_e32 v8, v5, v5
	v_mul_f32_e32 v9, v7, v7
	v_add_f32_e32 v12, v12, v13
	v_fmac_f32_e32 v8, v4, v4
	v_fmac_f32_e32 v9, v6, v6
	v_add_f32_e32 v12, v18, v12
	v_add_f32_e32 v8, v8, v9
	v_add_f32_e32 v12, v12, v8
	v_pk_fma_f32 v[10:11], v[2:3], 0.5, v[34:35] op_sel_hi:[1,0,1]
	v_pk_fma_f32 v[8:9], v[0:1], 0.5, v[32:33] op_sel_hi:[1,0,1]
	v_mul_f32_e32 v1, v11, v11
	v_mul_f32_e32 v0, v9, v9
	v_fmac_f32_e32 v0, v8, v8
	v_fmac_f32_e32 v1, v10, v10
	v_add_f32_e32 v0, v0, v1
	v_add_f32_e32 v2, v12, v0
	ds_bpermute_b32 v3, v175, v2
	v_cvt_pk_bf16_f32 v0, v4, v5
	v_cvt_pk_bf16_f32 v1, v6, v7
	global_store_dwordx4 v[66:67], v[4:7], off offset:512
	global_store_dwordx2 v[16:17], v[0:1], off offset:256
	s_waitcnt lgkmcnt(0)
	v_add_f32_e32 v0, v2, v3
	ds_bpermute_b32 v1, v176, v0
	v_cvt_pk_bf16_f32 v2, v8, v9
	v_cvt_pk_bf16_f32 v3, v10, v11
	global_store_dwordx4 v[66:67], v[8:11], off offset:576
	global_store_dwordx2 v[16:17], v[2:3], off offset:288
	s_mov_b32 vcc_lo, 0x11111111
	s_mov_b32 vcc_hi, 0x11111111
	s_and_saveexec_b64 s[24:25], vcc
	s_cbranch_execz .LBB0_1516
	v_lshl_add_u64 v[2:3], v[64:65], 2, s[16:17]
	s_waitcnt lgkmcnt(0)
	v_add_f32_e32 v0, v0, v1
	global_atomic_add_f32 v[2:3], v0, off

.LBB0_1605:
	ds_read_b128 v[146:149], v152
	ds_read_b128 v[156:159], v152 offset:1024
	ds_read_b128 v[160:163], v152 offset:2048
	ds_read_b128 v[164:167], v152 offset:3072
	ds_read_b128 v[168:171], v153
	ds_read_b128 v[172:175], v153 offset:1024
	ds_read_b128 v[176:179], v153 offset:2048
	ds_read_b128 v[180:183], v153 offset:3072
	s_add_u32 s36, s34, 0xfffc0080
	s_addc_u32 s37, s35, -1
	s_cmp_eq_u32 s66, 12
	s_cselect_b32 s39, s27, s37
	s_cselect_b32 s38, s62, s36
	s_cselect_b32 s37, s25, s65
	s_cselect_b32 s36, s63, s64
	v_lshl_add_u64 v[188:189], s[34:35], 0, v[140:141]
	s_add_i32 m0, s46, 0xc000
	ds_read_b128 v[184:187], v154
	ds_read_b128 v[192:195], v154 offset:1024
	ds_read_b128 v[196:199], v154 offset:2048
	ds_read_b128 v[200:203], v154 offset:3072
	ds_read_b128 v[204:207], v154 offset:4096
	ds_read_b128 v[208:211], v154 offset:5120
	ds_read_b128 v[212:215], v154 offset:6144
	ds_read_b128 v[216:219], v154 offset:7168
	global_load_lds_dwordx4 v[188:189], off
	v_lshl_add_u64 v[188:189], s[34:35], 0, v[138:139]
	s_add_i32 m0, s46, 0xe000
	s_nop 0
	global_load_lds_dwordx4 v[188:189], off
	s_waitcnt vmcnt(8)
	s_waitcnt lgkmcnt(0)
	s_barrier
	s_setprio 1
	s_waitcnt lgkmcnt(0)
	v_mfma_f32_16x16x32_bf16 v[124:127], v[146:149], v[184:187], v[124:127]
	v_mfma_f32_16x16x32_bf16 v[120:123], v[160:163], v[184:187], v[120:123]
	v_mfma_f32_16x16x32_bf16 v[108:111], v[146:149], v[196:199], v[108:111]
	v_mfma_f32_16x16x32_bf16 v[104:107], v[160:163], v[196:199], v[104:107]
	v_mfma_f32_16x16x32_bf16 v[92:95], v[146:149], v[204:207], v[92:95]
	v_mfma_f32_16x16x32_bf16 v[88:91], v[160:163], v[204:207], v[88:91]
	v_mfma_f32_16x16x32_bf16 v[76:79], v[146:149], v[212:215], v[76:79]
	v_mfma_f32_16x16x32_bf16 v[72:75], v[160:163], v[212:215], v[72:75]
	v_mfma_f32_16x16x32_bf16 v[124:127], v[156:159], v[192:195], v[124:127]
	v_mfma_f32_16x16x32_bf16 v[120:123], v[164:167], v[192:195], v[120:123]
	v_mfma_f32_16x16x32_bf16 v[108:111], v[156:159], v[200:203], v[108:111]
	v_mfma_f32_16x16x32_bf16 v[104:107], v[164:167], v[200:203], v[104:107]
	v_mfma_f32_16x16x32_bf16 v[92:95], v[156:159], v[208:211], v[92:95]
	v_mfma_f32_16x16x32_bf16 v[88:91], v[164:167], v[208:211], v[88:91]
	v_mfma_f32_16x16x32_bf16 v[76:79], v[156:159], v[216:219], v[76:79]
	v_mfma_f32_16x16x32_bf16 v[72:75], v[164:167], v[216:219], v[72:75]
	s_setprio 0
	s_setprio 1
	v_mfma_f32_16x16x32_bf16 v[116:119], v[168:171], v[184:187], v[116:119]
	v_mfma_f32_16x16x32_bf16 v[112:115], v[176:179], v[184:187], v[112:115]
	v_mfma_f32_16x16x32_bf16 v[100:103], v[168:171], v[196:199], v[100:103]
	v_mfma_f32_16x16x32_bf16 v[96:99], v[176:179], v[196:199], v[96:99]
	v_mfma_f32_16x16x32_bf16 v[84:87], v[168:171], v[204:207], v[84:87]
	v_mfma_f32_16x16x32_bf16 v[80:83], v[176:179], v[204:207], v[80:83]
	v_mfma_f32_16x16x32_bf16 v[68:71], v[168:171], v[212:215], v[68:71]
	v_mfma_f32_16x16x32_bf16 v[64:67], v[176:179], v[212:215], v[64:67]
	v_mfma_f32_16x16x32_bf16 v[116:119], v[172:175], v[192:195], v[116:119]
	v_mfma_f32_16x16x32_bf16 v[112:115], v[180:183], v[192:195], v[112:115]
	v_mfma_f32_16x16x32_bf16 v[100:103], v[172:175], v[200:203], v[100:103]
	v_mfma_f32_16x16x32_bf16 v[96:99], v[180:183], v[200:203], v[96:99]
	v_mfma_f32_16x16x32_bf16 v[84:87], v[172:175], v[208:211], v[84:87]
	v_mfma_f32_16x16x32_bf16 v[80:83], v[180:183], v[208:211], v[80:83]
	v_mfma_f32_16x16x32_bf16 v[68:71], v[172:175], v[216:219], v[68:71]
	v_mfma_f32_16x16x32_bf16 v[64:67], v[180:183], v[216:219], v[64:67]
	s_setprio 0
	s_barrier
	s_add_i32 s67, s54, s43
	v_lshl_add_u64 v[188:189], s[36:37], 0, v[132:133]
	s_mov_b32 m0, s67
	ds_read_b128 v[184:187], v154 offset:16384
	ds_read_b128 v[192:195], v154 offset:17408
	ds_read_b128 v[196:199], v154 offset:18432
	ds_read_b128 v[200:203], v154 offset:19456
	ds_read_b128 v[204:207], v154 offset:20480
	ds_read_b128 v[208:211], v154 offset:21504
	ds_read_b128 v[212:215], v154 offset:22528
	ds_read_b128 v[216:219], v154 offset:23552
	global_load_lds_dwordx4 v[188:189], off
	s_add_i32 m0, s67, 0x2000
	s_add_u32 s68, s36, 0x40000
	v_lshl_add_u64 v[220:221], s[36:37], 0, v[128:129]
	s_addc_u32 s69, s37, 0
	s_add_i32 s67, s55, s43
	global_load_lds_dwordx4 v[220:221], off
	v_lshl_add_u64 v[222:223], s[68:69], 0, v[132:133]
	s_mov_b32 m0, s67
	v_lshl_add_u64 v[224:225], s[38:39], 0, v[130:131]
	global_load_lds_dwordx4 v[222:223], off
	v_lshl_add_u64 v[222:223], s[68:69], 0, v[128:129]
	s_add_i32 m0, s67, 0x2000
	s_nop 0
	global_load_lds_dwordx4 v[222:223], off
	v_lshl_add_u64 v[222:223], s[38:39], 0, v[134:135]
	s_mov_b32 m0, s46
	s_nop 0
	global_load_lds_dwordx4 v[222:223], off
	s_mov_b32 m0, s47
	s_nop 0
	global_load_lds_dwordx4 v[224:225], off
	s_waitcnt vmcnt(8)
	s_waitcnt lgkmcnt(0)
	s_barrier
	s_setprio 1
	s_waitcnt lgkmcnt(0)
	v_mfma_f32_16x16x32_bf16 v[60:63], v[146:149], v[184:187], v[60:63]
	v_mfma_f32_16x16x32_bf16 v[56:59], v[160:163], v[184:187], v[56:59]
	v_mfma_f32_16x16x32_bf16 v[44:47], v[146:149], v[196:199], v[44:47]
	v_mfma_f32_16x16x32_bf16 v[40:43], v[160:163], v[196:199], v[40:43]
	v_mfma_f32_16x16x32_bf16 v[28:31], v[146:149], v[204:207], v[28:31]
	v_mfma_f32_16x16x32_bf16 v[24:27], v[160:163], v[204:207], v[24:27]
	v_mfma_f32_16x16x32_bf16 v[12:15], v[146:149], v[212:215], v[12:15]
	v_mfma_f32_16x16x32_bf16 v[8:11], v[160:163], v[212:215], v[8:11]
	v_mfma_f32_16x16x32_bf16 v[60:63], v[156:159], v[192:195], v[60:63]
	v_mfma_f32_16x16x32_bf16 v[56:59], v[164:167], v[192:195], v[56:59]
	v_mfma_f32_16x16x32_bf16 v[44:47], v[156:159], v[200:203], v[44:47]
	v_mfma_f32_16x16x32_bf16 v[40:43], v[164:167], v[200:203], v[40:43]
	v_mfma_f32_16x16x32_bf16 v[28:31], v[156:159], v[208:211], v[28:31]
	v_mfma_f32_16x16x32_bf16 v[24:27], v[164:167], v[208:211], v[24:27]
	v_mfma_f32_16x16x32_bf16 v[12:15], v[156:159], v[216:219], v[12:15]
	v_mfma_f32_16x16x32_bf16 v[8:11], v[164:167], v[216:219], v[8:11]
	s_setprio 0
	s_setprio 1
	v_mfma_f32_16x16x32_bf16 v[52:55], v[168:171], v[184:187], v[52:55]
	v_mfma_f32_16x16x32_bf16 v[48:51], v[176:179], v[184:187], v[48:51]
	v_mfma_f32_16x16x32_bf16 v[36:39], v[168:171], v[196:199], v[36:39]
	v_mfma_f32_16x16x32_bf16 v[32:35], v[176:179], v[196:199], v[32:35]
	v_mfma_f32_16x16x32_bf16 v[20:23], v[168:171], v[204:207], v[20:23]
	v_mfma_f32_16x16x32_bf16 v[16:19], v[176:179], v[204:207], v[16:19]
	v_mfma_f32_16x16x32_bf16 v[4:7], v[168:171], v[212:215], v[4:7]
	v_mfma_f32_16x16x32_bf16 v[0:3], v[176:179], v[212:215], v[0:3]
	v_mfma_f32_16x16x32_bf16 v[52:55], v[172:175], v[192:195], v[52:55]
	v_mfma_f32_16x16x32_bf16 v[48:51], v[180:183], v[192:195], v[48:51]
	v_mfma_f32_16x16x32_bf16 v[36:39], v[172:175], v[200:203], v[36:39]
	v_mfma_f32_16x16x32_bf16 v[32:35], v[180:183], v[200:203], v[32:35]
	v_mfma_f32_16x16x32_bf16 v[20:23], v[172:175], v[208:211], v[20:23]
	v_mfma_f32_16x16x32_bf16 v[16:19], v[180:183], v[208:211], v[16:19]
	v_mfma_f32_16x16x32_bf16 v[4:7], v[172:175], v[216:219], v[4:7]
	v_mfma_f32_16x16x32_bf16 v[0:3], v[180:183], v[216:219], v[0:3]
	s_setprio 0
	s_barrier
	s_add_i32 s67, 0, 0x18000
	s_add_i32 s68, 0, 0x1c000
	v_add_u32_e32 v164, s67, v151
	v_add_u32_e32 v180, s68, v151
	ds_read_b128 v[146:149], v164
	ds_read_b128 v[156:159], v164 offset:1024
	ds_read_b128 v[160:163], v164 offset:2048
	ds_read_b128 v[164:167], v164 offset:3072
	ds_read_b128 v[168:171], v180
	ds_read_b128 v[172:175], v180 offset:1024
	ds_read_b128 v[176:179], v180 offset:2048
	ds_read_b128 v[180:183], v180 offset:3072
	s_add_u32 s38, s38, 0x40000
	s_addc_u32 s39, s39, 0
	s_mov_b32 m0, s48
	v_lshl_add_u64 v[226:227], s[38:39], 0, v[134:135]
	ds_read_b128 v[184:187], v154 offset:32768
	ds_read_b128 v[192:195], v154 offset:33792
	ds_read_b128 v[196:199], v154 offset:34816
	ds_read_b128 v[200:203], v154 offset:35840
	ds_read_b128 v[204:207], v154 offset:36864
	ds_read_b128 v[208:211], v154 offset:37888
	ds_read_b128 v[212:215], v154 offset:38912
	ds_read_b128 v[216:219], v154 offset:39936
	global_load_lds_dwordx4 v[226:227], off
	v_lshl_add_u64 v[226:227], s[38:39], 0, v[130:131]
	s_mov_b32 m0, s49
	s_nop 0
	global_load_lds_dwordx4 v[226:227], off
	s_waitcnt vmcnt(8)
	s_waitcnt lgkmcnt(0)
	s_barrier
	s_setprio 1
	s_waitcnt lgkmcnt(0)
	v_mfma_f32_16x16x32_bf16 v[124:127], v[146:149], v[184:187], v[124:127]
	v_mfma_f32_16x16x32_bf16 v[120:123], v[160:163], v[184:187], v[120:123]
	v_mfma_f32_16x16x32_bf16 v[108:111], v[146:149], v[196:199], v[108:111]
	v_mfma_f32_16x16x32_bf16 v[104:107], v[160:163], v[196:199], v[104:107]
	v_mfma_f32_16x16x32_bf16 v[92:95], v[146:149], v[204:207], v[92:95]
	v_mfma_f32_16x16x32_bf16 v[88:91], v[160:163], v[204:207], v[88:91]
	v_mfma_f32_16x16x32_bf16 v[76:79], v[146:149], v[212:215], v[76:79]
	v_mfma_f32_16x16x32_bf16 v[72:75], v[160:163], v[212:215], v[72:75]
	v_mfma_f32_16x16x32_bf16 v[124:127], v[156:159], v[192:195], v[124:127]
	v_mfma_f32_16x16x32_bf16 v[120:123], v[164:167], v[192:195], v[120:123]
	v_mfma_f32_16x16x32_bf16 v[108:111], v[156:159], v[200:203], v[108:111]
	v_mfma_f32_16x16x32_bf16 v[104:107], v[164:167], v[200:203], v[104:107]
	v_mfma_f32_16x16x32_bf16 v[92:95], v[156:159], v[208:211], v[92:95]
	v_mfma_f32_16x16x32_bf16 v[88:91], v[164:167], v[208:211], v[88:91]
	v_mfma_f32_16x16x32_bf16 v[76:79], v[156:159], v[216:219], v[76:79]
	v_mfma_f32_16x16x32_bf16 v[72:75], v[164:167], v[216:219], v[72:75]
	s_setprio 0
	s_setprio 1
	v_mfma_f32_16x16x32_bf16 v[116:119], v[168:171], v[184:187], v[116:119]
	v_mfma_f32_16x16x32_bf16 v[112:115], v[176:179], v[184:187], v[112:115]
	v_mfma_f32_16x16x32_bf16 v[100:103], v[168:171], v[196:199], v[100:103]
	v_mfma_f32_16x16x32_bf16 v[96:99], v[176:179], v[196:199], v[96:99]
	v_mfma_f32_16x16x32_bf16 v[84:87], v[168:171], v[204:207], v[84:87]
	v_mfma_f32_16x16x32_bf16 v[80:83], v[176:179], v[204:207], v[80:83]
	v_mfma_f32_16x16x32_bf16 v[68:71], v[168:171], v[212:215], v[68:71]
	v_mfma_f32_16x16x32_bf16 v[64:67], v[176:179], v[212:215], v[64:67]
	v_mfma_f32_16x16x32_bf16 v[116:119], v[172:175], v[192:195], v[116:119]
	v_mfma_f32_16x16x32_bf16 v[112:115], v[180:183], v[192:195], v[112:115]
	v_mfma_f32_16x16x32_bf16 v[100:103], v[172:175], v[200:203], v[100:103]
	v_mfma_f32_16x16x32_bf16 v[96:99], v[180:183], v[200:203], v[96:99]
	v_mfma_f32_16x16x32_bf16 v[84:87], v[172:175], v[208:211], v[84:87]
	v_mfma_f32_16x16x32_bf16 v[80:83], v[180:183], v[208:211], v[80:83]
	v_mfma_f32_16x16x32_bf16 v[68:71], v[172:175], v[216:219], v[68:71]
	v_mfma_f32_16x16x32_bf16 v[64:67], v[180:183], v[216:219], v[64:67]
	s_setprio 0
	s_barrier
	s_add_i32 s38, s67, s43
	v_lshl_add_u64 v[188:189], v[188:189], 0, s[14:15]
	s_mov_b32 m0, s38
	ds_read_b128 v[184:187], v154 offset:49152
	ds_read_b128 v[192:195], v154 offset:50176
	ds_read_b128 v[196:199], v154 offset:51200
	ds_read_b128 v[200:203], v154 offset:52224
	ds_read_b128 v[204:207], v154 offset:53248
	ds_read_b128 v[208:211], v154 offset:54272
	ds_read_b128 v[212:215], v154 offset:55296
	ds_read_b128 v[216:219], v154 offset:56320
	global_load_lds_dwordx4 v[188:189], off
	s_add_i32 m0, s38, 0x2000
	s_add_u32 s36, s36, 0x40080
	v_lshl_add_u64 v[188:189], v[220:221], 0, s[14:15]
	s_addc_u32 s37, s37, 0
	s_add_i32 s38, s68, s43
	global_load_lds_dwordx4 v[188:189], off
	v_lshl_add_u64 v[188:189], s[36:37], 0, v[132:133]
	s_mov_b32 m0, s38
	s_nop 0
	global_load_lds_dwordx4 v[188:189], off
	v_lshl_add_u64 v[188:189], s[36:37], 0, v[128:129]
	s_add_i32 m0, s38, 0x2000
	s_nop 0
	global_load_lds_dwordx4 v[188:189], off
	v_lshl_add_u64 v[188:189], v[222:223], 0, s[14:15]
	s_mov_b32 m0, s50
	s_nop 0
	global_load_lds_dwordx4 v[188:189], off
	v_lshl_add_u64 v[188:189], v[224:225], 0, s[14:15]
	s_mov_b32 m0, s51
	s_nop 0
	global_load_lds_dwordx4 v[188:189], off
	s_waitcnt vmcnt(8)
	s_waitcnt lgkmcnt(0)
	s_barrier
	s_setprio 1
	s_waitcnt lgkmcnt(0)
	v_mfma_f32_16x16x32_bf16 v[60:63], v[146:149], v[184:187], v[60:63]
	v_mfma_f32_16x16x32_bf16 v[56:59], v[160:163], v[184:187], v[56:59]
	v_mfma_f32_16x16x32_bf16 v[44:47], v[146:149], v[196:199], v[44:47]
	v_mfma_f32_16x16x32_bf16 v[40:43], v[160:163], v[196:199], v[40:43]
	v_mfma_f32_16x16x32_bf16 v[28:31], v[146:149], v[204:207], v[28:31]
	v_mfma_f32_16x16x32_bf16 v[24:27], v[160:163], v[204:207], v[24:27]
	v_mfma_f32_16x16x32_bf16 v[12:15], v[146:149], v[212:215], v[12:15]
	v_mfma_f32_16x16x32_bf16 v[8:11], v[160:163], v[212:215], v[8:11]
	v_mfma_f32_16x16x32_bf16 v[60:63], v[156:159], v[192:195], v[60:63]
	v_mfma_f32_16x16x32_bf16 v[56:59], v[164:167], v[192:195], v[56:59]
	v_mfma_f32_16x16x32_bf16 v[44:47], v[156:159], v[200:203], v[44:47]
	v_mfma_f32_16x16x32_bf16 v[40:43], v[164:167], v[200:203], v[40:43]
	v_mfma_f32_16x16x32_bf16 v[28:31], v[156:159], v[208:211], v[28:31]
	v_mfma_f32_16x16x32_bf16 v[24:27], v[164:167], v[208:211], v[24:27]
	v_mfma_f32_16x16x32_bf16 v[12:15], v[156:159], v[216:219], v[12:15]
	v_mfma_f32_16x16x32_bf16 v[8:11], v[164:167], v[216:219], v[8:11]
	s_setprio 0
	s_setprio 1
	v_mfma_f32_16x16x32_bf16 v[52:55], v[168:171], v[184:187], v[52:55]
	v_mfma_f32_16x16x32_bf16 v[48:51], v[176:179], v[184:187], v[48:51]
	v_mfma_f32_16x16x32_bf16 v[36:39], v[168:171], v[196:199], v[36:39]
	v_mfma_f32_16x16x32_bf16 v[32:35], v[176:179], v[196:199], v[32:35]
	v_mfma_f32_16x16x32_bf16 v[20:23], v[168:171], v[204:207], v[20:23]
	v_mfma_f32_16x16x32_bf16 v[16:19], v[176:179], v[204:207], v[16:19]
	v_mfma_f32_16x16x32_bf16 v[4:7], v[168:171], v[212:215], v[4:7]
	v_mfma_f32_16x16x32_bf16 v[0:3], v[176:179], v[212:215], v[0:3]
	v_mfma_f32_16x16x32_bf16 v[52:55], v[172:175], v[192:195], v[52:55]
	v_mfma_f32_16x16x32_bf16 v[48:51], v[180:183], v[192:195], v[48:51]
	v_mfma_f32_16x16x32_bf16 v[36:39], v[172:175], v[200:203], v[36:39]
	v_mfma_f32_16x16x32_bf16 v[32:35], v[180:183], v[200:203], v[32:35]
	v_mfma_f32_16x16x32_bf16 v[20:23], v[172:175], v[208:211], v[20:23]
	v_mfma_f32_16x16x32_bf16 v[16:19], v[180:183], v[208:211], v[16:19]
	v_mfma_f32_16x16x32_bf16 v[4:7], v[172:175], v[216:219], v[4:7]
	v_mfma_f32_16x16x32_bf16 v[0:3], v[180:183], v[216:219], v[0:3]
	s_setprio 0
	s_barrier
	s_add_i32 s66, s66, 2
	s_add_u32 s64, s64, 0x100
	s_addc_u32 s65, s65, 0
	s_add_u32 s34, s34, 0x100
	s_addc_u32 s35, s35, 0
	s_cmp_gt_u32 s66, 13
	s_cbranch_scc0 .LBB0_1605
	v_lshl_add_u32 v210, s4, 8, v150
	v_ashrrev_i32_e32 v211, 31, v210
	v_lshl_add_u64 v[208:209], v[210:211], 2, s[12:13]
	global_load_dword v200, v[208:209], off
	global_load_dword v201, v[208:209], off offset:64
	global_load_dword v202, v[208:209], off offset:128
	global_load_dword v203, v[208:209], off offset:192
	global_load_dword v204, v[208:209], off offset:512
	global_load_dword v205, v[208:209], off offset:576
	global_load_dword v206, v[208:209], off offset:640
	global_load_dword v207, v[208:209], off offset:704
	s_and_b64 vcc, exec, s[16:17]
	s_cbranch_vccz .LBB0_1608
	s_barrier
.LBB0_1608:
	v_lshl_add_u32 v156, s4, 8, v150
	v_ashrrev_i32_e32 v157, 31, v156
	v_lshl_add_u64 v[146:147], v[156:157], 2, s[12:13]
	v_lshlrev_b64 v[148:149], 11, v[156:157]
	s_lshl_b32 s4, s5, 8
	s_ashr_i32 s5, s4, 31
	s_lshl_b64 s[4:5], s[4:5], 1
	v_lshl_add_u64 v[148:149], s[10:11], 0, v[148:149]
	v_lshl_add_u64 v[148:149], v[148:149], 0, s[4:5]
	v_or_b32_e32 v158, 16, v156
	v_lshl_add_u64 v[148:149], v[148:149], 0, s[0:1]
	v_ashrrev_i32_e32 v159, 31, v158
	v_lshl_add_u64 v[148:149], v[148:149], 0, v[136:137]
	v_lshl_add_u64 v[160:161], v[158:159], 2, s[12:13]
	s_waitcnt vmcnt(0) lgkmcnt(0)
	v_fmamk_f32 v157, v200, 0x3a800000, v155
	v_mul_f32_e32 v162, 0x4b800000, v157
	v_cmp_gt_f32_e32 vcc, s56, v157
	s_nop 1
	v_cndmask_b32_e32 v157, v157, v162, vcc
	v_rsq_f32_e32 v157, v157
	s_nop 0
	v_mul_f32_e32 v162, 0x45800000, v157
	v_cndmask_b32_e32 v162, v157, v162, vcc
	v_pk_mul_f32 v[126:127], v[126:127], v[162:163] op_sel_hi:[1,0]
	v_pk_mul_f32 v[124:125], v[124:125], v[162:163] op_sel_hi:[1,0]
	v_pk_mul_f32 v[122:123], v[122:123], v[162:163] op_sel_hi:[1,0]
	v_pk_mul_f32 v[120:121], v[120:121], v[162:163] op_sel_hi:[1,0]
	v_pk_mul_f32 v[118:119], v[118:119], v[162:163] op_sel_hi:[1,0]
	v_pk_mul_f32 v[116:117], v[116:117], v[162:163] op_sel_hi:[1,0]
	v_pk_mul_f32 v[164:165], v[114:115], v[162:163] op_sel_hi:[1,0]
	v_pk_mul_f32 v[162:163], v[112:113], v[162:163] op_sel_hi:[1,0]
	v_cvt_pk_bf16_f32 v112, v124, v125
	v_cvt_pk_bf16_f32 v113, v126, v127
	v_cvt_pk_bf16_f32 v114, v120, v121
	v_cvt_pk_bf16_f32 v115, v122, v123
	v_cvt_pk_bf16_f32 v116, v116, v117
	v_cvt_pk_bf16_f32 v117, v118, v119
	v_cvt_pk_bf16_f32 v118, v162, v163
	v_cvt_pk_bf16_f32 v119, v164, v165
	global_store_dwordx4 v[148:149], v[112:115], off
	global_store_dwordx4 v[148:149], v[116:119], off offset:256
	s_nop 1
	v_lshlrev_b64 v[114:115], 11, v[158:159]
	v_lshl_add_u64 v[114:115], s[10:11], 0, v[114:115]
	v_lshl_add_u64 v[114:115], v[114:115], 0, s[4:5]
	v_or_b32_e32 v112, 32, v156
	v_lshl_add_u64 v[114:115], v[114:115], 0, s[0:1]
	v_ashrrev_i32_e32 v113, 31, v112
	v_lshl_add_u64 v[114:115], v[114:115], 0, v[136:137]
	v_lshl_add_u64 v[116:117], v[112:113], 2, s[12:13]
	v_fmamk_f32 v118, v201, 0x3a800000, v155
	v_mul_f32_e32 v119, 0x4b800000, v118
	v_cmp_gt_f32_e32 vcc, s56, v118
	s_nop 1
	v_cndmask_b32_e32 v118, v118, v119, vcc
	v_rsq_f32_e32 v118, v118
	s_nop 0
	v_mul_f32_e32 v119, 0x45800000, v118
	v_cndmask_b32_e32 v118, v118, v119, vcc
	v_pk_mul_f32 v[110:111], v[110:111], v[118:119] op_sel_hi:[1,0]
	v_pk_mul_f32 v[108:109], v[108:109], v[118:119] op_sel_hi:[1,0]
	v_pk_mul_f32 v[106:107], v[106:107], v[118:119] op_sel_hi:[1,0]
	v_pk_mul_f32 v[104:105], v[104:105], v[118:119] op_sel_hi:[1,0]
	v_pk_mul_f32 v[102:103], v[102:103], v[118:119] op_sel_hi:[1,0]
	v_pk_mul_f32 v[100:101], v[100:101], v[118:119] op_sel_hi:[1,0]
	v_pk_mul_f32 v[120:121], v[98:99], v[118:119] op_sel_hi:[1,0]
	v_pk_mul_f32 v[118:119], v[96:97], v[118:119] op_sel_hi:[1,0]
	v_cvt_pk_bf16_f32 v96, v108, v109
	v_cvt_pk_bf16_f32 v97, v110, v111
	v_cvt_pk_bf16_f32 v98, v104, v105
	v_cvt_pk_bf16_f32 v99, v106, v107
	v_cvt_pk_bf16_f32 v100, v100, v101
	v_cvt_pk_bf16_f32 v101, v102, v103
	v_cvt_pk_bf16_f32 v102, v118, v119
	v_cvt_pk_bf16_f32 v103, v120, v121
	global_store_dwordx4 v[114:115], v[96:99], off
	global_store_dwordx4 v[114:115], v[100:103], off offset:256
	s_nop 1
	v_lshlrev_b64 v[98:99], 11, v[112:113]
	v_lshl_add_u64 v[98:99], s[10:11], 0, v[98:99]
	v_lshl_add_u64 v[98:99], v[98:99], 0, s[4:5]
	v_or_b32_e32 v96, 48, v156
	v_lshl_add_u64 v[98:99], v[98:99], 0, s[0:1]
	v_ashrrev_i32_e32 v97, 31, v96
	v_lshl_add_u64 v[98:99], v[98:99], 0, v[136:137]
	v_lshl_add_u64 v[100:101], v[96:97], 2, s[12:13]
	v_fmamk_f32 v102, v202, 0x3a800000, v155
	v_mul_f32_e32 v103, 0x4b800000, v102
	v_cmp_gt_f32_e32 vcc, s56, v102
	s_nop 1
	v_cndmask_b32_e32 v102, v102, v103, vcc
	v_rsq_f32_e32 v102, v102
	s_nop 0
	v_mul_f32_e32 v103, 0x45800000, v102
	v_cndmask_b32_e32 v102, v102, v103, vcc
	v_pk_mul_f32 v[94:95], v[94:95], v[102:103] op_sel_hi:[1,0]
	v_pk_mul_f32 v[92:93], v[92:93], v[102:103] op_sel_hi:[1,0]
	v_pk_mul_f32 v[90:91], v[90:91], v[102:103] op_sel_hi:[1,0]
	v_pk_mul_f32 v[88:89], v[88:89], v[102:103] op_sel_hi:[1,0]
	v_pk_mul_f32 v[86:87], v[86:87], v[102:103] op_sel_hi:[1,0]
	v_pk_mul_f32 v[84:85], v[84:85], v[102:103] op_sel_hi:[1,0]
	v_pk_mul_f32 v[104:105], v[82:83], v[102:103] op_sel_hi:[1,0]
	v_pk_mul_f32 v[102:103], v[80:81], v[102:103] op_sel_hi:[1,0]
	v_cvt_pk_bf16_f32 v80, v92, v93
	v_cvt_pk_bf16_f32 v81, v94, v95
	v_cvt_pk_bf16_f32 v82, v88, v89
	v_cvt_pk_bf16_f32 v83, v90, v91
	v_cvt_pk_bf16_f32 v84, v84, v85
	v_cvt_pk_bf16_f32 v85, v86, v87
	v_cvt_pk_bf16_f32 v86, v102, v103
	v_cvt_pk_bf16_f32 v87, v104, v105
	global_store_dwordx4 v[98:99], v[80:83], off
	global_store_dwordx4 v[98:99], v[84:87], off offset:256
	s_nop 1
	v_lshlrev_b64 v[80:81], 11, v[96:97]
	v_lshl_add_u64 v[80:81], s[10:11], 0, v[80:81]
	v_lshl_add_u64 v[80:81], v[80:81], 0, s[4:5]
	v_lshl_add_u64 v[80:81], v[80:81], 0, s[0:1]
	v_lshl_add_u64 v[80:81], v[80:81], 0, v[136:137]
	v_fmamk_f32 v82, v203, 0x3a800000, v155
	v_mul_f32_e32 v83, 0x4b800000, v82
	v_cmp_gt_f32_e32 vcc, s56, v82
	s_nop 1
	v_cndmask_b32_e32 v82, v82, v83, vcc
	v_rsq_f32_e32 v82, v82
	s_nop 0
	v_mul_f32_e32 v83, 0x45800000, v82
	v_cndmask_b32_e32 v82, v82, v83, vcc
	v_pk_mul_f32 v[78:79], v[78:79], v[82:83] op_sel_hi:[1,0]
	v_pk_mul_f32 v[76:77], v[76:77], v[82:83] op_sel_hi:[1,0]
	v_pk_mul_f32 v[74:75], v[74:75], v[82:83] op_sel_hi:[1,0]
	v_pk_mul_f32 v[72:73], v[72:73], v[82:83] op_sel_hi:[1,0]
	v_pk_mul_f32 v[70:71], v[70:71], v[82:83] op_sel_hi:[1,0]
	v_pk_mul_f32 v[68:69], v[68:69], v[82:83] op_sel_hi:[1,0]
	v_pk_mul_f32 v[84:85], v[66:67], v[82:83] op_sel_hi:[1,0]
	v_pk_mul_f32 v[82:83], v[64:65], v[82:83] op_sel_hi:[1,0]
	v_cvt_pk_bf16_f32 v64, v76, v77
	v_cvt_pk_bf16_f32 v65, v78, v79
	v_cvt_pk_bf16_f32 v66, v72, v73
	v_cvt_pk_bf16_f32 v67, v74, v75
	v_cvt_pk_bf16_f32 v68, v68, v69
	v_cvt_pk_bf16_f32 v69, v70, v71
	v_cvt_pk_bf16_f32 v70, v82, v83
	v_cvt_pk_bf16_f32 v71, v84, v85
	global_store_dwordx4 v[80:81], v[64:67], off
	global_store_dwordx4 v[80:81], v[68:71], off offset:256
	s_nop 1
	v_lshl_add_u64 v[64:65], v[148:149], 0, s[6:7]
	v_fmamk_f32 v66, v204, 0x3a800000, v155
	v_mul_f32_e32 v67, 0x4b800000, v66
	v_cmp_gt_f32_e32 vcc, s56, v66
	s_nop 1
	v_cndmask_b32_e32 v66, v66, v67, vcc
	v_rsq_f32_e32 v68, v66
	v_add_co_u32_e64 v66, s[4:5], s57, v148
	v_mul_f32_e32 v69, 0x45800000, v68
	v_cndmask_b32_e32 v68, v68, v69, vcc
	v_pk_mul_f32 v[62:63], v[62:63], v[68:69] op_sel_hi:[1,0]
	v_pk_mul_f32 v[60:61], v[60:61], v[68:69] op_sel_hi:[1,0]
	v_pk_mul_f32 v[58:59], v[58:59], v[68:69] op_sel_hi:[1,0]
	v_pk_mul_f32 v[56:57], v[56:57], v[68:69] op_sel_hi:[1,0]
	v_addc_co_u32_e64 v67, s[4:5], 0, v149, s[4:5]
	v_pk_mul_f32 v[54:55], v[54:55], v[68:69] op_sel_hi:[1,0]
	v_pk_mul_f32 v[52:53], v[52:53], v[68:69] op_sel_hi:[1,0]
	v_pk_mul_f32 v[70:71], v[50:51], v[68:69] op_sel_hi:[1,0]
	v_pk_mul_f32 v[68:69], v[48:49], v[68:69] op_sel_hi:[1,0]
	v_cvt_pk_bf16_f32 v48, v60, v61
	v_cvt_pk_bf16_f32 v49, v62, v63
	v_cvt_pk_bf16_f32 v50, v56, v57
	v_cvt_pk_bf16_f32 v51, v58, v59
	v_cvt_pk_bf16_f32 v52, v52, v53
	v_cvt_pk_bf16_f32 v53, v54, v55
	v_cvt_pk_bf16_f32 v54, v68, v69
	v_cvt_pk_bf16_f32 v55, v70, v71
	global_store_dwordx4 v[66:67], v[48:51], off
	global_store_dwordx4 v[64:65], v[52:55], off offset:256
	s_nop 1
	v_lshl_add_u64 v[48:49], v[148:149], 0, s[18:19]
	v_fmamk_f32 v50, v205, 0x3a800000, v155
	v_mul_f32_e32 v51, 0x4b800000, v50
	v_cmp_gt_f32_e32 vcc, s56, v50
	s_nop 1
	v_cndmask_b32_e32 v50, v50, v51, vcc
	v_rsq_f32_e32 v52, v50
	v_add_co_u32_e64 v50, s[4:5], s58, v148
	v_mul_f32_e32 v53, 0x45800000, v52
	v_cndmask_b32_e32 v52, v52, v53, vcc
	v_pk_mul_f32 v[46:47], v[46:47], v[52:53] op_sel_hi:[1,0]
	v_pk_mul_f32 v[44:45], v[44:45], v[52:53] op_sel_hi:[1,0]
	v_pk_mul_f32 v[42:43], v[42:43], v[52:53] op_sel_hi:[1,0]
	v_pk_mul_f32 v[40:41], v[40:41], v[52:53] op_sel_hi:[1,0]
	v_addc_co_u32_e64 v51, s[4:5], 0, v149, s[4:5]
	v_pk_mul_f32 v[38:39], v[38:39], v[52:53] op_sel_hi:[1,0]
	v_pk_mul_f32 v[36:37], v[36:37], v[52:53] op_sel_hi:[1,0]
	v_pk_mul_f32 v[54:55], v[34:35], v[52:53] op_sel_hi:[1,0]
	v_pk_mul_f32 v[52:53], v[32:33], v[52:53] op_sel_hi:[1,0]
	v_cvt_pk_bf16_f32 v32, v44, v45
	v_cvt_pk_bf16_f32 v33, v46, v47
	v_cvt_pk_bf16_f32 v34, v40, v41
	v_cvt_pk_bf16_f32 v35, v42, v43
	v_cvt_pk_bf16_f32 v36, v36, v37
	v_cvt_pk_bf16_f32 v37, v38, v39
	v_cvt_pk_bf16_f32 v38, v52, v53
	v_cvt_pk_bf16_f32 v39, v54, v55
	global_store_dwordx4 v[50:51], v[32:35], off
	global_store_dwordx4 v[48:49], v[36:39], off offset:256
	s_nop 1
	v_lshl_add_u64 v[32:33], v[148:149], 0, s[20:21]
	v_fmamk_f32 v34, v206, 0x3a800000, v155
	v_mul_f32_e32 v35, 0x4b800000, v34
	v_cmp_gt_f32_e32 vcc, s56, v34
	s_nop 1
	v_cndmask_b32_e32 v34, v34, v35, vcc
	v_rsq_f32_e32 v36, v34
	v_add_co_u32_e64 v34, s[4:5], s59, v148
	v_mul_f32_e32 v37, 0x45800000, v36
	v_cndmask_b32_e32 v36, v36, v37, vcc
	v_pk_mul_f32 v[30:31], v[30:31], v[36:37] op_sel_hi:[1,0]
	v_pk_mul_f32 v[28:29], v[28:29], v[36:37] op_sel_hi:[1,0]
	v_pk_mul_f32 v[26:27], v[26:27], v[36:37] op_sel_hi:[1,0]
	v_pk_mul_f32 v[24:25], v[24:25], v[36:37] op_sel_hi:[1,0]
	v_addc_co_u32_e64 v35, s[4:5], 0, v149, s[4:5]
	v_pk_mul_f32 v[22:23], v[22:23], v[36:37] op_sel_hi:[1,0]
	v_pk_mul_f32 v[20:21], v[20:21], v[36:37] op_sel_hi:[1,0]
	v_pk_mul_f32 v[38:39], v[18:19], v[36:37] op_sel_hi:[1,0]
	v_pk_mul_f32 v[36:37], v[16:17], v[36:37] op_sel_hi:[1,0]
	v_cvt_pk_bf16_f32 v16, v28, v29
	v_cvt_pk_bf16_f32 v17, v30, v31
	v_cvt_pk_bf16_f32 v18, v24, v25
	v_cvt_pk_bf16_f32 v19, v26, v27
	v_cvt_pk_bf16_f32 v20, v20, v21
	v_cvt_pk_bf16_f32 v21, v22, v23
	v_cvt_pk_bf16_f32 v22, v36, v37
	v_cvt_pk_bf16_f32 v23, v38, v39
	global_store_dwordx4 v[34:35], v[16:19], off
	global_store_dwordx4 v[32:33], v[20:23], off offset:256
	s_nop 1
	s_andn2_b64 vcc, exec, s[2:3]
	v_lshl_add_u64 v[16:17], v[148:149], 0, s[22:23]
	v_fmamk_f32 v18, v207, 0x3a800000, v155
	v_mul_f32_e32 v19, 0x4b800000, v18
	v_cmp_gt_f32_e64 s[2:3], s56, v18
	s_nop 1
	v_cndmask_b32_e64 v18, v18, v19, s[2:3]
	v_rsq_f32_e32 v20, v18
	v_add_co_u32_e64 v18, s[4:5], s60, v148
	v_mul_f32_e32 v21, 0x45800000, v20
	v_cndmask_b32_e64 v20, v20, v21, s[2:3]
	v_pk_mul_f32 v[14:15], v[14:15], v[20:21] op_sel_hi:[1,0]
	v_pk_mul_f32 v[12:13], v[12:13], v[20:21] op_sel_hi:[1,0]
	v_pk_mul_f32 v[10:11], v[10:11], v[20:21] op_sel_hi:[1,0]
	v_pk_mul_f32 v[8:9], v[8:9], v[20:21] op_sel_hi:[1,0]
	v_addc_co_u32_e64 v19, s[4:5], 0, v149, s[4:5]
	v_pk_mul_f32 v[6:7], v[6:7], v[20:21] op_sel_hi:[1,0]
	v_pk_mul_f32 v[4:5], v[4:5], v[20:21] op_sel_hi:[1,0]
	v_pk_mul_f32 v[22:23], v[2:3], v[20:21] op_sel_hi:[1,0]
	v_pk_mul_f32 v[20:21], v[0:1], v[20:21] op_sel_hi:[1,0]
	v_cvt_pk_bf16_f32 v0, v12, v13
	v_cvt_pk_bf16_f32 v1, v14, v15
	v_cvt_pk_bf16_f32 v2, v8, v9
	v_cvt_pk_bf16_f32 v3, v10, v11
	s_mov_b64 s[2:3], -1
	v_cvt_pk_bf16_f32 v4, v4, v5
	v_cvt_pk_bf16_f32 v5, v6, v7
	v_cvt_pk_bf16_f32 v6, v20, v21
	v_cvt_pk_bf16_f32 v7, v22, v23
	global_store_dwordx4 v[18:19], v[0:3], off
	global_store_dwordx4 v[16:17], v[4:7], off offset:256
	s_cbranch_vccnz .LBB0_1601
	s_andn2_b64 vcc, exec, s[8:9]
	s_cbranch_vccnz .LBB0_1600
	s_barrier
	s_branch .LBB0_1600

.LBB0_1813:
	v_mbcnt_lo_u32_b32 v235, -1, 0
	v_mbcnt_hi_u32_b32 v235, -1, v235
	v_lshrrev_b32_e32 v236, 2, v235
	v_and_b32_e32 v237, 3, v235
	v_lshl_add_u32 v232, v237, 4, v236
	v_lshlrev_b32_e32 v232, 2, v232
	v_and_b32_e32 v233, -16, v168
	v_or_b32_e32 v233, v233, v236
	v_lshlrev_b32_e32 v237, 2, v237
	v_and_b32_e32 v234, -13, v170
	v_or_b32_e32 v234, v234, v237
	ds_bpermute_b32 v127, v232, v127
	ds_bpermute_b32 v126, v232, v126
	ds_bpermute_b32 v125, v232, v125
	ds_bpermute_b32 v124, v232, v124
	ds_bpermute_b32 v123, v232, v123
	ds_bpermute_b32 v122, v232, v122
	ds_bpermute_b32 v121, v232, v121
	ds_bpermute_b32 v120, v232, v120
	ds_bpermute_b32 v119, v232, v119
	ds_bpermute_b32 v118, v232, v118
	ds_bpermute_b32 v117, v232, v117
	ds_bpermute_b32 v116, v232, v116
	ds_bpermute_b32 v115, v232, v115
	ds_bpermute_b32 v114, v232, v114
	ds_bpermute_b32 v113, v232, v113
	ds_bpermute_b32 v112, v232, v112
	ds_bpermute_b32 v111, v232, v111
	ds_bpermute_b32 v110, v232, v110
	ds_bpermute_b32 v109, v232, v109
	ds_bpermute_b32 v108, v232, v108
	ds_bpermute_b32 v107, v232, v107
	ds_bpermute_b32 v106, v232, v106
	ds_bpermute_b32 v105, v232, v105
	ds_bpermute_b32 v104, v232, v104
	ds_bpermute_b32 v103, v232, v103
	ds_bpermute_b32 v102, v232, v102
	ds_bpermute_b32 v101, v232, v101
	ds_bpermute_b32 v100, v232, v100
	ds_bpermute_b32 v99, v232, v99
	ds_bpermute_b32 v98, v232, v98
	ds_bpermute_b32 v97, v232, v97
	ds_bpermute_b32 v96, v232, v96
	ds_bpermute_b32 v95, v232, v95
	ds_bpermute_b32 v94, v232, v94
	ds_bpermute_b32 v93, v232, v93
	ds_bpermute_b32 v92, v232, v92
	ds_bpermute_b32 v91, v232, v91
	ds_bpermute_b32 v90, v232, v90
	ds_bpermute_b32 v89, v232, v89
	ds_bpermute_b32 v88, v232, v88
	ds_bpermute_b32 v87, v232, v87
	ds_bpermute_b32 v86, v232, v86
	ds_bpermute_b32 v85, v232, v85
	ds_bpermute_b32 v84, v232, v84
	ds_bpermute_b32 v83, v232, v83
	ds_bpermute_b32 v82, v232, v82
	ds_bpermute_b32 v81, v232, v81
	ds_bpermute_b32 v80, v232, v80
	ds_bpermute_b32 v79, v232, v79
	ds_bpermute_b32 v78, v232, v78
	ds_bpermute_b32 v77, v232, v77
	ds_bpermute_b32 v76, v232, v76
	ds_bpermute_b32 v75, v232, v75
	ds_bpermute_b32 v74, v232, v74
	ds_bpermute_b32 v73, v232, v73
	ds_bpermute_b32 v72, v232, v72
	ds_bpermute_b32 v71, v232, v71
	ds_bpermute_b32 v70, v232, v70
	ds_bpermute_b32 v69, v232, v69
	ds_bpermute_b32 v68, v232, v68
	ds_bpermute_b32 v67, v232, v67
	ds_bpermute_b32 v66, v232, v66
	ds_bpermute_b32 v65, v232, v65
	ds_bpermute_b32 v64, v232, v64
	ds_bpermute_b32 v63, v232, v63
	ds_bpermute_b32 v62, v232, v62
	ds_bpermute_b32 v61, v232, v61
	ds_bpermute_b32 v60, v232, v60
	ds_bpermute_b32 v59, v232, v59
	ds_bpermute_b32 v58, v232, v58
	ds_bpermute_b32 v57, v232, v57
	ds_bpermute_b32 v56, v232, v56
	ds_bpermute_b32 v55, v232, v55
	ds_bpermute_b32 v54, v232, v54
	ds_bpermute_b32 v53, v232, v53
	ds_bpermute_b32 v52, v232, v52
	ds_bpermute_b32 v51, v232, v51
	ds_bpermute_b32 v50, v232, v50
	ds_bpermute_b32 v49, v232, v49
	ds_bpermute_b32 v48, v232, v48
	ds_bpermute_b32 v47, v232, v47
	ds_bpermute_b32 v46, v232, v46
	ds_bpermute_b32 v45, v232, v45
	ds_bpermute_b32 v44, v232, v44
	ds_bpermute_b32 v43, v232, v43
	ds_bpermute_b32 v42, v232, v42
	ds_bpermute_b32 v41, v232, v41
	ds_bpermute_b32 v40, v232, v40
	ds_bpermute_b32 v39, v232, v39
	ds_bpermute_b32 v38, v232, v38
	ds_bpermute_b32 v37, v232, v37
	ds_bpermute_b32 v36, v232, v36
	ds_bpermute_b32 v35, v232, v35
	ds_bpermute_b32 v34, v232, v34
	ds_bpermute_b32 v33, v232, v33
	ds_bpermute_b32 v32, v232, v32
	ds_bpermute_b32 v31, v232, v31
	ds_bpermute_b32 v30, v232, v30
	ds_bpermute_b32 v29, v232, v29
	ds_bpermute_b32 v28, v232, v28
	ds_bpermute_b32 v27, v232, v27
	ds_bpermute_b32 v26, v232, v26
	ds_bpermute_b32 v25, v232, v25
	ds_bpermute_b32 v24, v232, v24
	ds_bpermute_b32 v23, v232, v23
	ds_bpermute_b32 v22, v232, v22
	ds_bpermute_b32 v21, v232, v21
	ds_bpermute_b32 v20, v232, v20
	ds_bpermute_b32 v19, v232, v19
	ds_bpermute_b32 v18, v232, v18
	ds_bpermute_b32 v17, v232, v17
	ds_bpermute_b32 v16, v232, v16
	ds_bpermute_b32 v15, v232, v15
	ds_bpermute_b32 v14, v232, v14
	ds_bpermute_b32 v13, v232, v13
	ds_bpermute_b32 v12, v232, v12
	ds_bpermute_b32 v11, v232, v11
	ds_bpermute_b32 v10, v232, v10
	ds_bpermute_b32 v9, v232, v9
	ds_bpermute_b32 v8, v232, v8
	ds_bpermute_b32 v7, v232, v7
	ds_bpermute_b32 v6, v232, v6
	ds_bpermute_b32 v5, v232, v5
	ds_bpermute_b32 v4, v232, v4
	ds_bpermute_b32 v3, v232, v3
	ds_bpermute_b32 v2, v232, v2
	ds_bpermute_b32 v1, v232, v1
	ds_bpermute_b32 v0, v232, v0
	s_waitcnt lgkmcnt(0)
	v_lshl_add_u32 v158, s24, 8, v233
	v_lshl_or_b32 v156, s26, 8, v234
	v_ashrrev_i32_e32 v159, 31, v158
	v_lshlrev_b64 v[128:129], 12, v[158:159]
	v_ashrrev_i32_e32 v157, 31, v156
	v_lshl_add_u64 v[128:129], s[0:1], 0, v[128:129]
	v_lshlrev_b64 v[130:131], 2, v[156:157]
	v_lshl_add_u64 v[188:189], v[128:129], 0, v[130:131]
	global_load_dwordx4 v[164:167], v[188:189], off
	global_load_dwordx4 v[176:179], v[188:189], off offset:64
	global_load_dwordx4 v[180:183], v[188:189], off offset:512
	global_load_dwordx4 v[184:187], v[188:189], off offset:576
	v_or_b32_e32 v160, 16, v158
	v_ashrrev_i32_e32 v161, 31, v160
	v_lshlrev_b64 v[128:129], 12, v[160:161]
	v_lshl_add_u64 v[128:129], s[0:1], 0, v[128:129]
	v_lshl_add_u64 v[162:163], v[128:129], 0, v[130:131]
	global_load_dwordx4 v[140:143], v[162:163], off
	global_load_dwordx4 v[136:139], v[162:163], off offset:64
	global_load_dwordx4 v[132:135], v[162:163], off offset:512
	global_load_dwordx4 v[128:131], v[162:163], off offset:576
	v_lshlrev_b64 v[192:193], 11, v[158:159]
	v_lshl_add_u64 v[192:193], s[8:9], 0, v[192:193]
	v_and_b32_e32 v191, 64, v174
	v_lshl_add_u64 v[192:193], v[156:157], 1, v[192:193]
	v_xor_b32_e32 v175, 1, v174
	v_add_u32_e32 v191, 64, v191
	v_cmp_lt_i32_e32 vcc, v175, v191
	v_xor_b32_e32 v194, 2, v174
	s_waitcnt vmcnt(0) lgkmcnt(0)
	v_pk_add_f32 v[126:127], v[126:127], v[166:167]
	v_pk_add_f32 v[124:125], v[124:125], v[164:165]
	v_pk_add_f32 v[122:123], v[122:123], v[178:179]
	v_pk_add_f32 v[120:121], v[120:121], v[176:177]
	v_pk_add_f32 v[118:119], v[118:119], v[182:183]
	v_pk_add_f32 v[116:117], v[116:117], v[180:181]
	v_pk_add_f32 v[164:165], v[112:113], v[184:185]
	v_mul_f32_e32 v178, v125, v125
	v_mul_f32_e32 v179, v127, v127
	global_store_dwordx4 v[188:189], v[124:127], off
	v_cvt_pk_bf16_f32 v112, v124, v125
	v_cvt_pk_bf16_f32 v113, v126, v127
	v_mul_f32_e32 v125, v121, v121
	v_mul_f32_e32 v127, v123, v123
	v_pk_add_f32 v[166:167], v[114:115], v[186:187]
	v_mul_f32_e32 v180, v117, v117
	v_mul_f32_e32 v181, v119, v119
	v_fmac_f32_e32 v178, v124, v124
	v_fmac_f32_e32 v179, v126, v126
	v_fmac_f32_e32 v125, v120, v120
	v_fmac_f32_e32 v127, v122, v122
	v_mul_f32_e32 v182, v165, v165
	v_mul_f32_e32 v183, v167, v167
	global_store_dwordx2 v[192:193], v[112:113], off
	v_fmac_f32_e32 v180, v116, v116
	v_fmac_f32_e32 v181, v118, v118
	v_add_f32_e32 v112, v178, v179
	v_add_f32_e32 v113, v125, v127
	v_fmac_f32_e32 v182, v164, v164
	v_fmac_f32_e32 v183, v166, v166
	v_add_f32_e32 v124, v180, v181
	v_add_f32_e32 v112, v112, v113
	v_cndmask_b32_e32 v175, v174, v175, vcc
	v_add_f32_e32 v125, v182, v183
	v_add_f32_e32 v112, v112, v124
	v_lshlrev_b32_e32 v175, 2, v175
	v_add_f32_e32 v112, v112, v125
	ds_bpermute_b32 v113, v175, v112
	v_cmp_lt_i32_e32 vcc, v194, v191
	v_cvt_pk_bf16_f32 v176, v116, v117
	v_cvt_pk_bf16_f32 v114, v120, v121
	v_cndmask_b32_e32 v191, v174, v194, vcc
	v_cvt_pk_bf16_f32 v115, v122, v123
	v_cvt_pk_bf16_f32 v177, v118, v119
	global_store_dwordx4 v[188:189], v[120:123], off offset:64
	global_store_dwordx2 v[192:193], v[114:115], off offset:32
	global_store_dwordx4 v[188:189], v[116:119], off offset:512
	global_store_dwordx2 v[192:193], v[176:177], off offset:256
	s_waitcnt lgkmcnt(0)
	v_add_f32_e32 v112, v112, v113
	v_lshlrev_b32_e32 v176, 2, v191
	ds_bpermute_b32 v113, v176, v112
	v_cvt_pk_bf16_f32 v114, v164, v165
	v_cvt_pk_bf16_f32 v115, v166, v167
	global_store_dwordx4 v[188:189], v[164:167], off offset:576
	global_store_dwordx2 v[192:193], v[114:115], off offset:288
	s_mov_b32 vcc_lo, 0x11111111
	s_mov_b32 vcc_hi, 0x11111111
	s_and_saveexec_b64 s[24:25], vcc
	s_cbranch_execz .LBB0_1815
	v_lshl_add_u64 v[114:115], v[158:159], 2, s[10:11]
	s_waitcnt lgkmcnt(0)
	v_add_f32_e32 v112, v112, v113
	global_atomic_add_f32 v[114:115], v112, off
.LBB0_1815:
	s_or_b64 exec, exec, s[24:25]
	v_or_b32_e32 v164, 32, v158
	v_ashrrev_i32_e32 v165, 31, v164
	s_waitcnt lgkmcnt(0)
	v_lshlrev_b64 v[112:113], 12, v[164:165]
	v_lshl_add_u64 v[112:113], s[0:1], 0, v[112:113]
	v_lshl_add_u64 v[166:167], v[156:157], 2, v[112:113]
	global_load_dwordx4 v[124:127], v[166:167], off
	global_load_dwordx4 v[120:123], v[166:167], off offset:64
	global_load_dwordx4 v[116:119], v[166:167], off offset:512
	global_load_dwordx4 v[112:115], v[166:167], off offset:576
	v_pk_add_f32 v[110:111], v[110:111], v[142:143]
	v_pk_add_f32 v[108:109], v[108:109], v[140:141]
	v_mul_f32_e32 v141, v111, v111
	v_mul_f32_e32 v140, v109, v109
	v_fmac_f32_e32 v140, v108, v108
	v_fmac_f32_e32 v141, v110, v110
	v_add_f32_e32 v142, v140, v141
	v_lshlrev_b64 v[140:141], 11, v[160:161]
	v_lshl_add_u64 v[140:141], s[8:9], 0, v[140:141]
	global_store_dwordx4 v[162:163], v[108:111], off
	v_lshl_add_u64 v[140:141], v[156:157], 1, v[140:141]
	v_pk_add_f32 v[104:105], v[104:105], v[136:137]
	v_cvt_pk_bf16_f32 v108, v108, v109
	v_cvt_pk_bf16_f32 v109, v110, v111
	global_store_dwordx2 v[140:141], v[108:109], off
	v_pk_add_f32 v[106:107], v[106:107], v[138:139]
	v_mul_f32_e32 v108, v105, v105
	v_fmac_f32_e32 v108, v104, v104
	v_mul_f32_e32 v109, v107, v107
	global_store_dwordx4 v[162:163], v[104:107], off offset:64
	v_pk_add_f32 v[102:103], v[102:103], v[134:135]
	v_pk_add_f32 v[100:101], v[100:101], v[132:133]
	v_cvt_pk_bf16_f32 v104, v104, v105
	v_cvt_pk_bf16_f32 v105, v106, v107
	v_fmac_f32_e32 v109, v106, v106
	global_store_dwordx2 v[140:141], v[104:105], off offset:32
	v_mul_f32_e32 v104, v101, v101
	v_mul_f32_e32 v105, v103, v103
	v_add_f32_e32 v108, v108, v109
	v_fmac_f32_e32 v104, v100, v100
	v_fmac_f32_e32 v105, v102, v102
	v_add_f32_e32 v108, v142, v108
	v_add_f32_e32 v104, v104, v105
	v_add_f32_e32 v108, v108, v104
	v_pk_add_f32 v[106:107], v[98:99], v[130:131]
	v_pk_add_f32 v[104:105], v[96:97], v[128:129]
	v_mul_f32_e32 v97, v107, v107
	v_mul_f32_e32 v96, v105, v105
	v_fmac_f32_e32 v96, v104, v104
	v_fmac_f32_e32 v97, v106, v106
	v_add_f32_e32 v96, v96, v97
	v_add_f32_e32 v98, v108, v96
	ds_bpermute_b32 v99, v175, v98
	v_cvt_pk_bf16_f32 v96, v100, v101
	v_cvt_pk_bf16_f32 v97, v102, v103
	global_store_dwordx4 v[162:163], v[100:103], off offset:512
	global_store_dwordx2 v[140:141], v[96:97], off offset:256
	s_waitcnt lgkmcnt(0)
	v_add_f32_e32 v96, v98, v99
	ds_bpermute_b32 v97, v176, v96
	v_cvt_pk_bf16_f32 v98, v104, v105
	v_cvt_pk_bf16_f32 v99, v106, v107
	global_store_dwordx4 v[162:163], v[104:107], off offset:576
	global_store_dwordx2 v[140:141], v[98:99], off offset:288
	s_mov_b32 vcc_lo, 0x11111111
	s_mov_b32 vcc_hi, 0x11111111
	s_and_saveexec_b64 s[24:25], vcc
	s_cbranch_execz .LBB0_1817
	v_lshl_add_u64 v[98:99], v[160:161], 2, s[10:11]
	s_waitcnt lgkmcnt(0)
	v_add_f32_e32 v96, v96, v97
	global_atomic_add_f32 v[98:99], v96, off
.LBB0_1817:
	s_or_b64 exec, exec, s[24:25]
	v_or_b32_e32 v128, 48, v158
	v_ashrrev_i32_e32 v129, 31, v128
	s_waitcnt lgkmcnt(0)
	v_lshlrev_b64 v[96:97], 12, v[128:129]
	v_lshl_add_u64 v[96:97], s[0:1], 0, v[96:97]
	v_lshl_add_u64 v[130:131], v[156:157], 2, v[96:97]
	global_load_dwordx4 v[108:111], v[130:131], off
	global_load_dwordx4 v[104:107], v[130:131], off offset:64
	global_load_dwordx4 v[100:103], v[130:131], off offset:512
	global_load_dwordx4 v[96:99], v[130:131], off offset:576
	s_waitcnt vmcnt(0)
	v_pk_add_f32 v[94:95], v[94:95], v[126:127]
	v_pk_add_f32 v[92:93], v[92:93], v[124:125]
	v_mul_f32_e32 v125, v95, v95
	v_mul_f32_e32 v124, v93, v93
	v_fmac_f32_e32 v124, v92, v92
	v_fmac_f32_e32 v125, v94, v94
	v_add_f32_e32 v126, v124, v125
	v_lshlrev_b64 v[124:125], 11, v[164:165]
	v_lshl_add_u64 v[124:125], s[8:9], 0, v[124:125]
	global_store_dwordx4 v[166:167], v[92:95], off
	v_lshl_add_u64 v[124:125], v[156:157], 1, v[124:125]
	v_pk_add_f32 v[88:89], v[88:89], v[120:121]
	v_cvt_pk_bf16_f32 v92, v92, v93
	v_cvt_pk_bf16_f32 v93, v94, v95
	global_store_dwordx2 v[124:125], v[92:93], off
	v_pk_add_f32 v[90:91], v[90:91], v[122:123]
	v_mul_f32_e32 v92, v89, v89
	v_fmac_f32_e32 v92, v88, v88
	v_mul_f32_e32 v93, v91, v91
	global_store_dwordx4 v[166:167], v[88:91], off offset:64
	v_pk_add_f32 v[86:87], v[86:87], v[118:119]
	v_pk_add_f32 v[84:85], v[84:85], v[116:117]
	v_cvt_pk_bf16_f32 v88, v88, v89
	v_cvt_pk_bf16_f32 v89, v90, v91
	v_fmac_f32_e32 v93, v90, v90
	global_store_dwordx2 v[124:125], v[88:89], off offset:32
	v_mul_f32_e32 v88, v85, v85
	v_mul_f32_e32 v89, v87, v87
	v_add_f32_e32 v92, v92, v93
	v_fmac_f32_e32 v88, v84, v84
	v_fmac_f32_e32 v89, v86, v86
	v_add_f32_e32 v92, v126, v92
	v_add_f32_e32 v88, v88, v89
	v_add_f32_e32 v92, v92, v88
	v_pk_add_f32 v[90:91], v[82:83], v[114:115]
	v_pk_add_f32 v[88:89], v[80:81], v[112:113]
	v_mul_f32_e32 v81, v91, v91
	v_mul_f32_e32 v80, v89, v89
	v_fmac_f32_e32 v80, v88, v88
	v_fmac_f32_e32 v81, v90, v90
	v_add_f32_e32 v80, v80, v81
	v_add_f32_e32 v82, v92, v80
	ds_bpermute_b32 v83, v175, v82
	v_cvt_pk_bf16_f32 v80, v84, v85
	v_cvt_pk_bf16_f32 v81, v86, v87
	global_store_dwordx4 v[166:167], v[84:87], off offset:512
	global_store_dwordx2 v[124:125], v[80:81], off offset:256
	s_waitcnt lgkmcnt(0)
	v_add_f32_e32 v80, v82, v83
	ds_bpermute_b32 v81, v176, v80
	v_cvt_pk_bf16_f32 v82, v88, v89
	v_cvt_pk_bf16_f32 v83, v90, v91
	global_store_dwordx4 v[166:167], v[88:91], off offset:576
	global_store_dwordx2 v[124:125], v[82:83], off offset:288
	s_mov_b32 vcc_lo, 0x11111111
	s_mov_b32 vcc_hi, 0x11111111
	s_and_saveexec_b64 s[24:25], vcc
	s_cbranch_execz .LBB0_1819
	v_lshl_add_u64 v[82:83], v[164:165], 2, s[10:11]
	s_waitcnt lgkmcnt(0)
	v_add_f32_e32 v80, v80, v81
	global_atomic_add_f32 v[82:83], v80, off
.LBB0_1819:
	s_or_b64 exec, exec, s[24:25]
	v_add_u32_e32 v112, 0x80, v158
	v_ashrrev_i32_e32 v113, 31, v112
	s_waitcnt lgkmcnt(0)
	v_lshlrev_b64 v[80:81], 12, v[112:113]
	v_lshl_add_u64 v[80:81], s[0:1], 0, v[80:81]
	v_lshl_add_u64 v[114:115], v[156:157], 2, v[80:81]
	global_load_dwordx4 v[92:95], v[114:115], off
	global_load_dwordx4 v[88:91], v[114:115], off offset:64
	global_load_dwordx4 v[84:87], v[114:115], off offset:512
	global_load_dwordx4 v[80:83], v[114:115], off offset:576
	v_pk_add_f32 v[78:79], v[78:79], v[110:111]
	v_pk_add_f32 v[76:77], v[76:77], v[108:109]
	v_mul_f32_e32 v109, v79, v79
	v_mul_f32_e32 v108, v77, v77
	v_fmac_f32_e32 v108, v76, v76
	v_fmac_f32_e32 v109, v78, v78
	v_add_f32_e32 v110, v108, v109
	v_lshlrev_b64 v[108:109], 11, v[128:129]
	v_lshl_add_u64 v[108:109], s[8:9], 0, v[108:109]
	global_store_dwordx4 v[130:131], v[76:79], off
	v_lshl_add_u64 v[108:109], v[156:157], 1, v[108:109]
	v_pk_add_f32 v[72:73], v[72:73], v[104:105]
	v_cvt_pk_bf16_f32 v76, v76, v77
	v_cvt_pk_bf16_f32 v77, v78, v79
	global_store_dwordx2 v[108:109], v[76:77], off
	v_pk_add_f32 v[74:75], v[74:75], v[106:107]
	v_mul_f32_e32 v76, v73, v73
	v_fmac_f32_e32 v76, v72, v72
	v_mul_f32_e32 v77, v75, v75
	global_store_dwordx4 v[130:131], v[72:75], off offset:64
	v_pk_add_f32 v[70:71], v[70:71], v[102:103]
	v_pk_add_f32 v[68:69], v[68:69], v[100:101]
	v_cvt_pk_bf16_f32 v72, v72, v73
	v_cvt_pk_bf16_f32 v73, v74, v75
	v_fmac_f32_e32 v77, v74, v74
	global_store_dwordx2 v[108:109], v[72:73], off offset:32
	v_mul_f32_e32 v72, v69, v69
	v_mul_f32_e32 v73, v71, v71
	v_add_f32_e32 v76, v76, v77
	v_fmac_f32_e32 v72, v68, v68
	v_fmac_f32_e32 v73, v70, v70
	v_add_f32_e32 v76, v110, v76
	v_add_f32_e32 v72, v72, v73
	v_add_f32_e32 v76, v76, v72
	v_pk_add_f32 v[74:75], v[66:67], v[98:99]
	v_pk_add_f32 v[72:73], v[64:65], v[96:97]
	v_mul_f32_e32 v65, v75, v75
	v_mul_f32_e32 v64, v73, v73
	v_fmac_f32_e32 v64, v72, v72
	v_fmac_f32_e32 v65, v74, v74
	v_add_f32_e32 v64, v64, v65
	v_add_f32_e32 v66, v76, v64
	ds_bpermute_b32 v67, v175, v66
	v_cvt_pk_bf16_f32 v64, v68, v69
	v_cvt_pk_bf16_f32 v65, v70, v71
	global_store_dwordx4 v[130:131], v[68:71], off offset:512
	global_store_dwordx2 v[108:109], v[64:65], off offset:256
	s_waitcnt lgkmcnt(0)
	v_add_f32_e32 v64, v66, v67
	ds_bpermute_b32 v65, v176, v64
	v_cvt_pk_bf16_f32 v66, v72, v73
	v_cvt_pk_bf16_f32 v67, v74, v75
	global_store_dwordx4 v[130:131], v[72:75], off offset:576
	global_store_dwordx2 v[108:109], v[66:67], off offset:288
	s_mov_b32 vcc_lo, 0x11111111
	s_mov_b32 vcc_hi, 0x11111111
	s_and_saveexec_b64 s[24:25], vcc
	s_cbranch_execz .LBB0_1821
	v_lshl_add_u64 v[66:67], v[128:129], 2, s[10:11]
	s_waitcnt lgkmcnt(0)
	v_add_f32_e32 v64, v64, v65
	global_atomic_add_f32 v[66:67], v64, off
.LBB0_1821:
	s_or_b64 exec, exec, s[24:25]
	v_or_b32_e32 v96, 16, v112
	v_ashrrev_i32_e32 v97, 31, v96
	s_waitcnt lgkmcnt(0)
	v_lshlrev_b64 v[64:65], 12, v[96:97]
	v_lshl_add_u64 v[64:65], s[0:1], 0, v[64:65]
	v_lshl_add_u64 v[98:99], v[156:157], 2, v[64:65]
	global_load_dwordx4 v[76:79], v[98:99], off
	global_load_dwordx4 v[72:75], v[98:99], off offset:64
	global_load_dwordx4 v[68:71], v[98:99], off offset:512
	global_load_dwordx4 v[64:67], v[98:99], off offset:576
	s_waitcnt vmcnt(0)
	v_pk_add_f32 v[62:63], v[62:63], v[94:95]
	v_pk_add_f32 v[60:61], v[60:61], v[92:93]
	v_mul_f32_e32 v93, v63, v63
	v_mul_f32_e32 v92, v61, v61
	v_fmac_f32_e32 v92, v60, v60
	v_fmac_f32_e32 v93, v62, v62
	v_add_f32_e32 v94, v92, v93
	v_lshlrev_b64 v[92:93], 11, v[112:113]
	v_lshl_add_u64 v[92:93], s[8:9], 0, v[92:93]
	global_store_dwordx4 v[114:115], v[60:63], off
	v_lshl_add_u64 v[92:93], v[156:157], 1, v[92:93]
	v_pk_add_f32 v[56:57], v[56:57], v[88:89]
	v_cvt_pk_bf16_f32 v60, v60, v61
	v_cvt_pk_bf16_f32 v61, v62, v63
	global_store_dwordx2 v[92:93], v[60:61], off
	v_pk_add_f32 v[58:59], v[58:59], v[90:91]
	v_mul_f32_e32 v60, v57, v57
	v_fmac_f32_e32 v60, v56, v56
	v_mul_f32_e32 v61, v59, v59
	global_store_dwordx4 v[114:115], v[56:59], off offset:64
	v_pk_add_f32 v[54:55], v[54:55], v[86:87]
	v_pk_add_f32 v[52:53], v[52:53], v[84:85]
	v_cvt_pk_bf16_f32 v56, v56, v57
	v_cvt_pk_bf16_f32 v57, v58, v59
	v_fmac_f32_e32 v61, v58, v58
	global_store_dwordx2 v[92:93], v[56:57], off offset:32
	v_mul_f32_e32 v56, v53, v53
	v_mul_f32_e32 v57, v55, v55
	v_add_f32_e32 v60, v60, v61
	v_fmac_f32_e32 v56, v52, v52
	v_fmac_f32_e32 v57, v54, v54
	v_add_f32_e32 v60, v94, v60
	v_add_f32_e32 v56, v56, v57
	v_add_f32_e32 v60, v60, v56
	v_pk_add_f32 v[58:59], v[50:51], v[82:83]
	v_pk_add_f32 v[56:57], v[48:49], v[80:81]
	v_mul_f32_e32 v49, v59, v59
	v_mul_f32_e32 v48, v57, v57
	v_fmac_f32_e32 v48, v56, v56
	v_fmac_f32_e32 v49, v58, v58
	v_add_f32_e32 v48, v48, v49
	v_add_f32_e32 v50, v60, v48
	ds_bpermute_b32 v51, v175, v50
	v_cvt_pk_bf16_f32 v48, v52, v53
	v_cvt_pk_bf16_f32 v49, v54, v55
	global_store_dwordx4 v[114:115], v[52:55], off offset:512
	global_store_dwordx2 v[92:93], v[48:49], off offset:256
	s_waitcnt lgkmcnt(0)
	v_add_f32_e32 v48, v50, v51
	ds_bpermute_b32 v49, v176, v48
	v_cvt_pk_bf16_f32 v50, v56, v57
	v_cvt_pk_bf16_f32 v51, v58, v59
	global_store_dwordx4 v[114:115], v[56:59], off offset:576
	global_store_dwordx2 v[92:93], v[50:51], off offset:288
	s_mov_b32 vcc_lo, 0x11111111
	s_mov_b32 vcc_hi, 0x11111111
	s_and_saveexec_b64 s[24:25], vcc
	s_cbranch_execz .LBB0_1823
	v_lshl_add_u64 v[50:51], v[112:113], 2, s[10:11]
	s_waitcnt lgkmcnt(0)
	v_add_f32_e32 v48, v48, v49
	global_atomic_add_f32 v[50:51], v48, off
.LBB0_1823:
	s_or_b64 exec, exec, s[24:25]
	v_or_b32_e32 v80, 32, v112
	v_ashrrev_i32_e32 v81, 31, v80
	s_waitcnt lgkmcnt(0)
	v_lshlrev_b64 v[48:49], 12, v[80:81]
	v_lshl_add_u64 v[48:49], s[0:1], 0, v[48:49]
	v_lshl_add_u64 v[82:83], v[156:157], 2, v[48:49]
	global_load_dwordx4 v[60:63], v[82:83], off
	global_load_dwordx4 v[56:59], v[82:83], off offset:64
	global_load_dwordx4 v[52:55], v[82:83], off offset:512
	global_load_dwordx4 v[48:51], v[82:83], off offset:576
	v_pk_add_f32 v[46:47], v[46:47], v[78:79]
	v_pk_add_f32 v[44:45], v[44:45], v[76:77]
	v_mul_f32_e32 v77, v47, v47
	v_mul_f32_e32 v76, v45, v45
	v_fmac_f32_e32 v76, v44, v44
	v_fmac_f32_e32 v77, v46, v46
	v_add_f32_e32 v78, v76, v77
	v_lshlrev_b64 v[76:77], 11, v[96:97]
	v_lshl_add_u64 v[76:77], s[8:9], 0, v[76:77]
	global_store_dwordx4 v[98:99], v[44:47], off
	v_lshl_add_u64 v[76:77], v[156:157], 1, v[76:77]
	v_pk_add_f32 v[40:41], v[40:41], v[72:73]
	v_cvt_pk_bf16_f32 v44, v44, v45
	v_cvt_pk_bf16_f32 v45, v46, v47
	global_store_dwordx2 v[76:77], v[44:45], off
	v_pk_add_f32 v[42:43], v[42:43], v[74:75]
	v_mul_f32_e32 v44, v41, v41
	v_fmac_f32_e32 v44, v40, v40
	v_mul_f32_e32 v45, v43, v43
	global_store_dwordx4 v[98:99], v[40:43], off offset:64
	v_pk_add_f32 v[38:39], v[38:39], v[70:71]
	v_pk_add_f32 v[36:37], v[36:37], v[68:69]
	v_cvt_pk_bf16_f32 v40, v40, v41
	v_cvt_pk_bf16_f32 v41, v42, v43
	v_fmac_f32_e32 v45, v42, v42
	global_store_dwordx2 v[76:77], v[40:41], off offset:32
	v_mul_f32_e32 v40, v37, v37
	v_mul_f32_e32 v41, v39, v39
	v_add_f32_e32 v44, v44, v45
	v_fmac_f32_e32 v40, v36, v36
	v_fmac_f32_e32 v41, v38, v38
	v_add_f32_e32 v44, v78, v44
	v_add_f32_e32 v40, v40, v41
	v_add_f32_e32 v44, v44, v40
	v_pk_add_f32 v[42:43], v[34:35], v[66:67]
	v_pk_add_f32 v[40:41], v[32:33], v[64:65]
	v_mul_f32_e32 v33, v43, v43
	v_mul_f32_e32 v32, v41, v41
	v_fmac_f32_e32 v32, v40, v40
	v_fmac_f32_e32 v33, v42, v42
	v_add_f32_e32 v32, v32, v33
	v_add_f32_e32 v34, v44, v32
	ds_bpermute_b32 v35, v175, v34
	v_cvt_pk_bf16_f32 v32, v36, v37
	v_cvt_pk_bf16_f32 v33, v38, v39
	global_store_dwordx4 v[98:99], v[36:39], off offset:512
	global_store_dwordx2 v[76:77], v[32:33], off offset:256
	s_waitcnt lgkmcnt(0)
	v_add_f32_e32 v32, v34, v35
	ds_bpermute_b32 v33, v176, v32
	v_cvt_pk_bf16_f32 v34, v40, v41
	v_cvt_pk_bf16_f32 v35, v42, v43
	global_store_dwordx4 v[98:99], v[40:43], off offset:576
	global_store_dwordx2 v[76:77], v[34:35], off offset:288
	s_mov_b32 vcc_lo, 0x11111111
	s_mov_b32 vcc_hi, 0x11111111
	s_and_saveexec_b64 s[24:25], vcc
	s_cbranch_execz .LBB0_1825
	v_lshl_add_u64 v[34:35], v[96:97], 2, s[10:11]
	s_waitcnt lgkmcnt(0)
	v_add_f32_e32 v32, v32, v33
	global_atomic_add_f32 v[34:35], v32, off
.LBB0_1825:
	s_or_b64 exec, exec, s[24:25]
	v_or_b32_e32 v64, 48, v112
	v_ashrrev_i32_e32 v65, 31, v64
	s_waitcnt lgkmcnt(0)
	v_lshlrev_b64 v[32:33], 12, v[64:65]
	v_lshl_add_u64 v[32:33], s[0:1], 0, v[32:33]
	v_lshl_add_u64 v[66:67], v[156:157], 2, v[32:33]
	global_load_dwordx4 v[44:47], v[66:67], off
	global_load_dwordx4 v[40:43], v[66:67], off offset:64
	global_load_dwordx4 v[36:39], v[66:67], off offset:512
	global_load_dwordx4 v[32:35], v[66:67], off offset:576
	s_waitcnt vmcnt(0)
	v_pk_add_f32 v[30:31], v[30:31], v[62:63]
	v_pk_add_f32 v[28:29], v[28:29], v[60:61]
	v_mul_f32_e32 v61, v31, v31
	v_mul_f32_e32 v60, v29, v29
	v_fmac_f32_e32 v60, v28, v28
	v_fmac_f32_e32 v61, v30, v30
	v_add_f32_e32 v62, v60, v61
	v_lshlrev_b64 v[60:61], 11, v[80:81]
	v_lshl_add_u64 v[60:61], s[8:9], 0, v[60:61]
	global_store_dwordx4 v[82:83], v[28:31], off
	v_lshl_add_u64 v[60:61], v[156:157], 1, v[60:61]
	v_pk_add_f32 v[24:25], v[24:25], v[56:57]
	v_cvt_pk_bf16_f32 v28, v28, v29
	v_cvt_pk_bf16_f32 v29, v30, v31
	global_store_dwordx2 v[60:61], v[28:29], off
	v_pk_add_f32 v[26:27], v[26:27], v[58:59]
	v_mul_f32_e32 v28, v25, v25
	v_fmac_f32_e32 v28, v24, v24
	v_mul_f32_e32 v29, v27, v27
	global_store_dwordx4 v[82:83], v[24:27], off offset:64
	v_pk_add_f32 v[22:23], v[22:23], v[54:55]
	v_pk_add_f32 v[20:21], v[20:21], v[52:53]
	v_cvt_pk_bf16_f32 v24, v24, v25
	v_cvt_pk_bf16_f32 v25, v26, v27
	v_fmac_f32_e32 v29, v26, v26
	global_store_dwordx2 v[60:61], v[24:25], off offset:32
	v_mul_f32_e32 v24, v21, v21
	v_mul_f32_e32 v25, v23, v23
	v_add_f32_e32 v28, v28, v29
	v_fmac_f32_e32 v24, v20, v20
	v_fmac_f32_e32 v25, v22, v22
	v_add_f32_e32 v28, v62, v28
	v_add_f32_e32 v24, v24, v25
	v_add_f32_e32 v28, v28, v24
	v_pk_add_f32 v[26:27], v[18:19], v[50:51]
	v_pk_add_f32 v[24:25], v[16:17], v[48:49]
	v_mul_f32_e32 v17, v27, v27
	v_mul_f32_e32 v16, v25, v25
	v_fmac_f32_e32 v16, v24, v24
	v_fmac_f32_e32 v17, v26, v26
	v_add_f32_e32 v16, v16, v17
	v_add_f32_e32 v18, v28, v16
	ds_bpermute_b32 v19, v175, v18
	v_cvt_pk_bf16_f32 v16, v20, v21
	v_cvt_pk_bf16_f32 v17, v22, v23
	global_store_dwordx4 v[82:83], v[20:23], off offset:512
	global_store_dwordx2 v[60:61], v[16:17], off offset:256
	s_waitcnt lgkmcnt(0)
	v_add_f32_e32 v16, v18, v19
	ds_bpermute_b32 v17, v176, v16
	v_cvt_pk_bf16_f32 v18, v24, v25
	v_cvt_pk_bf16_f32 v19, v26, v27
	global_store_dwordx4 v[82:83], v[24:27], off offset:576
	global_store_dwordx2 v[60:61], v[18:19], off offset:288
	s_mov_b32 vcc_lo, 0x11111111
	s_mov_b32 vcc_hi, 0x11111111
	s_and_saveexec_b64 s[24:25], vcc
	s_cbranch_execz .LBB0_1827
	v_lshl_add_u64 v[18:19], v[80:81], 2, s[10:11]
	s_waitcnt lgkmcnt(0)
	v_add_f32_e32 v16, v16, v17
	global_atomic_add_f32 v[18:19], v16, off
.LBB0_1827:
	s_or_b64 exec, exec, s[24:25]
	v_pk_add_f32 v[14:15], v[14:15], v[46:47]
	v_pk_add_f32 v[12:13], v[12:13], v[44:45]
	s_waitcnt lgkmcnt(0)
	v_mul_f32_e32 v17, v15, v15
	v_mul_f32_e32 v16, v13, v13
	v_fmac_f32_e32 v16, v12, v12
	v_fmac_f32_e32 v17, v14, v14
	v_add_f32_e32 v18, v16, v17
	v_lshlrev_b64 v[16:17], 11, v[64:65]
	v_lshl_add_u64 v[16:17], s[8:9], 0, v[16:17]
	global_store_dwordx4 v[66:67], v[12:15], off
	v_lshl_add_u64 v[16:17], v[156:157], 1, v[16:17]
	v_pk_add_f32 v[8:9], v[8:9], v[40:41]
	v_cvt_pk_bf16_f32 v12, v12, v13
	v_cvt_pk_bf16_f32 v13, v14, v15
	global_store_dwordx2 v[16:17], v[12:13], off
	v_pk_add_f32 v[10:11], v[10:11], v[42:43]
	v_mul_f32_e32 v12, v9, v9
	v_fmac_f32_e32 v12, v8, v8
	v_mul_f32_e32 v13, v11, v11
	global_store_dwordx4 v[66:67], v[8:11], off offset:64
	v_pk_add_f32 v[6:7], v[6:7], v[38:39]
	v_pk_add_f32 v[4:5], v[4:5], v[36:37]
	v_cvt_pk_bf16_f32 v8, v8, v9
	v_cvt_pk_bf16_f32 v9, v10, v11
	v_fmac_f32_e32 v13, v10, v10
	global_store_dwordx2 v[16:17], v[8:9], off offset:32
	v_mul_f32_e32 v8, v5, v5
	v_mul_f32_e32 v9, v7, v7
	v_add_f32_e32 v12, v12, v13
	v_fmac_f32_e32 v8, v4, v4
	v_fmac_f32_e32 v9, v6, v6
	v_add_f32_e32 v12, v18, v12
	v_add_f32_e32 v8, v8, v9
	v_add_f32_e32 v12, v12, v8
	v_pk_add_f32 v[10:11], v[2:3], v[34:35]
	v_pk_add_f32 v[8:9], v[0:1], v[32:33]
	v_mul_f32_e32 v1, v11, v11
	v_mul_f32_e32 v0, v9, v9
	v_fmac_f32_e32 v0, v8, v8
	v_fmac_f32_e32 v1, v10, v10
	v_add_f32_e32 v0, v0, v1
	v_add_f32_e32 v2, v12, v0
	ds_bpermute_b32 v3, v175, v2
	v_cvt_pk_bf16_f32 v0, v4, v5
	v_cvt_pk_bf16_f32 v1, v6, v7
	global_store_dwordx4 v[66:67], v[4:7], off offset:512
	global_store_dwordx2 v[16:17], v[0:1], off offset:256
	s_waitcnt lgkmcnt(0)
	v_add_f32_e32 v0, v2, v3
	ds_bpermute_b32 v1, v176, v0
	v_cvt_pk_bf16_f32 v2, v8, v9
	v_cvt_pk_bf16_f32 v3, v10, v11
	global_store_dwordx4 v[66:67], v[8:11], off offset:576
	global_store_dwordx2 v[16:17], v[2:3], off offset:288
	s_mov_b32 vcc_lo, 0x11111111
	s_mov_b32 vcc_hi, 0x11111111
	s_and_saveexec_b64 s[24:25], vcc
	s_cbranch_execz .LBB0_1829
	v_lshl_add_u64 v[2:3], v[64:65], 2, s[10:11]
	s_waitcnt lgkmcnt(0)
	v_add_f32_e32 v0, v0, v1
	global_atomic_add_f32 v[2:3], v0, off

.LBB0_1917:
	ds_read_b128 v[150:153], v163
	ds_read_b128 v[154:157], v163 offset:1024
	ds_read_b128 v[158:161], v163 offset:2048
	ds_read_b128 v[168:171], v163 offset:3072
	ds_read_b128 v[172:175], v164
	ds_read_b128 v[176:179], v164 offset:1024
	ds_read_b128 v[180:183], v164 offset:2048
	ds_read_b128 v[184:187], v164 offset:3072
	s_add_u32 s34, s30, 0xfffc0080
	s_addc_u32 s35, s31, -1
	s_cmp_eq_u32 s61, 12
	s_cselect_b32 s37, s8, s35
	s_cselect_b32 s36, s21, s34
	s_cselect_b32 s35, s23, s60
	s_cselect_b32 s34, s25, s33
	v_lshl_add_u64 v[188:189], s[30:31], 0, v[142:143]
	s_add_i32 m0, s45, 0xc000
	ds_read_b128 v[192:195], v165
	ds_read_b128 v[196:199], v165 offset:1024
	ds_read_b128 v[200:203], v165 offset:2048
	ds_read_b128 v[204:207], v165 offset:3072
	ds_read_b128 v[208:211], v165 offset:4096
	ds_read_b128 v[212:215], v165 offset:5120
	ds_read_b128 v[216:219], v165 offset:6144
	ds_read_b128 v[220:223], v165 offset:7168
	global_load_lds_dwordx4 v[188:189], off
	v_lshl_add_u64 v[188:189], s[30:31], 0, v[140:141]
	s_add_i32 m0, s45, 0xe000
	s_nop 0
	global_load_lds_dwordx4 v[188:189], off
	s_waitcnt vmcnt(8)
	s_waitcnt lgkmcnt(0)
	s_barrier
	s_setprio 1
	s_waitcnt lgkmcnt(0)
	v_mfma_f32_16x16x32_bf16 v[124:127], v[150:153], v[192:195], v[124:127]
	v_mfma_f32_16x16x32_bf16 v[120:123], v[158:161], v[192:195], v[120:123]
	v_mfma_f32_16x16x32_bf16 v[108:111], v[150:153], v[200:203], v[108:111]
	v_mfma_f32_16x16x32_bf16 v[104:107], v[158:161], v[200:203], v[104:107]
	v_mfma_f32_16x16x32_bf16 v[92:95], v[150:153], v[208:211], v[92:95]
	v_mfma_f32_16x16x32_bf16 v[88:91], v[158:161], v[208:211], v[88:91]
	v_mfma_f32_16x16x32_bf16 v[76:79], v[150:153], v[216:219], v[76:79]
	v_mfma_f32_16x16x32_bf16 v[72:75], v[158:161], v[216:219], v[72:75]
	v_mfma_f32_16x16x32_bf16 v[124:127], v[154:157], v[196:199], v[124:127]
	v_mfma_f32_16x16x32_bf16 v[120:123], v[168:171], v[196:199], v[120:123]
	v_mfma_f32_16x16x32_bf16 v[108:111], v[154:157], v[204:207], v[108:111]
	v_mfma_f32_16x16x32_bf16 v[104:107], v[168:171], v[204:207], v[104:107]
	v_mfma_f32_16x16x32_bf16 v[92:95], v[154:157], v[212:215], v[92:95]
	v_mfma_f32_16x16x32_bf16 v[88:91], v[168:171], v[212:215], v[88:91]
	v_mfma_f32_16x16x32_bf16 v[76:79], v[154:157], v[220:223], v[76:79]
	v_mfma_f32_16x16x32_bf16 v[72:75], v[168:171], v[220:223], v[72:75]
	s_setprio 0
	s_setprio 1
	v_mfma_f32_16x16x32_bf16 v[116:119], v[172:175], v[192:195], v[116:119]
	v_mfma_f32_16x16x32_bf16 v[112:115], v[180:183], v[192:195], v[112:115]
	v_mfma_f32_16x16x32_bf16 v[100:103], v[172:175], v[200:203], v[100:103]
	v_mfma_f32_16x16x32_bf16 v[96:99], v[180:183], v[200:203], v[96:99]
	v_mfma_f32_16x16x32_bf16 v[84:87], v[172:175], v[208:211], v[84:87]
	v_mfma_f32_16x16x32_bf16 v[80:83], v[180:183], v[208:211], v[80:83]
	v_mfma_f32_16x16x32_bf16 v[68:71], v[172:175], v[216:219], v[68:71]
	v_mfma_f32_16x16x32_bf16 v[64:67], v[180:183], v[216:219], v[64:67]
	v_mfma_f32_16x16x32_bf16 v[116:119], v[176:179], v[196:199], v[116:119]
	v_mfma_f32_16x16x32_bf16 v[112:115], v[184:187], v[196:199], v[112:115]
	v_mfma_f32_16x16x32_bf16 v[100:103], v[176:179], v[204:207], v[100:103]
	v_mfma_f32_16x16x32_bf16 v[96:99], v[184:187], v[204:207], v[96:99]
	v_mfma_f32_16x16x32_bf16 v[84:87], v[176:179], v[212:215], v[84:87]
	v_mfma_f32_16x16x32_bf16 v[80:83], v[184:187], v[212:215], v[80:83]
	v_mfma_f32_16x16x32_bf16 v[68:71], v[176:179], v[220:223], v[68:71]
	v_mfma_f32_16x16x32_bf16 v[64:67], v[184:187], v[220:223], v[64:67]
	s_setprio 0
	s_barrier
	s_add_i32 s62, s53, s42
	v_lshl_add_u64 v[188:189], s[34:35], 0, v[132:133]
	s_mov_b32 m0, s62
	ds_read_b128 v[192:195], v165 offset:16384
	ds_read_b128 v[196:199], v165 offset:17408
	ds_read_b128 v[200:203], v165 offset:18432
	ds_read_b128 v[204:207], v165 offset:19456
	ds_read_b128 v[208:211], v165 offset:20480
	ds_read_b128 v[212:215], v165 offset:21504
	ds_read_b128 v[216:219], v165 offset:22528
	ds_read_b128 v[220:223], v165 offset:23552
	global_load_lds_dwordx4 v[188:189], off
	s_add_i32 m0, s62, 0x2000
	s_add_u32 s62, s34, 0x40000
	v_lshl_add_u64 v[224:225], s[34:35], 0, v[128:129]
	s_addc_u32 s63, s35, 0
	s_add_i32 s64, s54, s42
	global_load_lds_dwordx4 v[224:225], off
	v_lshl_add_u64 v[226:227], s[62:63], 0, v[132:133]
	s_mov_b32 m0, s64
	v_lshl_add_u64 v[228:229], s[36:37], 0, v[130:131]
	global_load_lds_dwordx4 v[226:227], off
	v_lshl_add_u64 v[226:227], s[62:63], 0, v[128:129]
	s_add_i32 m0, s64, 0x2000
	s_nop 0
	global_load_lds_dwordx4 v[226:227], off
	v_lshl_add_u64 v[226:227], s[36:37], 0, v[134:135]
	s_mov_b32 m0, s45
	s_nop 0
	global_load_lds_dwordx4 v[226:227], off
	s_mov_b32 m0, s46
	s_nop 0
	global_load_lds_dwordx4 v[228:229], off
	s_waitcnt vmcnt(8)
	s_waitcnt lgkmcnt(0)
	s_barrier
	s_setprio 1
	s_waitcnt lgkmcnt(0)
	v_mfma_f32_16x16x32_bf16 v[60:63], v[150:153], v[192:195], v[60:63]
	v_mfma_f32_16x16x32_bf16 v[56:59], v[158:161], v[192:195], v[56:59]
	v_mfma_f32_16x16x32_bf16 v[44:47], v[150:153], v[200:203], v[44:47]
	v_mfma_f32_16x16x32_bf16 v[40:43], v[158:161], v[200:203], v[40:43]
	v_mfma_f32_16x16x32_bf16 v[28:31], v[150:153], v[208:211], v[28:31]
	v_mfma_f32_16x16x32_bf16 v[24:27], v[158:161], v[208:211], v[24:27]
	v_mfma_f32_16x16x32_bf16 v[12:15], v[150:153], v[216:219], v[12:15]
	v_mfma_f32_16x16x32_bf16 v[8:11], v[158:161], v[216:219], v[8:11]
	v_mfma_f32_16x16x32_bf16 v[60:63], v[154:157], v[196:199], v[60:63]
	v_mfma_f32_16x16x32_bf16 v[56:59], v[168:171], v[196:199], v[56:59]
	v_mfma_f32_16x16x32_bf16 v[44:47], v[154:157], v[204:207], v[44:47]
	v_mfma_f32_16x16x32_bf16 v[40:43], v[168:171], v[204:207], v[40:43]
	v_mfma_f32_16x16x32_bf16 v[28:31], v[154:157], v[212:215], v[28:31]
	v_mfma_f32_16x16x32_bf16 v[24:27], v[168:171], v[212:215], v[24:27]
	v_mfma_f32_16x16x32_bf16 v[12:15], v[154:157], v[220:223], v[12:15]
	v_mfma_f32_16x16x32_bf16 v[8:11], v[168:171], v[220:223], v[8:11]
	s_setprio 0
	s_setprio 1
	v_mfma_f32_16x16x32_bf16 v[52:55], v[172:175], v[192:195], v[52:55]
	v_mfma_f32_16x16x32_bf16 v[48:51], v[180:183], v[192:195], v[48:51]
	v_mfma_f32_16x16x32_bf16 v[36:39], v[172:175], v[200:203], v[36:39]
	v_mfma_f32_16x16x32_bf16 v[32:35], v[180:183], v[200:203], v[32:35]
	v_mfma_f32_16x16x32_bf16 v[20:23], v[172:175], v[208:211], v[20:23]
	v_mfma_f32_16x16x32_bf16 v[16:19], v[180:183], v[208:211], v[16:19]
	v_mfma_f32_16x16x32_bf16 v[4:7], v[172:175], v[216:219], v[4:7]
	v_mfma_f32_16x16x32_bf16 v[0:3], v[180:183], v[216:219], v[0:3]
	v_mfma_f32_16x16x32_bf16 v[52:55], v[176:179], v[196:199], v[52:55]
	v_mfma_f32_16x16x32_bf16 v[48:51], v[184:187], v[196:199], v[48:51]
	v_mfma_f32_16x16x32_bf16 v[36:39], v[176:179], v[204:207], v[36:39]
	v_mfma_f32_16x16x32_bf16 v[32:35], v[184:187], v[204:207], v[32:35]
	v_mfma_f32_16x16x32_bf16 v[20:23], v[176:179], v[212:215], v[20:23]
	v_mfma_f32_16x16x32_bf16 v[16:19], v[184:187], v[212:215], v[16:19]
	v_mfma_f32_16x16x32_bf16 v[4:7], v[176:179], v[220:223], v[4:7]
	v_mfma_f32_16x16x32_bf16 v[0:3], v[184:187], v[220:223], v[0:3]
	s_setprio 0
	s_barrier
	s_add_i32 s62, 0, 0x18000
	v_add_u32_e32 v136, s62, v162
	s_add_i32 s63, 0, 0x1c000
	ds_read_b128 v[150:153], v136
	ds_read_b128 v[154:157], v136 offset:1024
	ds_read_b128 v[158:161], v136 offset:2048
	ds_read_b128 v[168:171], v136 offset:3072
	v_add_u32_e32 v136, s63, v162
	ds_read_b128 v[172:175], v136
	ds_read_b128 v[176:179], v136 offset:1024
	ds_read_b128 v[180:183], v136 offset:2048
	ds_read_b128 v[184:187], v136 offset:3072
	s_add_u32 s36, s36, 0x40000
	s_addc_u32 s37, s37, 0
	s_mov_b32 m0, s47
	v_lshl_add_u64 v[230:231], s[36:37], 0, v[134:135]
	ds_read_b128 v[192:195], v165 offset:32768
	ds_read_b128 v[196:199], v165 offset:33792
	ds_read_b128 v[200:203], v165 offset:34816
	ds_read_b128 v[204:207], v165 offset:35840
	ds_read_b128 v[208:211], v165 offset:36864
	ds_read_b128 v[212:215], v165 offset:37888
	ds_read_b128 v[216:219], v165 offset:38912
	ds_read_b128 v[220:223], v165 offset:39936
	global_load_lds_dwordx4 v[230:231], off
	v_lshl_add_u64 v[230:231], s[36:37], 0, v[130:131]
	s_mov_b32 m0, s48
	s_nop 0
	global_load_lds_dwordx4 v[230:231], off
	s_waitcnt vmcnt(8)
	s_waitcnt lgkmcnt(0)
	s_barrier
	s_setprio 1
	s_waitcnt lgkmcnt(0)
	v_mfma_f32_16x16x32_bf16 v[124:127], v[150:153], v[192:195], v[124:127]
	v_mfma_f32_16x16x32_bf16 v[120:123], v[158:161], v[192:195], v[120:123]
	v_mfma_f32_16x16x32_bf16 v[108:111], v[150:153], v[200:203], v[108:111]
	v_mfma_f32_16x16x32_bf16 v[104:107], v[158:161], v[200:203], v[104:107]
	v_mfma_f32_16x16x32_bf16 v[92:95], v[150:153], v[208:211], v[92:95]
	v_mfma_f32_16x16x32_bf16 v[88:91], v[158:161], v[208:211], v[88:91]
	v_mfma_f32_16x16x32_bf16 v[76:79], v[150:153], v[216:219], v[76:79]
	v_mfma_f32_16x16x32_bf16 v[72:75], v[158:161], v[216:219], v[72:75]
	v_mfma_f32_16x16x32_bf16 v[124:127], v[154:157], v[196:199], v[124:127]
	v_mfma_f32_16x16x32_bf16 v[120:123], v[168:171], v[196:199], v[120:123]
	v_mfma_f32_16x16x32_bf16 v[108:111], v[154:157], v[204:207], v[108:111]
	v_mfma_f32_16x16x32_bf16 v[104:107], v[168:171], v[204:207], v[104:107]
	v_mfma_f32_16x16x32_bf16 v[92:95], v[154:157], v[212:215], v[92:95]
	v_mfma_f32_16x16x32_bf16 v[88:91], v[168:171], v[212:215], v[88:91]
	v_mfma_f32_16x16x32_bf16 v[76:79], v[154:157], v[220:223], v[76:79]
	v_mfma_f32_16x16x32_bf16 v[72:75], v[168:171], v[220:223], v[72:75]
	s_setprio 0
	s_setprio 1
	v_mfma_f32_16x16x32_bf16 v[116:119], v[172:175], v[192:195], v[116:119]
	v_mfma_f32_16x16x32_bf16 v[112:115], v[180:183], v[192:195], v[112:115]
	v_mfma_f32_16x16x32_bf16 v[100:103], v[172:175], v[200:203], v[100:103]
	v_mfma_f32_16x16x32_bf16 v[96:99], v[180:183], v[200:203], v[96:99]
	v_mfma_f32_16x16x32_bf16 v[84:87], v[172:175], v[208:211], v[84:87]
	v_mfma_f32_16x16x32_bf16 v[80:83], v[180:183], v[208:211], v[80:83]
	v_mfma_f32_16x16x32_bf16 v[68:71], v[172:175], v[216:219], v[68:71]
	v_mfma_f32_16x16x32_bf16 v[64:67], v[180:183], v[216:219], v[64:67]
	v_mfma_f32_16x16x32_bf16 v[116:119], v[176:179], v[196:199], v[116:119]
	v_mfma_f32_16x16x32_bf16 v[112:115], v[184:187], v[196:199], v[112:115]
	v_mfma_f32_16x16x32_bf16 v[100:103], v[176:179], v[204:207], v[100:103]
	v_mfma_f32_16x16x32_bf16 v[96:99], v[184:187], v[204:207], v[96:99]
	v_mfma_f32_16x16x32_bf16 v[84:87], v[176:179], v[212:215], v[84:87]
	v_mfma_f32_16x16x32_bf16 v[80:83], v[184:187], v[212:215], v[80:83]
	v_mfma_f32_16x16x32_bf16 v[68:71], v[176:179], v[220:223], v[68:71]
	v_mfma_f32_16x16x32_bf16 v[64:67], v[184:187], v[220:223], v[64:67]
	s_setprio 0
	s_barrier
	s_add_i32 s36, s62, s42
	v_lshl_add_u64 v[188:189], v[188:189], 0, s[16:17]
	s_mov_b32 m0, s36
	ds_read_b128 v[192:195], v165 offset:49152
	ds_read_b128 v[196:199], v165 offset:50176
	ds_read_b128 v[200:203], v165 offset:51200
	ds_read_b128 v[204:207], v165 offset:52224
	ds_read_b128 v[208:211], v165 offset:53248
	ds_read_b128 v[212:215], v165 offset:54272
	ds_read_b128 v[216:219], v165 offset:55296
	ds_read_b128 v[220:223], v165 offset:56320
	global_load_lds_dwordx4 v[188:189], off
	s_add_i32 m0, s36, 0x2000
	s_add_u32 s34, s34, 0x40080
	v_lshl_add_u64 v[188:189], v[224:225], 0, s[16:17]
	s_addc_u32 s35, s35, 0
	s_add_i32 s36, s63, s42
	global_load_lds_dwordx4 v[188:189], off
	v_lshl_add_u64 v[188:189], s[34:35], 0, v[132:133]
	s_mov_b32 m0, s36
	s_nop 0
	global_load_lds_dwordx4 v[188:189], off
	v_lshl_add_u64 v[188:189], s[34:35], 0, v[128:129]
	s_add_i32 m0, s36, 0x2000
	s_nop 0
	global_load_lds_dwordx4 v[188:189], off
	v_lshl_add_u64 v[188:189], v[226:227], 0, s[16:17]
	s_mov_b32 m0, s49
	s_nop 0
	global_load_lds_dwordx4 v[188:189], off
	v_lshl_add_u64 v[188:189], v[228:229], 0, s[16:17]
	s_mov_b32 m0, s50
	s_nop 0
	global_load_lds_dwordx4 v[188:189], off
	s_waitcnt vmcnt(8)
	s_waitcnt lgkmcnt(0)
	s_barrier
	s_setprio 1
	s_waitcnt lgkmcnt(0)
	v_mfma_f32_16x16x32_bf16 v[60:63], v[150:153], v[192:195], v[60:63]
	v_mfma_f32_16x16x32_bf16 v[56:59], v[158:161], v[192:195], v[56:59]
	v_mfma_f32_16x16x32_bf16 v[44:47], v[150:153], v[200:203], v[44:47]
	v_mfma_f32_16x16x32_bf16 v[40:43], v[158:161], v[200:203], v[40:43]
	v_mfma_f32_16x16x32_bf16 v[28:31], v[150:153], v[208:211], v[28:31]
	v_mfma_f32_16x16x32_bf16 v[24:27], v[158:161], v[208:211], v[24:27]
	v_mfma_f32_16x16x32_bf16 v[12:15], v[150:153], v[216:219], v[12:15]
	v_mfma_f32_16x16x32_bf16 v[8:11], v[158:161], v[216:219], v[8:11]
	v_mfma_f32_16x16x32_bf16 v[60:63], v[154:157], v[196:199], v[60:63]
	v_mfma_f32_16x16x32_bf16 v[56:59], v[168:171], v[196:199], v[56:59]
	v_mfma_f32_16x16x32_bf16 v[44:47], v[154:157], v[204:207], v[44:47]
	v_mfma_f32_16x16x32_bf16 v[40:43], v[168:171], v[204:207], v[40:43]
	v_mfma_f32_16x16x32_bf16 v[28:31], v[154:157], v[212:215], v[28:31]
	v_mfma_f32_16x16x32_bf16 v[24:27], v[168:171], v[212:215], v[24:27]
	v_mfma_f32_16x16x32_bf16 v[12:15], v[154:157], v[220:223], v[12:15]
	v_mfma_f32_16x16x32_bf16 v[8:11], v[168:171], v[220:223], v[8:11]
	s_setprio 0
	s_setprio 1
	v_mfma_f32_16x16x32_bf16 v[52:55], v[172:175], v[192:195], v[52:55]
	v_mfma_f32_16x16x32_bf16 v[48:51], v[180:183], v[192:195], v[48:51]
	v_mfma_f32_16x16x32_bf16 v[36:39], v[172:175], v[200:203], v[36:39]
	v_mfma_f32_16x16x32_bf16 v[32:35], v[180:183], v[200:203], v[32:35]
	v_mfma_f32_16x16x32_bf16 v[20:23], v[172:175], v[208:211], v[20:23]
	v_mfma_f32_16x16x32_bf16 v[16:19], v[180:183], v[208:211], v[16:19]
	v_mfma_f32_16x16x32_bf16 v[4:7], v[172:175], v[216:219], v[4:7]
	v_mfma_f32_16x16x32_bf16 v[0:3], v[180:183], v[216:219], v[0:3]
	v_mfma_f32_16x16x32_bf16 v[52:55], v[176:179], v[196:199], v[52:55]
	v_mfma_f32_16x16x32_bf16 v[48:51], v[184:187], v[196:199], v[48:51]
	v_mfma_f32_16x16x32_bf16 v[36:39], v[176:179], v[204:207], v[36:39]
	v_mfma_f32_16x16x32_bf16 v[32:35], v[184:187], v[204:207], v[32:35]
	v_mfma_f32_16x16x32_bf16 v[20:23], v[176:179], v[212:215], v[20:23]
	v_mfma_f32_16x16x32_bf16 v[16:19], v[184:187], v[212:215], v[16:19]
	v_mfma_f32_16x16x32_bf16 v[4:7], v[176:179], v[220:223], v[4:7]
	v_mfma_f32_16x16x32_bf16 v[0:3], v[184:187], v[220:223], v[0:3]
	s_setprio 0
	s_barrier
	s_add_i32 s61, s61, 2
	s_add_u32 s33, s33, 0x100
	s_addc_u32 s60, s60, 0
	s_add_u32 s30, s30, 0x100
	s_addc_u32 s31, s31, 0
	s_cmp_gt_u32 s61, 13
	s_cbranch_scc0 .LBB0_1917
	v_lshl_add_u32 v214, s0, 8, v139
	v_ashrrev_i32_e32 v215, 31, v214
	v_lshl_add_u64 v[212:213], v[214:215], 2, s[14:15]
	global_load_dword v204, v[212:213], off
	global_load_dword v205, v[212:213], off offset:64
	global_load_dword v206, v[212:213], off offset:128
	global_load_dword v207, v[212:213], off offset:192
	global_load_dword v208, v[212:213], off offset:512
	global_load_dword v209, v[212:213], off offset:576
	global_load_dword v210, v[212:213], off offset:640
	global_load_dword v211, v[212:213], off offset:704
	s_and_b64 vcc, exec, s[18:19]
	s_cbranch_vccz .LBB0_1920
	s_barrier

.LBB0_1923:
	v_lshl_add_u64 v[158:159], v[156:157], 2, s[14:15]
	v_mov_b64_e32 v[160:161], s[12:13]
	s_lshl_b32 s8, s1, 8
	v_mad_i64_i32 v[168:169], s[30:31], v156, s56, v[160:161]
	s_mov_b32 s21, s9
	v_lshl_add_u64 v[168:169], v[168:169], 0, s[8:9]
	v_mov_b32_e32 v149, v137
	v_lshl_add_u64 v[168:169], v[168:169], 0, s[20:21]
	v_lshl_add_u64 v[174:175], v[168:169], 0, v[148:149]
	v_lshl_add_u64 v[172:173], v[154:155], 2, s[14:15]
	s_waitcnt vmcnt(0) lgkmcnt(0)
	v_fmamk_f32 v136, v204, 0x3a800000, v166
	v_mul_f32_e32 v167, 0x4b800000, v136
	v_cmp_gt_f32_e32 vcc, s55, v136
	s_nop 1
	v_cndmask_b32_e32 v136, v136, v167, vcc
	v_rsq_f32_e32 v136, v136
	s_nop 0
	v_mul_f32_e32 v167, 0x45800000, v136
	v_cndmask_b32_e32 v136, v136, v167, vcc
	v_pk_mul_f32 v[168:169], v[126:127], v[136:137] op_sel_hi:[1,0]
	v_pk_mul_f32 v[170:171], v[124:125], v[136:137] op_sel_hi:[1,0]
	v_pk_mul_f32 v[176:177], v[122:123], v[136:137] op_sel_hi:[1,0]
	v_pk_mul_f32 v[178:179], v[120:121], v[136:137] op_sel_hi:[1,0]
	v_pk_mul_f32 v[180:181], v[118:119], v[136:137] op_sel_hi:[1,0]
	v_pk_mul_f32 v[182:183], v[116:117], v[136:137] op_sel_hi:[1,0]
	v_pk_mul_f32 v[184:185], v[114:115], v[136:137] op_sel_hi:[1,0]
	v_pk_mul_f32 v[186:187], v[112:113], v[136:137] op_sel_hi:[1,0]
	v_mul_f32_e32 v136, 0xbfb8aa3b, v170
	v_mul_f32_e32 v167, 0xbfb8aa3b, v171
	v_mul_f32_e32 v188, 0xbfb8aa3b, v168
	v_mul_f32_e32 v189, 0xbfb8aa3b, v169
	v_mul_f32_e32 v191, 0xbfb8aa3b, v178
	v_mul_f32_e32 v192, 0xbfb8aa3b, v179
	v_mul_f32_e32 v193, 0xbfb8aa3b, v176
	v_mul_f32_e32 v194, 0xbfb8aa3b, v177
	v_exp_f32_e32 v136, v136
	v_exp_f32_e32 v167, v167
	v_exp_f32_e32 v188, v188
	v_exp_f32_e32 v189, v189
	v_exp_f32_e32 v191, v191
	v_exp_f32_e32 v192, v192
	v_exp_f32_e32 v193, v193
	v_exp_f32_e32 v194, v194
	v_add_f32_e32 v136, 1.0, v136
	v_add_f32_e32 v167, 1.0, v167
	v_add_f32_e32 v195, 1.0, v188
	v_add_f32_e32 v196, 1.0, v189
	v_add_f32_e32 v191, 1.0, v191
	v_add_f32_e32 v197, 1.0, v192
	v_add_f32_e32 v198, 1.0, v193
	v_add_f32_e32 v199, 1.0, v194
	v_rcp_f32_e32 v188, v136
	v_rcp_f32_e32 v189, v167
	v_rcp_f32_e32 v192, v195
	v_rcp_f32_e32 v193, v196
	v_rcp_f32_e32 v194, v191
	v_rcp_f32_e32 v195, v197
	v_rcp_f32_e32 v196, v198
	v_rcp_f32_e32 v197, v199
	v_pk_mul_f32 v[170:171], v[170:171], v[188:189]
	v_pk_mul_f32 v[168:169], v[168:169], v[192:193]
	v_pk_mul_f32 v[178:179], v[178:179], v[194:195]
	v_pk_mul_f32 v[176:177], v[176:177], v[196:197]
	v_pk_mul_f32 v[170:171], v[182:183], v[170:171]
	v_pk_mul_f32 v[180:181], v[180:181], v[168:169]
	v_pk_mul_f32 v[178:179], v[186:187], v[178:179]
	v_pk_mul_f32 v[176:177], v[184:185], v[176:177]
	v_cvt_pk_bf16_f32 v168, v170, v171
	v_cvt_pk_bf16_f32 v169, v180, v181
	v_cvt_pk_bf16_f32 v170, v178, v179
	v_cvt_pk_bf16_f32 v171, v176, v177
	global_store_dwordx4 v[174:175], v[168:171], off
	s_nop 1
	v_lshl_add_u64 v[172:173], v[152:153], 2, s[14:15]
	v_mad_i64_i32 v[168:169], s[30:31], v154, s56, v[160:161]
	v_lshl_add_u64 v[168:169], v[168:169], 0, s[8:9]
	v_lshl_add_u64 v[168:169], v[168:169], 0, s[20:21]
	v_lshl_add_u64 v[174:175], v[168:169], 0, v[148:149]
	v_fmamk_f32 v136, v205, 0x3a800000, v166
	v_mul_f32_e32 v167, 0x4b800000, v136
	v_cmp_gt_f32_e32 vcc, s55, v136
	s_nop 1
	v_cndmask_b32_e32 v136, v136, v167, vcc
	v_rsq_f32_e32 v136, v136
	s_nop 0
	v_mul_f32_e32 v167, 0x45800000, v136
	v_cndmask_b32_e32 v136, v136, v167, vcc
	v_pk_mul_f32 v[168:169], v[110:111], v[136:137] op_sel_hi:[1,0]
	v_pk_mul_f32 v[170:171], v[108:109], v[136:137] op_sel_hi:[1,0]
	v_pk_mul_f32 v[176:177], v[106:107], v[136:137] op_sel_hi:[1,0]
	v_pk_mul_f32 v[178:179], v[104:105], v[136:137] op_sel_hi:[1,0]
	v_pk_mul_f32 v[180:181], v[102:103], v[136:137] op_sel_hi:[1,0]
	v_pk_mul_f32 v[182:183], v[100:101], v[136:137] op_sel_hi:[1,0]
	v_pk_mul_f32 v[184:185], v[98:99], v[136:137] op_sel_hi:[1,0]
	v_pk_mul_f32 v[186:187], v[96:97], v[136:137] op_sel_hi:[1,0]
	v_mul_f32_e32 v136, 0xbfb8aa3b, v170
	v_mul_f32_e32 v167, 0xbfb8aa3b, v171
	v_mul_f32_e32 v188, 0xbfb8aa3b, v168
	v_mul_f32_e32 v189, 0xbfb8aa3b, v169
	v_mul_f32_e32 v191, 0xbfb8aa3b, v178
	v_mul_f32_e32 v192, 0xbfb8aa3b, v179
	v_mul_f32_e32 v193, 0xbfb8aa3b, v176
	v_mul_f32_e32 v194, 0xbfb8aa3b, v177
	v_exp_f32_e32 v136, v136
	v_exp_f32_e32 v167, v167
	v_exp_f32_e32 v188, v188
	v_exp_f32_e32 v189, v189
	v_exp_f32_e32 v191, v191
	v_exp_f32_e32 v192, v192
	v_exp_f32_e32 v193, v193
	v_exp_f32_e32 v194, v194
	v_add_f32_e32 v136, 1.0, v136
	v_add_f32_e32 v167, 1.0, v167
	v_add_f32_e32 v195, 1.0, v188
	v_add_f32_e32 v196, 1.0, v189
	v_add_f32_e32 v191, 1.0, v191
	v_add_f32_e32 v197, 1.0, v192
	v_add_f32_e32 v198, 1.0, v193
	v_add_f32_e32 v199, 1.0, v194
	v_rcp_f32_e32 v188, v136
	v_rcp_f32_e32 v189, v167
	v_rcp_f32_e32 v192, v195
	v_rcp_f32_e32 v193, v196
	v_rcp_f32_e32 v194, v191
	v_rcp_f32_e32 v195, v197
	v_rcp_f32_e32 v196, v198
	v_rcp_f32_e32 v197, v199
	v_pk_mul_f32 v[170:171], v[170:171], v[188:189]
	v_pk_mul_f32 v[168:169], v[168:169], v[192:193]
	v_pk_mul_f32 v[178:179], v[178:179], v[194:195]
	v_pk_mul_f32 v[176:177], v[176:177], v[196:197]
	v_pk_mul_f32 v[170:171], v[182:183], v[170:171]
	v_pk_mul_f32 v[180:181], v[180:181], v[168:169]
	v_pk_mul_f32 v[178:179], v[186:187], v[178:179]
	v_pk_mul_f32 v[176:177], v[184:185], v[176:177]
	v_cvt_pk_bf16_f32 v168, v170, v171
	v_cvt_pk_bf16_f32 v169, v180, v181
	v_cvt_pk_bf16_f32 v170, v178, v179
	v_cvt_pk_bf16_f32 v171, v176, v177
	global_store_dwordx4 v[174:175], v[168:171], off
	s_nop 1
	v_lshl_add_u64 v[172:173], v[150:151], 2, s[14:15]
	v_mad_i64_i32 v[168:169], s[30:31], v152, s56, v[160:161]
	v_lshl_add_u64 v[168:169], v[168:169], 0, s[8:9]
	v_lshl_add_u64 v[168:169], v[168:169], 0, s[20:21]
	v_lshl_add_u64 v[174:175], v[168:169], 0, v[148:149]
	v_fmamk_f32 v136, v206, 0x3a800000, v166
	v_mul_f32_e32 v167, 0x4b800000, v136
	v_cmp_gt_f32_e32 vcc, s55, v136
	s_nop 1
	v_cndmask_b32_e32 v136, v136, v167, vcc
	v_rsq_f32_e32 v136, v136
	s_nop 0
	v_mul_f32_e32 v167, 0x45800000, v136
	v_cndmask_b32_e32 v136, v136, v167, vcc
	v_pk_mul_f32 v[168:169], v[94:95], v[136:137] op_sel_hi:[1,0]
	v_pk_mul_f32 v[170:171], v[92:93], v[136:137] op_sel_hi:[1,0]
	v_pk_mul_f32 v[176:177], v[90:91], v[136:137] op_sel_hi:[1,0]
	v_pk_mul_f32 v[178:179], v[88:89], v[136:137] op_sel_hi:[1,0]
	v_pk_mul_f32 v[180:181], v[86:87], v[136:137] op_sel_hi:[1,0]
	v_pk_mul_f32 v[182:183], v[84:85], v[136:137] op_sel_hi:[1,0]
	v_pk_mul_f32 v[184:185], v[82:83], v[136:137] op_sel_hi:[1,0]
	v_pk_mul_f32 v[186:187], v[80:81], v[136:137] op_sel_hi:[1,0]
	v_mul_f32_e32 v136, 0xbfb8aa3b, v170
	v_mul_f32_e32 v167, 0xbfb8aa3b, v171
	v_mul_f32_e32 v188, 0xbfb8aa3b, v168
	v_mul_f32_e32 v189, 0xbfb8aa3b, v169
	v_mul_f32_e32 v191, 0xbfb8aa3b, v178
	v_mul_f32_e32 v192, 0xbfb8aa3b, v179
	v_mul_f32_e32 v193, 0xbfb8aa3b, v176
	v_mul_f32_e32 v194, 0xbfb8aa3b, v177
	v_exp_f32_e32 v136, v136
	v_exp_f32_e32 v167, v167
	v_exp_f32_e32 v188, v188
	v_exp_f32_e32 v189, v189
	v_exp_f32_e32 v191, v191
	v_exp_f32_e32 v192, v192
	v_exp_f32_e32 v193, v193
	v_exp_f32_e32 v194, v194
	v_add_f32_e32 v136, 1.0, v136
	v_add_f32_e32 v167, 1.0, v167
	v_add_f32_e32 v195, 1.0, v188
	v_add_f32_e32 v196, 1.0, v189
	v_add_f32_e32 v191, 1.0, v191
	v_add_f32_e32 v197, 1.0, v192
	v_add_f32_e32 v198, 1.0, v193
	v_add_f32_e32 v199, 1.0, v194
	v_rcp_f32_e32 v188, v136
	v_rcp_f32_e32 v189, v167
	v_rcp_f32_e32 v192, v195
	v_rcp_f32_e32 v193, v196
	v_rcp_f32_e32 v194, v191
	v_rcp_f32_e32 v195, v197
	v_rcp_f32_e32 v196, v198
	v_rcp_f32_e32 v197, v199
	v_pk_mul_f32 v[170:171], v[170:171], v[188:189]
	v_pk_mul_f32 v[168:169], v[168:169], v[192:193]
	v_pk_mul_f32 v[178:179], v[178:179], v[194:195]
	v_pk_mul_f32 v[176:177], v[176:177], v[196:197]
	v_pk_mul_f32 v[170:171], v[182:183], v[170:171]
	v_pk_mul_f32 v[180:181], v[180:181], v[168:169]
	v_pk_mul_f32 v[178:179], v[186:187], v[178:179]
	v_pk_mul_f32 v[176:177], v[184:185], v[176:177]
	v_cvt_pk_bf16_f32 v168, v170, v171
	v_cvt_pk_bf16_f32 v169, v180, v181
	v_cvt_pk_bf16_f32 v170, v178, v179
	v_cvt_pk_bf16_f32 v171, v176, v177
	global_store_dwordx4 v[174:175], v[168:171], off
	s_nop 1
	v_fmamk_f32 v136, v207, 0x3a800000, v166
	v_mul_f32_e32 v167, 0x4b800000, v136
	v_cmp_gt_f32_e32 vcc, s55, v136
	v_mad_i64_i32 v[168:169], s[30:31], v150, s56, v[160:161]
	s_nop 0
	v_cndmask_b32_e32 v136, v136, v167, vcc
	v_rsq_f32_e32 v136, v136
	v_lshl_add_u64 v[168:169], v[168:169], 0, s[8:9]
	v_lshl_add_u64 v[168:169], v[168:169], 0, s[20:21]
	v_lshl_add_u64 v[172:173], v[168:169], 0, v[148:149]
	v_mul_f32_e32 v167, 0x45800000, v136
	v_cndmask_b32_e32 v136, v136, v167, vcc
	v_pk_mul_f32 v[168:169], v[78:79], v[136:137] op_sel_hi:[1,0]
	v_pk_mul_f32 v[170:171], v[76:77], v[136:137] op_sel_hi:[1,0]
	v_pk_mul_f32 v[174:175], v[74:75], v[136:137] op_sel_hi:[1,0]
	v_pk_mul_f32 v[176:177], v[72:73], v[136:137] op_sel_hi:[1,0]
	v_pk_mul_f32 v[178:179], v[70:71], v[136:137] op_sel_hi:[1,0]
	v_pk_mul_f32 v[180:181], v[68:69], v[136:137] op_sel_hi:[1,0]
	v_pk_mul_f32 v[182:183], v[66:67], v[136:137] op_sel_hi:[1,0]
	v_pk_mul_f32 v[184:185], v[64:65], v[136:137] op_sel_hi:[1,0]
	v_mul_f32_e32 v136, 0xbfb8aa3b, v170
	v_mul_f32_e32 v167, 0xbfb8aa3b, v171
	v_mul_f32_e32 v186, 0xbfb8aa3b, v168
	v_mul_f32_e32 v187, 0xbfb8aa3b, v169
	v_mul_f32_e32 v188, 0xbfb8aa3b, v176
	v_mul_f32_e32 v189, 0xbfb8aa3b, v177
	v_mul_f32_e32 v191, 0xbfb8aa3b, v174
	v_mul_f32_e32 v192, 0xbfb8aa3b, v175
	v_exp_f32_e32 v136, v136
	v_exp_f32_e32 v167, v167
	v_exp_f32_e32 v186, v186
	v_exp_f32_e32 v187, v187
	v_exp_f32_e32 v188, v188
	v_exp_f32_e32 v189, v189
	v_exp_f32_e32 v191, v191
	v_exp_f32_e32 v192, v192
	v_add_f32_e32 v136, 1.0, v136
	v_add_f32_e32 v167, 1.0, v167
	v_add_f32_e32 v193, 1.0, v186
	v_add_f32_e32 v194, 1.0, v187
	v_add_f32_e32 v195, 1.0, v188
	v_add_f32_e32 v196, 1.0, v189
	v_add_f32_e32 v191, 1.0, v191
	v_add_f32_e32 v197, 1.0, v192
	v_rcp_f32_e32 v186, v136
	v_rcp_f32_e32 v187, v167
	v_rcp_f32_e32 v188, v193
	v_rcp_f32_e32 v189, v194
	v_rcp_f32_e32 v192, v195
	v_rcp_f32_e32 v193, v196
	v_rcp_f32_e32 v194, v191
	v_rcp_f32_e32 v195, v197
	v_pk_mul_f32 v[170:171], v[170:171], v[186:187]
	v_pk_mul_f32 v[168:169], v[168:169], v[188:189]
	v_pk_mul_f32 v[176:177], v[176:177], v[192:193]
	v_pk_mul_f32 v[174:175], v[174:175], v[194:195]
	v_pk_mul_f32 v[170:171], v[180:181], v[170:171]
	v_pk_mul_f32 v[178:179], v[178:179], v[168:169]
	v_pk_mul_f32 v[176:177], v[184:185], v[176:177]
	v_pk_mul_f32 v[174:175], v[182:183], v[174:175]
	v_cvt_pk_bf16_f32 v168, v170, v171
	v_cvt_pk_bf16_f32 v169, v178, v179
	v_cvt_pk_bf16_f32 v170, v176, v177
	v_cvt_pk_bf16_f32 v171, v174, v175
	global_store_dwordx4 v[172:173], v[168:171], off
	s_nop 1
	v_add_u32_e32 v167, 0x80, v156
	v_mad_i64_i32 v[168:169], s[30:31], v167, s56, v[160:161]
	v_lshl_add_u64 v[168:169], v[168:169], 0, s[8:9]
	v_lshl_add_u64 v[168:169], v[168:169], 0, s[20:21]
	v_lshl_add_u64 v[172:173], v[168:169], 0, v[148:149]
	v_fmamk_f32 v136, v208, 0x3a800000, v166
	v_mul_f32_e32 v167, 0x4b800000, v136
	v_cmp_gt_f32_e32 vcc, s55, v136
	s_nop 1
	v_cndmask_b32_e32 v136, v136, v167, vcc
	v_rsq_f32_e32 v136, v136
	s_nop 0
	v_mul_f32_e32 v167, 0x45800000, v136
	v_cndmask_b32_e32 v136, v136, v167, vcc
	v_pk_mul_f32 v[168:169], v[62:63], v[136:137] op_sel_hi:[1,0]
	v_pk_mul_f32 v[170:171], v[60:61], v[136:137] op_sel_hi:[1,0]
	v_pk_mul_f32 v[174:175], v[58:59], v[136:137] op_sel_hi:[1,0]
	v_pk_mul_f32 v[176:177], v[56:57], v[136:137] op_sel_hi:[1,0]
	v_pk_mul_f32 v[178:179], v[54:55], v[136:137] op_sel_hi:[1,0]
	v_pk_mul_f32 v[180:181], v[52:53], v[136:137] op_sel_hi:[1,0]
	v_pk_mul_f32 v[182:183], v[50:51], v[136:137] op_sel_hi:[1,0]
	v_pk_mul_f32 v[184:185], v[48:49], v[136:137] op_sel_hi:[1,0]
	v_mul_f32_e32 v136, 0xbfb8aa3b, v170
	v_mul_f32_e32 v167, 0xbfb8aa3b, v171
	v_mul_f32_e32 v186, 0xbfb8aa3b, v168
	v_mul_f32_e32 v187, 0xbfb8aa3b, v169
	v_mul_f32_e32 v188, 0xbfb8aa3b, v176
	v_mul_f32_e32 v189, 0xbfb8aa3b, v177
	v_mul_f32_e32 v191, 0xbfb8aa3b, v174
	v_mul_f32_e32 v192, 0xbfb8aa3b, v175
	v_exp_f32_e32 v136, v136
	v_exp_f32_e32 v167, v167
	v_exp_f32_e32 v186, v186
	v_exp_f32_e32 v187, v187
	v_exp_f32_e32 v188, v188
	v_exp_f32_e32 v189, v189
	v_exp_f32_e32 v191, v191
	v_exp_f32_e32 v192, v192
	v_add_f32_e32 v136, 1.0, v136
	v_add_f32_e32 v167, 1.0, v167
	v_add_f32_e32 v193, 1.0, v186
	v_add_f32_e32 v194, 1.0, v187
	v_add_f32_e32 v195, 1.0, v188
	v_add_f32_e32 v196, 1.0, v189
	v_add_f32_e32 v191, 1.0, v191
	v_add_f32_e32 v197, 1.0, v192
	v_rcp_f32_e32 v186, v136
	v_rcp_f32_e32 v187, v167
	v_rcp_f32_e32 v188, v193
	v_rcp_f32_e32 v189, v194
	v_rcp_f32_e32 v192, v195
	v_rcp_f32_e32 v193, v196
	v_rcp_f32_e32 v194, v191
	v_rcp_f32_e32 v195, v197
	v_pk_mul_f32 v[170:171], v[170:171], v[186:187]
	v_pk_mul_f32 v[168:169], v[168:169], v[188:189]
	v_pk_mul_f32 v[176:177], v[176:177], v[192:193]
	v_pk_mul_f32 v[174:175], v[174:175], v[194:195]
	v_pk_mul_f32 v[170:171], v[180:181], v[170:171]
	v_pk_mul_f32 v[178:179], v[178:179], v[168:169]
	v_pk_mul_f32 v[176:177], v[184:185], v[176:177]
	v_pk_mul_f32 v[174:175], v[182:183], v[174:175]
	v_cvt_pk_bf16_f32 v168, v170, v171
	v_cvt_pk_bf16_f32 v169, v178, v179
	v_cvt_pk_bf16_f32 v170, v176, v177
	v_cvt_pk_bf16_f32 v171, v174, v175
	global_store_dwordx4 v[172:173], v[168:171], off
	s_nop 1
	v_add_u32_e32 v167, 0x90, v156
	v_mad_i64_i32 v[168:169], s[30:31], v167, s56, v[160:161]
	v_lshl_add_u64 v[168:169], v[168:169], 0, s[8:9]
	v_lshl_add_u64 v[168:169], v[168:169], 0, s[20:21]
	v_lshl_add_u64 v[172:173], v[168:169], 0, v[148:149]
	v_fmamk_f32 v136, v209, 0x3a800000, v166
	v_mul_f32_e32 v167, 0x4b800000, v136
	v_cmp_gt_f32_e32 vcc, s55, v136
	s_nop 1
	v_cndmask_b32_e32 v136, v136, v167, vcc
	v_rsq_f32_e32 v136, v136
	s_nop 0
	v_mul_f32_e32 v167, 0x45800000, v136
	v_cndmask_b32_e32 v136, v136, v167, vcc
	v_pk_mul_f32 v[168:169], v[46:47], v[136:137] op_sel_hi:[1,0]
	v_pk_mul_f32 v[170:171], v[44:45], v[136:137] op_sel_hi:[1,0]
	v_pk_mul_f32 v[174:175], v[42:43], v[136:137] op_sel_hi:[1,0]
	v_pk_mul_f32 v[176:177], v[40:41], v[136:137] op_sel_hi:[1,0]
	v_pk_mul_f32 v[178:179], v[38:39], v[136:137] op_sel_hi:[1,0]
	v_pk_mul_f32 v[180:181], v[36:37], v[136:137] op_sel_hi:[1,0]
	v_pk_mul_f32 v[182:183], v[34:35], v[136:137] op_sel_hi:[1,0]
	v_pk_mul_f32 v[184:185], v[32:33], v[136:137] op_sel_hi:[1,0]
	v_mul_f32_e32 v136, 0xbfb8aa3b, v170
	v_mul_f32_e32 v167, 0xbfb8aa3b, v171
	v_mul_f32_e32 v186, 0xbfb8aa3b, v168
	v_mul_f32_e32 v187, 0xbfb8aa3b, v169
	v_mul_f32_e32 v188, 0xbfb8aa3b, v176
	v_mul_f32_e32 v189, 0xbfb8aa3b, v177
	v_mul_f32_e32 v191, 0xbfb8aa3b, v174
	v_mul_f32_e32 v192, 0xbfb8aa3b, v175
	v_exp_f32_e32 v136, v136
	v_exp_f32_e32 v167, v167
	v_exp_f32_e32 v186, v186
	v_exp_f32_e32 v187, v187
	v_exp_f32_e32 v188, v188
	v_exp_f32_e32 v189, v189
	v_exp_f32_e32 v191, v191
	v_exp_f32_e32 v192, v192
	v_add_f32_e32 v136, 1.0, v136
	v_add_f32_e32 v167, 1.0, v167
	v_add_f32_e32 v193, 1.0, v186
	v_add_f32_e32 v194, 1.0, v187
	v_add_f32_e32 v195, 1.0, v188
	v_add_f32_e32 v196, 1.0, v189
	v_add_f32_e32 v191, 1.0, v191
	v_add_f32_e32 v197, 1.0, v192
	v_rcp_f32_e32 v186, v136
	v_rcp_f32_e32 v187, v167
	v_rcp_f32_e32 v188, v193
	v_rcp_f32_e32 v189, v194
	v_rcp_f32_e32 v192, v195
	v_rcp_f32_e32 v193, v196
	v_rcp_f32_e32 v194, v191
	v_rcp_f32_e32 v195, v197
	v_pk_mul_f32 v[170:171], v[170:171], v[186:187]
	v_pk_mul_f32 v[168:169], v[168:169], v[188:189]
	v_pk_mul_f32 v[176:177], v[176:177], v[192:193]
	v_pk_mul_f32 v[174:175], v[174:175], v[194:195]
	v_pk_mul_f32 v[170:171], v[180:181], v[170:171]
	v_pk_mul_f32 v[178:179], v[178:179], v[168:169]
	v_pk_mul_f32 v[176:177], v[184:185], v[176:177]
	v_pk_mul_f32 v[174:175], v[182:183], v[174:175]
	v_cvt_pk_bf16_f32 v168, v170, v171
	v_cvt_pk_bf16_f32 v169, v178, v179
	v_cvt_pk_bf16_f32 v170, v176, v177
	v_cvt_pk_bf16_f32 v171, v174, v175
	global_store_dwordx4 v[172:173], v[168:171], off
	s_nop 1
	v_add_u32_e32 v167, 0xa0, v156
	v_mad_i64_i32 v[168:169], s[30:31], v167, s56, v[160:161]
	v_lshl_add_u64 v[168:169], v[168:169], 0, s[8:9]
	v_lshl_add_u64 v[168:169], v[168:169], 0, s[20:21]
	v_lshl_add_u64 v[172:173], v[168:169], 0, v[148:149]
	v_fmamk_f32 v136, v210, 0x3a800000, v166
	v_mul_f32_e32 v167, 0x4b800000, v136
	v_cmp_gt_f32_e32 vcc, s55, v136
	s_nop 1
	v_cndmask_b32_e32 v136, v136, v167, vcc
	v_rsq_f32_e32 v136, v136
	s_nop 0
	v_mul_f32_e32 v167, 0x45800000, v136
	v_cndmask_b32_e32 v136, v136, v167, vcc
	v_pk_mul_f32 v[168:169], v[30:31], v[136:137] op_sel_hi:[1,0]
	v_pk_mul_f32 v[170:171], v[28:29], v[136:137] op_sel_hi:[1,0]
	v_pk_mul_f32 v[174:175], v[26:27], v[136:137] op_sel_hi:[1,0]
	v_pk_mul_f32 v[176:177], v[24:25], v[136:137] op_sel_hi:[1,0]
	v_pk_mul_f32 v[178:179], v[22:23], v[136:137] op_sel_hi:[1,0]
	v_pk_mul_f32 v[180:181], v[20:21], v[136:137] op_sel_hi:[1,0]
	v_pk_mul_f32 v[182:183], v[18:19], v[136:137] op_sel_hi:[1,0]
	v_pk_mul_f32 v[184:185], v[16:17], v[136:137] op_sel_hi:[1,0]
	v_mul_f32_e32 v136, 0xbfb8aa3b, v170
	v_mul_f32_e32 v167, 0xbfb8aa3b, v171
	v_mul_f32_e32 v186, 0xbfb8aa3b, v168
	v_mul_f32_e32 v187, 0xbfb8aa3b, v169
	v_mul_f32_e32 v188, 0xbfb8aa3b, v176
	v_mul_f32_e32 v189, 0xbfb8aa3b, v177
	v_mul_f32_e32 v191, 0xbfb8aa3b, v174
	v_mul_f32_e32 v192, 0xbfb8aa3b, v175
	v_exp_f32_e32 v136, v136
	v_exp_f32_e32 v167, v167
	v_exp_f32_e32 v186, v186
	v_exp_f32_e32 v187, v187
	v_exp_f32_e32 v188, v188
	v_exp_f32_e32 v189, v189
	v_exp_f32_e32 v191, v191
	v_exp_f32_e32 v192, v192
	v_add_f32_e32 v136, 1.0, v136
	v_add_f32_e32 v167, 1.0, v167
	v_add_f32_e32 v193, 1.0, v186
	v_add_f32_e32 v194, 1.0, v187
	v_add_f32_e32 v195, 1.0, v188
	v_add_f32_e32 v196, 1.0, v189
	v_add_f32_e32 v191, 1.0, v191
	v_add_f32_e32 v197, 1.0, v192
	v_rcp_f32_e32 v186, v136
	v_rcp_f32_e32 v187, v167
	v_rcp_f32_e32 v188, v193
	v_rcp_f32_e32 v189, v194
	v_rcp_f32_e32 v192, v195
	v_rcp_f32_e32 v193, v196
	v_rcp_f32_e32 v194, v191
	v_rcp_f32_e32 v195, v197
	v_pk_mul_f32 v[170:171], v[170:171], v[186:187]
	v_pk_mul_f32 v[168:169], v[168:169], v[188:189]
	v_pk_mul_f32 v[176:177], v[176:177], v[192:193]
	v_pk_mul_f32 v[174:175], v[174:175], v[194:195]
	v_pk_mul_f32 v[170:171], v[180:181], v[170:171]
	v_pk_mul_f32 v[178:179], v[178:179], v[168:169]
	v_pk_mul_f32 v[176:177], v[184:185], v[176:177]
	v_pk_mul_f32 v[174:175], v[182:183], v[174:175]
	v_cvt_pk_bf16_f32 v168, v170, v171
	v_cvt_pk_bf16_f32 v169, v178, v179
	v_cvt_pk_bf16_f32 v170, v176, v177
	v_cvt_pk_bf16_f32 v171, v174, v175
	global_store_dwordx4 v[172:173], v[168:171], off
	s_nop 1
	v_add_u32_e32 v158, 0xb0, v156
	v_mad_i64_i32 v[158:159], s[30:31], v158, s56, v[160:161]
	v_lshl_add_u64 v[158:159], v[158:159], 0, s[8:9]
	v_lshl_add_u64 v[158:159], v[158:159], 0, s[20:21]
	v_lshl_add_u64 v[168:169], v[158:159], 0, v[148:149]
	v_fmamk_f32 v136, v211, 0x3a800000, v166
	v_mul_f32_e32 v160, 0x4b800000, v136
	v_cmp_gt_f32_e32 vcc, s55, v136
	s_nop 1
	v_cndmask_b32_e32 v136, v136, v160, vcc
	v_rsq_f32_e32 v136, v136
	s_nop 0
	v_mul_f32_e32 v149, 0x45800000, v136
	v_cndmask_b32_e32 v136, v136, v149, vcc
	v_pk_mul_f32 v[158:159], v[14:15], v[136:137] op_sel_hi:[1,0]
	v_pk_mul_f32 v[160:161], v[12:13], v[136:137] op_sel_hi:[1,0]
	v_pk_mul_f32 v[170:171], v[10:11], v[136:137] op_sel_hi:[1,0]
	v_pk_mul_f32 v[172:173], v[8:9], v[136:137] op_sel_hi:[1,0]
	v_pk_mul_f32 v[174:175], v[6:7], v[136:137] op_sel_hi:[1,0]
	v_pk_mul_f32 v[176:177], v[4:5], v[136:137] op_sel_hi:[1,0]
	v_pk_mul_f32 v[178:179], v[2:3], v[136:137] op_sel_hi:[1,0]
	v_pk_mul_f32 v[180:181], v[0:1], v[136:137] op_sel_hi:[1,0]
	v_mul_f32_e32 v136, 0xbfb8aa3b, v160
	v_mul_f32_e32 v149, 0xbfb8aa3b, v161
	v_mul_f32_e32 v167, 0xbfb8aa3b, v158
	v_mul_f32_e32 v182, 0xbfb8aa3b, v159
	v_mul_f32_e32 v183, 0xbfb8aa3b, v172
	v_mul_f32_e32 v184, 0xbfb8aa3b, v173
	v_mul_f32_e32 v185, 0xbfb8aa3b, v170
	v_mul_f32_e32 v186, 0xbfb8aa3b, v171
	v_exp_f32_e32 v136, v136
	v_exp_f32_e32 v149, v149
	v_exp_f32_e32 v167, v167
	v_exp_f32_e32 v182, v182
	v_exp_f32_e32 v183, v183
	v_exp_f32_e32 v184, v184
	v_exp_f32_e32 v185, v185
	v_exp_f32_e32 v186, v186
	v_add_f32_e32 v136, 1.0, v136
	v_add_f32_e32 v149, 1.0, v149
	v_add_f32_e32 v167, 1.0, v167
	v_add_f32_e32 v187, 1.0, v182
	v_add_f32_e32 v188, 1.0, v183
	v_add_f32_e32 v189, 1.0, v184
	v_add_f32_e32 v191, 1.0, v185
	v_add_f32_e32 v192, 1.0, v186
	v_rcp_f32_e32 v182, v136
	v_rcp_f32_e32 v183, v149
	v_rcp_f32_e32 v184, v167
	v_rcp_f32_e32 v185, v187
	v_rcp_f32_e32 v186, v188
	v_rcp_f32_e32 v187, v189
	v_rcp_f32_e32 v188, v191
	v_rcp_f32_e32 v189, v192
	v_pk_mul_f32 v[160:161], v[160:161], v[182:183]
	v_pk_mul_f32 v[158:159], v[158:159], v[184:185]
	v_pk_mul_f32 v[172:173], v[172:173], v[186:187]
	v_pk_mul_f32 v[170:171], v[170:171], v[188:189]
	v_pk_mul_f32 v[160:161], v[176:177], v[160:161]
	v_pk_mul_f32 v[174:175], v[174:175], v[158:159]
	v_pk_mul_f32 v[172:173], v[180:181], v[172:173]
	v_pk_mul_f32 v[170:171], v[178:179], v[170:171]
	v_cvt_pk_bf16_f32 v158, v160, v161
	v_cvt_pk_bf16_f32 v159, v174, v175
	v_cvt_pk_bf16_f32 v160, v172, v173
	v_cvt_pk_bf16_f32 v161, v170, v171
	global_store_dwordx4 v[168:169], v[158:161], off
	s_cbranch_execnz .LBB0_1922

.LBB0_2001:
	v_mbcnt_lo_u32_b32 v235, -1, 0
	v_mbcnt_hi_u32_b32 v235, -1, v235
	v_lshrrev_b32_e32 v236, 2, v235
	v_and_b32_e32 v237, 3, v235
	v_lshl_add_u32 v232, v237, 4, v236
	v_lshlrev_b32_e32 v232, 2, v232
	v_and_b32_e32 v233, -16, v168
	v_or_b32_e32 v233, v233, v236
	v_lshlrev_b32_e32 v237, 2, v237
	v_and_b32_e32 v234, -13, v170
	v_or_b32_e32 v234, v234, v237
	ds_bpermute_b32 v127, v232, v127
	ds_bpermute_b32 v126, v232, v126
	ds_bpermute_b32 v125, v232, v125
	ds_bpermute_b32 v124, v232, v124
	ds_bpermute_b32 v123, v232, v123
	ds_bpermute_b32 v122, v232, v122
	ds_bpermute_b32 v121, v232, v121
	ds_bpermute_b32 v120, v232, v120
	ds_bpermute_b32 v119, v232, v119
	ds_bpermute_b32 v118, v232, v118
	ds_bpermute_b32 v117, v232, v117
	ds_bpermute_b32 v116, v232, v116
	ds_bpermute_b32 v115, v232, v115
	ds_bpermute_b32 v114, v232, v114
	ds_bpermute_b32 v113, v232, v113
	ds_bpermute_b32 v112, v232, v112
	ds_bpermute_b32 v111, v232, v111
	ds_bpermute_b32 v110, v232, v110
	ds_bpermute_b32 v109, v232, v109
	ds_bpermute_b32 v108, v232, v108
	ds_bpermute_b32 v107, v232, v107
	ds_bpermute_b32 v106, v232, v106
	ds_bpermute_b32 v105, v232, v105
	ds_bpermute_b32 v104, v232, v104
	ds_bpermute_b32 v103, v232, v103
	ds_bpermute_b32 v102, v232, v102
	ds_bpermute_b32 v101, v232, v101
	ds_bpermute_b32 v100, v232, v100
	ds_bpermute_b32 v99, v232, v99
	ds_bpermute_b32 v98, v232, v98
	ds_bpermute_b32 v97, v232, v97
	ds_bpermute_b32 v96, v232, v96
	ds_bpermute_b32 v95, v232, v95
	ds_bpermute_b32 v94, v232, v94
	ds_bpermute_b32 v93, v232, v93
	ds_bpermute_b32 v92, v232, v92
	ds_bpermute_b32 v91, v232, v91
	ds_bpermute_b32 v90, v232, v90
	ds_bpermute_b32 v89, v232, v89
	ds_bpermute_b32 v88, v232, v88
	ds_bpermute_b32 v87, v232, v87
	ds_bpermute_b32 v86, v232, v86
	ds_bpermute_b32 v85, v232, v85
	ds_bpermute_b32 v84, v232, v84
	ds_bpermute_b32 v83, v232, v83
	ds_bpermute_b32 v82, v232, v82
	ds_bpermute_b32 v81, v232, v81
	ds_bpermute_b32 v80, v232, v80
	ds_bpermute_b32 v79, v232, v79
	ds_bpermute_b32 v78, v232, v78
	ds_bpermute_b32 v77, v232, v77
	ds_bpermute_b32 v76, v232, v76
	ds_bpermute_b32 v75, v232, v75
	ds_bpermute_b32 v74, v232, v74
	ds_bpermute_b32 v73, v232, v73
	ds_bpermute_b32 v72, v232, v72
	ds_bpermute_b32 v71, v232, v71
	ds_bpermute_b32 v70, v232, v70
	ds_bpermute_b32 v69, v232, v69
	ds_bpermute_b32 v68, v232, v68
	ds_bpermute_b32 v67, v232, v67
	ds_bpermute_b32 v66, v232, v66
	ds_bpermute_b32 v65, v232, v65
	ds_bpermute_b32 v64, v232, v64
	ds_bpermute_b32 v63, v232, v63
	ds_bpermute_b32 v62, v232, v62
	ds_bpermute_b32 v61, v232, v61
	ds_bpermute_b32 v60, v232, v60
	ds_bpermute_b32 v59, v232, v59
	ds_bpermute_b32 v58, v232, v58
	ds_bpermute_b32 v57, v232, v57
	ds_bpermute_b32 v56, v232, v56
	ds_bpermute_b32 v55, v232, v55
	ds_bpermute_b32 v54, v232, v54
	ds_bpermute_b32 v53, v232, v53
	ds_bpermute_b32 v52, v232, v52
	ds_bpermute_b32 v51, v232, v51
	ds_bpermute_b32 v50, v232, v50
	ds_bpermute_b32 v49, v232, v49
	ds_bpermute_b32 v48, v232, v48
	ds_bpermute_b32 v47, v232, v47
	ds_bpermute_b32 v46, v232, v46
	ds_bpermute_b32 v45, v232, v45
	ds_bpermute_b32 v44, v232, v44
	ds_bpermute_b32 v43, v232, v43
	ds_bpermute_b32 v42, v232, v42
	ds_bpermute_b32 v41, v232, v41
	ds_bpermute_b32 v40, v232, v40
	ds_bpermute_b32 v39, v232, v39
	ds_bpermute_b32 v38, v232, v38
	ds_bpermute_b32 v37, v232, v37
	ds_bpermute_b32 v36, v232, v36
	ds_bpermute_b32 v35, v232, v35
	ds_bpermute_b32 v34, v232, v34
	ds_bpermute_b32 v33, v232, v33
	ds_bpermute_b32 v32, v232, v32
	ds_bpermute_b32 v31, v232, v31
	ds_bpermute_b32 v30, v232, v30
	ds_bpermute_b32 v29, v232, v29
	ds_bpermute_b32 v28, v232, v28
	ds_bpermute_b32 v27, v232, v27
	ds_bpermute_b32 v26, v232, v26
	ds_bpermute_b32 v25, v232, v25
	ds_bpermute_b32 v24, v232, v24
	ds_bpermute_b32 v23, v232, v23
	ds_bpermute_b32 v22, v232, v22
	ds_bpermute_b32 v21, v232, v21
	ds_bpermute_b32 v20, v232, v20
	ds_bpermute_b32 v19, v232, v19
	ds_bpermute_b32 v18, v232, v18
	ds_bpermute_b32 v17, v232, v17
	ds_bpermute_b32 v16, v232, v16
	ds_bpermute_b32 v15, v232, v15
	ds_bpermute_b32 v14, v232, v14
	ds_bpermute_b32 v13, v232, v13
	ds_bpermute_b32 v12, v232, v12
	ds_bpermute_b32 v11, v232, v11
	ds_bpermute_b32 v10, v232, v10
	ds_bpermute_b32 v9, v232, v9
	ds_bpermute_b32 v8, v232, v8
	ds_bpermute_b32 v7, v232, v7
	ds_bpermute_b32 v6, v232, v6
	ds_bpermute_b32 v5, v232, v5
	ds_bpermute_b32 v4, v232, v4
	ds_bpermute_b32 v3, v232, v3
	ds_bpermute_b32 v2, v232, v2
	ds_bpermute_b32 v1, v232, v1
	ds_bpermute_b32 v0, v232, v0
	s_waitcnt lgkmcnt(0)
	v_lshl_add_u32 v158, s52, 8, v233
	v_lshl_or_b32 v156, s51, 8, v234
	v_ashrrev_i32_e32 v159, 31, v158
	v_lshlrev_b64 v[128:129], 12, v[158:159]
	v_ashrrev_i32_e32 v157, 31, v156
	v_lshl_add_u64 v[128:129], s[8:9], 0, v[128:129]
	v_lshlrev_b64 v[130:131], 2, v[156:157]
	v_lshl_add_u64 v[188:189], v[128:129], 0, v[130:131]
	global_load_dwordx4 v[164:167], v[188:189], off
	global_load_dwordx4 v[176:179], v[188:189], off offset:64
	global_load_dwordx4 v[180:183], v[188:189], off offset:512
	global_load_dwordx4 v[184:187], v[188:189], off offset:576
	v_or_b32_e32 v160, 16, v158
	v_ashrrev_i32_e32 v161, 31, v160
	v_lshlrev_b64 v[128:129], 12, v[160:161]
	v_lshl_add_u64 v[128:129], s[8:9], 0, v[128:129]
	v_lshl_add_u64 v[162:163], v[128:129], 0, v[130:131]
	global_load_dwordx4 v[140:143], v[162:163], off
	global_load_dwordx4 v[136:139], v[162:163], off offset:64
	global_load_dwordx4 v[132:135], v[162:163], off offset:512
	global_load_dwordx4 v[128:131], v[162:163], off offset:576
	v_lshlrev_b64 v[192:193], 11, v[158:159]
	v_lshl_add_u64 v[192:193], s[12:13], 0, v[192:193]
	v_and_b32_e32 v191, 64, v174
	v_lshl_add_u64 v[192:193], v[156:157], 1, v[192:193]
	v_xor_b32_e32 v175, 1, v174
	v_add_u32_e32 v191, 64, v191
	v_cmp_lt_i32_e32 vcc, v175, v191
	v_xor_b32_e32 v194, 2, v174
	s_waitcnt vmcnt(0) lgkmcnt(0)
	v_pk_fma_f32 v[126:127], v[126:127], 0.5, v[166:167] op_sel_hi:[1,0,1]
	v_pk_fma_f32 v[124:125], v[124:125], 0.5, v[164:165] op_sel_hi:[1,0,1]
	v_pk_fma_f32 v[122:123], v[122:123], 0.5, v[178:179] op_sel_hi:[1,0,1]
	v_pk_fma_f32 v[120:121], v[120:121], 0.5, v[176:177] op_sel_hi:[1,0,1]
	v_pk_fma_f32 v[118:119], v[118:119], 0.5, v[182:183] op_sel_hi:[1,0,1]
	v_pk_fma_f32 v[116:117], v[116:117], 0.5, v[180:181] op_sel_hi:[1,0,1]
	v_pk_fma_f32 v[164:165], v[112:113], 0.5, v[184:185] op_sel_hi:[1,0,1]
	v_mul_f32_e32 v178, v125, v125
	v_mul_f32_e32 v179, v127, v127
	global_store_dwordx4 v[188:189], v[124:127], off
	v_cvt_pk_bf16_f32 v112, v124, v125
	v_cvt_pk_bf16_f32 v113, v126, v127
	v_mul_f32_e32 v125, v121, v121
	v_mul_f32_e32 v127, v123, v123
	v_pk_fma_f32 v[166:167], v[114:115], 0.5, v[186:187] op_sel_hi:[1,0,1]
	v_mul_f32_e32 v180, v117, v117
	v_mul_f32_e32 v181, v119, v119
	v_fmac_f32_e32 v178, v124, v124
	v_fmac_f32_e32 v179, v126, v126
	v_fmac_f32_e32 v125, v120, v120
	v_fmac_f32_e32 v127, v122, v122
	v_mul_f32_e32 v182, v165, v165
	v_mul_f32_e32 v183, v167, v167
	global_store_dwordx2 v[192:193], v[112:113], off
	v_fmac_f32_e32 v180, v116, v116
	v_fmac_f32_e32 v181, v118, v118
	v_add_f32_e32 v112, v178, v179
	v_add_f32_e32 v113, v125, v127
	v_fmac_f32_e32 v182, v164, v164
	v_fmac_f32_e32 v183, v166, v166
	v_add_f32_e32 v124, v180, v181
	v_add_f32_e32 v112, v112, v113
	v_cndmask_b32_e32 v175, v174, v175, vcc
	v_add_f32_e32 v125, v182, v183
	v_add_f32_e32 v112, v112, v124
	v_lshlrev_b32_e32 v175, 2, v175
	v_add_f32_e32 v112, v112, v125
	ds_bpermute_b32 v113, v175, v112
	v_cmp_lt_i32_e32 vcc, v194, v191
	v_cvt_pk_bf16_f32 v176, v116, v117
	v_cvt_pk_bf16_f32 v114, v120, v121
	v_cndmask_b32_e32 v191, v174, v194, vcc
	v_cvt_pk_bf16_f32 v115, v122, v123
	v_cvt_pk_bf16_f32 v177, v118, v119
	global_store_dwordx4 v[188:189], v[120:123], off offset:64
	global_store_dwordx2 v[192:193], v[114:115], off offset:32
	global_store_dwordx4 v[188:189], v[116:119], off offset:512
	global_store_dwordx2 v[192:193], v[176:177], off offset:256
	s_waitcnt lgkmcnt(0)
	v_add_f32_e32 v112, v112, v113
	v_lshlrev_b32_e32 v176, 2, v191
	ds_bpermute_b32 v113, v176, v112
	v_cvt_pk_bf16_f32 v114, v164, v165
	v_cvt_pk_bf16_f32 v115, v166, v167
	global_store_dwordx4 v[188:189], v[164:167], off offset:576
	global_store_dwordx2 v[192:193], v[114:115], off offset:288
	s_mov_b32 vcc_lo, 0x11111111
	s_mov_b32 vcc_hi, 0x11111111
	s_and_saveexec_b64 s[22:23], vcc
	s_cbranch_execz .LBB0_2003
	v_lshl_add_u64 v[114:115], v[158:159], 2, s[14:15]
	s_waitcnt lgkmcnt(0)
	v_add_f32_e32 v112, v112, v113
	global_atomic_add_f32 v[114:115], v112, off
